# GEMM K-loops: the per-phase s_setprio 1/0 flips around the MFMA blocks removed in all 14 loops (A/B on the FFN-up GEMM with an amplified run: about 2 percent faster without them); otherwise as v94
# speedup vs baseline: 1.0042x; 1.0035x over previous
; #define PG8_STAGE(bufoff, gbase, voff) do { _Pragma("unroll") for (int _i = 0; _i < 2; ++_i) \
;         __builtin_amdgcn_global_load_lds((const unsigned*)((const char*)(gbase) + (voff)[_i]), (PG8_LAS unsigned*)(lds + (bufoff) + ldsw + _i * 8192), 16, 0, 0); } while (0)
; #define PG8_LDA(dst, b, h) do { _Pragma("unroll") for (int m = 0; m < 4; ++m) _Pragma("unroll") for (int k = 0; k < 2; ++k) dst[m][k] = *(const PG8_LAS bf16x8*)(lds + PG8_SA(b, h) + aoff + m * 2048 + k * 1024); } while (0)
; #define PG8_LDB(dst, b, h) do { _Pragma("unroll") for (int n = 0; n < 2; ++n) _Pragma("unroll") for (int k = 0; k < 2; ++k) dst[n][k] = *(const PG8_LAS bf16x8*)(lds + PG8_SB(b, h) + boff + n * 2048 + k * 1024); } while (0)
; #define PG8_MMA(ai, bj, At, Bt) do { __builtin_amdgcn_s_setprio(1); _Pragma("unroll") for (int m = 0; m < 4; ++m) _Pragma("unroll") for (int n = 0; n < 2; ++n) _Pragma("unroll") for (int k = 0; k < 2; ++k) \
;         acc[ai][bj][m][n] = __builtin_amdgcn_mfma_f32_16x16x32_bf16(Bt[n][k], At[m][k], acc[ai][bj][m][n], 0, 0, 0); __builtin_amdgcn_s_setprio(0); } while (0)
; #define PG8_WAIT_V(n) asm volatile("s_waitcnt vmcnt(" #n ")" ::: "memory")
; #define PG8_WAIT_L(n) asm volatile("s_waitcnt lgkmcnt(" #n ")" ::: "memory")
; template <class Epi, class Sched, bool ALIGN_EPI = false, bool SP2 = false>
; __device__ __forceinline__ void gemm_phase(PG8_LAS unsigned char* lds, const Gemm g, const Sched& S, const Epi& E) {
;     ...
;             const bool last = (t == nt - 2);
;             const char* a1 = cA + (size_t)(t + 1) * kstep;
;             const char* a2 = last ? nA : cA + (size_t)(t + 2) * kstep; const char* b2 = last ? nB : cB + (size_t)(t + 2) * kstep;
;             const char* a3 = a2 + kstep; const char* b3 = b2 + kstep;
;             if (last && has_next) S.a_ready(nxt);
;             if constexpr (SP2) {
;             PG8_LDB(B0, 0, 0); PG8_LDB(B1, 0, 1); PG8_SCHED; PG8_LDA(At, 0, 0); PG8_STAGE(PG8_SA(1, 1), a1 + hstep, voffA);
;             PG8_WAIT_V(8); PG8_WAIT_L(0); PG8_BAR; PG8_MMA(0, 0, At, B0); PG8_MMA(0, 1, At, B1); PG8_BAR; PG8_SCHED;
;             PG8_LDA(At, 0, 1); PG8_STAGE(PG8_SB(0, 0), b2, voffB); PG8_STAGE(PG8_SB(0, 1), b2 + hstep, voffB); PG8_STAGE(PG8_SA(0, 0), a2, voffA);
;             PG8_WAIT_V(8); PG8_WAIT_L(0); PG8_BAR; PG8_MMA(1, 0, At, B0); PG8_MMA(1, 1, At, B1); PG8_BAR; PG8_SCHED;
.LBB0_53:
	s_add_i32 s66, s0, 2
	s_add_u32 s67, s24, 0x80
	s_addc_u32 s1, s25, 0
	s_add_i32 s70, 0, 0x10000
	s_cmp_eq_u32 s59, s0
	s_cselect_b32 s1, s35, s1
	s_cselect_b32 s0, s34, s67
	v_add_u32_e32 v160, s70, v162
	s_cselect_b32 s69, s41, s19
	s_cselect_b32 s68, s40, s18
	s_add_i32 s67, 0, 0x14000
	ds_read_b128 v[148:151], v160
	ds_read_b128 v[152:155], v160 offset:1024
	ds_read_b128 v[156:159], v160 offset:2048
	ds_read_b128 v[164:167], v160 offset:3072
	v_add_u32_e32 v160, s67, v162
	ds_read_b128 v[168:171], v160
	ds_read_b128 v[172:175], v160 offset:1024
	ds_read_b128 v[176:179], v160 offset:2048
	ds_read_b128 v[180:183], v160 offset:3072
	v_lshl_add_u64 v[160:161], s[24:25], 0, v[144:145]
	s_add_i32 m0, s50, 0xc000
	ds_read_b128 v[184:187], v163
	ds_read_b128 v[188:191], v163 offset:1024
	ds_read_b128 v[192:195], v163 offset:2048
	ds_read_b128 v[196:199], v163 offset:3072
	ds_read_b128 v[204:207], v163 offset:4096
	ds_read_b128 v[208:211], v163 offset:5120
	ds_read_b128 v[212:215], v163 offset:6144
	ds_read_b128 v[236:239], v163 offset:7168
	global_load_lds_dwordx4 v[160:161], off
	v_lshl_add_u64 v[160:161], s[24:25], 0, v[146:147]
	s_add_i32 m0, s50, 0xe000
	s_nop 0
	global_load_lds_dwordx4 v[160:161], off
	s_waitcnt vmcnt(8)
	s_waitcnt lgkmcnt(0)
	s_barrier
	s_waitcnt lgkmcnt(0)
	v_mfma_f32_16x16x32_bf16 v[132:135], v[148:151], v[184:187], v[132:135]
	v_mfma_f32_16x16x32_bf16 v[136:139], v[156:159], v[184:187], v[136:139]
	v_mfma_f32_16x16x32_bf16 v[128:131], v[148:151], v[192:195], v[128:131]
	v_mfma_f32_16x16x32_bf16 v[124:127], v[156:159], v[192:195], v[124:127]
	v_mfma_f32_16x16x32_bf16 v[120:123], v[148:151], v[204:207], v[120:123]
	v_mfma_f32_16x16x32_bf16 v[116:119], v[156:159], v[204:207], v[116:119]
	v_mfma_f32_16x16x32_bf16 v[112:115], v[148:151], v[212:215], v[112:115]
	v_mfma_f32_16x16x32_bf16 v[108:111], v[156:159], v[212:215], v[108:111]
	v_mfma_f32_16x16x32_bf16 v[132:135], v[152:155], v[188:191], v[132:135]
	v_mfma_f32_16x16x32_bf16 v[136:139], v[164:167], v[188:191], v[136:139]
	v_mfma_f32_16x16x32_bf16 v[128:131], v[152:155], v[196:199], v[128:131]
	v_mfma_f32_16x16x32_bf16 v[124:127], v[164:167], v[196:199], v[124:127]
	v_mfma_f32_16x16x32_bf16 v[120:123], v[152:155], v[208:211], v[120:123]
	v_mfma_f32_16x16x32_bf16 v[116:119], v[164:167], v[208:211], v[116:119]
	v_mfma_f32_16x16x32_bf16 v[112:115], v[152:155], v[236:239], v[112:115]
	v_mfma_f32_16x16x32_bf16 v[108:111], v[164:167], v[236:239], v[108:111]
	v_mfma_f32_16x16x32_bf16 v[72:75], v[168:171], v[184:187], v[72:75]
	v_mfma_f32_16x16x32_bf16 v[68:71], v[176:179], v[184:187], v[68:71]
	v_mfma_f32_16x16x32_bf16 v[64:67], v[168:171], v[192:195], v[64:67]
	v_mfma_f32_16x16x32_bf16 v[60:63], v[176:179], v[192:195], v[60:63]
	v_mfma_f32_16x16x32_bf16 v[56:59], v[168:171], v[204:207], v[56:59]
	v_mfma_f32_16x16x32_bf16 v[52:55], v[176:179], v[204:207], v[52:55]
	v_mfma_f32_16x16x32_bf16 v[48:51], v[168:171], v[212:215], v[48:51]
	v_mfma_f32_16x16x32_bf16 v[32:35], v[176:179], v[212:215], v[32:35]
	v_mfma_f32_16x16x32_bf16 v[72:75], v[172:175], v[188:191], v[72:75]
	v_mfma_f32_16x16x32_bf16 v[68:71], v[180:183], v[188:191], v[68:71]
	v_mfma_f32_16x16x32_bf16 v[64:67], v[172:175], v[196:199], v[64:67]
	v_mfma_f32_16x16x32_bf16 v[60:63], v[180:183], v[196:199], v[60:63]
	v_mfma_f32_16x16x32_bf16 v[56:59], v[172:175], v[208:211], v[56:59]
	v_mfma_f32_16x16x32_bf16 v[52:55], v[180:183], v[208:211], v[52:55]
	v_mfma_f32_16x16x32_bf16 v[48:51], v[172:175], v[236:239], v[48:51]
	v_mfma_f32_16x16x32_bf16 v[32:35], v[180:183], v[236:239], v[32:35]
	s_barrier
	s_add_i32 s70, s70, s43
	v_lshl_add_u64 v[160:161], s[68:69], 0, v[140:141]
	s_mov_b32 m0, s70
	ds_read_b128 v[184:187], v163 offset:16384
	ds_read_b128 v[188:191], v163 offset:17408
	ds_read_b128 v[192:195], v163 offset:18432
	ds_read_b128 v[196:199], v163 offset:19456
	ds_read_b128 v[204:207], v163 offset:20480
	ds_read_b128 v[208:211], v163 offset:21504
	ds_read_b128 v[212:215], v163 offset:22528
	ds_read_b128 v[236:239], v163 offset:23552
	global_load_lds_dwordx4 v[160:161], off
	s_add_i32 m0, s70, 0x2000
	v_lshl_add_u64 v[240:241], s[68:69], 0, v[38:39]
	s_add_u32 s68, s68, s10
	s_addc_u32 s69, s69, s11
	s_add_i32 s67, s67, s43
	global_load_lds_dwordx4 v[240:241], off
	v_lshl_add_u64 v[242:243], s[68:69], 0, v[140:141]
	s_mov_b32 m0, s67
	v_lshl_add_u64 v[244:245], s[68:69], 0, v[38:39]
	global_load_lds_dwordx4 v[242:243], off
	s_add_i32 m0, s67, 0x2000
	v_lshl_add_u64 v[246:247], s[0:1], 0, v[142:143]
	global_load_lds_dwordx4 v[244:245], off
	s_mov_b32 m0, s50
	v_lshl_add_u64 v[248:249], s[0:1], 0, v[42:43]
	global_load_lds_dwordx4 v[246:247], off
	s_mov_b32 m0, s51
	s_nop 0
	global_load_lds_dwordx4 v[248:249], off
	s_waitcnt vmcnt(8)
	s_waitcnt lgkmcnt(0)
	s_barrier
; #define PG8_STAGE(bufoff, gbase, voff) do { _Pragma("unroll") for (int _i = 0; _i < 2; ++_i) \
;         __builtin_amdgcn_global_load_lds((const unsigned*)((const char*)(gbase) + (voff)[_i]), (PG8_LAS unsigned*)(lds + (bufoff) + ldsw + _i * 8192), 16, 0, 0); } while (0)
; #define PG8_LDA(dst, b, h) do { _Pragma("unroll") for (int m = 0; m < 4; ++m) _Pragma("unroll") for (int k = 0; k < 2; ++k) dst[m][k] = *(const PG8_LAS bf16x8*)(lds + PG8_SA(b, h) + aoff + m * 2048 + k * 1024); } while (0)
; #define PG8_LDB(dst, b, h) do { _Pragma("unroll") for (int n = 0; n < 2; ++n) _Pragma("unroll") for (int k = 0; k < 2; ++k) dst[n][k] = *(const PG8_LAS bf16x8*)(lds + PG8_SB(b, h) + boff + n * 2048 + k * 1024); } while (0)
; #define PG8_MMA(ai, bj, At, Bt) do { __builtin_amdgcn_s_setprio(1); _Pragma("unroll") for (int m = 0; m < 4; ++m) _Pragma("unroll") for (int n = 0; n < 2; ++n) _Pragma("unroll") for (int k = 0; k < 2; ++k) \
;         acc[ai][bj][m][n] = __builtin_amdgcn_mfma_f32_16x16x32_bf16(Bt[n][k], At[m][k], acc[ai][bj][m][n], 0, 0, 0); __builtin_amdgcn_s_setprio(0); } while (0)
; #define PG8_WAIT_V(n) asm volatile("s_waitcnt vmcnt(" #n ")" ::: "memory")
; #define PG8_WAIT_L(n) asm volatile("s_waitcnt lgkmcnt(" #n ")" ::: "memory")
; #define PG8_BAR __builtin_amdgcn_s_barrier()
; #define PG8_SCHED __builtin_amdgcn_sched_barrier(0)
; template <class Epi, class Sched, bool ALIGN_EPI = false, bool SP2 = false>
; __device__ __forceinline__ void gemm_phase(PG8_LAS unsigned char* lds, const Gemm g, const Sched& S, const Epi& E) {
;     ...
;             PG8_WAIT_V(8); PG8_WAIT_L(0); PG8_BAR; PG8_MMA(1, 0, At, B0); PG8_MMA(1, 1, At, B1); PG8_BAR; PG8_SCHED;
;             PG8_LDB(B0, 1, 0); PG8_LDB(B1, 1, 1); PG8_SCHED; PG8_LDA(At, 1, 0); PG8_STAGE(PG8_SA(0, 1), a2 + hstep, voffA);
;             PG8_WAIT_V(8); PG8_WAIT_L(0); PG8_BAR; PG8_MMA(0, 0, At, B0); PG8_MMA(0, 1, At, B1); PG8_BAR; PG8_SCHED;
	s_waitcnt lgkmcnt(0)
	v_mfma_f32_16x16x32_bf16 v[104:107], v[148:151], v[184:187], v[104:107]
	v_mfma_f32_16x16x32_bf16 v[100:103], v[156:159], v[184:187], v[100:103]
	v_mfma_f32_16x16x32_bf16 v[96:99], v[148:151], v[192:195], v[96:99]
	v_mfma_f32_16x16x32_bf16 v[92:95], v[156:159], v[192:195], v[92:95]
	v_mfma_f32_16x16x32_bf16 v[88:91], v[148:151], v[204:207], v[88:91]
	v_mfma_f32_16x16x32_bf16 v[84:87], v[156:159], v[204:207], v[84:87]
	v_mfma_f32_16x16x32_bf16 v[80:83], v[148:151], v[212:215], v[80:83]
	v_mfma_f32_16x16x32_bf16 v[76:79], v[156:159], v[212:215], v[76:79]
	v_mfma_f32_16x16x32_bf16 v[104:107], v[152:155], v[188:191], v[104:107]
	v_mfma_f32_16x16x32_bf16 v[100:103], v[164:167], v[188:191], v[100:103]
	v_mfma_f32_16x16x32_bf16 v[96:99], v[152:155], v[196:199], v[96:99]
	v_mfma_f32_16x16x32_bf16 v[92:95], v[164:167], v[196:199], v[92:95]
	v_mfma_f32_16x16x32_bf16 v[88:91], v[152:155], v[208:211], v[88:91]
	v_mfma_f32_16x16x32_bf16 v[84:87], v[164:167], v[208:211], v[84:87]
	v_mfma_f32_16x16x32_bf16 v[80:83], v[152:155], v[236:239], v[80:83]
	v_mfma_f32_16x16x32_bf16 v[76:79], v[164:167], v[236:239], v[76:79]
	v_mfma_f32_16x16x32_bf16 v[28:31], v[168:171], v[184:187], v[28:31]
	v_mfma_f32_16x16x32_bf16 v[24:27], v[176:179], v[184:187], v[24:27]
	v_mfma_f32_16x16x32_bf16 v[20:23], v[168:171], v[192:195], v[20:23]
	v_mfma_f32_16x16x32_bf16 v[16:19], v[176:179], v[192:195], v[16:19]
	v_mfma_f32_16x16x32_bf16 v[12:15], v[168:171], v[204:207], v[12:15]
	v_mfma_f32_16x16x32_bf16 v[8:11], v[176:179], v[204:207], v[8:11]
	v_mfma_f32_16x16x32_bf16 v[4:7], v[168:171], v[212:215], v[4:7]
	v_mfma_f32_16x16x32_bf16 v[0:3], v[176:179], v[212:215], v[0:3]
	v_mfma_f32_16x16x32_bf16 v[28:31], v[172:175], v[188:191], v[28:31]
	v_mfma_f32_16x16x32_bf16 v[24:27], v[180:183], v[188:191], v[24:27]
	v_mfma_f32_16x16x32_bf16 v[20:23], v[172:175], v[196:199], v[20:23]
	v_mfma_f32_16x16x32_bf16 v[16:19], v[180:183], v[196:199], v[16:19]
	v_mfma_f32_16x16x32_bf16 v[12:15], v[172:175], v[208:211], v[12:15]
	v_mfma_f32_16x16x32_bf16 v[8:11], v[180:183], v[208:211], v[8:11]
	v_mfma_f32_16x16x32_bf16 v[4:7], v[172:175], v[236:239], v[4:7]
	v_mfma_f32_16x16x32_bf16 v[0:3], v[180:183], v[236:239], v[0:3]
	s_barrier
	s_add_i32 s67, 0, 0x18000
	s_add_i32 s68, 0, 0x1c000
	v_add_u32_e32 v164, s67, v162
	v_add_u32_e32 v180, s68, v162
	ds_read_b128 v[148:151], v164
	ds_read_b128 v[152:155], v164 offset:1024
	ds_read_b128 v[156:159], v164 offset:2048
	ds_read_b128 v[164:167], v164 offset:3072
	ds_read_b128 v[168:171], v180
	ds_read_b128 v[172:175], v180 offset:1024
	ds_read_b128 v[176:179], v180 offset:2048
	ds_read_b128 v[180:183], v180 offset:3072
	s_add_u32 s0, s0, s10
	s_addc_u32 s1, s1, s11
	s_mov_b32 m0, s52
	v_lshl_add_u64 v[250:251], s[0:1], 0, v[142:143]
	ds_read_b128 v[184:187], v163 offset:32768
	ds_read_b128 v[188:191], v163 offset:33792
	ds_read_b128 v[192:195], v163 offset:34816
	ds_read_b128 v[196:199], v163 offset:35840
	ds_read_b128 v[204:207], v163 offset:36864
	ds_read_b128 v[208:211], v163 offset:37888
	ds_read_b128 v[212:215], v163 offset:38912
	ds_read_b128 v[236:239], v163 offset:39936
	global_load_lds_dwordx4 v[250:251], off
	v_lshl_add_u64 v[250:251], s[0:1], 0, v[42:43]
	s_mov_b32 m0, s53
	s_nop 0
	global_load_lds_dwordx4 v[250:251], off
	s_waitcnt vmcnt(8)
	s_waitcnt lgkmcnt(0)
	s_barrier
	s_waitcnt lgkmcnt(0)
	v_mfma_f32_16x16x32_bf16 v[132:135], v[148:151], v[184:187], v[132:135]
	v_mfma_f32_16x16x32_bf16 v[136:139], v[156:159], v[184:187], v[136:139]
	v_mfma_f32_16x16x32_bf16 v[128:131], v[148:151], v[192:195], v[128:131]
	v_mfma_f32_16x16x32_bf16 v[124:127], v[156:159], v[192:195], v[124:127]
	v_mfma_f32_16x16x32_bf16 v[120:123], v[148:151], v[204:207], v[120:123]
	v_mfma_f32_16x16x32_bf16 v[116:119], v[156:159], v[204:207], v[116:119]
	v_mfma_f32_16x16x32_bf16 v[112:115], v[148:151], v[212:215], v[112:115]
	v_mfma_f32_16x16x32_bf16 v[108:111], v[156:159], v[212:215], v[108:111]
	v_mfma_f32_16x16x32_bf16 v[132:135], v[152:155], v[188:191], v[132:135]
	v_mfma_f32_16x16x32_bf16 v[136:139], v[164:167], v[188:191], v[136:139]
	v_mfma_f32_16x16x32_bf16 v[128:131], v[152:155], v[196:199], v[128:131]
	v_mfma_f32_16x16x32_bf16 v[124:127], v[164:167], v[196:199], v[124:127]
	v_mfma_f32_16x16x32_bf16 v[120:123], v[152:155], v[208:211], v[120:123]
	v_mfma_f32_16x16x32_bf16 v[116:119], v[164:167], v[208:211], v[116:119]
	v_mfma_f32_16x16x32_bf16 v[112:115], v[152:155], v[236:239], v[112:115]
	v_mfma_f32_16x16x32_bf16 v[108:111], v[164:167], v[236:239], v[108:111]
	v_mfma_f32_16x16x32_bf16 v[72:75], v[168:171], v[184:187], v[72:75]
	v_mfma_f32_16x16x32_bf16 v[68:71], v[176:179], v[184:187], v[68:71]
	v_mfma_f32_16x16x32_bf16 v[64:67], v[168:171], v[192:195], v[64:67]
	v_mfma_f32_16x16x32_bf16 v[60:63], v[176:179], v[192:195], v[60:63]
	v_mfma_f32_16x16x32_bf16 v[56:59], v[168:171], v[204:207], v[56:59]
	v_mfma_f32_16x16x32_bf16 v[52:55], v[176:179], v[204:207], v[52:55]
	v_mfma_f32_16x16x32_bf16 v[48:51], v[168:171], v[212:215], v[48:51]
	v_mfma_f32_16x16x32_bf16 v[32:35], v[176:179], v[212:215], v[32:35]
	v_mfma_f32_16x16x32_bf16 v[72:75], v[172:175], v[188:191], v[72:75]
	v_mfma_f32_16x16x32_bf16 v[68:71], v[180:183], v[188:191], v[68:71]
	v_mfma_f32_16x16x32_bf16 v[64:67], v[172:175], v[196:199], v[64:67]
	v_mfma_f32_16x16x32_bf16 v[60:63], v[180:183], v[196:199], v[60:63]
	v_mfma_f32_16x16x32_bf16 v[56:59], v[172:175], v[208:211], v[56:59]
	v_mfma_f32_16x16x32_bf16 v[52:55], v[180:183], v[208:211], v[52:55]
	v_mfma_f32_16x16x32_bf16 v[48:51], v[172:175], v[236:239], v[48:51]
	v_mfma_f32_16x16x32_bf16 v[32:35], v[180:183], v[236:239], v[32:35]
	s_barrier
; #define PG8_STAGE(bufoff, gbase, voff) do { _Pragma("unroll") for (int _i = 0; _i < 2; ++_i) \
;         __builtin_amdgcn_global_load_lds((const unsigned*)((const char*)(gbase) + (voff)[_i]), (PG8_LAS unsigned*)(lds + (bufoff) + ldsw + _i * 8192), 16, 0, 0); } while (0)
; #define PG8_LDA(dst, b, h) do { _Pragma("unroll") for (int m = 0; m < 4; ++m) _Pragma("unroll") for (int k = 0; k < 2; ++k) dst[m][k] = *(const PG8_LAS bf16x8*)(lds + PG8_SA(b, h) + aoff + m * 2048 + k * 1024); } while (0)
; #define PG8_MMA(ai, bj, At, Bt) do { __builtin_amdgcn_s_setprio(1); _Pragma("unroll") for (int m = 0; m < 4; ++m) _Pragma("unroll") for (int n = 0; n < 2; ++n) _Pragma("unroll") for (int k = 0; k < 2; ++k) \
;         acc[ai][bj][m][n] = __builtin_amdgcn_mfma_f32_16x16x32_bf16(Bt[n][k], At[m][k], acc[ai][bj][m][n], 0, 0, 0); __builtin_amdgcn_s_setprio(0); } while (0)
; #define PG8_WAIT_V(n) asm volatile("s_waitcnt vmcnt(" #n ")" ::: "memory")
; #define PG8_WAIT_L(n) asm volatile("s_waitcnt lgkmcnt(" #n ")" ::: "memory")
; #define PG8_BAR __builtin_amdgcn_s_barrier()
; #define PG8_SCHED __builtin_amdgcn_sched_barrier(0)
; template <class Epi, class Sched, bool ALIGN_EPI = false, bool SP2 = false>
; __device__ __forceinline__ void gemm_phase(PG8_LAS unsigned char* lds, const Gemm g, const Sched& S, const Epi& E) {
;     ...
;         for (int t = 0; t < nt; t += 2) {
;             const bool last = (t == nt - 2);
;             const char* a1 = cA + (size_t)(t + 1) * kstep;
;             const char* a2 = last ? nA : cA + (size_t)(t + 2) * kstep; const char* b2 = last ? nB : cB + (size_t)(t + 2) * kstep;
;     ...
;             PG8_LDA(At, 1, 1); PG8_STAGE(PG8_SB(1, 0), b3, voffB); PG8_STAGE(PG8_SB(1, 1), b3 + hstep, voffB); PG8_STAGE(PG8_SA(1, 0), a3, voffA);
;             PG8_WAIT_V(8); PG8_WAIT_L(0); PG8_BAR; PG8_MMA(1, 0, At, B0); PG8_MMA(1, 1, At, B1); PG8_BAR; PG8_SCHED;
	s_add_i32 s0, s67, s43
	v_lshl_add_u64 v[160:161], v[160:161], 0, s[22:23]
	s_mov_b32 m0, s0
	ds_read_b128 v[184:187], v163 offset:49152
	ds_read_b128 v[188:191], v163 offset:50176
	ds_read_b128 v[192:195], v163 offset:51200
	ds_read_b128 v[196:199], v163 offset:52224
	ds_read_b128 v[204:207], v163 offset:53248
	ds_read_b128 v[208:211], v163 offset:54272
	ds_read_b128 v[212:215], v163 offset:55296
	ds_read_b128 v[236:239], v163 offset:56320
	global_load_lds_dwordx4 v[160:161], off
	v_lshl_add_u64 v[160:161], v[240:241], 0, s[22:23]
	s_add_i32 m0, s0, 0x2000
	s_add_i32 s0, s68, s43
	global_load_lds_dwordx4 v[160:161], off
	v_lshl_add_u64 v[160:161], v[242:243], 0, s[22:23]
	s_mov_b32 m0, s0
	s_nop 0
	global_load_lds_dwordx4 v[160:161], off
	v_lshl_add_u64 v[160:161], v[244:245], 0, s[22:23]
	s_add_i32 m0, s0, 0x2000
	s_nop 0
	global_load_lds_dwordx4 v[160:161], off
	v_lshl_add_u64 v[160:161], v[246:247], 0, s[22:23]
	s_mov_b32 m0, s57
	s_nop 0
	global_load_lds_dwordx4 v[160:161], off
	v_lshl_add_u64 v[160:161], v[248:249], 0, s[22:23]
	s_mov_b32 m0, s58
	s_nop 0
	global_load_lds_dwordx4 v[160:161], off
	s_waitcnt vmcnt(8)
	s_waitcnt lgkmcnt(0)
	s_barrier
	s_waitcnt lgkmcnt(0)
	v_mfma_f32_16x16x32_bf16 v[104:107], v[148:151], v[184:187], v[104:107]
	v_mfma_f32_16x16x32_bf16 v[100:103], v[156:159], v[184:187], v[100:103]
	v_mfma_f32_16x16x32_bf16 v[96:99], v[148:151], v[192:195], v[96:99]
	v_mfma_f32_16x16x32_bf16 v[92:95], v[156:159], v[192:195], v[92:95]
	v_mfma_f32_16x16x32_bf16 v[88:91], v[148:151], v[204:207], v[88:91]
	v_mfma_f32_16x16x32_bf16 v[84:87], v[156:159], v[204:207], v[84:87]
	v_mfma_f32_16x16x32_bf16 v[80:83], v[148:151], v[212:215], v[80:83]
	v_mfma_f32_16x16x32_bf16 v[76:79], v[156:159], v[212:215], v[76:79]
	v_mfma_f32_16x16x32_bf16 v[104:107], v[152:155], v[188:191], v[104:107]
	v_mfma_f32_16x16x32_bf16 v[100:103], v[164:167], v[188:191], v[100:103]
	v_mfma_f32_16x16x32_bf16 v[96:99], v[152:155], v[196:199], v[96:99]
	v_mfma_f32_16x16x32_bf16 v[92:95], v[164:167], v[196:199], v[92:95]
	v_mfma_f32_16x16x32_bf16 v[88:91], v[152:155], v[208:211], v[88:91]
	v_mfma_f32_16x16x32_bf16 v[84:87], v[164:167], v[208:211], v[84:87]
	v_mfma_f32_16x16x32_bf16 v[80:83], v[152:155], v[236:239], v[80:83]
	v_mfma_f32_16x16x32_bf16 v[76:79], v[164:167], v[236:239], v[76:79]
	v_mfma_f32_16x16x32_bf16 v[28:31], v[168:171], v[184:187], v[28:31]
	v_mfma_f32_16x16x32_bf16 v[24:27], v[176:179], v[184:187], v[24:27]
	v_mfma_f32_16x16x32_bf16 v[20:23], v[168:171], v[192:195], v[20:23]
	v_mfma_f32_16x16x32_bf16 v[16:19], v[176:179], v[192:195], v[16:19]
	v_mfma_f32_16x16x32_bf16 v[12:15], v[168:171], v[204:207], v[12:15]
	v_mfma_f32_16x16x32_bf16 v[8:11], v[176:179], v[204:207], v[8:11]
	v_mfma_f32_16x16x32_bf16 v[4:7], v[168:171], v[212:215], v[4:7]
	v_mfma_f32_16x16x32_bf16 v[0:3], v[176:179], v[212:215], v[0:3]
	v_mfma_f32_16x16x32_bf16 v[28:31], v[172:175], v[188:191], v[28:31]
	v_mfma_f32_16x16x32_bf16 v[24:27], v[180:183], v[188:191], v[24:27]
	v_mfma_f32_16x16x32_bf16 v[20:23], v[172:175], v[196:199], v[20:23]
	v_mfma_f32_16x16x32_bf16 v[16:19], v[180:183], v[196:199], v[16:19]
	v_mfma_f32_16x16x32_bf16 v[12:15], v[172:175], v[208:211], v[12:15]
	v_mfma_f32_16x16x32_bf16 v[8:11], v[180:183], v[208:211], v[8:11]
	v_mfma_f32_16x16x32_bf16 v[4:7], v[172:175], v[236:239], v[4:7]
	v_mfma_f32_16x16x32_bf16 v[0:3], v[180:183], v[236:239], v[0:3]
	s_barrier
	s_add_u32 s24, s24, 0x100
	s_addc_u32 s25, s25, 0
	s_add_u32 s18, s18, 0x100
	s_addc_u32 s19, s19, 0
	s_cmp_ge_i32 s66, s54
	s_mov_b32 s0, s66
	s_cbranch_scc0 .LBB0_53
	s_movk_i32 s67, 0x2000
	s_movk_i32 s66, 0x3000
	s_movk_i32 s69, 0x1000

; #define PG8_STAGE(bufoff, gbase, voff) do { _Pragma("unroll") for (int _i = 0; _i < 2; ++_i) \
;         __builtin_amdgcn_global_load_lds((const unsigned*)((const char*)(gbase) + (voff)[_i]), (PG8_LAS unsigned*)(lds + (bufoff) + ldsw + _i * 8192), 16, 0, 0); } while (0)
; #define PG8_LDA(dst, b, h) do { _Pragma("unroll") for (int m = 0; m < 4; ++m) _Pragma("unroll") for (int k = 0; k < 2; ++k) dst[m][k] = *(const PG8_LAS bf16x8*)(lds + PG8_SA(b, h) + aoff + m * 2048 + k * 1024); } while (0)
; #define PG8_LDB(dst, b, h) do { _Pragma("unroll") for (int n = 0; n < 2; ++n) _Pragma("unroll") for (int k = 0; k < 2; ++k) dst[n][k] = *(const PG8_LAS bf16x8*)(lds + PG8_SB(b, h) + boff + n * 2048 + k * 1024); } while (0)
; #define PG8_MMA(ai, bj, At, Bt) do { __builtin_amdgcn_s_setprio(1); _Pragma("unroll") for (int m = 0; m < 4; ++m) _Pragma("unroll") for (int n = 0; n < 2; ++n) _Pragma("unroll") for (int k = 0; k < 2; ++k) \
;         acc[ai][bj][m][n] = __builtin_amdgcn_mfma_f32_16x16x32_bf16(Bt[n][k], At[m][k], acc[ai][bj][m][n], 0, 0, 0); __builtin_amdgcn_s_setprio(0); } while (0)
; #define PG8_WAIT_V(n) asm volatile("s_waitcnt vmcnt(" #n ")" ::: "memory")
; #define PG8_WAIT_L(n) asm volatile("s_waitcnt lgkmcnt(" #n ")" ::: "memory")
; template <class Epi, class Sched, bool ALIGN_EPI = false, bool SP2 = false>
; __device__ __forceinline__ void gemm_phase(PG8_LAS unsigned char* lds, const Gemm g, const Sched& S, const Epi& E) {
;     ...
;             const bool last = (t == nt - 2);
;             const char* a1 = cA + (size_t)(t + 1) * kstep;
;             const char* a2 = last ? nA : cA + (size_t)(t + 2) * kstep; const char* b2 = last ? nB : cB + (size_t)(t + 2) * kstep;
;             const char* a3 = a2 + kstep; const char* b3 = b2 + kstep;
;             if (last && has_next) S.a_ready(nxt);
;             if constexpr (SP2) {
;             PG8_LDB(B0, 0, 0); PG8_LDB(B1, 0, 1); PG8_SCHED; PG8_LDA(At, 0, 0); PG8_STAGE(PG8_SA(1, 1), a1 + hstep, voffA);
;             PG8_WAIT_V(8); PG8_WAIT_L(0); PG8_BAR; PG8_MMA(0, 0, At, B0); PG8_MMA(0, 1, At, B1); PG8_BAR; PG8_SCHED;
;             PG8_LDA(At, 0, 1); PG8_STAGE(PG8_SB(0, 0), b2, voffB); PG8_STAGE(PG8_SB(0, 1), b2 + hstep, voffB); PG8_STAGE(PG8_SA(0, 0), a2, voffA);
;             PG8_WAIT_V(8); PG8_WAIT_L(0); PG8_BAR; PG8_MMA(1, 0, At, B0); PG8_MMA(1, 1, At, B1); PG8_BAR; PG8_SCHED;
.LBB0_75:
	s_add_i32 s71, s0, 2
	s_add_u32 s72, s24, 0x80
	s_addc_u32 s1, s25, 0
	s_add_i32 s74, 0, 0x10000
	s_cmp_eq_u32 s65, s0
	s_cselect_b32 s1, s35, s1
	s_cselect_b32 s0, s34, s72
	s_cselect_b32 s73, s41, s19
	s_cselect_b32 s72, s40, s18
	s_add_i32 s75, 0, 0x14000
	v_add_u32_e32 v162, s74, v148
	v_add_u32_e32 v178, s75, v148
	ds_read_b128 v[150:153], v162
	ds_read_b128 v[154:157], v162 offset:1024
	ds_read_b128 v[158:161], v162 offset:2048
	ds_read_b128 v[162:165], v162 offset:3072
	ds_read_b128 v[166:169], v178
	ds_read_b128 v[170:173], v178 offset:1024
	ds_read_b128 v[174:177], v178 offset:2048
	ds_read_b128 v[178:181], v178 offset:3072
	v_lshl_add_u64 v[198:199], s[24:25], 0, v[144:145]
	s_add_i32 m0, s53, 0xc000
	ds_read_b128 v[182:185], v149
	ds_read_b128 v[186:189], v149 offset:1024
	ds_read_b128 v[190:193], v149 offset:2048
	ds_read_b128 v[194:197], v149 offset:3072
	ds_read_b128 v[204:207], v149 offset:4096
	ds_read_b128 v[208:211], v149 offset:5120
	ds_read_b128 v[212:215], v149 offset:6144
	ds_read_b128 v[236:239], v149 offset:7168
	global_load_lds_dwordx4 v[198:199], off
	v_lshl_add_u64 v[198:199], s[24:25], 0, v[146:147]
	s_add_i32 m0, s53, 0xe000
	s_nop 0
	global_load_lds_dwordx4 v[198:199], off
	s_waitcnt vmcnt(8)
	s_waitcnt lgkmcnt(0)
	s_barrier
	s_waitcnt lgkmcnt(0)
	v_mfma_f32_16x16x32_bf16 v[136:139], v[150:153], v[182:185], v[136:139]
	v_mfma_f32_16x16x32_bf16 v[132:135], v[158:161], v[182:185], v[132:135]
	v_mfma_f32_16x16x32_bf16 v[128:131], v[150:153], v[190:193], v[128:131]
	v_mfma_f32_16x16x32_bf16 v[124:127], v[158:161], v[190:193], v[124:127]
	v_mfma_f32_16x16x32_bf16 v[120:123], v[150:153], v[204:207], v[120:123]
	v_mfma_f32_16x16x32_bf16 v[116:119], v[158:161], v[204:207], v[116:119]
	v_mfma_f32_16x16x32_bf16 v[112:115], v[150:153], v[212:215], v[112:115]
	v_mfma_f32_16x16x32_bf16 v[108:111], v[158:161], v[212:215], v[108:111]
	v_mfma_f32_16x16x32_bf16 v[136:139], v[154:157], v[186:189], v[136:139]
	v_mfma_f32_16x16x32_bf16 v[132:135], v[162:165], v[186:189], v[132:135]
	v_mfma_f32_16x16x32_bf16 v[128:131], v[154:157], v[194:197], v[128:131]
	v_mfma_f32_16x16x32_bf16 v[124:127], v[162:165], v[194:197], v[124:127]
	v_mfma_f32_16x16x32_bf16 v[120:123], v[154:157], v[208:211], v[120:123]
	v_mfma_f32_16x16x32_bf16 v[116:119], v[162:165], v[208:211], v[116:119]
	v_mfma_f32_16x16x32_bf16 v[112:115], v[154:157], v[236:239], v[112:115]
	v_mfma_f32_16x16x32_bf16 v[108:111], v[162:165], v[236:239], v[108:111]
	v_mfma_f32_16x16x32_bf16 v[72:75], v[166:169], v[182:185], v[72:75]
	v_mfma_f32_16x16x32_bf16 v[68:71], v[174:177], v[182:185], v[68:71]
	v_mfma_f32_16x16x32_bf16 v[64:67], v[166:169], v[190:193], v[64:67]
	v_mfma_f32_16x16x32_bf16 v[60:63], v[174:177], v[190:193], v[60:63]
	v_mfma_f32_16x16x32_bf16 v[56:59], v[166:169], v[204:207], v[56:59]
	v_mfma_f32_16x16x32_bf16 v[52:55], v[174:177], v[204:207], v[52:55]
	v_mfma_f32_16x16x32_bf16 v[48:51], v[166:169], v[212:215], v[48:51]
	v_mfma_f32_16x16x32_bf16 v[32:35], v[174:177], v[212:215], v[32:35]
	v_mfma_f32_16x16x32_bf16 v[72:75], v[170:173], v[186:189], v[72:75]
	v_mfma_f32_16x16x32_bf16 v[68:71], v[178:181], v[186:189], v[68:71]
	v_mfma_f32_16x16x32_bf16 v[64:67], v[170:173], v[194:197], v[64:67]
	v_mfma_f32_16x16x32_bf16 v[60:63], v[178:181], v[194:197], v[60:63]
	v_mfma_f32_16x16x32_bf16 v[56:59], v[170:173], v[208:211], v[56:59]
	v_mfma_f32_16x16x32_bf16 v[52:55], v[178:181], v[208:211], v[52:55]
	v_mfma_f32_16x16x32_bf16 v[48:51], v[170:173], v[236:239], v[48:51]
	v_mfma_f32_16x16x32_bf16 v[32:35], v[178:181], v[236:239], v[32:35]
	s_barrier
	s_add_i32 s74, s74, s49
	v_lshl_add_u64 v[198:199], s[72:73], 0, v[140:141]
	s_mov_b32 m0, s74
	ds_read_b128 v[182:185], v149 offset:16384
	ds_read_b128 v[186:189], v149 offset:17408
	ds_read_b128 v[190:193], v149 offset:18432
	ds_read_b128 v[194:197], v149 offset:19456
	ds_read_b128 v[204:207], v149 offset:20480
	ds_read_b128 v[208:211], v149 offset:21504
	ds_read_b128 v[212:215], v149 offset:22528
	ds_read_b128 v[236:239], v149 offset:23552
	global_load_lds_dwordx4 v[198:199], off
	s_add_i32 m0, s74, 0x2000
	v_lshl_add_u64 v[240:241], s[72:73], 0, v[38:39]
	s_add_u32 s72, s72, s2
	s_addc_u32 s73, s73, s3
	s_add_i32 s74, s75, s49
	global_load_lds_dwordx4 v[240:241], off
	v_lshl_add_u64 v[242:243], s[72:73], 0, v[140:141]
	s_mov_b32 m0, s74
	v_lshl_add_u64 v[244:245], s[72:73], 0, v[38:39]
	global_load_lds_dwordx4 v[242:243], off
	s_add_i32 m0, s74, 0x2000
	v_lshl_add_u64 v[246:247], s[0:1], 0, v[142:143]
	global_load_lds_dwordx4 v[244:245], off
	s_mov_b32 m0, s53
	v_lshl_add_u64 v[248:249], s[0:1], 0, v[42:43]
	global_load_lds_dwordx4 v[246:247], off
	s_mov_b32 m0, s54
	s_nop 0
	global_load_lds_dwordx4 v[248:249], off
	s_waitcnt vmcnt(8)
	s_waitcnt lgkmcnt(0)
	s_barrier
; #define PG8_STAGE(bufoff, gbase, voff) do { _Pragma("unroll") for (int _i = 0; _i < 2; ++_i) \
;         __builtin_amdgcn_global_load_lds((const unsigned*)((const char*)(gbase) + (voff)[_i]), (PG8_LAS unsigned*)(lds + (bufoff) + ldsw + _i * 8192), 16, 0, 0); } while (0)
; #define PG8_LDA(dst, b, h) do { _Pragma("unroll") for (int m = 0; m < 4; ++m) _Pragma("unroll") for (int k = 0; k < 2; ++k) dst[m][k] = *(const PG8_LAS bf16x8*)(lds + PG8_SA(b, h) + aoff + m * 2048 + k * 1024); } while (0)
; #define PG8_LDB(dst, b, h) do { _Pragma("unroll") for (int n = 0; n < 2; ++n) _Pragma("unroll") for (int k = 0; k < 2; ++k) dst[n][k] = *(const PG8_LAS bf16x8*)(lds + PG8_SB(b, h) + boff + n * 2048 + k * 1024); } while (0)
; #define PG8_MMA(ai, bj, At, Bt) do { __builtin_amdgcn_s_setprio(1); _Pragma("unroll") for (int m = 0; m < 4; ++m) _Pragma("unroll") for (int n = 0; n < 2; ++n) _Pragma("unroll") for (int k = 0; k < 2; ++k) \
;         acc[ai][bj][m][n] = __builtin_amdgcn_mfma_f32_16x16x32_bf16(Bt[n][k], At[m][k], acc[ai][bj][m][n], 0, 0, 0); __builtin_amdgcn_s_setprio(0); } while (0)
; #define PG8_WAIT_V(n) asm volatile("s_waitcnt vmcnt(" #n ")" ::: "memory")
; #define PG8_WAIT_L(n) asm volatile("s_waitcnt lgkmcnt(" #n ")" ::: "memory")
; #define PG8_BAR __builtin_amdgcn_s_barrier()
; #define PG8_SCHED __builtin_amdgcn_sched_barrier(0)
; template <class Epi, class Sched, bool ALIGN_EPI = false, bool SP2 = false>
; __device__ __forceinline__ void gemm_phase(PG8_LAS unsigned char* lds, const Gemm g, const Sched& S, const Epi& E) {
;     ...
;             PG8_WAIT_V(8); PG8_WAIT_L(0); PG8_BAR; PG8_MMA(1, 0, At, B0); PG8_MMA(1, 1, At, B1); PG8_BAR; PG8_SCHED;
;             PG8_LDB(B0, 1, 0); PG8_LDB(B1, 1, 1); PG8_SCHED; PG8_LDA(At, 1, 0); PG8_STAGE(PG8_SA(0, 1), a2 + hstep, voffA);
;             PG8_WAIT_V(8); PG8_WAIT_L(0); PG8_BAR; PG8_MMA(0, 0, At, B0); PG8_MMA(0, 1, At, B1); PG8_BAR; PG8_SCHED;
	s_waitcnt lgkmcnt(0)
	v_mfma_f32_16x16x32_bf16 v[104:107], v[150:153], v[182:185], v[104:107]
	v_mfma_f32_16x16x32_bf16 v[100:103], v[158:161], v[182:185], v[100:103]
	v_mfma_f32_16x16x32_bf16 v[96:99], v[150:153], v[190:193], v[96:99]
	v_mfma_f32_16x16x32_bf16 v[92:95], v[158:161], v[190:193], v[92:95]
	v_mfma_f32_16x16x32_bf16 v[88:91], v[150:153], v[204:207], v[88:91]
	v_mfma_f32_16x16x32_bf16 v[84:87], v[158:161], v[204:207], v[84:87]
	v_mfma_f32_16x16x32_bf16 v[80:83], v[150:153], v[212:215], v[80:83]
	v_mfma_f32_16x16x32_bf16 v[76:79], v[158:161], v[212:215], v[76:79]
	v_mfma_f32_16x16x32_bf16 v[104:107], v[154:157], v[186:189], v[104:107]
	v_mfma_f32_16x16x32_bf16 v[100:103], v[162:165], v[186:189], v[100:103]
	v_mfma_f32_16x16x32_bf16 v[96:99], v[154:157], v[194:197], v[96:99]
	v_mfma_f32_16x16x32_bf16 v[92:95], v[162:165], v[194:197], v[92:95]
	v_mfma_f32_16x16x32_bf16 v[88:91], v[154:157], v[208:211], v[88:91]
	v_mfma_f32_16x16x32_bf16 v[84:87], v[162:165], v[208:211], v[84:87]
	v_mfma_f32_16x16x32_bf16 v[80:83], v[154:157], v[236:239], v[80:83]
	v_mfma_f32_16x16x32_bf16 v[76:79], v[162:165], v[236:239], v[76:79]
	v_mfma_f32_16x16x32_bf16 v[28:31], v[166:169], v[182:185], v[28:31]
	v_mfma_f32_16x16x32_bf16 v[24:27], v[174:177], v[182:185], v[24:27]
	v_mfma_f32_16x16x32_bf16 v[20:23], v[166:169], v[190:193], v[20:23]
	v_mfma_f32_16x16x32_bf16 v[16:19], v[174:177], v[190:193], v[16:19]
	v_mfma_f32_16x16x32_bf16 v[12:15], v[166:169], v[204:207], v[12:15]
	v_mfma_f32_16x16x32_bf16 v[8:11], v[174:177], v[204:207], v[8:11]
	v_mfma_f32_16x16x32_bf16 v[4:7], v[166:169], v[212:215], v[4:7]
	v_mfma_f32_16x16x32_bf16 v[0:3], v[174:177], v[212:215], v[0:3]
	v_mfma_f32_16x16x32_bf16 v[28:31], v[170:173], v[186:189], v[28:31]
	v_mfma_f32_16x16x32_bf16 v[24:27], v[178:181], v[186:189], v[24:27]
	v_mfma_f32_16x16x32_bf16 v[20:23], v[170:173], v[194:197], v[20:23]
	v_mfma_f32_16x16x32_bf16 v[16:19], v[178:181], v[194:197], v[16:19]
	v_mfma_f32_16x16x32_bf16 v[12:15], v[170:173], v[208:211], v[12:15]
	v_mfma_f32_16x16x32_bf16 v[8:11], v[178:181], v[208:211], v[8:11]
	v_mfma_f32_16x16x32_bf16 v[4:7], v[170:173], v[236:239], v[4:7]
	v_mfma_f32_16x16x32_bf16 v[0:3], v[178:181], v[236:239], v[0:3]
	s_barrier
	s_add_i32 s72, 0, 0x18000
	s_add_i32 s73, 0, 0x1c000
	v_add_u32_e32 v162, s72, v148
	v_add_u32_e32 v178, s73, v148
	ds_read_b128 v[150:153], v162
	ds_read_b128 v[154:157], v162 offset:1024
	ds_read_b128 v[158:161], v162 offset:2048
	ds_read_b128 v[162:165], v162 offset:3072
	ds_read_b128 v[166:169], v178
	ds_read_b128 v[170:173], v178 offset:1024
	ds_read_b128 v[174:177], v178 offset:2048
	ds_read_b128 v[178:181], v178 offset:3072
	s_add_u32 s0, s0, s2
	s_addc_u32 s1, s1, s3
	s_mov_b32 m0, s55
	v_lshl_add_u64 v[250:251], s[0:1], 0, v[142:143]
	ds_read_b128 v[182:185], v149 offset:32768
	ds_read_b128 v[186:189], v149 offset:33792
	ds_read_b128 v[190:193], v149 offset:34816
	ds_read_b128 v[194:197], v149 offset:35840
	ds_read_b128 v[204:207], v149 offset:36864
	ds_read_b128 v[208:211], v149 offset:37888
	ds_read_b128 v[212:215], v149 offset:38912
	ds_read_b128 v[236:239], v149 offset:39936
	global_load_lds_dwordx4 v[250:251], off
	v_lshl_add_u64 v[250:251], s[0:1], 0, v[42:43]
	s_mov_b32 m0, s56
	s_nop 0
	global_load_lds_dwordx4 v[250:251], off
	s_waitcnt vmcnt(8)
	s_waitcnt lgkmcnt(0)
	s_barrier
	s_waitcnt lgkmcnt(0)
	v_mfma_f32_16x16x32_bf16 v[136:139], v[150:153], v[182:185], v[136:139]
	v_mfma_f32_16x16x32_bf16 v[132:135], v[158:161], v[182:185], v[132:135]
	v_mfma_f32_16x16x32_bf16 v[128:131], v[150:153], v[190:193], v[128:131]
	v_mfma_f32_16x16x32_bf16 v[124:127], v[158:161], v[190:193], v[124:127]
	v_mfma_f32_16x16x32_bf16 v[120:123], v[150:153], v[204:207], v[120:123]
	v_mfma_f32_16x16x32_bf16 v[116:119], v[158:161], v[204:207], v[116:119]
	v_mfma_f32_16x16x32_bf16 v[112:115], v[150:153], v[212:215], v[112:115]
	v_mfma_f32_16x16x32_bf16 v[108:111], v[158:161], v[212:215], v[108:111]
	v_mfma_f32_16x16x32_bf16 v[136:139], v[154:157], v[186:189], v[136:139]
	v_mfma_f32_16x16x32_bf16 v[132:135], v[162:165], v[186:189], v[132:135]
	v_mfma_f32_16x16x32_bf16 v[128:131], v[154:157], v[194:197], v[128:131]
	v_mfma_f32_16x16x32_bf16 v[124:127], v[162:165], v[194:197], v[124:127]
	v_mfma_f32_16x16x32_bf16 v[120:123], v[154:157], v[208:211], v[120:123]
	v_mfma_f32_16x16x32_bf16 v[116:119], v[162:165], v[208:211], v[116:119]
	v_mfma_f32_16x16x32_bf16 v[112:115], v[154:157], v[236:239], v[112:115]
	v_mfma_f32_16x16x32_bf16 v[108:111], v[162:165], v[236:239], v[108:111]
	v_mfma_f32_16x16x32_bf16 v[72:75], v[166:169], v[182:185], v[72:75]
	v_mfma_f32_16x16x32_bf16 v[68:71], v[174:177], v[182:185], v[68:71]
	v_mfma_f32_16x16x32_bf16 v[64:67], v[166:169], v[190:193], v[64:67]
	v_mfma_f32_16x16x32_bf16 v[60:63], v[174:177], v[190:193], v[60:63]
	v_mfma_f32_16x16x32_bf16 v[56:59], v[166:169], v[204:207], v[56:59]
	v_mfma_f32_16x16x32_bf16 v[52:55], v[174:177], v[204:207], v[52:55]
	v_mfma_f32_16x16x32_bf16 v[48:51], v[166:169], v[212:215], v[48:51]
	v_mfma_f32_16x16x32_bf16 v[32:35], v[174:177], v[212:215], v[32:35]
	v_mfma_f32_16x16x32_bf16 v[72:75], v[170:173], v[186:189], v[72:75]
	v_mfma_f32_16x16x32_bf16 v[68:71], v[178:181], v[186:189], v[68:71]
	v_mfma_f32_16x16x32_bf16 v[64:67], v[170:173], v[194:197], v[64:67]
	v_mfma_f32_16x16x32_bf16 v[60:63], v[178:181], v[194:197], v[60:63]
	v_mfma_f32_16x16x32_bf16 v[56:59], v[170:173], v[208:211], v[56:59]
	v_mfma_f32_16x16x32_bf16 v[52:55], v[178:181], v[208:211], v[52:55]
	v_mfma_f32_16x16x32_bf16 v[48:51], v[170:173], v[236:239], v[48:51]
	v_mfma_f32_16x16x32_bf16 v[32:35], v[178:181], v[236:239], v[32:35]
	s_barrier
; #define PG8_STAGE(bufoff, gbase, voff) do { _Pragma("unroll") for (int _i = 0; _i < 2; ++_i) \
;         __builtin_amdgcn_global_load_lds((const unsigned*)((const char*)(gbase) + (voff)[_i]), (PG8_LAS unsigned*)(lds + (bufoff) + ldsw + _i * 8192), 16, 0, 0); } while (0)
; #define PG8_LDA(dst, b, h) do { _Pragma("unroll") for (int m = 0; m < 4; ++m) _Pragma("unroll") for (int k = 0; k < 2; ++k) dst[m][k] = *(const PG8_LAS bf16x8*)(lds + PG8_SA(b, h) + aoff + m * 2048 + k * 1024); } while (0)
; #define PG8_MMA(ai, bj, At, Bt) do { __builtin_amdgcn_s_setprio(1); _Pragma("unroll") for (int m = 0; m < 4; ++m) _Pragma("unroll") for (int n = 0; n < 2; ++n) _Pragma("unroll") for (int k = 0; k < 2; ++k) \
;         acc[ai][bj][m][n] = __builtin_amdgcn_mfma_f32_16x16x32_bf16(Bt[n][k], At[m][k], acc[ai][bj][m][n], 0, 0, 0); __builtin_amdgcn_s_setprio(0); } while (0)
; #define PG8_WAIT_V(n) asm volatile("s_waitcnt vmcnt(" #n ")" ::: "memory")
; #define PG8_WAIT_L(n) asm volatile("s_waitcnt lgkmcnt(" #n ")" ::: "memory")
; #define PG8_BAR __builtin_amdgcn_s_barrier()
; #define PG8_SCHED __builtin_amdgcn_sched_barrier(0)
; template <class Epi, class Sched, bool ALIGN_EPI = false, bool SP2 = false>
; __device__ __forceinline__ void gemm_phase(PG8_LAS unsigned char* lds, const Gemm g, const Sched& S, const Epi& E) {
;     ...
;         for (int t = 0; t < nt; t += 2) {
;             const bool last = (t == nt - 2);
;             const char* a1 = cA + (size_t)(t + 1) * kstep;
;             const char* a2 = last ? nA : cA + (size_t)(t + 2) * kstep; const char* b2 = last ? nB : cB + (size_t)(t + 2) * kstep;
;     ...
;             PG8_LDA(At, 1, 1); PG8_STAGE(PG8_SB(1, 0), b3, voffB); PG8_STAGE(PG8_SB(1, 1), b3 + hstep, voffB); PG8_STAGE(PG8_SA(1, 0), a3, voffA);
;             PG8_WAIT_V(8); PG8_WAIT_L(0); PG8_BAR; PG8_MMA(1, 0, At, B0); PG8_MMA(1, 1, At, B1); PG8_BAR; PG8_SCHED;
	s_add_i32 s0, s72, s49
	v_lshl_add_u64 v[198:199], v[198:199], 0, s[22:23]
	s_mov_b32 m0, s0
	ds_read_b128 v[182:185], v149 offset:49152
	ds_read_b128 v[186:189], v149 offset:50176
	ds_read_b128 v[190:193], v149 offset:51200
	ds_read_b128 v[194:197], v149 offset:52224
	ds_read_b128 v[204:207], v149 offset:53248
	ds_read_b128 v[208:211], v149 offset:54272
	ds_read_b128 v[212:215], v149 offset:55296
	ds_read_b128 v[236:239], v149 offset:56320
	global_load_lds_dwordx4 v[198:199], off
	v_lshl_add_u64 v[198:199], v[240:241], 0, s[22:23]
	s_add_i32 m0, s0, 0x2000
	s_add_i32 s0, s73, s49
	global_load_lds_dwordx4 v[198:199], off
	v_lshl_add_u64 v[198:199], v[242:243], 0, s[22:23]
	s_mov_b32 m0, s0
	s_nop 0
	global_load_lds_dwordx4 v[198:199], off
	v_lshl_add_u64 v[198:199], v[244:245], 0, s[22:23]
	s_add_i32 m0, s0, 0x2000
	s_nop 0
	global_load_lds_dwordx4 v[198:199], off
	v_lshl_add_u64 v[198:199], v[246:247], 0, s[22:23]
	s_mov_b32 m0, s60
	s_nop 0
	global_load_lds_dwordx4 v[198:199], off
	v_lshl_add_u64 v[198:199], v[248:249], 0, s[22:23]
	s_mov_b32 m0, s61
	s_nop 0
	global_load_lds_dwordx4 v[198:199], off
	s_waitcnt vmcnt(8)
	s_waitcnt lgkmcnt(0)
	s_barrier
	s_waitcnt lgkmcnt(0)
	v_mfma_f32_16x16x32_bf16 v[104:107], v[150:153], v[182:185], v[104:107]
	v_mfma_f32_16x16x32_bf16 v[100:103], v[158:161], v[182:185], v[100:103]
	v_mfma_f32_16x16x32_bf16 v[96:99], v[150:153], v[190:193], v[96:99]
	v_mfma_f32_16x16x32_bf16 v[92:95], v[158:161], v[190:193], v[92:95]
	v_mfma_f32_16x16x32_bf16 v[88:91], v[150:153], v[204:207], v[88:91]
	v_mfma_f32_16x16x32_bf16 v[84:87], v[158:161], v[204:207], v[84:87]
	v_mfma_f32_16x16x32_bf16 v[80:83], v[150:153], v[212:215], v[80:83]
	v_mfma_f32_16x16x32_bf16 v[76:79], v[158:161], v[212:215], v[76:79]
	v_mfma_f32_16x16x32_bf16 v[104:107], v[154:157], v[186:189], v[104:107]
	v_mfma_f32_16x16x32_bf16 v[100:103], v[162:165], v[186:189], v[100:103]
	v_mfma_f32_16x16x32_bf16 v[96:99], v[154:157], v[194:197], v[96:99]
	v_mfma_f32_16x16x32_bf16 v[92:95], v[162:165], v[194:197], v[92:95]
	v_mfma_f32_16x16x32_bf16 v[88:91], v[154:157], v[208:211], v[88:91]
	v_mfma_f32_16x16x32_bf16 v[84:87], v[162:165], v[208:211], v[84:87]
	v_mfma_f32_16x16x32_bf16 v[80:83], v[154:157], v[236:239], v[80:83]
	v_mfma_f32_16x16x32_bf16 v[76:79], v[162:165], v[236:239], v[76:79]
	v_mfma_f32_16x16x32_bf16 v[28:31], v[166:169], v[182:185], v[28:31]
	v_mfma_f32_16x16x32_bf16 v[24:27], v[174:177], v[182:185], v[24:27]
	v_mfma_f32_16x16x32_bf16 v[20:23], v[166:169], v[190:193], v[20:23]
	v_mfma_f32_16x16x32_bf16 v[16:19], v[174:177], v[190:193], v[16:19]
	v_mfma_f32_16x16x32_bf16 v[12:15], v[166:169], v[204:207], v[12:15]
	v_mfma_f32_16x16x32_bf16 v[8:11], v[174:177], v[204:207], v[8:11]
	v_mfma_f32_16x16x32_bf16 v[4:7], v[166:169], v[212:215], v[4:7]
	v_mfma_f32_16x16x32_bf16 v[0:3], v[174:177], v[212:215], v[0:3]
	v_mfma_f32_16x16x32_bf16 v[28:31], v[170:173], v[186:189], v[28:31]
	v_mfma_f32_16x16x32_bf16 v[24:27], v[178:181], v[186:189], v[24:27]
	v_mfma_f32_16x16x32_bf16 v[20:23], v[170:173], v[194:197], v[20:23]
	v_mfma_f32_16x16x32_bf16 v[16:19], v[178:181], v[194:197], v[16:19]
	v_mfma_f32_16x16x32_bf16 v[12:15], v[170:173], v[208:211], v[12:15]
	v_mfma_f32_16x16x32_bf16 v[8:11], v[178:181], v[208:211], v[8:11]
	v_mfma_f32_16x16x32_bf16 v[4:7], v[170:173], v[236:239], v[4:7]
	v_mfma_f32_16x16x32_bf16 v[0:3], v[178:181], v[236:239], v[0:3]
	s_barrier
	s_add_u32 s24, s24, 0x100
	s_addc_u32 s25, s25, 0
	s_add_u32 s18, s18, 0x100
	s_addc_u32 s19, s19, 0
	s_cmp_ge_i32 s71, s57
	s_mov_b32 s0, s71
	s_cbranch_scc0 .LBB0_75

; #define PG8_STAGE(bufoff, gbase, voff) do { _Pragma("unroll") for (int _i = 0; _i < 2; ++_i) \
;         __builtin_amdgcn_global_load_lds((const unsigned*)((const char*)(gbase) + (voff)[_i]), (PG8_LAS unsigned*)(lds + (bufoff) + ldsw + _i * 8192), 16, 0, 0); } while (0)
; #define PG8_LDA(dst, b, h) do { _Pragma("unroll") for (int m = 0; m < 4; ++m) _Pragma("unroll") for (int k = 0; k < 2; ++k) dst[m][k] = *(const PG8_LAS bf16x8*)(lds + PG8_SA(b, h) + aoff + m * 2048 + k * 1024); } while (0)
; #define PG8_LDB(dst, b, h) do { _Pragma("unroll") for (int n = 0; n < 2; ++n) _Pragma("unroll") for (int k = 0; k < 2; ++k) dst[n][k] = *(const PG8_LAS bf16x8*)(lds + PG8_SB(b, h) + boff + n * 2048 + k * 1024); } while (0)
; #define PG8_MMA(ai, bj, At, Bt) do { __builtin_amdgcn_s_setprio(1); _Pragma("unroll") for (int m = 0; m < 4; ++m) _Pragma("unroll") for (int n = 0; n < 2; ++n) _Pragma("unroll") for (int k = 0; k < 2; ++k) \
;         acc[ai][bj][m][n] = __builtin_amdgcn_mfma_f32_16x16x32_bf16(Bt[n][k], At[m][k], acc[ai][bj][m][n], 0, 0, 0); __builtin_amdgcn_s_setprio(0); } while (0)
; #define PG8_WAIT_V(n) asm volatile("s_waitcnt vmcnt(" #n ")" ::: "memory")
; #define PG8_WAIT_L(n) asm volatile("s_waitcnt lgkmcnt(" #n ")" ::: "memory")
; template <class Epi, class Sched, bool ALIGN_EPI = false, bool SP2 = false>
; __device__ __forceinline__ void gemm_phase(PG8_LAS unsigned char* lds, const Gemm g, const Sched& S, const Epi& E) {
;     ...
;             const bool last = (t == nt - 2);
;             const char* a1 = cA + (size_t)(t + 1) * kstep;
;             const char* a2 = last ? nA : cA + (size_t)(t + 2) * kstep; const char* b2 = last ? nB : cB + (size_t)(t + 2) * kstep;
;             const char* a3 = a2 + kstep; const char* b3 = b2 + kstep;
;             if (last && has_next) S.a_ready(nxt);
;             if constexpr (SP2) {
;             PG8_LDB(B0, 0, 0); PG8_LDB(B1, 0, 1); PG8_SCHED; PG8_LDA(At, 0, 0); PG8_STAGE(PG8_SA(1, 1), a1 + hstep, voffA);
;             PG8_WAIT_V(8); PG8_WAIT_L(0); PG8_BAR; PG8_MMA(0, 0, At, B0); PG8_MMA(0, 1, At, B1); PG8_BAR; PG8_SCHED;
;             PG8_LDA(At, 0, 1); PG8_STAGE(PG8_SB(0, 0), b2, voffB); PG8_STAGE(PG8_SB(0, 1), b2 + hstep, voffB); PG8_STAGE(PG8_SA(0, 0), a2, voffA);
;             PG8_WAIT_V(8); PG8_WAIT_L(0); PG8_BAR; PG8_MMA(1, 0, At, B0); PG8_MMA(1, 1, At, B1); PG8_BAR; PG8_SCHED;
.LBB0_118:
	s_add_i32 s70, s0, 2
	s_add_u32 s71, s24, 0x80
	s_addc_u32 s1, s25, 0
	s_add_i32 s74, 0, 0x10000
	s_cmp_eq_u32 s65, s0
	s_cselect_b32 s1, s41, s1
	s_cselect_b32 s0, s40, s71
	s_cselect_b32 s73, s43, s19
	s_cselect_b32 s72, s42, s18
	s_add_i32 s71, 0, 0x14000
	v_add_u32_e32 v162, s74, v148
	v_add_u32_e32 v178, s71, v148
	ds_read_b128 v[150:153], v162
	ds_read_b128 v[154:157], v162 offset:1024
	ds_read_b128 v[158:161], v162 offset:2048
	ds_read_b128 v[162:165], v162 offset:3072
	ds_read_b128 v[166:169], v178
	ds_read_b128 v[170:173], v178 offset:1024
	ds_read_b128 v[174:177], v178 offset:2048
	ds_read_b128 v[178:181], v178 offset:3072
	v_lshl_add_u64 v[198:199], s[24:25], 0, v[144:145]
	s_add_i32 m0, s54, 0xc000
	ds_read_b128 v[182:185], v149
	ds_read_b128 v[186:189], v149 offset:1024
	ds_read_b128 v[190:193], v149 offset:2048
	ds_read_b128 v[194:197], v149 offset:3072
	ds_read_b128 v[204:207], v149 offset:4096
	ds_read_b128 v[208:211], v149 offset:5120
	ds_read_b128 v[212:215], v149 offset:6144
	ds_read_b128 v[236:239], v149 offset:7168
	global_load_lds_dwordx4 v[198:199], off
	v_lshl_add_u64 v[198:199], s[24:25], 0, v[146:147]
	s_add_i32 m0, s54, 0xe000
	s_nop 0
	global_load_lds_dwordx4 v[198:199], off
	s_waitcnt vmcnt(8)
	s_waitcnt lgkmcnt(0)
	s_barrier
	s_waitcnt lgkmcnt(0)
	v_mfma_f32_16x16x32_bf16 v[132:135], v[150:153], v[182:185], v[132:135]
	v_mfma_f32_16x16x32_bf16 v[136:139], v[158:161], v[182:185], v[136:139]
	v_mfma_f32_16x16x32_bf16 v[128:131], v[150:153], v[190:193], v[128:131]
	v_mfma_f32_16x16x32_bf16 v[124:127], v[158:161], v[190:193], v[124:127]
	v_mfma_f32_16x16x32_bf16 v[120:123], v[150:153], v[204:207], v[120:123]
	v_mfma_f32_16x16x32_bf16 v[116:119], v[158:161], v[204:207], v[116:119]
	v_mfma_f32_16x16x32_bf16 v[112:115], v[150:153], v[212:215], v[112:115]
	v_mfma_f32_16x16x32_bf16 v[108:111], v[158:161], v[212:215], v[108:111]
	v_mfma_f32_16x16x32_bf16 v[132:135], v[154:157], v[186:189], v[132:135]
	v_mfma_f32_16x16x32_bf16 v[136:139], v[162:165], v[186:189], v[136:139]
	v_mfma_f32_16x16x32_bf16 v[128:131], v[154:157], v[194:197], v[128:131]
	v_mfma_f32_16x16x32_bf16 v[124:127], v[162:165], v[194:197], v[124:127]
	v_mfma_f32_16x16x32_bf16 v[120:123], v[154:157], v[208:211], v[120:123]
	v_mfma_f32_16x16x32_bf16 v[116:119], v[162:165], v[208:211], v[116:119]
	v_mfma_f32_16x16x32_bf16 v[112:115], v[154:157], v[236:239], v[112:115]
	v_mfma_f32_16x16x32_bf16 v[108:111], v[162:165], v[236:239], v[108:111]
	v_mfma_f32_16x16x32_bf16 v[72:75], v[166:169], v[182:185], v[72:75]
	v_mfma_f32_16x16x32_bf16 v[68:71], v[174:177], v[182:185], v[68:71]
	v_mfma_f32_16x16x32_bf16 v[64:67], v[166:169], v[190:193], v[64:67]
	v_mfma_f32_16x16x32_bf16 v[60:63], v[174:177], v[190:193], v[60:63]
	v_mfma_f32_16x16x32_bf16 v[56:59], v[166:169], v[204:207], v[56:59]
	v_mfma_f32_16x16x32_bf16 v[52:55], v[174:177], v[204:207], v[52:55]
	v_mfma_f32_16x16x32_bf16 v[48:51], v[166:169], v[212:215], v[48:51]
	v_mfma_f32_16x16x32_bf16 v[32:35], v[174:177], v[212:215], v[32:35]
	v_mfma_f32_16x16x32_bf16 v[72:75], v[170:173], v[186:189], v[72:75]
	v_mfma_f32_16x16x32_bf16 v[68:71], v[178:181], v[186:189], v[68:71]
	v_mfma_f32_16x16x32_bf16 v[64:67], v[170:173], v[194:197], v[64:67]
	v_mfma_f32_16x16x32_bf16 v[60:63], v[178:181], v[194:197], v[60:63]
	v_mfma_f32_16x16x32_bf16 v[56:59], v[170:173], v[208:211], v[56:59]
	v_mfma_f32_16x16x32_bf16 v[52:55], v[178:181], v[208:211], v[52:55]
	v_mfma_f32_16x16x32_bf16 v[48:51], v[170:173], v[236:239], v[48:51]
	v_mfma_f32_16x16x32_bf16 v[32:35], v[178:181], v[236:239], v[32:35]
	s_barrier
	s_add_i32 s74, s74, s49
	v_lshl_add_u64 v[198:199], s[72:73], 0, v[42:43]
	s_mov_b32 m0, s74
	ds_read_b128 v[182:185], v149 offset:16384
	ds_read_b128 v[186:189], v149 offset:17408
	ds_read_b128 v[190:193], v149 offset:18432
	ds_read_b128 v[194:197], v149 offset:19456
	ds_read_b128 v[204:207], v149 offset:20480
	ds_read_b128 v[208:211], v149 offset:21504
	ds_read_b128 v[212:215], v149 offset:22528
	ds_read_b128 v[236:239], v149 offset:23552
	global_load_lds_dwordx4 v[198:199], off
	s_add_i32 m0, s74, 0x2000
	v_lshl_add_u64 v[240:241], s[72:73], 0, v[142:143]
	s_add_u32 s72, s72, s10
	s_addc_u32 s73, s73, s11
	s_add_i32 s71, s71, s49
	global_load_lds_dwordx4 v[240:241], off
	v_lshl_add_u64 v[242:243], s[72:73], 0, v[42:43]
	s_mov_b32 m0, s71
	v_lshl_add_u64 v[244:245], s[72:73], 0, v[142:143]
	global_load_lds_dwordx4 v[242:243], off
	s_add_i32 m0, s71, 0x2000
	v_lshl_add_u64 v[246:247], s[0:1], 0, v[38:39]
	global_load_lds_dwordx4 v[244:245], off
	s_mov_b32 m0, s54
	v_lshl_add_u64 v[248:249], s[0:1], 0, v[140:141]
	global_load_lds_dwordx4 v[246:247], off
	s_mov_b32 m0, s55
	s_nop 0
	global_load_lds_dwordx4 v[248:249], off
	s_waitcnt vmcnt(8)
	s_waitcnt lgkmcnt(0)
	s_barrier
; #define PG8_STAGE(bufoff, gbase, voff) do { _Pragma("unroll") for (int _i = 0; _i < 2; ++_i) \
;         __builtin_amdgcn_global_load_lds((const unsigned*)((const char*)(gbase) + (voff)[_i]), (PG8_LAS unsigned*)(lds + (bufoff) + ldsw + _i * 8192), 16, 0, 0); } while (0)
; #define PG8_LDA(dst, b, h) do { _Pragma("unroll") for (int m = 0; m < 4; ++m) _Pragma("unroll") for (int k = 0; k < 2; ++k) dst[m][k] = *(const PG8_LAS bf16x8*)(lds + PG8_SA(b, h) + aoff + m * 2048 + k * 1024); } while (0)
; #define PG8_LDB(dst, b, h) do { _Pragma("unroll") for (int n = 0; n < 2; ++n) _Pragma("unroll") for (int k = 0; k < 2; ++k) dst[n][k] = *(const PG8_LAS bf16x8*)(lds + PG8_SB(b, h) + boff + n * 2048 + k * 1024); } while (0)
; #define PG8_MMA(ai, bj, At, Bt) do { __builtin_amdgcn_s_setprio(1); _Pragma("unroll") for (int m = 0; m < 4; ++m) _Pragma("unroll") for (int n = 0; n < 2; ++n) _Pragma("unroll") for (int k = 0; k < 2; ++k) \
;         acc[ai][bj][m][n] = __builtin_amdgcn_mfma_f32_16x16x32_bf16(Bt[n][k], At[m][k], acc[ai][bj][m][n], 0, 0, 0); __builtin_amdgcn_s_setprio(0); } while (0)
; #define PG8_WAIT_V(n) asm volatile("s_waitcnt vmcnt(" #n ")" ::: "memory")
; #define PG8_WAIT_L(n) asm volatile("s_waitcnt lgkmcnt(" #n ")" ::: "memory")
; #define PG8_BAR __builtin_amdgcn_s_barrier()
; #define PG8_SCHED __builtin_amdgcn_sched_barrier(0)
; template <class Epi, class Sched, bool ALIGN_EPI = false, bool SP2 = false>
; __device__ __forceinline__ void gemm_phase(PG8_LAS unsigned char* lds, const Gemm g, const Sched& S, const Epi& E) {
;     ...
;             PG8_WAIT_V(8); PG8_WAIT_L(0); PG8_BAR; PG8_MMA(1, 0, At, B0); PG8_MMA(1, 1, At, B1); PG8_BAR; PG8_SCHED;
;             PG8_LDB(B0, 1, 0); PG8_LDB(B1, 1, 1); PG8_SCHED; PG8_LDA(At, 1, 0); PG8_STAGE(PG8_SA(0, 1), a2 + hstep, voffA);
;             PG8_WAIT_V(8); PG8_WAIT_L(0); PG8_BAR; PG8_MMA(0, 0, At, B0); PG8_MMA(0, 1, At, B1); PG8_BAR; PG8_SCHED;
	s_waitcnt lgkmcnt(0)
	v_mfma_f32_16x16x32_bf16 v[104:107], v[150:153], v[182:185], v[104:107]
	v_mfma_f32_16x16x32_bf16 v[100:103], v[158:161], v[182:185], v[100:103]
	v_mfma_f32_16x16x32_bf16 v[96:99], v[150:153], v[190:193], v[96:99]
	v_mfma_f32_16x16x32_bf16 v[92:95], v[158:161], v[190:193], v[92:95]
	v_mfma_f32_16x16x32_bf16 v[88:91], v[150:153], v[204:207], v[88:91]
	v_mfma_f32_16x16x32_bf16 v[84:87], v[158:161], v[204:207], v[84:87]
	v_mfma_f32_16x16x32_bf16 v[80:83], v[150:153], v[212:215], v[80:83]
	v_mfma_f32_16x16x32_bf16 v[76:79], v[158:161], v[212:215], v[76:79]
	v_mfma_f32_16x16x32_bf16 v[104:107], v[154:157], v[186:189], v[104:107]
	v_mfma_f32_16x16x32_bf16 v[100:103], v[162:165], v[186:189], v[100:103]
	v_mfma_f32_16x16x32_bf16 v[96:99], v[154:157], v[194:197], v[96:99]
	v_mfma_f32_16x16x32_bf16 v[92:95], v[162:165], v[194:197], v[92:95]
	v_mfma_f32_16x16x32_bf16 v[88:91], v[154:157], v[208:211], v[88:91]
	v_mfma_f32_16x16x32_bf16 v[84:87], v[162:165], v[208:211], v[84:87]
	v_mfma_f32_16x16x32_bf16 v[80:83], v[154:157], v[236:239], v[80:83]
	v_mfma_f32_16x16x32_bf16 v[76:79], v[162:165], v[236:239], v[76:79]
	v_mfma_f32_16x16x32_bf16 v[28:31], v[166:169], v[182:185], v[28:31]
	v_mfma_f32_16x16x32_bf16 v[24:27], v[174:177], v[182:185], v[24:27]
	v_mfma_f32_16x16x32_bf16 v[20:23], v[166:169], v[190:193], v[20:23]
	v_mfma_f32_16x16x32_bf16 v[16:19], v[174:177], v[190:193], v[16:19]
	v_mfma_f32_16x16x32_bf16 v[12:15], v[166:169], v[204:207], v[12:15]
	v_mfma_f32_16x16x32_bf16 v[8:11], v[174:177], v[204:207], v[8:11]
	v_mfma_f32_16x16x32_bf16 v[4:7], v[166:169], v[212:215], v[4:7]
	v_mfma_f32_16x16x32_bf16 v[0:3], v[174:177], v[212:215], v[0:3]
	v_mfma_f32_16x16x32_bf16 v[28:31], v[170:173], v[186:189], v[28:31]
	v_mfma_f32_16x16x32_bf16 v[24:27], v[178:181], v[186:189], v[24:27]
	v_mfma_f32_16x16x32_bf16 v[20:23], v[170:173], v[194:197], v[20:23]
	v_mfma_f32_16x16x32_bf16 v[16:19], v[178:181], v[194:197], v[16:19]
	v_mfma_f32_16x16x32_bf16 v[12:15], v[170:173], v[208:211], v[12:15]
	v_mfma_f32_16x16x32_bf16 v[8:11], v[178:181], v[208:211], v[8:11]
	v_mfma_f32_16x16x32_bf16 v[4:7], v[170:173], v[236:239], v[4:7]
	v_mfma_f32_16x16x32_bf16 v[0:3], v[178:181], v[236:239], v[0:3]
	s_barrier
	s_add_i32 s71, 0, 0x18000
	s_add_i32 s72, 0, 0x1c000
	v_add_u32_e32 v162, s71, v148
	v_add_u32_e32 v178, s72, v148
	ds_read_b128 v[150:153], v162
	ds_read_b128 v[154:157], v162 offset:1024
	ds_read_b128 v[158:161], v162 offset:2048
	ds_read_b128 v[162:165], v162 offset:3072
	ds_read_b128 v[166:169], v178
	ds_read_b128 v[170:173], v178 offset:1024
	ds_read_b128 v[174:177], v178 offset:2048
	ds_read_b128 v[178:181], v178 offset:3072
	s_add_u32 s0, s0, s10
	s_addc_u32 s1, s1, s11
	s_mov_b32 m0, s56
	v_lshl_add_u64 v[250:251], s[0:1], 0, v[38:39]
	ds_read_b128 v[182:185], v149 offset:32768
	ds_read_b128 v[186:189], v149 offset:33792
	ds_read_b128 v[190:193], v149 offset:34816
	ds_read_b128 v[194:197], v149 offset:35840
	ds_read_b128 v[204:207], v149 offset:36864
	ds_read_b128 v[208:211], v149 offset:37888
	ds_read_b128 v[212:215], v149 offset:38912
	ds_read_b128 v[236:239], v149 offset:39936
	global_load_lds_dwordx4 v[250:251], off
	v_lshl_add_u64 v[250:251], s[0:1], 0, v[140:141]
	s_mov_b32 m0, s57
	s_nop 0
	global_load_lds_dwordx4 v[250:251], off
	s_waitcnt vmcnt(8)
	s_waitcnt lgkmcnt(0)
	s_barrier
	s_waitcnt lgkmcnt(0)
	v_mfma_f32_16x16x32_bf16 v[132:135], v[150:153], v[182:185], v[132:135]
	v_mfma_f32_16x16x32_bf16 v[136:139], v[158:161], v[182:185], v[136:139]
	v_mfma_f32_16x16x32_bf16 v[128:131], v[150:153], v[190:193], v[128:131]
	v_mfma_f32_16x16x32_bf16 v[124:127], v[158:161], v[190:193], v[124:127]
	v_mfma_f32_16x16x32_bf16 v[120:123], v[150:153], v[204:207], v[120:123]
	v_mfma_f32_16x16x32_bf16 v[116:119], v[158:161], v[204:207], v[116:119]
	v_mfma_f32_16x16x32_bf16 v[112:115], v[150:153], v[212:215], v[112:115]
	v_mfma_f32_16x16x32_bf16 v[108:111], v[158:161], v[212:215], v[108:111]
	v_mfma_f32_16x16x32_bf16 v[132:135], v[154:157], v[186:189], v[132:135]
	v_mfma_f32_16x16x32_bf16 v[136:139], v[162:165], v[186:189], v[136:139]
	v_mfma_f32_16x16x32_bf16 v[128:131], v[154:157], v[194:197], v[128:131]
	v_mfma_f32_16x16x32_bf16 v[124:127], v[162:165], v[194:197], v[124:127]
	v_mfma_f32_16x16x32_bf16 v[120:123], v[154:157], v[208:211], v[120:123]
	v_mfma_f32_16x16x32_bf16 v[116:119], v[162:165], v[208:211], v[116:119]
	v_mfma_f32_16x16x32_bf16 v[112:115], v[154:157], v[236:239], v[112:115]
	v_mfma_f32_16x16x32_bf16 v[108:111], v[162:165], v[236:239], v[108:111]
	v_mfma_f32_16x16x32_bf16 v[72:75], v[166:169], v[182:185], v[72:75]
	v_mfma_f32_16x16x32_bf16 v[68:71], v[174:177], v[182:185], v[68:71]
	v_mfma_f32_16x16x32_bf16 v[64:67], v[166:169], v[190:193], v[64:67]
	v_mfma_f32_16x16x32_bf16 v[60:63], v[174:177], v[190:193], v[60:63]
	v_mfma_f32_16x16x32_bf16 v[56:59], v[166:169], v[204:207], v[56:59]
	v_mfma_f32_16x16x32_bf16 v[52:55], v[174:177], v[204:207], v[52:55]
	v_mfma_f32_16x16x32_bf16 v[48:51], v[166:169], v[212:215], v[48:51]
	v_mfma_f32_16x16x32_bf16 v[32:35], v[174:177], v[212:215], v[32:35]
	v_mfma_f32_16x16x32_bf16 v[72:75], v[170:173], v[186:189], v[72:75]
	v_mfma_f32_16x16x32_bf16 v[68:71], v[178:181], v[186:189], v[68:71]
	v_mfma_f32_16x16x32_bf16 v[64:67], v[170:173], v[194:197], v[64:67]
	v_mfma_f32_16x16x32_bf16 v[60:63], v[178:181], v[194:197], v[60:63]
	v_mfma_f32_16x16x32_bf16 v[56:59], v[170:173], v[208:211], v[56:59]
	v_mfma_f32_16x16x32_bf16 v[52:55], v[178:181], v[208:211], v[52:55]
	v_mfma_f32_16x16x32_bf16 v[48:51], v[170:173], v[236:239], v[48:51]
	v_mfma_f32_16x16x32_bf16 v[32:35], v[178:181], v[236:239], v[32:35]
	s_barrier
; #define PG8_STAGE(bufoff, gbase, voff) do { _Pragma("unroll") for (int _i = 0; _i < 2; ++_i) \
;         __builtin_amdgcn_global_load_lds((const unsigned*)((const char*)(gbase) + (voff)[_i]), (PG8_LAS unsigned*)(lds + (bufoff) + ldsw + _i * 8192), 16, 0, 0); } while (0)
; #define PG8_LDA(dst, b, h) do { _Pragma("unroll") for (int m = 0; m < 4; ++m) _Pragma("unroll") for (int k = 0; k < 2; ++k) dst[m][k] = *(const PG8_LAS bf16x8*)(lds + PG8_SA(b, h) + aoff + m * 2048 + k * 1024); } while (0)
; #define PG8_MMA(ai, bj, At, Bt) do { __builtin_amdgcn_s_setprio(1); _Pragma("unroll") for (int m = 0; m < 4; ++m) _Pragma("unroll") for (int n = 0; n < 2; ++n) _Pragma("unroll") for (int k = 0; k < 2; ++k) \
;         acc[ai][bj][m][n] = __builtin_amdgcn_mfma_f32_16x16x32_bf16(Bt[n][k], At[m][k], acc[ai][bj][m][n], 0, 0, 0); __builtin_amdgcn_s_setprio(0); } while (0)
; #define PG8_WAIT_V(n) asm volatile("s_waitcnt vmcnt(" #n ")" ::: "memory")
; #define PG8_WAIT_L(n) asm volatile("s_waitcnt lgkmcnt(" #n ")" ::: "memory")
; #define PG8_BAR __builtin_amdgcn_s_barrier()
; #define PG8_SCHED __builtin_amdgcn_sched_barrier(0)
; template <class Epi, class Sched, bool ALIGN_EPI = false, bool SP2 = false>
; __device__ __forceinline__ void gemm_phase(PG8_LAS unsigned char* lds, const Gemm g, const Sched& S, const Epi& E) {
;     ...
;         for (int t = 0; t < nt; t += 2) {
;             const bool last = (t == nt - 2);
;             const char* a1 = cA + (size_t)(t + 1) * kstep;
;             const char* a2 = last ? nA : cA + (size_t)(t + 2) * kstep; const char* b2 = last ? nB : cB + (size_t)(t + 2) * kstep;
;     ...
;             PG8_LDA(At, 1, 1); PG8_STAGE(PG8_SB(1, 0), b3, voffB); PG8_STAGE(PG8_SB(1, 1), b3 + hstep, voffB); PG8_STAGE(PG8_SA(1, 0), a3, voffA);
;             PG8_WAIT_V(8); PG8_WAIT_L(0); PG8_BAR; PG8_MMA(1, 0, At, B0); PG8_MMA(1, 1, At, B1); PG8_BAR; PG8_SCHED;
	s_add_i32 s0, s71, s49
	v_lshl_add_u64 v[198:199], v[198:199], 0, s[22:23]
	s_mov_b32 m0, s0
	ds_read_b128 v[182:185], v149 offset:49152
	ds_read_b128 v[186:189], v149 offset:50176
	ds_read_b128 v[190:193], v149 offset:51200
	ds_read_b128 v[194:197], v149 offset:52224
	ds_read_b128 v[204:207], v149 offset:53248
	ds_read_b128 v[208:211], v149 offset:54272
	ds_read_b128 v[212:215], v149 offset:55296
	ds_read_b128 v[236:239], v149 offset:56320
	global_load_lds_dwordx4 v[198:199], off
	v_lshl_add_u64 v[198:199], v[240:241], 0, s[22:23]
	s_add_i32 m0, s0, 0x2000
	s_add_i32 s0, s72, s49
	global_load_lds_dwordx4 v[198:199], off
	v_lshl_add_u64 v[198:199], v[242:243], 0, s[22:23]
	s_mov_b32 m0, s0
	s_nop 0
	global_load_lds_dwordx4 v[198:199], off
	v_lshl_add_u64 v[198:199], v[244:245], 0, s[22:23]
	s_add_i32 m0, s0, 0x2000
	s_nop 0
	global_load_lds_dwordx4 v[198:199], off
	v_lshl_add_u64 v[198:199], v[246:247], 0, s[22:23]
	s_mov_b32 m0, s63
	s_nop 0
	global_load_lds_dwordx4 v[198:199], off
	v_lshl_add_u64 v[198:199], v[248:249], 0, s[22:23]
	s_mov_b32 m0, s64
	s_nop 0
	global_load_lds_dwordx4 v[198:199], off
	s_waitcnt vmcnt(8)
	s_waitcnt lgkmcnt(0)
	s_barrier
	s_waitcnt lgkmcnt(0)
	v_mfma_f32_16x16x32_bf16 v[104:107], v[150:153], v[182:185], v[104:107]
	v_mfma_f32_16x16x32_bf16 v[100:103], v[158:161], v[182:185], v[100:103]
	v_mfma_f32_16x16x32_bf16 v[96:99], v[150:153], v[190:193], v[96:99]
	v_mfma_f32_16x16x32_bf16 v[92:95], v[158:161], v[190:193], v[92:95]
	v_mfma_f32_16x16x32_bf16 v[88:91], v[150:153], v[204:207], v[88:91]
	v_mfma_f32_16x16x32_bf16 v[84:87], v[158:161], v[204:207], v[84:87]
	v_mfma_f32_16x16x32_bf16 v[80:83], v[150:153], v[212:215], v[80:83]
	v_mfma_f32_16x16x32_bf16 v[76:79], v[158:161], v[212:215], v[76:79]
	v_mfma_f32_16x16x32_bf16 v[104:107], v[154:157], v[186:189], v[104:107]
	v_mfma_f32_16x16x32_bf16 v[100:103], v[162:165], v[186:189], v[100:103]
	v_mfma_f32_16x16x32_bf16 v[96:99], v[154:157], v[194:197], v[96:99]
	v_mfma_f32_16x16x32_bf16 v[92:95], v[162:165], v[194:197], v[92:95]
	v_mfma_f32_16x16x32_bf16 v[88:91], v[154:157], v[208:211], v[88:91]
	v_mfma_f32_16x16x32_bf16 v[84:87], v[162:165], v[208:211], v[84:87]
	v_mfma_f32_16x16x32_bf16 v[80:83], v[154:157], v[236:239], v[80:83]
	v_mfma_f32_16x16x32_bf16 v[76:79], v[162:165], v[236:239], v[76:79]
	v_mfma_f32_16x16x32_bf16 v[28:31], v[166:169], v[182:185], v[28:31]
	v_mfma_f32_16x16x32_bf16 v[24:27], v[174:177], v[182:185], v[24:27]
	v_mfma_f32_16x16x32_bf16 v[20:23], v[166:169], v[190:193], v[20:23]
	v_mfma_f32_16x16x32_bf16 v[16:19], v[174:177], v[190:193], v[16:19]
	v_mfma_f32_16x16x32_bf16 v[12:15], v[166:169], v[204:207], v[12:15]
	v_mfma_f32_16x16x32_bf16 v[8:11], v[174:177], v[204:207], v[8:11]
	v_mfma_f32_16x16x32_bf16 v[4:7], v[166:169], v[212:215], v[4:7]
	v_mfma_f32_16x16x32_bf16 v[0:3], v[174:177], v[212:215], v[0:3]
	v_mfma_f32_16x16x32_bf16 v[28:31], v[170:173], v[186:189], v[28:31]
	v_mfma_f32_16x16x32_bf16 v[24:27], v[178:181], v[186:189], v[24:27]
	v_mfma_f32_16x16x32_bf16 v[20:23], v[170:173], v[194:197], v[20:23]
	v_mfma_f32_16x16x32_bf16 v[16:19], v[178:181], v[194:197], v[16:19]
	v_mfma_f32_16x16x32_bf16 v[12:15], v[170:173], v[208:211], v[12:15]
	v_mfma_f32_16x16x32_bf16 v[8:11], v[178:181], v[208:211], v[8:11]
	v_mfma_f32_16x16x32_bf16 v[4:7], v[170:173], v[236:239], v[4:7]
	v_mfma_f32_16x16x32_bf16 v[0:3], v[178:181], v[236:239], v[0:3]
	s_barrier
	s_add_u32 s24, s24, 0x100
	s_addc_u32 s25, s25, 0
	s_add_u32 s18, s18, 0x100
	s_addc_u32 s19, s19, 0
	s_cmp_ge_i32 s70, s58
	s_mov_b32 s0, s70
	s_cbranch_scc0 .LBB0_118

; #define PG8_STAGE(bufoff, gbase, voff) do { _Pragma("unroll") for (int _i = 0; _i < 2; ++_i) \
;         __builtin_amdgcn_global_load_lds((const unsigned*)((const char*)(gbase) + (voff)[_i]), (PG8_LAS unsigned*)(lds + (bufoff) + ldsw + _i * 8192), 16, 0, 0); } while (0)
; #define PG8_LDA(dst, b, h) do { _Pragma("unroll") for (int m = 0; m < 4; ++m) _Pragma("unroll") for (int k = 0; k < 2; ++k) dst[m][k] = *(const PG8_LAS bf16x8*)(lds + PG8_SA(b, h) + aoff + m * 2048 + k * 1024); } while (0)
; #define PG8_LDB(dst, b, h) do { _Pragma("unroll") for (int n = 0; n < 2; ++n) _Pragma("unroll") for (int k = 0; k < 2; ++k) dst[n][k] = *(const PG8_LAS bf16x8*)(lds + PG8_SB(b, h) + boff + n * 2048 + k * 1024); } while (0)
; #define PG8_MMA(ai, bj, At, Bt) do { __builtin_amdgcn_s_setprio(1); _Pragma("unroll") for (int m = 0; m < 4; ++m) _Pragma("unroll") for (int n = 0; n < 2; ++n) _Pragma("unroll") for (int k = 0; k < 2; ++k) \
;         acc[ai][bj][m][n] = __builtin_amdgcn_mfma_f32_16x16x32_bf16(Bt[n][k], At[m][k], acc[ai][bj][m][n], 0, 0, 0); __builtin_amdgcn_s_setprio(0); } while (0)
; #define PG8_WAIT_V(n) asm volatile("s_waitcnt vmcnt(" #n ")" ::: "memory")
; #define PG8_WAIT_L(n) asm volatile("s_waitcnt lgkmcnt(" #n ")" ::: "memory")
; template <class Epi, class Sched, bool ALIGN_EPI = false, bool SP2 = false>
; __device__ __forceinline__ void gemm_phase(PG8_LAS unsigned char* lds, const Gemm g, const Sched& S, const Epi& E) {
;     ...
;             const bool last = (t == nt - 2);
;             const char* a1 = cA + (size_t)(t + 1) * kstep;
;             const char* a2 = last ? nA : cA + (size_t)(t + 2) * kstep; const char* b2 = last ? nB : cB + (size_t)(t + 2) * kstep;
;             const char* a3 = a2 + kstep; const char* b3 = b2 + kstep;
;             if (last && has_next) S.a_ready(nxt);
;             if constexpr (SP2) {
;             PG8_LDB(B0, 0, 0); PG8_LDB(B1, 0, 1); PG8_SCHED; PG8_LDA(At, 0, 0); PG8_STAGE(PG8_SA(1, 1), a1 + hstep, voffA);
;             PG8_WAIT_V(8); PG8_WAIT_L(0); PG8_BAR; PG8_MMA(0, 0, At, B0); PG8_MMA(0, 1, At, B1); PG8_BAR; PG8_SCHED;
;             PG8_LDA(At, 0, 1); PG8_STAGE(PG8_SB(0, 0), b2, voffB); PG8_STAGE(PG8_SB(0, 1), b2 + hstep, voffB); PG8_STAGE(PG8_SA(0, 0), a2, voffA);
;             PG8_WAIT_V(8); PG8_WAIT_L(0); PG8_BAR; PG8_MMA(1, 0, At, B0); PG8_MMA(1, 1, At, B1); PG8_BAR; PG8_SCHED;
.LBB0_225:
	s_add_i32 s64, s0, 2
	s_add_u32 s65, s24, 0x80
	s_addc_u32 s1, s25, 0
	s_add_i32 s68, 0, 0x10000
	s_cmp_eq_u32 s57, s0
	s_cselect_b32 s1, s35, s1
	s_cselect_b32 s0, s34, s65
	v_add_u32_e32 v160, s68, v162
	s_cselect_b32 s67, s41, s19
	s_cselect_b32 s66, s40, s18
	s_add_i32 s65, 0, 0x14000
	ds_read_b128 v[148:151], v160
	ds_read_b128 v[152:155], v160 offset:1024
	ds_read_b128 v[156:159], v160 offset:2048
	ds_read_b128 v[164:167], v160 offset:3072
	v_add_u32_e32 v160, s65, v162
	ds_read_b128 v[168:171], v160
	ds_read_b128 v[172:175], v160 offset:1024
	ds_read_b128 v[176:179], v160 offset:2048
	ds_read_b128 v[180:183], v160 offset:3072
	v_lshl_add_u64 v[160:161], s[24:25], 0, v[144:145]
	s_add_i32 m0, s48, 0xc000
	ds_read_b128 v[184:187], v163
	ds_read_b128 v[188:191], v163 offset:1024
	ds_read_b128 v[192:195], v163 offset:2048
	ds_read_b128 v[196:199], v163 offset:3072
	ds_read_b128 v[204:207], v163 offset:4096
	ds_read_b128 v[208:211], v163 offset:5120
	ds_read_b128 v[212:215], v163 offset:6144
	ds_read_b128 v[236:239], v163 offset:7168
	global_load_lds_dwordx4 v[160:161], off
	v_lshl_add_u64 v[160:161], s[24:25], 0, v[146:147]
	s_add_i32 m0, s48, 0xe000
	s_nop 0
	global_load_lds_dwordx4 v[160:161], off
	s_waitcnt vmcnt(8)
	s_waitcnt lgkmcnt(0)
	s_barrier
	s_waitcnt lgkmcnt(0)
	v_mfma_f32_16x16x32_bf16 v[132:135], v[148:151], v[184:187], v[132:135]
	v_mfma_f32_16x16x32_bf16 v[136:139], v[156:159], v[184:187], v[136:139]
	v_mfma_f32_16x16x32_bf16 v[128:131], v[148:151], v[192:195], v[128:131]
	v_mfma_f32_16x16x32_bf16 v[124:127], v[156:159], v[192:195], v[124:127]
	v_mfma_f32_16x16x32_bf16 v[120:123], v[148:151], v[204:207], v[120:123]
	v_mfma_f32_16x16x32_bf16 v[116:119], v[156:159], v[204:207], v[116:119]
	v_mfma_f32_16x16x32_bf16 v[112:115], v[148:151], v[212:215], v[112:115]
	v_mfma_f32_16x16x32_bf16 v[108:111], v[156:159], v[212:215], v[108:111]
	v_mfma_f32_16x16x32_bf16 v[132:135], v[152:155], v[188:191], v[132:135]
	v_mfma_f32_16x16x32_bf16 v[136:139], v[164:167], v[188:191], v[136:139]
	v_mfma_f32_16x16x32_bf16 v[128:131], v[152:155], v[196:199], v[128:131]
	v_mfma_f32_16x16x32_bf16 v[124:127], v[164:167], v[196:199], v[124:127]
	v_mfma_f32_16x16x32_bf16 v[120:123], v[152:155], v[208:211], v[120:123]
	v_mfma_f32_16x16x32_bf16 v[116:119], v[164:167], v[208:211], v[116:119]
	v_mfma_f32_16x16x32_bf16 v[112:115], v[152:155], v[236:239], v[112:115]
	v_mfma_f32_16x16x32_bf16 v[108:111], v[164:167], v[236:239], v[108:111]
	v_mfma_f32_16x16x32_bf16 v[72:75], v[168:171], v[184:187], v[72:75]
	v_mfma_f32_16x16x32_bf16 v[68:71], v[176:179], v[184:187], v[68:71]
	v_mfma_f32_16x16x32_bf16 v[64:67], v[168:171], v[192:195], v[64:67]
	v_mfma_f32_16x16x32_bf16 v[60:63], v[176:179], v[192:195], v[60:63]
	v_mfma_f32_16x16x32_bf16 v[56:59], v[168:171], v[204:207], v[56:59]
	v_mfma_f32_16x16x32_bf16 v[52:55], v[176:179], v[204:207], v[52:55]
	v_mfma_f32_16x16x32_bf16 v[48:51], v[168:171], v[212:215], v[48:51]
	v_mfma_f32_16x16x32_bf16 v[32:35], v[176:179], v[212:215], v[32:35]
	v_mfma_f32_16x16x32_bf16 v[72:75], v[172:175], v[188:191], v[72:75]
	v_mfma_f32_16x16x32_bf16 v[68:71], v[180:183], v[188:191], v[68:71]
	v_mfma_f32_16x16x32_bf16 v[64:67], v[172:175], v[196:199], v[64:67]
	v_mfma_f32_16x16x32_bf16 v[60:63], v[180:183], v[196:199], v[60:63]
	v_mfma_f32_16x16x32_bf16 v[56:59], v[172:175], v[208:211], v[56:59]
	v_mfma_f32_16x16x32_bf16 v[52:55], v[180:183], v[208:211], v[52:55]
	v_mfma_f32_16x16x32_bf16 v[48:51], v[172:175], v[236:239], v[48:51]
	v_mfma_f32_16x16x32_bf16 v[32:35], v[180:183], v[236:239], v[32:35]
	s_barrier
	s_add_i32 s68, s68, s37
	v_lshl_add_u64 v[160:161], s[66:67], 0, v[140:141]
	s_mov_b32 m0, s68
	ds_read_b128 v[184:187], v163 offset:16384
	ds_read_b128 v[188:191], v163 offset:17408
	ds_read_b128 v[192:195], v163 offset:18432
	ds_read_b128 v[196:199], v163 offset:19456
	ds_read_b128 v[204:207], v163 offset:20480
	ds_read_b128 v[208:211], v163 offset:21504
	ds_read_b128 v[212:215], v163 offset:22528
	ds_read_b128 v[236:239], v163 offset:23552
	global_load_lds_dwordx4 v[160:161], off
	s_add_i32 m0, s68, 0x2000
	v_lshl_add_u64 v[240:241], s[66:67], 0, v[38:39]
	s_add_u32 s66, s66, s10
	s_addc_u32 s67, s67, s11
	s_add_i32 s65, s65, s37
	global_load_lds_dwordx4 v[240:241], off
	v_lshl_add_u64 v[242:243], s[66:67], 0, v[140:141]
	s_mov_b32 m0, s65
	v_lshl_add_u64 v[244:245], s[66:67], 0, v[38:39]
	global_load_lds_dwordx4 v[242:243], off
	s_add_i32 m0, s65, 0x2000
	v_lshl_add_u64 v[246:247], s[0:1], 0, v[142:143]
	global_load_lds_dwordx4 v[244:245], off
	s_mov_b32 m0, s48
	v_lshl_add_u64 v[248:249], s[0:1], 0, v[42:43]
	global_load_lds_dwordx4 v[246:247], off
	s_mov_b32 m0, s49
	s_nop 0
	global_load_lds_dwordx4 v[248:249], off
	s_waitcnt vmcnt(8)
	s_waitcnt lgkmcnt(0)
	s_barrier
; #define PG8_STAGE(bufoff, gbase, voff) do { _Pragma("unroll") for (int _i = 0; _i < 2; ++_i) \
;         __builtin_amdgcn_global_load_lds((const unsigned*)((const char*)(gbase) + (voff)[_i]), (PG8_LAS unsigned*)(lds + (bufoff) + ldsw + _i * 8192), 16, 0, 0); } while (0)
; #define PG8_LDA(dst, b, h) do { _Pragma("unroll") for (int m = 0; m < 4; ++m) _Pragma("unroll") for (int k = 0; k < 2; ++k) dst[m][k] = *(const PG8_LAS bf16x8*)(lds + PG8_SA(b, h) + aoff + m * 2048 + k * 1024); } while (0)
; #define PG8_LDB(dst, b, h) do { _Pragma("unroll") for (int n = 0; n < 2; ++n) _Pragma("unroll") for (int k = 0; k < 2; ++k) dst[n][k] = *(const PG8_LAS bf16x8*)(lds + PG8_SB(b, h) + boff + n * 2048 + k * 1024); } while (0)
; #define PG8_MMA(ai, bj, At, Bt) do { __builtin_amdgcn_s_setprio(1); _Pragma("unroll") for (int m = 0; m < 4; ++m) _Pragma("unroll") for (int n = 0; n < 2; ++n) _Pragma("unroll") for (int k = 0; k < 2; ++k) \
;         acc[ai][bj][m][n] = __builtin_amdgcn_mfma_f32_16x16x32_bf16(Bt[n][k], At[m][k], acc[ai][bj][m][n], 0, 0, 0); __builtin_amdgcn_s_setprio(0); } while (0)
; #define PG8_WAIT_V(n) asm volatile("s_waitcnt vmcnt(" #n ")" ::: "memory")
; #define PG8_WAIT_L(n) asm volatile("s_waitcnt lgkmcnt(" #n ")" ::: "memory")
; #define PG8_BAR __builtin_amdgcn_s_barrier()
; #define PG8_SCHED __builtin_amdgcn_sched_barrier(0)
; template <class Epi, class Sched, bool ALIGN_EPI = false, bool SP2 = false>
; __device__ __forceinline__ void gemm_phase(PG8_LAS unsigned char* lds, const Gemm g, const Sched& S, const Epi& E) {
;     ...
;             PG8_WAIT_V(8); PG8_WAIT_L(0); PG8_BAR; PG8_MMA(1, 0, At, B0); PG8_MMA(1, 1, At, B1); PG8_BAR; PG8_SCHED;
;             PG8_LDB(B0, 1, 0); PG8_LDB(B1, 1, 1); PG8_SCHED; PG8_LDA(At, 1, 0); PG8_STAGE(PG8_SA(0, 1), a2 + hstep, voffA);
;             PG8_WAIT_V(8); PG8_WAIT_L(0); PG8_BAR; PG8_MMA(0, 0, At, B0); PG8_MMA(0, 1, At, B1); PG8_BAR; PG8_SCHED;
	s_waitcnt lgkmcnt(0)
	v_mfma_f32_16x16x32_bf16 v[104:107], v[148:151], v[184:187], v[104:107]
	v_mfma_f32_16x16x32_bf16 v[100:103], v[156:159], v[184:187], v[100:103]
	v_mfma_f32_16x16x32_bf16 v[96:99], v[148:151], v[192:195], v[96:99]
	v_mfma_f32_16x16x32_bf16 v[92:95], v[156:159], v[192:195], v[92:95]
	v_mfma_f32_16x16x32_bf16 v[88:91], v[148:151], v[204:207], v[88:91]
	v_mfma_f32_16x16x32_bf16 v[84:87], v[156:159], v[204:207], v[84:87]
	v_mfma_f32_16x16x32_bf16 v[80:83], v[148:151], v[212:215], v[80:83]
	v_mfma_f32_16x16x32_bf16 v[76:79], v[156:159], v[212:215], v[76:79]
	v_mfma_f32_16x16x32_bf16 v[104:107], v[152:155], v[188:191], v[104:107]
	v_mfma_f32_16x16x32_bf16 v[100:103], v[164:167], v[188:191], v[100:103]
	v_mfma_f32_16x16x32_bf16 v[96:99], v[152:155], v[196:199], v[96:99]
	v_mfma_f32_16x16x32_bf16 v[92:95], v[164:167], v[196:199], v[92:95]
	v_mfma_f32_16x16x32_bf16 v[88:91], v[152:155], v[208:211], v[88:91]
	v_mfma_f32_16x16x32_bf16 v[84:87], v[164:167], v[208:211], v[84:87]
	v_mfma_f32_16x16x32_bf16 v[80:83], v[152:155], v[236:239], v[80:83]
	v_mfma_f32_16x16x32_bf16 v[76:79], v[164:167], v[236:239], v[76:79]
	v_mfma_f32_16x16x32_bf16 v[28:31], v[168:171], v[184:187], v[28:31]
	v_mfma_f32_16x16x32_bf16 v[24:27], v[176:179], v[184:187], v[24:27]
	v_mfma_f32_16x16x32_bf16 v[20:23], v[168:171], v[192:195], v[20:23]
	v_mfma_f32_16x16x32_bf16 v[16:19], v[176:179], v[192:195], v[16:19]
	v_mfma_f32_16x16x32_bf16 v[12:15], v[168:171], v[204:207], v[12:15]
	v_mfma_f32_16x16x32_bf16 v[8:11], v[176:179], v[204:207], v[8:11]
	v_mfma_f32_16x16x32_bf16 v[4:7], v[168:171], v[212:215], v[4:7]
	v_mfma_f32_16x16x32_bf16 v[0:3], v[176:179], v[212:215], v[0:3]
	v_mfma_f32_16x16x32_bf16 v[28:31], v[172:175], v[188:191], v[28:31]
	v_mfma_f32_16x16x32_bf16 v[24:27], v[180:183], v[188:191], v[24:27]
	v_mfma_f32_16x16x32_bf16 v[20:23], v[172:175], v[196:199], v[20:23]
	v_mfma_f32_16x16x32_bf16 v[16:19], v[180:183], v[196:199], v[16:19]
	v_mfma_f32_16x16x32_bf16 v[12:15], v[172:175], v[208:211], v[12:15]
	v_mfma_f32_16x16x32_bf16 v[8:11], v[180:183], v[208:211], v[8:11]
	v_mfma_f32_16x16x32_bf16 v[4:7], v[172:175], v[236:239], v[4:7]
	v_mfma_f32_16x16x32_bf16 v[0:3], v[180:183], v[236:239], v[0:3]
	s_barrier
	s_add_i32 s65, 0, 0x18000
	s_add_i32 s66, 0, 0x1c000
	v_add_u32_e32 v164, s65, v162
	v_add_u32_e32 v180, s66, v162
	ds_read_b128 v[148:151], v164
	ds_read_b128 v[152:155], v164 offset:1024
	ds_read_b128 v[156:159], v164 offset:2048
	ds_read_b128 v[164:167], v164 offset:3072
	ds_read_b128 v[168:171], v180
	ds_read_b128 v[172:175], v180 offset:1024
	ds_read_b128 v[176:179], v180 offset:2048
	ds_read_b128 v[180:183], v180 offset:3072
	s_add_u32 s0, s0, s10
	s_addc_u32 s1, s1, s11
	s_mov_b32 m0, s50
	v_lshl_add_u64 v[250:251], s[0:1], 0, v[142:143]
	ds_read_b128 v[184:187], v163 offset:32768
	ds_read_b128 v[188:191], v163 offset:33792
	ds_read_b128 v[192:195], v163 offset:34816
	ds_read_b128 v[196:199], v163 offset:35840
	ds_read_b128 v[204:207], v163 offset:36864
	ds_read_b128 v[208:211], v163 offset:37888
	ds_read_b128 v[212:215], v163 offset:38912
	ds_read_b128 v[236:239], v163 offset:39936
	global_load_lds_dwordx4 v[250:251], off
	v_lshl_add_u64 v[250:251], s[0:1], 0, v[42:43]
	s_mov_b32 m0, s51
	s_nop 0
	global_load_lds_dwordx4 v[250:251], off
	s_waitcnt vmcnt(8)
	s_waitcnt lgkmcnt(0)
	s_barrier
	s_waitcnt lgkmcnt(0)
	v_mfma_f32_16x16x32_bf16 v[132:135], v[148:151], v[184:187], v[132:135]
	v_mfma_f32_16x16x32_bf16 v[136:139], v[156:159], v[184:187], v[136:139]
	v_mfma_f32_16x16x32_bf16 v[128:131], v[148:151], v[192:195], v[128:131]
	v_mfma_f32_16x16x32_bf16 v[124:127], v[156:159], v[192:195], v[124:127]
	v_mfma_f32_16x16x32_bf16 v[120:123], v[148:151], v[204:207], v[120:123]
	v_mfma_f32_16x16x32_bf16 v[116:119], v[156:159], v[204:207], v[116:119]
	v_mfma_f32_16x16x32_bf16 v[112:115], v[148:151], v[212:215], v[112:115]
	v_mfma_f32_16x16x32_bf16 v[108:111], v[156:159], v[212:215], v[108:111]
	v_mfma_f32_16x16x32_bf16 v[132:135], v[152:155], v[188:191], v[132:135]
	v_mfma_f32_16x16x32_bf16 v[136:139], v[164:167], v[188:191], v[136:139]
	v_mfma_f32_16x16x32_bf16 v[128:131], v[152:155], v[196:199], v[128:131]
	v_mfma_f32_16x16x32_bf16 v[124:127], v[164:167], v[196:199], v[124:127]
	v_mfma_f32_16x16x32_bf16 v[120:123], v[152:155], v[208:211], v[120:123]
	v_mfma_f32_16x16x32_bf16 v[116:119], v[164:167], v[208:211], v[116:119]
	v_mfma_f32_16x16x32_bf16 v[112:115], v[152:155], v[236:239], v[112:115]
	v_mfma_f32_16x16x32_bf16 v[108:111], v[164:167], v[236:239], v[108:111]
	v_mfma_f32_16x16x32_bf16 v[72:75], v[168:171], v[184:187], v[72:75]
	v_mfma_f32_16x16x32_bf16 v[68:71], v[176:179], v[184:187], v[68:71]
	v_mfma_f32_16x16x32_bf16 v[64:67], v[168:171], v[192:195], v[64:67]
	v_mfma_f32_16x16x32_bf16 v[60:63], v[176:179], v[192:195], v[60:63]
	v_mfma_f32_16x16x32_bf16 v[56:59], v[168:171], v[204:207], v[56:59]
	v_mfma_f32_16x16x32_bf16 v[52:55], v[176:179], v[204:207], v[52:55]
	v_mfma_f32_16x16x32_bf16 v[48:51], v[168:171], v[212:215], v[48:51]
	v_mfma_f32_16x16x32_bf16 v[32:35], v[176:179], v[212:215], v[32:35]
	v_mfma_f32_16x16x32_bf16 v[72:75], v[172:175], v[188:191], v[72:75]
	v_mfma_f32_16x16x32_bf16 v[68:71], v[180:183], v[188:191], v[68:71]
	v_mfma_f32_16x16x32_bf16 v[64:67], v[172:175], v[196:199], v[64:67]
	v_mfma_f32_16x16x32_bf16 v[60:63], v[180:183], v[196:199], v[60:63]
	v_mfma_f32_16x16x32_bf16 v[56:59], v[172:175], v[208:211], v[56:59]
	v_mfma_f32_16x16x32_bf16 v[52:55], v[180:183], v[208:211], v[52:55]
	v_mfma_f32_16x16x32_bf16 v[48:51], v[172:175], v[236:239], v[48:51]
	v_mfma_f32_16x16x32_bf16 v[32:35], v[180:183], v[236:239], v[32:35]
	s_barrier
; #define PG8_STAGE(bufoff, gbase, voff) do { _Pragma("unroll") for (int _i = 0; _i < 2; ++_i) \
;         __builtin_amdgcn_global_load_lds((const unsigned*)((const char*)(gbase) + (voff)[_i]), (PG8_LAS unsigned*)(lds + (bufoff) + ldsw + _i * 8192), 16, 0, 0); } while (0)
; #define PG8_LDA(dst, b, h) do { _Pragma("unroll") for (int m = 0; m < 4; ++m) _Pragma("unroll") for (int k = 0; k < 2; ++k) dst[m][k] = *(const PG8_LAS bf16x8*)(lds + PG8_SA(b, h) + aoff + m * 2048 + k * 1024); } while (0)
; #define PG8_MMA(ai, bj, At, Bt) do { __builtin_amdgcn_s_setprio(1); _Pragma("unroll") for (int m = 0; m < 4; ++m) _Pragma("unroll") for (int n = 0; n < 2; ++n) _Pragma("unroll") for (int k = 0; k < 2; ++k) \
;         acc[ai][bj][m][n] = __builtin_amdgcn_mfma_f32_16x16x32_bf16(Bt[n][k], At[m][k], acc[ai][bj][m][n], 0, 0, 0); __builtin_amdgcn_s_setprio(0); } while (0)
; #define PG8_WAIT_V(n) asm volatile("s_waitcnt vmcnt(" #n ")" ::: "memory")
; #define PG8_WAIT_L(n) asm volatile("s_waitcnt lgkmcnt(" #n ")" ::: "memory")
; #define PG8_BAR __builtin_amdgcn_s_barrier()
; #define PG8_SCHED __builtin_amdgcn_sched_barrier(0)
; template <class Epi, class Sched, bool ALIGN_EPI = false, bool SP2 = false>
; __device__ __forceinline__ void gemm_phase(PG8_LAS unsigned char* lds, const Gemm g, const Sched& S, const Epi& E) {
;     ...
;         for (int t = 0; t < nt; t += 2) {
;             const bool last = (t == nt - 2);
;             const char* a1 = cA + (size_t)(t + 1) * kstep;
;             const char* a2 = last ? nA : cA + (size_t)(t + 2) * kstep; const char* b2 = last ? nB : cB + (size_t)(t + 2) * kstep;
;     ...
;             PG8_LDA(At, 1, 1); PG8_STAGE(PG8_SB(1, 0), b3, voffB); PG8_STAGE(PG8_SB(1, 1), b3 + hstep, voffB); PG8_STAGE(PG8_SA(1, 0), a3, voffA);
;             PG8_WAIT_V(8); PG8_WAIT_L(0); PG8_BAR; PG8_MMA(1, 0, At, B0); PG8_MMA(1, 1, At, B1); PG8_BAR; PG8_SCHED;
	s_add_i32 s0, s65, s37
	v_lshl_add_u64 v[160:161], v[160:161], 0, s[22:23]
	s_mov_b32 m0, s0
	ds_read_b128 v[184:187], v163 offset:49152
	ds_read_b128 v[188:191], v163 offset:50176
	ds_read_b128 v[192:195], v163 offset:51200
	ds_read_b128 v[196:199], v163 offset:52224
	ds_read_b128 v[204:207], v163 offset:53248
	ds_read_b128 v[208:211], v163 offset:54272
	ds_read_b128 v[212:215], v163 offset:55296
	ds_read_b128 v[236:239], v163 offset:56320
	global_load_lds_dwordx4 v[160:161], off
	v_lshl_add_u64 v[160:161], v[240:241], 0, s[22:23]
	s_add_i32 m0, s0, 0x2000
	s_add_i32 s0, s66, s37
	global_load_lds_dwordx4 v[160:161], off
	v_lshl_add_u64 v[160:161], v[242:243], 0, s[22:23]
	s_mov_b32 m0, s0
	s_nop 0
	global_load_lds_dwordx4 v[160:161], off
	v_lshl_add_u64 v[160:161], v[244:245], 0, s[22:23]
	s_add_i32 m0, s0, 0x2000
	s_nop 0
	global_load_lds_dwordx4 v[160:161], off
	v_lshl_add_u64 v[160:161], v[246:247], 0, s[22:23]
	s_mov_b32 m0, s55
	s_nop 0
	global_load_lds_dwordx4 v[160:161], off
	v_lshl_add_u64 v[160:161], v[248:249], 0, s[22:23]
	s_mov_b32 m0, s56
	s_nop 0
	global_load_lds_dwordx4 v[160:161], off
	s_waitcnt vmcnt(8)
	s_waitcnt lgkmcnt(0)
	s_barrier
	s_waitcnt lgkmcnt(0)
	v_mfma_f32_16x16x32_bf16 v[104:107], v[148:151], v[184:187], v[104:107]
	v_mfma_f32_16x16x32_bf16 v[100:103], v[156:159], v[184:187], v[100:103]
	v_mfma_f32_16x16x32_bf16 v[96:99], v[148:151], v[192:195], v[96:99]
	v_mfma_f32_16x16x32_bf16 v[92:95], v[156:159], v[192:195], v[92:95]
	v_mfma_f32_16x16x32_bf16 v[88:91], v[148:151], v[204:207], v[88:91]
	v_mfma_f32_16x16x32_bf16 v[84:87], v[156:159], v[204:207], v[84:87]
	v_mfma_f32_16x16x32_bf16 v[80:83], v[148:151], v[212:215], v[80:83]
	v_mfma_f32_16x16x32_bf16 v[76:79], v[156:159], v[212:215], v[76:79]
	v_mfma_f32_16x16x32_bf16 v[104:107], v[152:155], v[188:191], v[104:107]
	v_mfma_f32_16x16x32_bf16 v[100:103], v[164:167], v[188:191], v[100:103]
	v_mfma_f32_16x16x32_bf16 v[96:99], v[152:155], v[196:199], v[96:99]
	v_mfma_f32_16x16x32_bf16 v[92:95], v[164:167], v[196:199], v[92:95]
	v_mfma_f32_16x16x32_bf16 v[88:91], v[152:155], v[208:211], v[88:91]
	v_mfma_f32_16x16x32_bf16 v[84:87], v[164:167], v[208:211], v[84:87]
	v_mfma_f32_16x16x32_bf16 v[80:83], v[152:155], v[236:239], v[80:83]
	v_mfma_f32_16x16x32_bf16 v[76:79], v[164:167], v[236:239], v[76:79]
	v_mfma_f32_16x16x32_bf16 v[28:31], v[168:171], v[184:187], v[28:31]
	v_mfma_f32_16x16x32_bf16 v[24:27], v[176:179], v[184:187], v[24:27]
	v_mfma_f32_16x16x32_bf16 v[20:23], v[168:171], v[192:195], v[20:23]
	v_mfma_f32_16x16x32_bf16 v[16:19], v[176:179], v[192:195], v[16:19]
	v_mfma_f32_16x16x32_bf16 v[12:15], v[168:171], v[204:207], v[12:15]
	v_mfma_f32_16x16x32_bf16 v[8:11], v[176:179], v[204:207], v[8:11]
	v_mfma_f32_16x16x32_bf16 v[4:7], v[168:171], v[212:215], v[4:7]
	v_mfma_f32_16x16x32_bf16 v[0:3], v[176:179], v[212:215], v[0:3]
	v_mfma_f32_16x16x32_bf16 v[28:31], v[172:175], v[188:191], v[28:31]
	v_mfma_f32_16x16x32_bf16 v[24:27], v[180:183], v[188:191], v[24:27]
	v_mfma_f32_16x16x32_bf16 v[20:23], v[172:175], v[196:199], v[20:23]
	v_mfma_f32_16x16x32_bf16 v[16:19], v[180:183], v[196:199], v[16:19]
	v_mfma_f32_16x16x32_bf16 v[12:15], v[172:175], v[208:211], v[12:15]
	v_mfma_f32_16x16x32_bf16 v[8:11], v[180:183], v[208:211], v[8:11]
	v_mfma_f32_16x16x32_bf16 v[4:7], v[172:175], v[236:239], v[4:7]
	v_mfma_f32_16x16x32_bf16 v[0:3], v[180:183], v[236:239], v[0:3]
	s_barrier
	s_add_u32 s24, s24, 0x100
	s_addc_u32 s25, s25, 0
	s_add_u32 s18, s18, 0x100
	s_addc_u32 s19, s19, 0
	s_cmp_ge_i32 s64, s52
	s_mov_b32 s0, s64
	s_cbranch_scc0 .LBB0_225
	s_movk_i32 s67, 0x2000
	s_movk_i32 s66, 0x3000

; #define PG8_STAGE(bufoff, gbase, voff) do { _Pragma("unroll") for (int _i = 0; _i < 2; ++_i) \
;         __builtin_amdgcn_global_load_lds((const unsigned*)((const char*)(gbase) + (voff)[_i]), (PG8_LAS unsigned*)(lds + (bufoff) + ldsw + _i * 8192), 16, 0, 0); } while (0)
; #define PG8_LDA(dst, b, h) do { _Pragma("unroll") for (int m = 0; m < 4; ++m) _Pragma("unroll") for (int k = 0; k < 2; ++k) dst[m][k] = *(const PG8_LAS bf16x8*)(lds + PG8_SA(b, h) + aoff + m * 2048 + k * 1024); } while (0)
; #define PG8_LDB(dst, b, h) do { _Pragma("unroll") for (int n = 0; n < 2; ++n) _Pragma("unroll") for (int k = 0; k < 2; ++k) dst[n][k] = *(const PG8_LAS bf16x8*)(lds + PG8_SB(b, h) + boff + n * 2048 + k * 1024); } while (0)
; #define PG8_MMA(ai, bj, At, Bt) do { __builtin_amdgcn_s_setprio(1); _Pragma("unroll") for (int m = 0; m < 4; ++m) _Pragma("unroll") for (int n = 0; n < 2; ++n) _Pragma("unroll") for (int k = 0; k < 2; ++k) \
;         acc[ai][bj][m][n] = __builtin_amdgcn_mfma_f32_16x16x32_bf16(Bt[n][k], At[m][k], acc[ai][bj][m][n], 0, 0, 0); __builtin_amdgcn_s_setprio(0); } while (0)
; #define PG8_WAIT_V(n) asm volatile("s_waitcnt vmcnt(" #n ")" ::: "memory")
; #define PG8_WAIT_L(n) asm volatile("s_waitcnt lgkmcnt(" #n ")" ::: "memory")
; template <class Epi, class Sched, bool ALIGN_EPI = false, bool SP2 = false>
; __device__ __forceinline__ void gemm_phase(PG8_LAS unsigned char* lds, const Gemm g, const Sched& S, const Epi& E) {
;     ...
;             const bool last = (t == nt - 2);
;             const char* a1 = cA + (size_t)(t + 1) * kstep;
;             const char* a2 = last ? nA : cA + (size_t)(t + 2) * kstep; const char* b2 = last ? nB : cB + (size_t)(t + 2) * kstep;
;             const char* a3 = a2 + kstep; const char* b3 = b2 + kstep;
;             if (last && has_next) S.a_ready(nxt);
;             if constexpr (SP2) {
;             PG8_LDB(B0, 0, 0); PG8_LDB(B1, 0, 1); PG8_SCHED; PG8_LDA(At, 0, 0); PG8_STAGE(PG8_SA(1, 1), a1 + hstep, voffA);
;             PG8_WAIT_V(8); PG8_WAIT_L(0); PG8_BAR; PG8_MMA(0, 0, At, B0); PG8_MMA(0, 1, At, B1); PG8_BAR; PG8_SCHED;
;             PG8_LDA(At, 0, 1); PG8_STAGE(PG8_SB(0, 0), b2, voffB); PG8_STAGE(PG8_SB(0, 1), b2 + hstep, voffB); PG8_STAGE(PG8_SA(0, 0), a2, voffA);
;             PG8_WAIT_V(8); PG8_WAIT_L(0); PG8_BAR; PG8_MMA(1, 0, At, B0); PG8_MMA(1, 1, At, B1); PG8_BAR; PG8_SCHED;
.LBB0_247:
	s_add_i32 s69, s0, 2
	s_add_u32 s70, s24, 0x80
	s_addc_u32 s1, s25, 0
	s_add_i32 s72, 0, 0x10000
	s_cmp_eq_u32 s63, s0
	s_cselect_b32 s1, s35, s1
	s_cselect_b32 s0, s34, s70
	s_cselect_b32 s71, s41, s19
	s_cselect_b32 s70, s40, s18
	s_add_i32 s73, 0, 0x14000
	v_add_u32_e32 v162, s72, v148
	v_add_u32_e32 v178, s73, v148
	ds_read_b128 v[150:153], v162
	ds_read_b128 v[154:157], v162 offset:1024
	ds_read_b128 v[158:161], v162 offset:2048
	ds_read_b128 v[162:165], v162 offset:3072
	ds_read_b128 v[166:169], v178
	ds_read_b128 v[170:173], v178 offset:1024
	ds_read_b128 v[174:177], v178 offset:2048
	ds_read_b128 v[178:181], v178 offset:3072
	v_lshl_add_u64 v[198:199], s[24:25], 0, v[144:145]
	s_add_i32 m0, s51, 0xc000
	ds_read_b128 v[182:185], v149
	ds_read_b128 v[186:189], v149 offset:1024
	ds_read_b128 v[190:193], v149 offset:2048
	ds_read_b128 v[194:197], v149 offset:3072
	ds_read_b128 v[204:207], v149 offset:4096
	ds_read_b128 v[208:211], v149 offset:5120
	ds_read_b128 v[212:215], v149 offset:6144
	ds_read_b128 v[236:239], v149 offset:7168
	global_load_lds_dwordx4 v[198:199], off
	v_lshl_add_u64 v[198:199], s[24:25], 0, v[146:147]
	s_add_i32 m0, s51, 0xe000
	s_nop 0
	global_load_lds_dwordx4 v[198:199], off
	s_waitcnt vmcnt(8)
	s_waitcnt lgkmcnt(0)
	s_barrier
	s_waitcnt lgkmcnt(0)
	v_mfma_f32_16x16x32_bf16 v[136:139], v[150:153], v[182:185], v[136:139]
	v_mfma_f32_16x16x32_bf16 v[132:135], v[158:161], v[182:185], v[132:135]
	v_mfma_f32_16x16x32_bf16 v[128:131], v[150:153], v[190:193], v[128:131]
	v_mfma_f32_16x16x32_bf16 v[124:127], v[158:161], v[190:193], v[124:127]
	v_mfma_f32_16x16x32_bf16 v[120:123], v[150:153], v[204:207], v[120:123]
	v_mfma_f32_16x16x32_bf16 v[116:119], v[158:161], v[204:207], v[116:119]
	v_mfma_f32_16x16x32_bf16 v[112:115], v[150:153], v[212:215], v[112:115]
	v_mfma_f32_16x16x32_bf16 v[108:111], v[158:161], v[212:215], v[108:111]
	v_mfma_f32_16x16x32_bf16 v[136:139], v[154:157], v[186:189], v[136:139]
	v_mfma_f32_16x16x32_bf16 v[132:135], v[162:165], v[186:189], v[132:135]
	v_mfma_f32_16x16x32_bf16 v[128:131], v[154:157], v[194:197], v[128:131]
	v_mfma_f32_16x16x32_bf16 v[124:127], v[162:165], v[194:197], v[124:127]
	v_mfma_f32_16x16x32_bf16 v[120:123], v[154:157], v[208:211], v[120:123]
	v_mfma_f32_16x16x32_bf16 v[116:119], v[162:165], v[208:211], v[116:119]
	v_mfma_f32_16x16x32_bf16 v[112:115], v[154:157], v[236:239], v[112:115]
	v_mfma_f32_16x16x32_bf16 v[108:111], v[162:165], v[236:239], v[108:111]
	v_mfma_f32_16x16x32_bf16 v[72:75], v[166:169], v[182:185], v[72:75]
	v_mfma_f32_16x16x32_bf16 v[68:71], v[174:177], v[182:185], v[68:71]
	v_mfma_f32_16x16x32_bf16 v[64:67], v[166:169], v[190:193], v[64:67]
	v_mfma_f32_16x16x32_bf16 v[60:63], v[174:177], v[190:193], v[60:63]
	v_mfma_f32_16x16x32_bf16 v[56:59], v[166:169], v[204:207], v[56:59]
	v_mfma_f32_16x16x32_bf16 v[52:55], v[174:177], v[204:207], v[52:55]
	v_mfma_f32_16x16x32_bf16 v[48:51], v[166:169], v[212:215], v[48:51]
	v_mfma_f32_16x16x32_bf16 v[32:35], v[174:177], v[212:215], v[32:35]
	v_mfma_f32_16x16x32_bf16 v[72:75], v[170:173], v[186:189], v[72:75]
	v_mfma_f32_16x16x32_bf16 v[68:71], v[178:181], v[186:189], v[68:71]
	v_mfma_f32_16x16x32_bf16 v[64:67], v[170:173], v[194:197], v[64:67]
	v_mfma_f32_16x16x32_bf16 v[60:63], v[178:181], v[194:197], v[60:63]
	v_mfma_f32_16x16x32_bf16 v[56:59], v[170:173], v[208:211], v[56:59]
	v_mfma_f32_16x16x32_bf16 v[52:55], v[178:181], v[208:211], v[52:55]
	v_mfma_f32_16x16x32_bf16 v[48:51], v[170:173], v[236:239], v[48:51]
	v_mfma_f32_16x16x32_bf16 v[32:35], v[178:181], v[236:239], v[32:35]
	s_barrier
	s_add_i32 s72, s72, s47
	v_lshl_add_u64 v[198:199], s[70:71], 0, v[140:141]
	s_mov_b32 m0, s72
	ds_read_b128 v[182:185], v149 offset:16384
	ds_read_b128 v[186:189], v149 offset:17408
	ds_read_b128 v[190:193], v149 offset:18432
	ds_read_b128 v[194:197], v149 offset:19456
	ds_read_b128 v[204:207], v149 offset:20480
	ds_read_b128 v[208:211], v149 offset:21504
	ds_read_b128 v[212:215], v149 offset:22528
	ds_read_b128 v[236:239], v149 offset:23552
	global_load_lds_dwordx4 v[198:199], off
	s_add_i32 m0, s72, 0x2000
	v_lshl_add_u64 v[240:241], s[70:71], 0, v[38:39]
	s_add_u32 s70, s70, s2
	s_addc_u32 s71, s71, s3
	s_add_i32 s72, s73, s47
	global_load_lds_dwordx4 v[240:241], off
	v_lshl_add_u64 v[242:243], s[70:71], 0, v[140:141]
	s_mov_b32 m0, s72
	v_lshl_add_u64 v[244:245], s[70:71], 0, v[38:39]
	global_load_lds_dwordx4 v[242:243], off
	s_add_i32 m0, s72, 0x2000
	v_lshl_add_u64 v[246:247], s[0:1], 0, v[142:143]
	global_load_lds_dwordx4 v[244:245], off
	s_mov_b32 m0, s51
	v_lshl_add_u64 v[248:249], s[0:1], 0, v[42:43]
	global_load_lds_dwordx4 v[246:247], off
	s_mov_b32 m0, s52
	s_nop 0
	global_load_lds_dwordx4 v[248:249], off
	s_waitcnt vmcnt(8)
	s_waitcnt lgkmcnt(0)
	s_barrier
; #define PG8_STAGE(bufoff, gbase, voff) do { _Pragma("unroll") for (int _i = 0; _i < 2; ++_i) \
;         __builtin_amdgcn_global_load_lds((const unsigned*)((const char*)(gbase) + (voff)[_i]), (PG8_LAS unsigned*)(lds + (bufoff) + ldsw + _i * 8192), 16, 0, 0); } while (0)
; #define PG8_LDA(dst, b, h) do { _Pragma("unroll") for (int m = 0; m < 4; ++m) _Pragma("unroll") for (int k = 0; k < 2; ++k) dst[m][k] = *(const PG8_LAS bf16x8*)(lds + PG8_SA(b, h) + aoff + m * 2048 + k * 1024); } while (0)
; #define PG8_LDB(dst, b, h) do { _Pragma("unroll") for (int n = 0; n < 2; ++n) _Pragma("unroll") for (int k = 0; k < 2; ++k) dst[n][k] = *(const PG8_LAS bf16x8*)(lds + PG8_SB(b, h) + boff + n * 2048 + k * 1024); } while (0)
; #define PG8_MMA(ai, bj, At, Bt) do { __builtin_amdgcn_s_setprio(1); _Pragma("unroll") for (int m = 0; m < 4; ++m) _Pragma("unroll") for (int n = 0; n < 2; ++n) _Pragma("unroll") for (int k = 0; k < 2; ++k) \
;         acc[ai][bj][m][n] = __builtin_amdgcn_mfma_f32_16x16x32_bf16(Bt[n][k], At[m][k], acc[ai][bj][m][n], 0, 0, 0); __builtin_amdgcn_s_setprio(0); } while (0)
; #define PG8_WAIT_V(n) asm volatile("s_waitcnt vmcnt(" #n ")" ::: "memory")
; #define PG8_WAIT_L(n) asm volatile("s_waitcnt lgkmcnt(" #n ")" ::: "memory")
; #define PG8_BAR __builtin_amdgcn_s_barrier()
; #define PG8_SCHED __builtin_amdgcn_sched_barrier(0)
; template <class Epi, class Sched, bool ALIGN_EPI = false, bool SP2 = false>
; __device__ __forceinline__ void gemm_phase(PG8_LAS unsigned char* lds, const Gemm g, const Sched& S, const Epi& E) {
;     ...
;             PG8_WAIT_V(8); PG8_WAIT_L(0); PG8_BAR; PG8_MMA(1, 0, At, B0); PG8_MMA(1, 1, At, B1); PG8_BAR; PG8_SCHED;
;             PG8_LDB(B0, 1, 0); PG8_LDB(B1, 1, 1); PG8_SCHED; PG8_LDA(At, 1, 0); PG8_STAGE(PG8_SA(0, 1), a2 + hstep, voffA);
;             PG8_WAIT_V(8); PG8_WAIT_L(0); PG8_BAR; PG8_MMA(0, 0, At, B0); PG8_MMA(0, 1, At, B1); PG8_BAR; PG8_SCHED;
	s_waitcnt lgkmcnt(0)
	v_mfma_f32_16x16x32_bf16 v[104:107], v[150:153], v[182:185], v[104:107]
	v_mfma_f32_16x16x32_bf16 v[100:103], v[158:161], v[182:185], v[100:103]
	v_mfma_f32_16x16x32_bf16 v[96:99], v[150:153], v[190:193], v[96:99]
	v_mfma_f32_16x16x32_bf16 v[92:95], v[158:161], v[190:193], v[92:95]
	v_mfma_f32_16x16x32_bf16 v[88:91], v[150:153], v[204:207], v[88:91]
	v_mfma_f32_16x16x32_bf16 v[84:87], v[158:161], v[204:207], v[84:87]
	v_mfma_f32_16x16x32_bf16 v[80:83], v[150:153], v[212:215], v[80:83]
	v_mfma_f32_16x16x32_bf16 v[76:79], v[158:161], v[212:215], v[76:79]
	v_mfma_f32_16x16x32_bf16 v[104:107], v[154:157], v[186:189], v[104:107]
	v_mfma_f32_16x16x32_bf16 v[100:103], v[162:165], v[186:189], v[100:103]
	v_mfma_f32_16x16x32_bf16 v[96:99], v[154:157], v[194:197], v[96:99]
	v_mfma_f32_16x16x32_bf16 v[92:95], v[162:165], v[194:197], v[92:95]
	v_mfma_f32_16x16x32_bf16 v[88:91], v[154:157], v[208:211], v[88:91]
	v_mfma_f32_16x16x32_bf16 v[84:87], v[162:165], v[208:211], v[84:87]
	v_mfma_f32_16x16x32_bf16 v[80:83], v[154:157], v[236:239], v[80:83]
	v_mfma_f32_16x16x32_bf16 v[76:79], v[162:165], v[236:239], v[76:79]
	v_mfma_f32_16x16x32_bf16 v[28:31], v[166:169], v[182:185], v[28:31]
	v_mfma_f32_16x16x32_bf16 v[24:27], v[174:177], v[182:185], v[24:27]
	v_mfma_f32_16x16x32_bf16 v[20:23], v[166:169], v[190:193], v[20:23]
	v_mfma_f32_16x16x32_bf16 v[16:19], v[174:177], v[190:193], v[16:19]
	v_mfma_f32_16x16x32_bf16 v[12:15], v[166:169], v[204:207], v[12:15]
	v_mfma_f32_16x16x32_bf16 v[8:11], v[174:177], v[204:207], v[8:11]
	v_mfma_f32_16x16x32_bf16 v[4:7], v[166:169], v[212:215], v[4:7]
	v_mfma_f32_16x16x32_bf16 v[0:3], v[174:177], v[212:215], v[0:3]
	v_mfma_f32_16x16x32_bf16 v[28:31], v[170:173], v[186:189], v[28:31]
	v_mfma_f32_16x16x32_bf16 v[24:27], v[178:181], v[186:189], v[24:27]
	v_mfma_f32_16x16x32_bf16 v[20:23], v[170:173], v[194:197], v[20:23]
	v_mfma_f32_16x16x32_bf16 v[16:19], v[178:181], v[194:197], v[16:19]
	v_mfma_f32_16x16x32_bf16 v[12:15], v[170:173], v[208:211], v[12:15]
	v_mfma_f32_16x16x32_bf16 v[8:11], v[178:181], v[208:211], v[8:11]
	v_mfma_f32_16x16x32_bf16 v[4:7], v[170:173], v[236:239], v[4:7]
	v_mfma_f32_16x16x32_bf16 v[0:3], v[178:181], v[236:239], v[0:3]
	s_barrier
	s_add_i32 s70, 0, 0x18000
	s_add_i32 s71, 0, 0x1c000
	v_add_u32_e32 v162, s70, v148
	v_add_u32_e32 v178, s71, v148
	ds_read_b128 v[150:153], v162
	ds_read_b128 v[154:157], v162 offset:1024
	ds_read_b128 v[158:161], v162 offset:2048
	ds_read_b128 v[162:165], v162 offset:3072
	ds_read_b128 v[166:169], v178
	ds_read_b128 v[170:173], v178 offset:1024
	ds_read_b128 v[174:177], v178 offset:2048
	ds_read_b128 v[178:181], v178 offset:3072
	s_add_u32 s0, s0, s2
	s_addc_u32 s1, s1, s3
	s_mov_b32 m0, s53
	v_lshl_add_u64 v[250:251], s[0:1], 0, v[142:143]
	ds_read_b128 v[182:185], v149 offset:32768
	ds_read_b128 v[186:189], v149 offset:33792
	ds_read_b128 v[190:193], v149 offset:34816
	ds_read_b128 v[194:197], v149 offset:35840
	ds_read_b128 v[204:207], v149 offset:36864
	ds_read_b128 v[208:211], v149 offset:37888
	ds_read_b128 v[212:215], v149 offset:38912
	ds_read_b128 v[236:239], v149 offset:39936
	global_load_lds_dwordx4 v[250:251], off
	v_lshl_add_u64 v[250:251], s[0:1], 0, v[42:43]
	s_mov_b32 m0, s54
	s_nop 0
	global_load_lds_dwordx4 v[250:251], off
	s_waitcnt vmcnt(8)
	s_waitcnt lgkmcnt(0)
	s_barrier
	s_waitcnt lgkmcnt(0)
	v_mfma_f32_16x16x32_bf16 v[136:139], v[150:153], v[182:185], v[136:139]
	v_mfma_f32_16x16x32_bf16 v[132:135], v[158:161], v[182:185], v[132:135]
	v_mfma_f32_16x16x32_bf16 v[128:131], v[150:153], v[190:193], v[128:131]
	v_mfma_f32_16x16x32_bf16 v[124:127], v[158:161], v[190:193], v[124:127]
	v_mfma_f32_16x16x32_bf16 v[120:123], v[150:153], v[204:207], v[120:123]
	v_mfma_f32_16x16x32_bf16 v[116:119], v[158:161], v[204:207], v[116:119]
	v_mfma_f32_16x16x32_bf16 v[112:115], v[150:153], v[212:215], v[112:115]
	v_mfma_f32_16x16x32_bf16 v[108:111], v[158:161], v[212:215], v[108:111]
	v_mfma_f32_16x16x32_bf16 v[136:139], v[154:157], v[186:189], v[136:139]
	v_mfma_f32_16x16x32_bf16 v[132:135], v[162:165], v[186:189], v[132:135]
	v_mfma_f32_16x16x32_bf16 v[128:131], v[154:157], v[194:197], v[128:131]
	v_mfma_f32_16x16x32_bf16 v[124:127], v[162:165], v[194:197], v[124:127]
	v_mfma_f32_16x16x32_bf16 v[120:123], v[154:157], v[208:211], v[120:123]
	v_mfma_f32_16x16x32_bf16 v[116:119], v[162:165], v[208:211], v[116:119]
	v_mfma_f32_16x16x32_bf16 v[112:115], v[154:157], v[236:239], v[112:115]
	v_mfma_f32_16x16x32_bf16 v[108:111], v[162:165], v[236:239], v[108:111]
	v_mfma_f32_16x16x32_bf16 v[72:75], v[166:169], v[182:185], v[72:75]
	v_mfma_f32_16x16x32_bf16 v[68:71], v[174:177], v[182:185], v[68:71]
	v_mfma_f32_16x16x32_bf16 v[64:67], v[166:169], v[190:193], v[64:67]
	v_mfma_f32_16x16x32_bf16 v[60:63], v[174:177], v[190:193], v[60:63]
	v_mfma_f32_16x16x32_bf16 v[56:59], v[166:169], v[204:207], v[56:59]
	v_mfma_f32_16x16x32_bf16 v[52:55], v[174:177], v[204:207], v[52:55]
	v_mfma_f32_16x16x32_bf16 v[48:51], v[166:169], v[212:215], v[48:51]
	v_mfma_f32_16x16x32_bf16 v[32:35], v[174:177], v[212:215], v[32:35]
	v_mfma_f32_16x16x32_bf16 v[72:75], v[170:173], v[186:189], v[72:75]
	v_mfma_f32_16x16x32_bf16 v[68:71], v[178:181], v[186:189], v[68:71]
	v_mfma_f32_16x16x32_bf16 v[64:67], v[170:173], v[194:197], v[64:67]
	v_mfma_f32_16x16x32_bf16 v[60:63], v[178:181], v[194:197], v[60:63]
	v_mfma_f32_16x16x32_bf16 v[56:59], v[170:173], v[208:211], v[56:59]
	v_mfma_f32_16x16x32_bf16 v[52:55], v[178:181], v[208:211], v[52:55]
	v_mfma_f32_16x16x32_bf16 v[48:51], v[170:173], v[236:239], v[48:51]
	v_mfma_f32_16x16x32_bf16 v[32:35], v[178:181], v[236:239], v[32:35]
	s_barrier
; #define PG8_STAGE(bufoff, gbase, voff) do { _Pragma("unroll") for (int _i = 0; _i < 2; ++_i) \
;         __builtin_amdgcn_global_load_lds((const unsigned*)((const char*)(gbase) + (voff)[_i]), (PG8_LAS unsigned*)(lds + (bufoff) + ldsw + _i * 8192), 16, 0, 0); } while (0)
; #define PG8_LDA(dst, b, h) do { _Pragma("unroll") for (int m = 0; m < 4; ++m) _Pragma("unroll") for (int k = 0; k < 2; ++k) dst[m][k] = *(const PG8_LAS bf16x8*)(lds + PG8_SA(b, h) + aoff + m * 2048 + k * 1024); } while (0)
; #define PG8_MMA(ai, bj, At, Bt) do { __builtin_amdgcn_s_setprio(1); _Pragma("unroll") for (int m = 0; m < 4; ++m) _Pragma("unroll") for (int n = 0; n < 2; ++n) _Pragma("unroll") for (int k = 0; k < 2; ++k) \
;         acc[ai][bj][m][n] = __builtin_amdgcn_mfma_f32_16x16x32_bf16(Bt[n][k], At[m][k], acc[ai][bj][m][n], 0, 0, 0); __builtin_amdgcn_s_setprio(0); } while (0)
; #define PG8_WAIT_V(n) asm volatile("s_waitcnt vmcnt(" #n ")" ::: "memory")
; #define PG8_WAIT_L(n) asm volatile("s_waitcnt lgkmcnt(" #n ")" ::: "memory")
; #define PG8_BAR __builtin_amdgcn_s_barrier()
; #define PG8_SCHED __builtin_amdgcn_sched_barrier(0)
; template <class Epi, class Sched, bool ALIGN_EPI = false, bool SP2 = false>
; __device__ __forceinline__ void gemm_phase(PG8_LAS unsigned char* lds, const Gemm g, const Sched& S, const Epi& E) {
;     ...
;         for (int t = 0; t < nt; t += 2) {
;             const bool last = (t == nt - 2);
;             const char* a1 = cA + (size_t)(t + 1) * kstep;
;             const char* a2 = last ? nA : cA + (size_t)(t + 2) * kstep; const char* b2 = last ? nB : cB + (size_t)(t + 2) * kstep;
;     ...
;             PG8_LDA(At, 1, 1); PG8_STAGE(PG8_SB(1, 0), b3, voffB); PG8_STAGE(PG8_SB(1, 1), b3 + hstep, voffB); PG8_STAGE(PG8_SA(1, 0), a3, voffA);
;             PG8_WAIT_V(8); PG8_WAIT_L(0); PG8_BAR; PG8_MMA(1, 0, At, B0); PG8_MMA(1, 1, At, B1); PG8_BAR; PG8_SCHED;
	s_add_i32 s0, s70, s47
	v_lshl_add_u64 v[198:199], v[198:199], 0, s[22:23]
	s_mov_b32 m0, s0
	ds_read_b128 v[182:185], v149 offset:49152
	ds_read_b128 v[186:189], v149 offset:50176
	ds_read_b128 v[190:193], v149 offset:51200
	ds_read_b128 v[194:197], v149 offset:52224
	ds_read_b128 v[204:207], v149 offset:53248
	ds_read_b128 v[208:211], v149 offset:54272
	ds_read_b128 v[212:215], v149 offset:55296
	ds_read_b128 v[236:239], v149 offset:56320
	global_load_lds_dwordx4 v[198:199], off
	v_lshl_add_u64 v[198:199], v[240:241], 0, s[22:23]
	s_add_i32 m0, s0, 0x2000
	s_add_i32 s0, s71, s47
	global_load_lds_dwordx4 v[198:199], off
	v_lshl_add_u64 v[198:199], v[242:243], 0, s[22:23]
	s_mov_b32 m0, s0
	s_nop 0
	global_load_lds_dwordx4 v[198:199], off
	v_lshl_add_u64 v[198:199], v[244:245], 0, s[22:23]
	s_add_i32 m0, s0, 0x2000
	s_nop 0
	global_load_lds_dwordx4 v[198:199], off
	v_lshl_add_u64 v[198:199], v[246:247], 0, s[22:23]
	s_mov_b32 m0, s58
	s_nop 0
	global_load_lds_dwordx4 v[198:199], off
	v_lshl_add_u64 v[198:199], v[248:249], 0, s[22:23]
	s_mov_b32 m0, s59
	s_nop 0
	global_load_lds_dwordx4 v[198:199], off
	s_waitcnt vmcnt(8)
	s_waitcnt lgkmcnt(0)
	s_barrier
	s_waitcnt lgkmcnt(0)
	v_mfma_f32_16x16x32_bf16 v[104:107], v[150:153], v[182:185], v[104:107]
	v_mfma_f32_16x16x32_bf16 v[100:103], v[158:161], v[182:185], v[100:103]
	v_mfma_f32_16x16x32_bf16 v[96:99], v[150:153], v[190:193], v[96:99]
	v_mfma_f32_16x16x32_bf16 v[92:95], v[158:161], v[190:193], v[92:95]
	v_mfma_f32_16x16x32_bf16 v[88:91], v[150:153], v[204:207], v[88:91]
	v_mfma_f32_16x16x32_bf16 v[84:87], v[158:161], v[204:207], v[84:87]
	v_mfma_f32_16x16x32_bf16 v[80:83], v[150:153], v[212:215], v[80:83]
	v_mfma_f32_16x16x32_bf16 v[76:79], v[158:161], v[212:215], v[76:79]
	v_mfma_f32_16x16x32_bf16 v[104:107], v[154:157], v[186:189], v[104:107]
	v_mfma_f32_16x16x32_bf16 v[100:103], v[162:165], v[186:189], v[100:103]
	v_mfma_f32_16x16x32_bf16 v[96:99], v[154:157], v[194:197], v[96:99]
	v_mfma_f32_16x16x32_bf16 v[92:95], v[162:165], v[194:197], v[92:95]
	v_mfma_f32_16x16x32_bf16 v[88:91], v[154:157], v[208:211], v[88:91]
	v_mfma_f32_16x16x32_bf16 v[84:87], v[162:165], v[208:211], v[84:87]
	v_mfma_f32_16x16x32_bf16 v[80:83], v[154:157], v[236:239], v[80:83]
	v_mfma_f32_16x16x32_bf16 v[76:79], v[162:165], v[236:239], v[76:79]
	v_mfma_f32_16x16x32_bf16 v[28:31], v[166:169], v[182:185], v[28:31]
	v_mfma_f32_16x16x32_bf16 v[24:27], v[174:177], v[182:185], v[24:27]
	v_mfma_f32_16x16x32_bf16 v[20:23], v[166:169], v[190:193], v[20:23]
	v_mfma_f32_16x16x32_bf16 v[16:19], v[174:177], v[190:193], v[16:19]
	v_mfma_f32_16x16x32_bf16 v[12:15], v[166:169], v[204:207], v[12:15]
	v_mfma_f32_16x16x32_bf16 v[8:11], v[174:177], v[204:207], v[8:11]
	v_mfma_f32_16x16x32_bf16 v[4:7], v[166:169], v[212:215], v[4:7]
	v_mfma_f32_16x16x32_bf16 v[0:3], v[174:177], v[212:215], v[0:3]
	v_mfma_f32_16x16x32_bf16 v[28:31], v[170:173], v[186:189], v[28:31]
	v_mfma_f32_16x16x32_bf16 v[24:27], v[178:181], v[186:189], v[24:27]
	v_mfma_f32_16x16x32_bf16 v[20:23], v[170:173], v[194:197], v[20:23]
	v_mfma_f32_16x16x32_bf16 v[16:19], v[178:181], v[194:197], v[16:19]
	v_mfma_f32_16x16x32_bf16 v[12:15], v[170:173], v[208:211], v[12:15]
	v_mfma_f32_16x16x32_bf16 v[8:11], v[178:181], v[208:211], v[8:11]
	v_mfma_f32_16x16x32_bf16 v[4:7], v[170:173], v[236:239], v[4:7]
	v_mfma_f32_16x16x32_bf16 v[0:3], v[178:181], v[236:239], v[0:3]
	s_barrier
	s_add_u32 s24, s24, 0x100
	s_addc_u32 s25, s25, 0
	s_add_u32 s18, s18, 0x100
	s_addc_u32 s19, s19, 0
	s_cmp_ge_i32 s69, s55
	s_mov_b32 s0, s69
	s_cbranch_scc0 .LBB0_247
	s_movk_i32 s69, 0x1000

; #define PG8_STAGE(bufoff, gbase, voff) do { _Pragma("unroll") for (int _i = 0; _i < 2; ++_i) \
;         __builtin_amdgcn_global_load_lds((const unsigned*)((const char*)(gbase) + (voff)[_i]), (PG8_LAS unsigned*)(lds + (bufoff) + ldsw + _i * 8192), 16, 0, 0); } while (0)
; #define PG8_LDA(dst, b, h) do { _Pragma("unroll") for (int m = 0; m < 4; ++m) _Pragma("unroll") for (int k = 0; k < 2; ++k) dst[m][k] = *(const PG8_LAS bf16x8*)(lds + PG8_SA(b, h) + aoff + m * 2048 + k * 1024); } while (0)
; #define PG8_LDB(dst, b, h) do { _Pragma("unroll") for (int n = 0; n < 2; ++n) _Pragma("unroll") for (int k = 0; k < 2; ++k) dst[n][k] = *(const PG8_LAS bf16x8*)(lds + PG8_SB(b, h) + boff + n * 2048 + k * 1024); } while (0)
; #define PG8_MMA(ai, bj, At, Bt) do { __builtin_amdgcn_s_setprio(1); _Pragma("unroll") for (int m = 0; m < 4; ++m) _Pragma("unroll") for (int n = 0; n < 2; ++n) _Pragma("unroll") for (int k = 0; k < 2; ++k) \
;         acc[ai][bj][m][n] = __builtin_amdgcn_mfma_f32_16x16x32_bf16(Bt[n][k], At[m][k], acc[ai][bj][m][n], 0, 0, 0); __builtin_amdgcn_s_setprio(0); } while (0)
; #define PG8_WAIT_V(n) asm volatile("s_waitcnt vmcnt(" #n ")" ::: "memory")
; #define PG8_WAIT_L(n) asm volatile("s_waitcnt lgkmcnt(" #n ")" ::: "memory")
; template <class Epi, class Sched, bool ALIGN_EPI = false, bool SP2 = false>
; __device__ __forceinline__ void gemm_phase(PG8_LAS unsigned char* lds, const Gemm g, const Sched& S, const Epi& E) {
;     ...
;             const bool last = (t == nt - 2);
;             const char* a1 = cA + (size_t)(t + 1) * kstep;
;             const char* a2 = last ? nA : cA + (size_t)(t + 2) * kstep; const char* b2 = last ? nB : cB + (size_t)(t + 2) * kstep;
;             const char* a3 = a2 + kstep; const char* b3 = b2 + kstep;
;             if (last && has_next) S.a_ready(nxt);
;             if constexpr (SP2) {
;             PG8_LDB(B0, 0, 0); PG8_LDB(B1, 0, 1); PG8_SCHED; PG8_LDA(At, 0, 0); PG8_STAGE(PG8_SA(1, 1), a1 + hstep, voffA);
;             PG8_WAIT_V(8); PG8_WAIT_L(0); PG8_BAR; PG8_MMA(0, 0, At, B0); PG8_MMA(0, 1, At, B1); PG8_BAR; PG8_SCHED;
;             PG8_LDA(At, 0, 1); PG8_STAGE(PG8_SB(0, 0), b2, voffB); PG8_STAGE(PG8_SB(0, 1), b2 + hstep, voffB); PG8_STAGE(PG8_SA(0, 0), a2, voffA);
;             PG8_WAIT_V(8); PG8_WAIT_L(0); PG8_BAR; PG8_MMA(1, 0, At, B0); PG8_MMA(1, 1, At, B1); PG8_BAR; PG8_SCHED;
.LBB0_271:
	s_add_i32 s68, s0, 2
	s_add_u32 s69, s24, 0x80
	s_addc_u32 s1, s25, 0
	s_add_i32 s72, 0, 0x10000
	s_cmp_eq_u32 s61, s0
	s_cselect_b32 s1, s41, s1
	s_cselect_b32 s0, s40, s69
	s_cselect_b32 s71, s43, s19
	s_cselect_b32 s70, s42, s18
	s_add_i32 s69, 0, 0x14000
	v_add_u32_e32 v162, s72, v156
	v_add_u32_e32 v178, s69, v156
	ds_read_b128 v[148:151], v162
	ds_read_b128 v[152:155], v162 offset:1024
	ds_read_b128 v[158:161], v162 offset:2048
	ds_read_b128 v[162:165], v162 offset:3072
	ds_read_b128 v[166:169], v178
	ds_read_b128 v[170:173], v178 offset:1024
	ds_read_b128 v[174:177], v178 offset:2048
	ds_read_b128 v[178:181], v178 offset:3072
	v_lshl_add_u64 v[198:199], s[24:25], 0, v[144:145]
	s_add_i32 m0, s52, 0xc000
	ds_read_b128 v[182:185], v157
	ds_read_b128 v[186:189], v157 offset:1024
	ds_read_b128 v[190:193], v157 offset:2048
	ds_read_b128 v[194:197], v157 offset:3072
	ds_read_b128 v[204:207], v157 offset:4096
	ds_read_b128 v[208:211], v157 offset:5120
	ds_read_b128 v[212:215], v157 offset:6144
	ds_read_b128 v[236:239], v157 offset:7168
	global_load_lds_dwordx4 v[198:199], off
	v_lshl_add_u64 v[198:199], s[24:25], 0, v[146:147]
	s_add_i32 m0, s52, 0xe000
	s_nop 0
	global_load_lds_dwordx4 v[198:199], off
	s_waitcnt vmcnt(8)
	s_waitcnt lgkmcnt(0)
	s_barrier
	s_waitcnt lgkmcnt(0)
	v_mfma_f32_16x16x32_bf16 v[136:139], v[148:151], v[182:185], v[136:139]
	v_mfma_f32_16x16x32_bf16 v[132:135], v[158:161], v[182:185], v[132:135]
	v_mfma_f32_16x16x32_bf16 v[128:131], v[148:151], v[190:193], v[128:131]
	v_mfma_f32_16x16x32_bf16 v[124:127], v[158:161], v[190:193], v[124:127]
	v_mfma_f32_16x16x32_bf16 v[120:123], v[148:151], v[204:207], v[120:123]
	v_mfma_f32_16x16x32_bf16 v[116:119], v[158:161], v[204:207], v[116:119]
	v_mfma_f32_16x16x32_bf16 v[112:115], v[148:151], v[212:215], v[112:115]
	v_mfma_f32_16x16x32_bf16 v[108:111], v[158:161], v[212:215], v[108:111]
	v_mfma_f32_16x16x32_bf16 v[136:139], v[152:155], v[186:189], v[136:139]
	v_mfma_f32_16x16x32_bf16 v[132:135], v[162:165], v[186:189], v[132:135]
	v_mfma_f32_16x16x32_bf16 v[128:131], v[152:155], v[194:197], v[128:131]
	v_mfma_f32_16x16x32_bf16 v[124:127], v[162:165], v[194:197], v[124:127]
	v_mfma_f32_16x16x32_bf16 v[120:123], v[152:155], v[208:211], v[120:123]
	v_mfma_f32_16x16x32_bf16 v[116:119], v[162:165], v[208:211], v[116:119]
	v_mfma_f32_16x16x32_bf16 v[112:115], v[152:155], v[236:239], v[112:115]
	v_mfma_f32_16x16x32_bf16 v[108:111], v[162:165], v[236:239], v[108:111]
	v_mfma_f32_16x16x32_bf16 v[72:75], v[166:169], v[182:185], v[72:75]
	v_mfma_f32_16x16x32_bf16 v[68:71], v[174:177], v[182:185], v[68:71]
	v_mfma_f32_16x16x32_bf16 v[64:67], v[166:169], v[190:193], v[64:67]
	v_mfma_f32_16x16x32_bf16 v[60:63], v[174:177], v[190:193], v[60:63]
	v_mfma_f32_16x16x32_bf16 v[56:59], v[166:169], v[204:207], v[56:59]
	v_mfma_f32_16x16x32_bf16 v[52:55], v[174:177], v[204:207], v[52:55]
	v_mfma_f32_16x16x32_bf16 v[48:51], v[166:169], v[212:215], v[48:51]
	v_mfma_f32_16x16x32_bf16 v[32:35], v[174:177], v[212:215], v[32:35]
	v_mfma_f32_16x16x32_bf16 v[72:75], v[170:173], v[186:189], v[72:75]
	v_mfma_f32_16x16x32_bf16 v[68:71], v[178:181], v[186:189], v[68:71]
	v_mfma_f32_16x16x32_bf16 v[64:67], v[170:173], v[194:197], v[64:67]
	v_mfma_f32_16x16x32_bf16 v[60:63], v[178:181], v[194:197], v[60:63]
	v_mfma_f32_16x16x32_bf16 v[56:59], v[170:173], v[208:211], v[56:59]
	v_mfma_f32_16x16x32_bf16 v[52:55], v[178:181], v[208:211], v[52:55]
	v_mfma_f32_16x16x32_bf16 v[48:51], v[170:173], v[236:239], v[48:51]
	v_mfma_f32_16x16x32_bf16 v[32:35], v[178:181], v[236:239], v[32:35]
	s_barrier
	s_add_i32 s72, s72, s45
	v_lshl_add_u64 v[198:199], s[70:71], 0, v[140:141]
	s_mov_b32 m0, s72
	ds_read_b128 v[182:185], v157 offset:16384
	ds_read_b128 v[186:189], v157 offset:17408
	ds_read_b128 v[190:193], v157 offset:18432
	ds_read_b128 v[194:197], v157 offset:19456
	ds_read_b128 v[204:207], v157 offset:20480
	ds_read_b128 v[208:211], v157 offset:21504
	ds_read_b128 v[212:215], v157 offset:22528
	ds_read_b128 v[236:239], v157 offset:23552
	global_load_lds_dwordx4 v[198:199], off
	s_add_i32 m0, s72, 0x2000
	v_lshl_add_u64 v[240:241], s[70:71], 0, v[38:39]
	s_add_u32 s70, s70, s10
	s_addc_u32 s71, s71, s11
	s_add_i32 s69, s69, s45
	global_load_lds_dwordx4 v[240:241], off
	v_lshl_add_u64 v[242:243], s[70:71], 0, v[140:141]
	s_mov_b32 m0, s69
	v_lshl_add_u64 v[244:245], s[70:71], 0, v[38:39]
	global_load_lds_dwordx4 v[242:243], off
	s_add_i32 m0, s69, 0x2000
	v_lshl_add_u64 v[246:247], s[0:1], 0, v[142:143]
	global_load_lds_dwordx4 v[244:245], off
	s_mov_b32 m0, s52
	v_lshl_add_u64 v[248:249], s[0:1], 0, v[42:43]
	global_load_lds_dwordx4 v[246:247], off
	s_mov_b32 m0, s53
	s_nop 0
	global_load_lds_dwordx4 v[248:249], off
	s_waitcnt vmcnt(8)
	s_waitcnt lgkmcnt(0)
	s_barrier
; #define PG8_STAGE(bufoff, gbase, voff) do { _Pragma("unroll") for (int _i = 0; _i < 2; ++_i) \
;         __builtin_amdgcn_global_load_lds((const unsigned*)((const char*)(gbase) + (voff)[_i]), (PG8_LAS unsigned*)(lds + (bufoff) + ldsw + _i * 8192), 16, 0, 0); } while (0)
; #define PG8_LDA(dst, b, h) do { _Pragma("unroll") for (int m = 0; m < 4; ++m) _Pragma("unroll") for (int k = 0; k < 2; ++k) dst[m][k] = *(const PG8_LAS bf16x8*)(lds + PG8_SA(b, h) + aoff + m * 2048 + k * 1024); } while (0)
; #define PG8_LDB(dst, b, h) do { _Pragma("unroll") for (int n = 0; n < 2; ++n) _Pragma("unroll") for (int k = 0; k < 2; ++k) dst[n][k] = *(const PG8_LAS bf16x8*)(lds + PG8_SB(b, h) + boff + n * 2048 + k * 1024); } while (0)
; #define PG8_MMA(ai, bj, At, Bt) do { __builtin_amdgcn_s_setprio(1); _Pragma("unroll") for (int m = 0; m < 4; ++m) _Pragma("unroll") for (int n = 0; n < 2; ++n) _Pragma("unroll") for (int k = 0; k < 2; ++k) \
;         acc[ai][bj][m][n] = __builtin_amdgcn_mfma_f32_16x16x32_bf16(Bt[n][k], At[m][k], acc[ai][bj][m][n], 0, 0, 0); __builtin_amdgcn_s_setprio(0); } while (0)
; #define PG8_WAIT_V(n) asm volatile("s_waitcnt vmcnt(" #n ")" ::: "memory")
; #define PG8_WAIT_L(n) asm volatile("s_waitcnt lgkmcnt(" #n ")" ::: "memory")
; #define PG8_BAR __builtin_amdgcn_s_barrier()
; #define PG8_SCHED __builtin_amdgcn_sched_barrier(0)
; template <class Epi, class Sched, bool ALIGN_EPI = false, bool SP2 = false>
; __device__ __forceinline__ void gemm_phase(PG8_LAS unsigned char* lds, const Gemm g, const Sched& S, const Epi& E) {
;     ...
;             PG8_WAIT_V(8); PG8_WAIT_L(0); PG8_BAR; PG8_MMA(1, 0, At, B0); PG8_MMA(1, 1, At, B1); PG8_BAR; PG8_SCHED;
;             PG8_LDB(B0, 1, 0); PG8_LDB(B1, 1, 1); PG8_SCHED; PG8_LDA(At, 1, 0); PG8_STAGE(PG8_SA(0, 1), a2 + hstep, voffA);
;             PG8_WAIT_V(8); PG8_WAIT_L(0); PG8_BAR; PG8_MMA(0, 0, At, B0); PG8_MMA(0, 1, At, B1); PG8_BAR; PG8_SCHED;
	s_waitcnt lgkmcnt(0)
	v_mfma_f32_16x16x32_bf16 v[104:107], v[148:151], v[182:185], v[104:107]
	v_mfma_f32_16x16x32_bf16 v[100:103], v[158:161], v[182:185], v[100:103]
	v_mfma_f32_16x16x32_bf16 v[96:99], v[148:151], v[190:193], v[96:99]
	v_mfma_f32_16x16x32_bf16 v[92:95], v[158:161], v[190:193], v[92:95]
	v_mfma_f32_16x16x32_bf16 v[88:91], v[148:151], v[204:207], v[88:91]
	v_mfma_f32_16x16x32_bf16 v[84:87], v[158:161], v[204:207], v[84:87]
	v_mfma_f32_16x16x32_bf16 v[80:83], v[148:151], v[212:215], v[80:83]
	v_mfma_f32_16x16x32_bf16 v[76:79], v[158:161], v[212:215], v[76:79]
	v_mfma_f32_16x16x32_bf16 v[104:107], v[152:155], v[186:189], v[104:107]
	v_mfma_f32_16x16x32_bf16 v[100:103], v[162:165], v[186:189], v[100:103]
	v_mfma_f32_16x16x32_bf16 v[96:99], v[152:155], v[194:197], v[96:99]
	v_mfma_f32_16x16x32_bf16 v[92:95], v[162:165], v[194:197], v[92:95]
	v_mfma_f32_16x16x32_bf16 v[88:91], v[152:155], v[208:211], v[88:91]
	v_mfma_f32_16x16x32_bf16 v[84:87], v[162:165], v[208:211], v[84:87]
	v_mfma_f32_16x16x32_bf16 v[80:83], v[152:155], v[236:239], v[80:83]
	v_mfma_f32_16x16x32_bf16 v[76:79], v[162:165], v[236:239], v[76:79]
	v_mfma_f32_16x16x32_bf16 v[28:31], v[166:169], v[182:185], v[28:31]
	v_mfma_f32_16x16x32_bf16 v[24:27], v[174:177], v[182:185], v[24:27]
	v_mfma_f32_16x16x32_bf16 v[20:23], v[166:169], v[190:193], v[20:23]
	v_mfma_f32_16x16x32_bf16 v[16:19], v[174:177], v[190:193], v[16:19]
	v_mfma_f32_16x16x32_bf16 v[12:15], v[166:169], v[204:207], v[12:15]
	v_mfma_f32_16x16x32_bf16 v[8:11], v[174:177], v[204:207], v[8:11]
	v_mfma_f32_16x16x32_bf16 v[4:7], v[166:169], v[212:215], v[4:7]
	v_mfma_f32_16x16x32_bf16 v[0:3], v[174:177], v[212:215], v[0:3]
	v_mfma_f32_16x16x32_bf16 v[28:31], v[170:173], v[186:189], v[28:31]
	v_mfma_f32_16x16x32_bf16 v[24:27], v[178:181], v[186:189], v[24:27]
	v_mfma_f32_16x16x32_bf16 v[20:23], v[170:173], v[194:197], v[20:23]
	v_mfma_f32_16x16x32_bf16 v[16:19], v[178:181], v[194:197], v[16:19]
	v_mfma_f32_16x16x32_bf16 v[12:15], v[170:173], v[208:211], v[12:15]
	v_mfma_f32_16x16x32_bf16 v[8:11], v[178:181], v[208:211], v[8:11]
	v_mfma_f32_16x16x32_bf16 v[4:7], v[170:173], v[236:239], v[4:7]
	v_mfma_f32_16x16x32_bf16 v[0:3], v[178:181], v[236:239], v[0:3]
	s_barrier
	s_add_i32 s69, 0, 0x18000
	s_add_i32 s70, 0, 0x1c000
	v_add_u32_e32 v162, s69, v156
	v_add_u32_e32 v178, s70, v156
	ds_read_b128 v[148:151], v162
	ds_read_b128 v[152:155], v162 offset:1024
	ds_read_b128 v[158:161], v162 offset:2048
	ds_read_b128 v[162:165], v162 offset:3072
	ds_read_b128 v[166:169], v178
	ds_read_b128 v[170:173], v178 offset:1024
	ds_read_b128 v[174:177], v178 offset:2048
	ds_read_b128 v[178:181], v178 offset:3072
	s_add_u32 s0, s0, s10
	s_addc_u32 s1, s1, s11
	s_mov_b32 m0, s54
	v_lshl_add_u64 v[250:251], s[0:1], 0, v[142:143]
	ds_read_b128 v[182:185], v157 offset:32768
	ds_read_b128 v[186:189], v157 offset:33792
	ds_read_b128 v[190:193], v157 offset:34816
	ds_read_b128 v[194:197], v157 offset:35840
	ds_read_b128 v[204:207], v157 offset:36864
	ds_read_b128 v[208:211], v157 offset:37888
	ds_read_b128 v[212:215], v157 offset:38912
	ds_read_b128 v[236:239], v157 offset:39936
	global_load_lds_dwordx4 v[250:251], off
	v_lshl_add_u64 v[250:251], s[0:1], 0, v[42:43]
	s_mov_b32 m0, s55
	s_nop 0
	global_load_lds_dwordx4 v[250:251], off
	s_waitcnt vmcnt(8)
	s_waitcnt lgkmcnt(0)
	s_barrier
	s_waitcnt lgkmcnt(0)
	v_mfma_f32_16x16x32_bf16 v[136:139], v[148:151], v[182:185], v[136:139]
	v_mfma_f32_16x16x32_bf16 v[132:135], v[158:161], v[182:185], v[132:135]
	v_mfma_f32_16x16x32_bf16 v[128:131], v[148:151], v[190:193], v[128:131]
	v_mfma_f32_16x16x32_bf16 v[124:127], v[158:161], v[190:193], v[124:127]
	v_mfma_f32_16x16x32_bf16 v[120:123], v[148:151], v[204:207], v[120:123]
	v_mfma_f32_16x16x32_bf16 v[116:119], v[158:161], v[204:207], v[116:119]
	v_mfma_f32_16x16x32_bf16 v[112:115], v[148:151], v[212:215], v[112:115]
	v_mfma_f32_16x16x32_bf16 v[108:111], v[158:161], v[212:215], v[108:111]
	v_mfma_f32_16x16x32_bf16 v[136:139], v[152:155], v[186:189], v[136:139]
	v_mfma_f32_16x16x32_bf16 v[132:135], v[162:165], v[186:189], v[132:135]
	v_mfma_f32_16x16x32_bf16 v[128:131], v[152:155], v[194:197], v[128:131]
	v_mfma_f32_16x16x32_bf16 v[124:127], v[162:165], v[194:197], v[124:127]
	v_mfma_f32_16x16x32_bf16 v[120:123], v[152:155], v[208:211], v[120:123]
	v_mfma_f32_16x16x32_bf16 v[116:119], v[162:165], v[208:211], v[116:119]
	v_mfma_f32_16x16x32_bf16 v[112:115], v[152:155], v[236:239], v[112:115]
	v_mfma_f32_16x16x32_bf16 v[108:111], v[162:165], v[236:239], v[108:111]
	v_mfma_f32_16x16x32_bf16 v[72:75], v[166:169], v[182:185], v[72:75]
	v_mfma_f32_16x16x32_bf16 v[68:71], v[174:177], v[182:185], v[68:71]
	v_mfma_f32_16x16x32_bf16 v[64:67], v[166:169], v[190:193], v[64:67]
	v_mfma_f32_16x16x32_bf16 v[60:63], v[174:177], v[190:193], v[60:63]
	v_mfma_f32_16x16x32_bf16 v[56:59], v[166:169], v[204:207], v[56:59]
	v_mfma_f32_16x16x32_bf16 v[52:55], v[174:177], v[204:207], v[52:55]
	v_mfma_f32_16x16x32_bf16 v[48:51], v[166:169], v[212:215], v[48:51]
	v_mfma_f32_16x16x32_bf16 v[32:35], v[174:177], v[212:215], v[32:35]
	v_mfma_f32_16x16x32_bf16 v[72:75], v[170:173], v[186:189], v[72:75]
	v_mfma_f32_16x16x32_bf16 v[68:71], v[178:181], v[186:189], v[68:71]
	v_mfma_f32_16x16x32_bf16 v[64:67], v[170:173], v[194:197], v[64:67]
	v_mfma_f32_16x16x32_bf16 v[60:63], v[178:181], v[194:197], v[60:63]
	v_mfma_f32_16x16x32_bf16 v[56:59], v[170:173], v[208:211], v[56:59]
	v_mfma_f32_16x16x32_bf16 v[52:55], v[178:181], v[208:211], v[52:55]
	v_mfma_f32_16x16x32_bf16 v[48:51], v[170:173], v[236:239], v[48:51]
	v_mfma_f32_16x16x32_bf16 v[32:35], v[178:181], v[236:239], v[32:35]
	s_barrier
; #define PG8_STAGE(bufoff, gbase, voff) do { _Pragma("unroll") for (int _i = 0; _i < 2; ++_i) \
;         __builtin_amdgcn_global_load_lds((const unsigned*)((const char*)(gbase) + (voff)[_i]), (PG8_LAS unsigned*)(lds + (bufoff) + ldsw + _i * 8192), 16, 0, 0); } while (0)
; #define PG8_LDA(dst, b, h) do { _Pragma("unroll") for (int m = 0; m < 4; ++m) _Pragma("unroll") for (int k = 0; k < 2; ++k) dst[m][k] = *(const PG8_LAS bf16x8*)(lds + PG8_SA(b, h) + aoff + m * 2048 + k * 1024); } while (0)
; #define PG8_MMA(ai, bj, At, Bt) do { __builtin_amdgcn_s_setprio(1); _Pragma("unroll") for (int m = 0; m < 4; ++m) _Pragma("unroll") for (int n = 0; n < 2; ++n) _Pragma("unroll") for (int k = 0; k < 2; ++k) \
;         acc[ai][bj][m][n] = __builtin_amdgcn_mfma_f32_16x16x32_bf16(Bt[n][k], At[m][k], acc[ai][bj][m][n], 0, 0, 0); __builtin_amdgcn_s_setprio(0); } while (0)
; #define PG8_WAIT_V(n) asm volatile("s_waitcnt vmcnt(" #n ")" ::: "memory")
; #define PG8_WAIT_L(n) asm volatile("s_waitcnt lgkmcnt(" #n ")" ::: "memory")
; #define PG8_BAR __builtin_amdgcn_s_barrier()
; #define PG8_SCHED __builtin_amdgcn_sched_barrier(0)
; template <class Epi, class Sched, bool ALIGN_EPI = false, bool SP2 = false>
; __device__ __forceinline__ void gemm_phase(PG8_LAS unsigned char* lds, const Gemm g, const Sched& S, const Epi& E) {
;     ...
;         for (int t = 0; t < nt; t += 2) {
;             const bool last = (t == nt - 2);
;             const char* a1 = cA + (size_t)(t + 1) * kstep;
;             const char* a2 = last ? nA : cA + (size_t)(t + 2) * kstep; const char* b2 = last ? nB : cB + (size_t)(t + 2) * kstep;
;     ...
;             PG8_LDA(At, 1, 1); PG8_STAGE(PG8_SB(1, 0), b3, voffB); PG8_STAGE(PG8_SB(1, 1), b3 + hstep, voffB); PG8_STAGE(PG8_SA(1, 0), a3, voffA);
;             PG8_WAIT_V(8); PG8_WAIT_L(0); PG8_BAR; PG8_MMA(1, 0, At, B0); PG8_MMA(1, 1, At, B1); PG8_BAR; PG8_SCHED;
	s_add_i32 s0, s69, s45
	v_lshl_add_u64 v[198:199], v[198:199], 0, s[22:23]
	s_mov_b32 m0, s0
	ds_read_b128 v[182:185], v157 offset:49152
	ds_read_b128 v[186:189], v157 offset:50176
	ds_read_b128 v[190:193], v157 offset:51200
	ds_read_b128 v[194:197], v157 offset:52224
	ds_read_b128 v[204:207], v157 offset:53248
	ds_read_b128 v[208:211], v157 offset:54272
	ds_read_b128 v[212:215], v157 offset:55296
	ds_read_b128 v[236:239], v157 offset:56320
	global_load_lds_dwordx4 v[198:199], off
	v_lshl_add_u64 v[198:199], v[240:241], 0, s[22:23]
	s_add_i32 m0, s0, 0x2000
	s_add_i32 s0, s70, s45
	global_load_lds_dwordx4 v[198:199], off
	v_lshl_add_u64 v[198:199], v[242:243], 0, s[22:23]
	s_mov_b32 m0, s0
	s_nop 0
	global_load_lds_dwordx4 v[198:199], off
	v_lshl_add_u64 v[198:199], v[244:245], 0, s[22:23]
	s_add_i32 m0, s0, 0x2000
	s_nop 0
	global_load_lds_dwordx4 v[198:199], off
	v_lshl_add_u64 v[198:199], v[246:247], 0, s[22:23]
	s_mov_b32 m0, s59
	s_nop 0
	global_load_lds_dwordx4 v[198:199], off
	v_lshl_add_u64 v[198:199], v[248:249], 0, s[22:23]
	s_mov_b32 m0, s60
	s_nop 0
	global_load_lds_dwordx4 v[198:199], off
	s_waitcnt vmcnt(8)
	s_waitcnt lgkmcnt(0)
	s_barrier
	s_waitcnt lgkmcnt(0)
	v_mfma_f32_16x16x32_bf16 v[104:107], v[148:151], v[182:185], v[104:107]
	v_mfma_f32_16x16x32_bf16 v[100:103], v[158:161], v[182:185], v[100:103]
	v_mfma_f32_16x16x32_bf16 v[96:99], v[148:151], v[190:193], v[96:99]
	v_mfma_f32_16x16x32_bf16 v[92:95], v[158:161], v[190:193], v[92:95]
	v_mfma_f32_16x16x32_bf16 v[88:91], v[148:151], v[204:207], v[88:91]
	v_mfma_f32_16x16x32_bf16 v[84:87], v[158:161], v[204:207], v[84:87]
	v_mfma_f32_16x16x32_bf16 v[80:83], v[148:151], v[212:215], v[80:83]
	v_mfma_f32_16x16x32_bf16 v[76:79], v[158:161], v[212:215], v[76:79]
	v_mfma_f32_16x16x32_bf16 v[104:107], v[152:155], v[186:189], v[104:107]
	v_mfma_f32_16x16x32_bf16 v[100:103], v[162:165], v[186:189], v[100:103]
	v_mfma_f32_16x16x32_bf16 v[96:99], v[152:155], v[194:197], v[96:99]
	v_mfma_f32_16x16x32_bf16 v[92:95], v[162:165], v[194:197], v[92:95]
	v_mfma_f32_16x16x32_bf16 v[88:91], v[152:155], v[208:211], v[88:91]
	v_mfma_f32_16x16x32_bf16 v[84:87], v[162:165], v[208:211], v[84:87]
	v_mfma_f32_16x16x32_bf16 v[80:83], v[152:155], v[236:239], v[80:83]
	v_mfma_f32_16x16x32_bf16 v[76:79], v[162:165], v[236:239], v[76:79]
	v_mfma_f32_16x16x32_bf16 v[28:31], v[166:169], v[182:185], v[28:31]
	v_mfma_f32_16x16x32_bf16 v[24:27], v[174:177], v[182:185], v[24:27]
	v_mfma_f32_16x16x32_bf16 v[20:23], v[166:169], v[190:193], v[20:23]
	v_mfma_f32_16x16x32_bf16 v[16:19], v[174:177], v[190:193], v[16:19]
	v_mfma_f32_16x16x32_bf16 v[12:15], v[166:169], v[204:207], v[12:15]
	v_mfma_f32_16x16x32_bf16 v[8:11], v[174:177], v[204:207], v[8:11]
	v_mfma_f32_16x16x32_bf16 v[4:7], v[166:169], v[212:215], v[4:7]
	v_mfma_f32_16x16x32_bf16 v[0:3], v[174:177], v[212:215], v[0:3]
	v_mfma_f32_16x16x32_bf16 v[28:31], v[170:173], v[186:189], v[28:31]
	v_mfma_f32_16x16x32_bf16 v[24:27], v[178:181], v[186:189], v[24:27]
	v_mfma_f32_16x16x32_bf16 v[20:23], v[170:173], v[194:197], v[20:23]
	v_mfma_f32_16x16x32_bf16 v[16:19], v[178:181], v[194:197], v[16:19]
	v_mfma_f32_16x16x32_bf16 v[12:15], v[170:173], v[208:211], v[12:15]
	v_mfma_f32_16x16x32_bf16 v[8:11], v[178:181], v[208:211], v[8:11]
	v_mfma_f32_16x16x32_bf16 v[4:7], v[170:173], v[236:239], v[4:7]
	v_mfma_f32_16x16x32_bf16 v[0:3], v[178:181], v[236:239], v[0:3]
	s_barrier
	s_add_u32 s24, s24, 0x100
	s_addc_u32 s25, s25, 0
	s_add_u32 s18, s18, 0x100
	s_addc_u32 s19, s19, 0
	s_cmp_ge_i32 s68, s56
	s_mov_b32 s0, s68
	s_cbranch_scc0 .LBB0_271
	s_movk_i32 s69, 0x1000

; #define PG8_STAGE(bufoff, gbase, voff) do { _Pragma("unroll") for (int _i = 0; _i < 2; ++_i) \
;         __builtin_amdgcn_global_load_lds((const unsigned*)((const char*)(gbase) + (voff)[_i]), (PG8_LAS unsigned*)(lds + (bufoff) + ldsw + _i * 8192), 16, 0, 0); } while (0)
; #define PG8_LDA(dst, b, h) do { _Pragma("unroll") for (int m = 0; m < 4; ++m) _Pragma("unroll") for (int k = 0; k < 2; ++k) dst[m][k] = *(const PG8_LAS bf16x8*)(lds + PG8_SA(b, h) + aoff + m * 2048 + k * 1024); } while (0)
; #define PG8_LDB(dst, b, h) do { _Pragma("unroll") for (int n = 0; n < 2; ++n) _Pragma("unroll") for (int k = 0; k < 2; ++k) dst[n][k] = *(const PG8_LAS bf16x8*)(lds + PG8_SB(b, h) + boff + n * 2048 + k * 1024); } while (0)
; #define PG8_MMA(ai, bj, At, Bt) do { __builtin_amdgcn_s_setprio(1); _Pragma("unroll") for (int m = 0; m < 4; ++m) _Pragma("unroll") for (int n = 0; n < 2; ++n) _Pragma("unroll") for (int k = 0; k < 2; ++k) \
;         acc[ai][bj][m][n] = __builtin_amdgcn_mfma_f32_16x16x32_bf16(Bt[n][k], At[m][k], acc[ai][bj][m][n], 0, 0, 0); __builtin_amdgcn_s_setprio(0); } while (0)
; #define PG8_WAIT_V(n) asm volatile("s_waitcnt vmcnt(" #n ")" ::: "memory")
; #define PG8_WAIT_L(n) asm volatile("s_waitcnt lgkmcnt(" #n ")" ::: "memory")
; #define PG8_BAR __builtin_amdgcn_s_barrier()
; #define PG8_SCHED __builtin_amdgcn_sched_barrier(0)
; template <class Epi, class Sched, bool ALIGN_EPI = false, bool SP2 = false>
; __device__ __forceinline__ void gemm_phase(PG8_LAS unsigned char* lds, const Gemm g, const Sched& S, const Epi& E) {
;     ...
;         for (int t = 0; t < nt; t += 2) {
;             const bool last = (t == nt - 2);
;             const char* a1 = cA + (size_t)(t + 1) * kstep;
;             const char* a2 = last ? nA : cA + (size_t)(t + 2) * kstep; const char* b2 = last ? nB : cB + (size_t)(t + 2) * kstep;
;             const char* a3 = a2 + kstep; const char* b3 = b2 + kstep;
;             if (last && has_next) S.a_ready(nxt);
;             if constexpr (SP2) {
;             PG8_LDB(B0, 0, 0); PG8_LDB(B1, 0, 1); PG8_SCHED; PG8_LDA(At, 0, 0); PG8_STAGE(PG8_SA(1, 1), a1 + hstep, voffA);
;             PG8_WAIT_V(8); PG8_WAIT_L(0); PG8_BAR; PG8_MMA(0, 0, At, B0); PG8_MMA(0, 1, At, B1); PG8_BAR; PG8_SCHED;
;             PG8_LDA(At, 0, 1); PG8_STAGE(PG8_SB(0, 0), b2, voffB); PG8_STAGE(PG8_SB(0, 1), b2 + hstep, voffB); PG8_STAGE(PG8_SA(0, 0), a2, voffA);
.LBB0_293:
	s_add_i32 s70, s0, 2
	s_add_u32 s71, s24, 0x80
	s_addc_u32 s1, s25, 0
	s_add_i32 s74, 0, 0x10000
	s_cmp_eq_u32 s63, s0
	s_cselect_b32 s1, s35, s1
	s_cselect_b32 s0, s34, s71
	s_cselect_b32 s73, s41, s19
	s_cselect_b32 s72, s40, s18
	s_add_i32 s71, 0, 0x14000
	v_add_u32_e32 v162, s74, v160
	v_add_u32_e32 v178, s71, v160
	ds_read_b128 v[148:151], v162
	ds_read_b128 v[152:155], v162 offset:1024
	ds_read_b128 v[156:159], v162 offset:2048
	ds_read_b128 v[162:165], v162 offset:3072
	ds_read_b128 v[166:169], v178
	ds_read_b128 v[170:173], v178 offset:1024
	ds_read_b128 v[174:177], v178 offset:2048
	ds_read_b128 v[178:181], v178 offset:3072
	v_lshl_add_u64 v[198:199], s[24:25], 0, v[144:145]
	s_add_i32 m0, s54, 0xc000
	ds_read_b128 v[182:185], v161
	ds_read_b128 v[186:189], v161 offset:1024
	ds_read_b128 v[190:193], v161 offset:2048
	ds_read_b128 v[194:197], v161 offset:3072
	ds_read_b128 v[204:207], v161 offset:4096
	ds_read_b128 v[208:211], v161 offset:5120
	ds_read_b128 v[212:215], v161 offset:6144
	ds_read_b128 v[236:239], v161 offset:7168
	global_load_lds_dwordx4 v[198:199], off
	v_lshl_add_u64 v[198:199], s[24:25], 0, v[146:147]
	s_add_i32 m0, s54, 0xe000
	s_nop 0
	global_load_lds_dwordx4 v[198:199], off
	s_waitcnt vmcnt(8)
	s_waitcnt lgkmcnt(0)
	s_barrier
	s_waitcnt lgkmcnt(0)
	v_mfma_f32_16x16x32_bf16 v[136:139], v[148:151], v[182:185], v[136:139]
	v_mfma_f32_16x16x32_bf16 v[132:135], v[156:159], v[182:185], v[132:135]
	v_mfma_f32_16x16x32_bf16 v[128:131], v[148:151], v[190:193], v[128:131]
	v_mfma_f32_16x16x32_bf16 v[124:127], v[156:159], v[190:193], v[124:127]
	v_mfma_f32_16x16x32_bf16 v[120:123], v[148:151], v[204:207], v[120:123]
	v_mfma_f32_16x16x32_bf16 v[116:119], v[156:159], v[204:207], v[116:119]
	v_mfma_f32_16x16x32_bf16 v[112:115], v[148:151], v[212:215], v[112:115]
	v_mfma_f32_16x16x32_bf16 v[108:111], v[156:159], v[212:215], v[108:111]
	v_mfma_f32_16x16x32_bf16 v[136:139], v[152:155], v[186:189], v[136:139]
	v_mfma_f32_16x16x32_bf16 v[132:135], v[162:165], v[186:189], v[132:135]
	v_mfma_f32_16x16x32_bf16 v[128:131], v[152:155], v[194:197], v[128:131]
	v_mfma_f32_16x16x32_bf16 v[124:127], v[162:165], v[194:197], v[124:127]
	v_mfma_f32_16x16x32_bf16 v[120:123], v[152:155], v[208:211], v[120:123]
	v_mfma_f32_16x16x32_bf16 v[116:119], v[162:165], v[208:211], v[116:119]
	v_mfma_f32_16x16x32_bf16 v[112:115], v[152:155], v[236:239], v[112:115]
	v_mfma_f32_16x16x32_bf16 v[108:111], v[162:165], v[236:239], v[108:111]
	v_mfma_f32_16x16x32_bf16 v[72:75], v[166:169], v[182:185], v[72:75]
	v_mfma_f32_16x16x32_bf16 v[68:71], v[174:177], v[182:185], v[68:71]
	v_mfma_f32_16x16x32_bf16 v[64:67], v[166:169], v[190:193], v[64:67]
	v_mfma_f32_16x16x32_bf16 v[60:63], v[174:177], v[190:193], v[60:63]
	v_mfma_f32_16x16x32_bf16 v[56:59], v[166:169], v[204:207], v[56:59]
	v_mfma_f32_16x16x32_bf16 v[52:55], v[174:177], v[204:207], v[52:55]
	v_mfma_f32_16x16x32_bf16 v[48:51], v[166:169], v[212:215], v[48:51]
	v_mfma_f32_16x16x32_bf16 v[32:35], v[174:177], v[212:215], v[32:35]
	v_mfma_f32_16x16x32_bf16 v[72:75], v[170:173], v[186:189], v[72:75]
	v_mfma_f32_16x16x32_bf16 v[68:71], v[178:181], v[186:189], v[68:71]
	v_mfma_f32_16x16x32_bf16 v[64:67], v[170:173], v[194:197], v[64:67]
	v_mfma_f32_16x16x32_bf16 v[60:63], v[178:181], v[194:197], v[60:63]
	v_mfma_f32_16x16x32_bf16 v[56:59], v[170:173], v[208:211], v[56:59]
	v_mfma_f32_16x16x32_bf16 v[52:55], v[178:181], v[208:211], v[52:55]
	v_mfma_f32_16x16x32_bf16 v[48:51], v[170:173], v[236:239], v[48:51]
	v_mfma_f32_16x16x32_bf16 v[32:35], v[178:181], v[236:239], v[32:35]
	s_barrier
	s_add_i32 s74, s74, s47
	v_lshl_add_u64 v[198:199], s[72:73], 0, v[140:141]
	s_mov_b32 m0, s74
	ds_read_b128 v[182:185], v161 offset:16384
	ds_read_b128 v[186:189], v161 offset:17408
	ds_read_b128 v[190:193], v161 offset:18432
	ds_read_b128 v[194:197], v161 offset:19456
	ds_read_b128 v[204:207], v161 offset:20480
	ds_read_b128 v[208:211], v161 offset:21504
	ds_read_b128 v[212:215], v161 offset:22528
	ds_read_b128 v[236:239], v161 offset:23552
	global_load_lds_dwordx4 v[198:199], off
	s_add_i32 m0, s74, 0x2000
	v_lshl_add_u64 v[240:241], s[72:73], 0, v[38:39]
	s_add_u32 s72, s72, s10
	s_addc_u32 s73, s73, s11
	s_add_i32 s71, s71, s47
	global_load_lds_dwordx4 v[240:241], off
	v_lshl_add_u64 v[242:243], s[72:73], 0, v[140:141]
	s_mov_b32 m0, s71
	v_lshl_add_u64 v[244:245], s[72:73], 0, v[38:39]
	global_load_lds_dwordx4 v[242:243], off
	s_add_i32 m0, s71, 0x2000
	v_lshl_add_u64 v[246:247], s[0:1], 0, v[142:143]
	global_load_lds_dwordx4 v[244:245], off
	s_mov_b32 m0, s54
	v_lshl_add_u64 v[248:249], s[0:1], 0, v[42:43]
	global_load_lds_dwordx4 v[246:247], off
	s_mov_b32 m0, s55
	s_nop 0
	global_load_lds_dwordx4 v[248:249], off
	s_waitcnt vmcnt(8)
	s_waitcnt lgkmcnt(0)
	s_barrier
; #define PG8_STAGE(bufoff, gbase, voff) do { _Pragma("unroll") for (int _i = 0; _i < 2; ++_i) \
;         __builtin_amdgcn_global_load_lds((const unsigned*)((const char*)(gbase) + (voff)[_i]), (PG8_LAS unsigned*)(lds + (bufoff) + ldsw + _i * 8192), 16, 0, 0); } while (0)
; #define PG8_LDA(dst, b, h) do { _Pragma("unroll") for (int m = 0; m < 4; ++m) _Pragma("unroll") for (int k = 0; k < 2; ++k) dst[m][k] = *(const PG8_LAS bf16x8*)(lds + PG8_SA(b, h) + aoff + m * 2048 + k * 1024); } while (0)
; #define PG8_LDB(dst, b, h) do { _Pragma("unroll") for (int n = 0; n < 2; ++n) _Pragma("unroll") for (int k = 0; k < 2; ++k) dst[n][k] = *(const PG8_LAS bf16x8*)(lds + PG8_SB(b, h) + boff + n * 2048 + k * 1024); } while (0)
; #define PG8_MMA(ai, bj, At, Bt) do { __builtin_amdgcn_s_setprio(1); _Pragma("unroll") for (int m = 0; m < 4; ++m) _Pragma("unroll") for (int n = 0; n < 2; ++n) _Pragma("unroll") for (int k = 0; k < 2; ++k) \
;         acc[ai][bj][m][n] = __builtin_amdgcn_mfma_f32_16x16x32_bf16(Bt[n][k], At[m][k], acc[ai][bj][m][n], 0, 0, 0); __builtin_amdgcn_s_setprio(0); } while (0)
; #define PG8_WAIT_V(n) asm volatile("s_waitcnt vmcnt(" #n ")" ::: "memory")
; #define PG8_WAIT_L(n) asm volatile("s_waitcnt lgkmcnt(" #n ")" ::: "memory")
; #define PG8_BAR __builtin_amdgcn_s_barrier()
; #define PG8_SCHED __builtin_amdgcn_sched_barrier(0)
; template <class Epi, class Sched, bool ALIGN_EPI = false, bool SP2 = false>
; __device__ __forceinline__ void gemm_phase(PG8_LAS unsigned char* lds, const Gemm g, const Sched& S, const Epi& E) {
;     ...
;             PG8_WAIT_V(8); PG8_WAIT_L(0); PG8_BAR; PG8_MMA(1, 0, At, B0); PG8_MMA(1, 1, At, B1); PG8_BAR; PG8_SCHED;
;             PG8_LDB(B0, 1, 0); PG8_LDB(B1, 1, 1); PG8_SCHED; PG8_LDA(At, 1, 0); PG8_STAGE(PG8_SA(0, 1), a2 + hstep, voffA);
;             PG8_WAIT_V(8); PG8_WAIT_L(0); PG8_BAR; PG8_MMA(0, 0, At, B0); PG8_MMA(0, 1, At, B1); PG8_BAR; PG8_SCHED;
	s_waitcnt lgkmcnt(0)
	v_mfma_f32_16x16x32_bf16 v[104:107], v[148:151], v[182:185], v[104:107]
	v_mfma_f32_16x16x32_bf16 v[100:103], v[156:159], v[182:185], v[100:103]
	v_mfma_f32_16x16x32_bf16 v[96:99], v[148:151], v[190:193], v[96:99]
	v_mfma_f32_16x16x32_bf16 v[92:95], v[156:159], v[190:193], v[92:95]
	v_mfma_f32_16x16x32_bf16 v[88:91], v[148:151], v[204:207], v[88:91]
	v_mfma_f32_16x16x32_bf16 v[84:87], v[156:159], v[204:207], v[84:87]
	v_mfma_f32_16x16x32_bf16 v[80:83], v[148:151], v[212:215], v[80:83]
	v_mfma_f32_16x16x32_bf16 v[76:79], v[156:159], v[212:215], v[76:79]
	v_mfma_f32_16x16x32_bf16 v[104:107], v[152:155], v[186:189], v[104:107]
	v_mfma_f32_16x16x32_bf16 v[100:103], v[162:165], v[186:189], v[100:103]
	v_mfma_f32_16x16x32_bf16 v[96:99], v[152:155], v[194:197], v[96:99]
	v_mfma_f32_16x16x32_bf16 v[92:95], v[162:165], v[194:197], v[92:95]
	v_mfma_f32_16x16x32_bf16 v[88:91], v[152:155], v[208:211], v[88:91]
	v_mfma_f32_16x16x32_bf16 v[84:87], v[162:165], v[208:211], v[84:87]
	v_mfma_f32_16x16x32_bf16 v[80:83], v[152:155], v[236:239], v[80:83]
	v_mfma_f32_16x16x32_bf16 v[76:79], v[162:165], v[236:239], v[76:79]
	v_mfma_f32_16x16x32_bf16 v[28:31], v[166:169], v[182:185], v[28:31]
	v_mfma_f32_16x16x32_bf16 v[24:27], v[174:177], v[182:185], v[24:27]
	v_mfma_f32_16x16x32_bf16 v[20:23], v[166:169], v[190:193], v[20:23]
	v_mfma_f32_16x16x32_bf16 v[16:19], v[174:177], v[190:193], v[16:19]
	v_mfma_f32_16x16x32_bf16 v[12:15], v[166:169], v[204:207], v[12:15]
	v_mfma_f32_16x16x32_bf16 v[8:11], v[174:177], v[204:207], v[8:11]
	v_mfma_f32_16x16x32_bf16 v[4:7], v[166:169], v[212:215], v[4:7]
	v_mfma_f32_16x16x32_bf16 v[0:3], v[174:177], v[212:215], v[0:3]
	v_mfma_f32_16x16x32_bf16 v[28:31], v[170:173], v[186:189], v[28:31]
	v_mfma_f32_16x16x32_bf16 v[24:27], v[178:181], v[186:189], v[24:27]
	v_mfma_f32_16x16x32_bf16 v[20:23], v[170:173], v[194:197], v[20:23]
	v_mfma_f32_16x16x32_bf16 v[16:19], v[178:181], v[194:197], v[16:19]
	v_mfma_f32_16x16x32_bf16 v[12:15], v[170:173], v[208:211], v[12:15]
	v_mfma_f32_16x16x32_bf16 v[8:11], v[178:181], v[208:211], v[8:11]
	v_mfma_f32_16x16x32_bf16 v[4:7], v[170:173], v[236:239], v[4:7]
	v_mfma_f32_16x16x32_bf16 v[0:3], v[178:181], v[236:239], v[0:3]
	s_barrier
	s_add_i32 s71, 0, 0x18000
	s_add_i32 s72, 0, 0x1c000
	v_add_u32_e32 v162, s71, v160
	v_add_u32_e32 v178, s72, v160
	ds_read_b128 v[148:151], v162
	ds_read_b128 v[152:155], v162 offset:1024
	ds_read_b128 v[156:159], v162 offset:2048
	ds_read_b128 v[162:165], v162 offset:3072
	ds_read_b128 v[166:169], v178
	ds_read_b128 v[170:173], v178 offset:1024
	ds_read_b128 v[174:177], v178 offset:2048
	ds_read_b128 v[178:181], v178 offset:3072
	s_add_u32 s0, s0, s10
	s_addc_u32 s1, s1, s11
	s_mov_b32 m0, s56
	v_lshl_add_u64 v[250:251], s[0:1], 0, v[142:143]
	ds_read_b128 v[182:185], v161 offset:32768
	ds_read_b128 v[186:189], v161 offset:33792
	ds_read_b128 v[190:193], v161 offset:34816
	ds_read_b128 v[194:197], v161 offset:35840
	ds_read_b128 v[204:207], v161 offset:36864
	ds_read_b128 v[208:211], v161 offset:37888
	ds_read_b128 v[212:215], v161 offset:38912
	ds_read_b128 v[236:239], v161 offset:39936
	global_load_lds_dwordx4 v[250:251], off
	v_lshl_add_u64 v[250:251], s[0:1], 0, v[42:43]
	s_mov_b32 m0, s57
	s_nop 0
	global_load_lds_dwordx4 v[250:251], off
	s_waitcnt vmcnt(8)
	s_waitcnt lgkmcnt(0)
	s_barrier
	s_waitcnt lgkmcnt(0)
	v_mfma_f32_16x16x32_bf16 v[136:139], v[148:151], v[182:185], v[136:139]
	v_mfma_f32_16x16x32_bf16 v[132:135], v[156:159], v[182:185], v[132:135]
	v_mfma_f32_16x16x32_bf16 v[128:131], v[148:151], v[190:193], v[128:131]
	v_mfma_f32_16x16x32_bf16 v[124:127], v[156:159], v[190:193], v[124:127]
	v_mfma_f32_16x16x32_bf16 v[120:123], v[148:151], v[204:207], v[120:123]
	v_mfma_f32_16x16x32_bf16 v[116:119], v[156:159], v[204:207], v[116:119]
	v_mfma_f32_16x16x32_bf16 v[112:115], v[148:151], v[212:215], v[112:115]
	v_mfma_f32_16x16x32_bf16 v[108:111], v[156:159], v[212:215], v[108:111]
	v_mfma_f32_16x16x32_bf16 v[136:139], v[152:155], v[186:189], v[136:139]
	v_mfma_f32_16x16x32_bf16 v[132:135], v[162:165], v[186:189], v[132:135]
	v_mfma_f32_16x16x32_bf16 v[128:131], v[152:155], v[194:197], v[128:131]
	v_mfma_f32_16x16x32_bf16 v[124:127], v[162:165], v[194:197], v[124:127]
	v_mfma_f32_16x16x32_bf16 v[120:123], v[152:155], v[208:211], v[120:123]
	v_mfma_f32_16x16x32_bf16 v[116:119], v[162:165], v[208:211], v[116:119]
	v_mfma_f32_16x16x32_bf16 v[112:115], v[152:155], v[236:239], v[112:115]
	v_mfma_f32_16x16x32_bf16 v[108:111], v[162:165], v[236:239], v[108:111]
	v_mfma_f32_16x16x32_bf16 v[72:75], v[166:169], v[182:185], v[72:75]
	v_mfma_f32_16x16x32_bf16 v[68:71], v[174:177], v[182:185], v[68:71]
	v_mfma_f32_16x16x32_bf16 v[64:67], v[166:169], v[190:193], v[64:67]
	v_mfma_f32_16x16x32_bf16 v[60:63], v[174:177], v[190:193], v[60:63]
	v_mfma_f32_16x16x32_bf16 v[56:59], v[166:169], v[204:207], v[56:59]
	v_mfma_f32_16x16x32_bf16 v[52:55], v[174:177], v[204:207], v[52:55]
	v_mfma_f32_16x16x32_bf16 v[48:51], v[166:169], v[212:215], v[48:51]
	v_mfma_f32_16x16x32_bf16 v[32:35], v[174:177], v[212:215], v[32:35]
	v_mfma_f32_16x16x32_bf16 v[72:75], v[170:173], v[186:189], v[72:75]
	v_mfma_f32_16x16x32_bf16 v[68:71], v[178:181], v[186:189], v[68:71]
	v_mfma_f32_16x16x32_bf16 v[64:67], v[170:173], v[194:197], v[64:67]
	v_mfma_f32_16x16x32_bf16 v[60:63], v[178:181], v[194:197], v[60:63]
	v_mfma_f32_16x16x32_bf16 v[56:59], v[170:173], v[208:211], v[56:59]
	v_mfma_f32_16x16x32_bf16 v[52:55], v[178:181], v[208:211], v[52:55]
	v_mfma_f32_16x16x32_bf16 v[48:51], v[170:173], v[236:239], v[48:51]
	v_mfma_f32_16x16x32_bf16 v[32:35], v[178:181], v[236:239], v[32:35]
	s_barrier
; #define PG8_STAGE(bufoff, gbase, voff) do { _Pragma("unroll") for (int _i = 0; _i < 2; ++_i) \
;         __builtin_amdgcn_global_load_lds((const unsigned*)((const char*)(gbase) + (voff)[_i]), (PG8_LAS unsigned*)(lds + (bufoff) + ldsw + _i * 8192), 16, 0, 0); } while (0)
; #define PG8_LDA(dst, b, h) do { _Pragma("unroll") for (int m = 0; m < 4; ++m) _Pragma("unroll") for (int k = 0; k < 2; ++k) dst[m][k] = *(const PG8_LAS bf16x8*)(lds + PG8_SA(b, h) + aoff + m * 2048 + k * 1024); } while (0)
; #define PG8_MMA(ai, bj, At, Bt) do { __builtin_amdgcn_s_setprio(1); _Pragma("unroll") for (int m = 0; m < 4; ++m) _Pragma("unroll") for (int n = 0; n < 2; ++n) _Pragma("unroll") for (int k = 0; k < 2; ++k) \
;         acc[ai][bj][m][n] = __builtin_amdgcn_mfma_f32_16x16x32_bf16(Bt[n][k], At[m][k], acc[ai][bj][m][n], 0, 0, 0); __builtin_amdgcn_s_setprio(0); } while (0)
; #define PG8_WAIT_V(n) asm volatile("s_waitcnt vmcnt(" #n ")" ::: "memory")
; #define PG8_WAIT_L(n) asm volatile("s_waitcnt lgkmcnt(" #n ")" ::: "memory")
; #define PG8_BAR __builtin_amdgcn_s_barrier()
; #define PG8_SCHED __builtin_amdgcn_sched_barrier(0)
; template <class Epi, class Sched, bool ALIGN_EPI = false, bool SP2 = false>
; __device__ __forceinline__ void gemm_phase(PG8_LAS unsigned char* lds, const Gemm g, const Sched& S, const Epi& E) {
;     ...
;         for (int t = 0; t < nt; t += 2) {
;     ...
;             PG8_LDA(At, 1, 1); PG8_STAGE(PG8_SB(1, 0), b3, voffB); PG8_STAGE(PG8_SB(1, 1), b3 + hstep, voffB); PG8_STAGE(PG8_SA(1, 0), a3, voffA);
;             PG8_WAIT_V(8); PG8_WAIT_L(0); PG8_BAR; PG8_MMA(1, 0, At, B0); PG8_MMA(1, 1, At, B1); PG8_BAR; PG8_SCHED;
	s_add_i32 s0, s71, s47
	v_lshl_add_u64 v[198:199], v[198:199], 0, s[22:23]
	s_mov_b32 m0, s0
	ds_read_b128 v[182:185], v161 offset:49152
	ds_read_b128 v[186:189], v161 offset:50176
	ds_read_b128 v[190:193], v161 offset:51200
	ds_read_b128 v[194:197], v161 offset:52224
	ds_read_b128 v[204:207], v161 offset:53248
	ds_read_b128 v[208:211], v161 offset:54272
	ds_read_b128 v[212:215], v161 offset:55296
	ds_read_b128 v[236:239], v161 offset:56320
	global_load_lds_dwordx4 v[198:199], off
	v_lshl_add_u64 v[198:199], v[240:241], 0, s[22:23]
	s_add_i32 m0, s0, 0x2000
	s_add_i32 s0, s72, s47
	global_load_lds_dwordx4 v[198:199], off
	v_lshl_add_u64 v[198:199], v[242:243], 0, s[22:23]
	s_mov_b32 m0, s0
	s_nop 0
	global_load_lds_dwordx4 v[198:199], off
	v_lshl_add_u64 v[198:199], v[244:245], 0, s[22:23]
	s_add_i32 m0, s0, 0x2000
	s_nop 0
	global_load_lds_dwordx4 v[198:199], off
	v_lshl_add_u64 v[198:199], v[246:247], 0, s[22:23]
	s_mov_b32 m0, s61
	s_nop 0
	global_load_lds_dwordx4 v[198:199], off
	v_lshl_add_u64 v[198:199], v[248:249], 0, s[22:23]
	s_mov_b32 m0, s62
	s_nop 0
	global_load_lds_dwordx4 v[198:199], off
	s_waitcnt vmcnt(8)
	s_waitcnt lgkmcnt(0)
	s_barrier
	s_waitcnt lgkmcnt(0)
	v_mfma_f32_16x16x32_bf16 v[104:107], v[148:151], v[182:185], v[104:107]
	v_mfma_f32_16x16x32_bf16 v[100:103], v[156:159], v[182:185], v[100:103]
	v_mfma_f32_16x16x32_bf16 v[96:99], v[148:151], v[190:193], v[96:99]
	v_mfma_f32_16x16x32_bf16 v[92:95], v[156:159], v[190:193], v[92:95]
	v_mfma_f32_16x16x32_bf16 v[88:91], v[148:151], v[204:207], v[88:91]
	v_mfma_f32_16x16x32_bf16 v[84:87], v[156:159], v[204:207], v[84:87]
	v_mfma_f32_16x16x32_bf16 v[80:83], v[148:151], v[212:215], v[80:83]
	v_mfma_f32_16x16x32_bf16 v[76:79], v[156:159], v[212:215], v[76:79]
	v_mfma_f32_16x16x32_bf16 v[104:107], v[152:155], v[186:189], v[104:107]
	v_mfma_f32_16x16x32_bf16 v[100:103], v[162:165], v[186:189], v[100:103]
	v_mfma_f32_16x16x32_bf16 v[96:99], v[152:155], v[194:197], v[96:99]
	v_mfma_f32_16x16x32_bf16 v[92:95], v[162:165], v[194:197], v[92:95]
	v_mfma_f32_16x16x32_bf16 v[88:91], v[152:155], v[208:211], v[88:91]
	v_mfma_f32_16x16x32_bf16 v[84:87], v[162:165], v[208:211], v[84:87]
	v_mfma_f32_16x16x32_bf16 v[80:83], v[152:155], v[236:239], v[80:83]
	v_mfma_f32_16x16x32_bf16 v[76:79], v[162:165], v[236:239], v[76:79]
	v_mfma_f32_16x16x32_bf16 v[28:31], v[166:169], v[182:185], v[28:31]
	v_mfma_f32_16x16x32_bf16 v[24:27], v[174:177], v[182:185], v[24:27]
	v_mfma_f32_16x16x32_bf16 v[20:23], v[166:169], v[190:193], v[20:23]
	v_mfma_f32_16x16x32_bf16 v[16:19], v[174:177], v[190:193], v[16:19]
	v_mfma_f32_16x16x32_bf16 v[12:15], v[166:169], v[204:207], v[12:15]
	v_mfma_f32_16x16x32_bf16 v[8:11], v[174:177], v[204:207], v[8:11]
	v_mfma_f32_16x16x32_bf16 v[4:7], v[166:169], v[212:215], v[4:7]
	v_mfma_f32_16x16x32_bf16 v[0:3], v[174:177], v[212:215], v[0:3]
	v_mfma_f32_16x16x32_bf16 v[28:31], v[170:173], v[186:189], v[28:31]
	v_mfma_f32_16x16x32_bf16 v[24:27], v[178:181], v[186:189], v[24:27]
	v_mfma_f32_16x16x32_bf16 v[20:23], v[170:173], v[194:197], v[20:23]
	v_mfma_f32_16x16x32_bf16 v[16:19], v[178:181], v[194:197], v[16:19]
	v_mfma_f32_16x16x32_bf16 v[12:15], v[170:173], v[208:211], v[12:15]
	v_mfma_f32_16x16x32_bf16 v[8:11], v[178:181], v[208:211], v[8:11]
	v_mfma_f32_16x16x32_bf16 v[4:7], v[170:173], v[236:239], v[4:7]
	v_mfma_f32_16x16x32_bf16 v[0:3], v[178:181], v[236:239], v[0:3]
	s_barrier
	s_add_u32 s24, s24, 0x100
	s_addc_u32 s25, s25, 0
	s_add_u32 s18, s18, 0x100
	s_addc_u32 s19, s19, 0
	s_cmp_ge_i32 s70, s58
	s_mov_b32 s0, s70
	s_cbranch_scc0 .LBB0_293

; #define PG8_STAGE(bufoff, gbase, voff) do { _Pragma("unroll") for (int _i = 0; _i < 2; ++_i) \
;         __builtin_amdgcn_global_load_lds((const unsigned*)((const char*)(gbase) + (voff)[_i]), (PG8_LAS unsigned*)(lds + (bufoff) + ldsw + _i * 8192), 16, 0, 0); } while (0)
; #define PG8_LDA(dst, b, h) do { _Pragma("unroll") for (int m = 0; m < 4; ++m) _Pragma("unroll") for (int k = 0; k < 2; ++k) dst[m][k] = *(const PG8_LAS bf16x8*)(lds + PG8_SA(b, h) + aoff + m * 2048 + k * 1024); } while (0)
; #define PG8_LDB(dst, b, h) do { _Pragma("unroll") for (int n = 0; n < 2; ++n) _Pragma("unroll") for (int k = 0; k < 2; ++k) dst[n][k] = *(const PG8_LAS bf16x8*)(lds + PG8_SB(b, h) + boff + n * 2048 + k * 1024); } while (0)
; #define PG8_MMA(ai, bj, At, Bt) do { __builtin_amdgcn_s_setprio(1); _Pragma("unroll") for (int m = 0; m < 4; ++m) _Pragma("unroll") for (int n = 0; n < 2; ++n) _Pragma("unroll") for (int k = 0; k < 2; ++k) \
;         acc[ai][bj][m][n] = __builtin_amdgcn_mfma_f32_16x16x32_bf16(Bt[n][k], At[m][k], acc[ai][bj][m][n], 0, 0, 0); __builtin_amdgcn_s_setprio(0); } while (0)
; #define PG8_WAIT_V(n) asm volatile("s_waitcnt vmcnt(" #n ")" ::: "memory")
; #define PG8_WAIT_L(n) asm volatile("s_waitcnt lgkmcnt(" #n ")" ::: "memory")
; #define PG8_BAR __builtin_amdgcn_s_barrier()
; #define PG8_SCHED __builtin_amdgcn_sched_barrier(0)
; template <class Epi, class Sched, bool ALIGN_EPI = false, bool SP2 = false>
; __device__ __forceinline__ void gemm_phase(PG8_LAS unsigned char* lds, const Gemm g, const Sched& S, const Epi& E) {
;     ...
;         for (int t = 0; t < nt; t += 2) {
;             const bool last = (t == nt - 2);
;             const char* a1 = cA + (size_t)(t + 1) * kstep;
;             const char* a2 = last ? nA : cA + (size_t)(t + 2) * kstep; const char* b2 = last ? nB : cB + (size_t)(t + 2) * kstep;
;             const char* a3 = a2 + kstep; const char* b3 = b2 + kstep;
;             if (last && has_next) S.a_ready(nxt);
;             if constexpr (SP2) {
;             PG8_LDB(B0, 0, 0); PG8_LDB(B1, 0, 1); PG8_SCHED; PG8_LDA(At, 0, 0); PG8_STAGE(PG8_SA(1, 1), a1 + hstep, voffA);
;             PG8_WAIT_V(8); PG8_WAIT_L(0); PG8_BAR; PG8_MMA(0, 0, At, B0); PG8_MMA(0, 1, At, B1); PG8_BAR; PG8_SCHED;
;             PG8_LDA(At, 0, 1); PG8_STAGE(PG8_SB(0, 0), b2, voffB); PG8_STAGE(PG8_SB(0, 1), b2 + hstep, voffB); PG8_STAGE(PG8_SA(0, 0), a2, voffA);
.LBB0_314:
	s_add_i32 s74, s0, 2
	s_add_u32 s75, s24, 0x80
	s_addc_u32 s1, s25, 0
	s_add_i32 s78, 0, 0x10000
	s_cmp_eq_u32 s67, s0
	s_cselect_b32 s1, s35, s1
	s_cselect_b32 s0, s34, s75
	s_cselect_b32 s77, s41, s19
	s_cselect_b32 s76, s40, s18
	s_add_i32 s75, 0, 0x14000
	v_add_u32_e32 v162, s78, v160
	v_add_u32_e32 v178, s75, v160
	ds_read_b128 v[148:151], v162
	ds_read_b128 v[152:155], v162 offset:1024
	ds_read_b128 v[156:159], v162 offset:2048
	ds_read_b128 v[162:165], v162 offset:3072
	ds_read_b128 v[166:169], v178
	ds_read_b128 v[170:173], v178 offset:1024
	ds_read_b128 v[174:177], v178 offset:2048
	ds_read_b128 v[178:181], v178 offset:3072
	v_lshl_add_u64 v[198:199], s[24:25], 0, v[144:145]
	s_add_i32 m0, s58, 0xc000
	ds_read_b128 v[182:185], v161
	ds_read_b128 v[186:189], v161 offset:1024
	ds_read_b128 v[190:193], v161 offset:2048
	ds_read_b128 v[194:197], v161 offset:3072
	ds_read_b128 v[204:207], v161 offset:4096
	ds_read_b128 v[208:211], v161 offset:5120
	ds_read_b128 v[212:215], v161 offset:6144
	ds_read_b128 v[236:239], v161 offset:7168
	global_load_lds_dwordx4 v[198:199], off
	v_lshl_add_u64 v[198:199], s[24:25], 0, v[146:147]
	s_add_i32 m0, s58, 0xe000
	s_nop 0
	global_load_lds_dwordx4 v[198:199], off
	s_waitcnt vmcnt(8)
	s_waitcnt lgkmcnt(0)
	s_barrier
	s_waitcnt lgkmcnt(0)
	v_mfma_f32_16x16x32_bf16 v[136:139], v[148:151], v[182:185], v[136:139]
	v_mfma_f32_16x16x32_bf16 v[132:135], v[156:159], v[182:185], v[132:135]
	v_mfma_f32_16x16x32_bf16 v[128:131], v[148:151], v[190:193], v[128:131]
	v_mfma_f32_16x16x32_bf16 v[124:127], v[156:159], v[190:193], v[124:127]
	v_mfma_f32_16x16x32_bf16 v[120:123], v[148:151], v[204:207], v[120:123]
	v_mfma_f32_16x16x32_bf16 v[116:119], v[156:159], v[204:207], v[116:119]
	v_mfma_f32_16x16x32_bf16 v[112:115], v[148:151], v[212:215], v[112:115]
	v_mfma_f32_16x16x32_bf16 v[108:111], v[156:159], v[212:215], v[108:111]
	v_mfma_f32_16x16x32_bf16 v[136:139], v[152:155], v[186:189], v[136:139]
	v_mfma_f32_16x16x32_bf16 v[132:135], v[162:165], v[186:189], v[132:135]
	v_mfma_f32_16x16x32_bf16 v[128:131], v[152:155], v[194:197], v[128:131]
	v_mfma_f32_16x16x32_bf16 v[124:127], v[162:165], v[194:197], v[124:127]
	v_mfma_f32_16x16x32_bf16 v[120:123], v[152:155], v[208:211], v[120:123]
	v_mfma_f32_16x16x32_bf16 v[116:119], v[162:165], v[208:211], v[116:119]
	v_mfma_f32_16x16x32_bf16 v[112:115], v[152:155], v[236:239], v[112:115]
	v_mfma_f32_16x16x32_bf16 v[108:111], v[162:165], v[236:239], v[108:111]
	v_mfma_f32_16x16x32_bf16 v[72:75], v[166:169], v[182:185], v[72:75]
	v_mfma_f32_16x16x32_bf16 v[68:71], v[174:177], v[182:185], v[68:71]
	v_mfma_f32_16x16x32_bf16 v[64:67], v[166:169], v[190:193], v[64:67]
	v_mfma_f32_16x16x32_bf16 v[60:63], v[174:177], v[190:193], v[60:63]
	v_mfma_f32_16x16x32_bf16 v[56:59], v[166:169], v[204:207], v[56:59]
	v_mfma_f32_16x16x32_bf16 v[52:55], v[174:177], v[204:207], v[52:55]
	v_mfma_f32_16x16x32_bf16 v[48:51], v[166:169], v[212:215], v[48:51]
	v_mfma_f32_16x16x32_bf16 v[32:35], v[174:177], v[212:215], v[32:35]
	v_mfma_f32_16x16x32_bf16 v[72:75], v[170:173], v[186:189], v[72:75]
	v_mfma_f32_16x16x32_bf16 v[68:71], v[178:181], v[186:189], v[68:71]
	v_mfma_f32_16x16x32_bf16 v[64:67], v[170:173], v[194:197], v[64:67]
	v_mfma_f32_16x16x32_bf16 v[60:63], v[178:181], v[194:197], v[60:63]
	v_mfma_f32_16x16x32_bf16 v[56:59], v[170:173], v[208:211], v[56:59]
	v_mfma_f32_16x16x32_bf16 v[52:55], v[178:181], v[208:211], v[52:55]
	v_mfma_f32_16x16x32_bf16 v[48:51], v[170:173], v[236:239], v[48:51]
	v_mfma_f32_16x16x32_bf16 v[32:35], v[178:181], v[236:239], v[32:35]
	s_barrier
	s_add_i32 s78, s78, s51
	v_lshl_add_u64 v[198:199], s[76:77], 0, v[140:141]
	s_mov_b32 m0, s78
	ds_read_b128 v[182:185], v161 offset:16384
	ds_read_b128 v[186:189], v161 offset:17408
	ds_read_b128 v[190:193], v161 offset:18432
	ds_read_b128 v[194:197], v161 offset:19456
	ds_read_b128 v[204:207], v161 offset:20480
	ds_read_b128 v[208:211], v161 offset:21504
	ds_read_b128 v[212:215], v161 offset:22528
	ds_read_b128 v[236:239], v161 offset:23552
	global_load_lds_dwordx4 v[198:199], off
	s_add_i32 m0, s78, 0x2000
	v_lshl_add_u64 v[240:241], s[76:77], 0, v[38:39]
	s_add_u32 s76, s76, s10
	s_addc_u32 s77, s77, s11
	s_add_i32 s75, s75, s51
	global_load_lds_dwordx4 v[240:241], off
	v_lshl_add_u64 v[242:243], s[76:77], 0, v[140:141]
	s_mov_b32 m0, s75
	v_lshl_add_u64 v[244:245], s[76:77], 0, v[38:39]
	global_load_lds_dwordx4 v[242:243], off
	s_add_i32 m0, s75, 0x2000
	v_lshl_add_u64 v[246:247], s[0:1], 0, v[142:143]
	global_load_lds_dwordx4 v[244:245], off
	s_mov_b32 m0, s58
	v_lshl_add_u64 v[248:249], s[0:1], 0, v[42:43]
	global_load_lds_dwordx4 v[246:247], off
	s_mov_b32 m0, s59
	s_nop 0
	global_load_lds_dwordx4 v[248:249], off
	s_waitcnt vmcnt(8)
	s_waitcnt lgkmcnt(0)
	s_barrier
; #define PG8_STAGE(bufoff, gbase, voff) do { _Pragma("unroll") for (int _i = 0; _i < 2; ++_i) \
;         __builtin_amdgcn_global_load_lds((const unsigned*)((const char*)(gbase) + (voff)[_i]), (PG8_LAS unsigned*)(lds + (bufoff) + ldsw + _i * 8192), 16, 0, 0); } while (0)
; #define PG8_LDA(dst, b, h) do { _Pragma("unroll") for (int m = 0; m < 4; ++m) _Pragma("unroll") for (int k = 0; k < 2; ++k) dst[m][k] = *(const PG8_LAS bf16x8*)(lds + PG8_SA(b, h) + aoff + m * 2048 + k * 1024); } while (0)
; #define PG8_LDB(dst, b, h) do { _Pragma("unroll") for (int n = 0; n < 2; ++n) _Pragma("unroll") for (int k = 0; k < 2; ++k) dst[n][k] = *(const PG8_LAS bf16x8*)(lds + PG8_SB(b, h) + boff + n * 2048 + k * 1024); } while (0)
; #define PG8_MMA(ai, bj, At, Bt) do { __builtin_amdgcn_s_setprio(1); _Pragma("unroll") for (int m = 0; m < 4; ++m) _Pragma("unroll") for (int n = 0; n < 2; ++n) _Pragma("unroll") for (int k = 0; k < 2; ++k) \
;         acc[ai][bj][m][n] = __builtin_amdgcn_mfma_f32_16x16x32_bf16(Bt[n][k], At[m][k], acc[ai][bj][m][n], 0, 0, 0); __builtin_amdgcn_s_setprio(0); } while (0)
; #define PG8_WAIT_V(n) asm volatile("s_waitcnt vmcnt(" #n ")" ::: "memory")
; #define PG8_WAIT_L(n) asm volatile("s_waitcnt lgkmcnt(" #n ")" ::: "memory")
; #define PG8_BAR __builtin_amdgcn_s_barrier()
; #define PG8_SCHED __builtin_amdgcn_sched_barrier(0)
; template <class Epi, class Sched, bool ALIGN_EPI = false, bool SP2 = false>
; __device__ __forceinline__ void gemm_phase(PG8_LAS unsigned char* lds, const Gemm g, const Sched& S, const Epi& E) {
;     ...
;             PG8_WAIT_V(8); PG8_WAIT_L(0); PG8_BAR; PG8_MMA(1, 0, At, B0); PG8_MMA(1, 1, At, B1); PG8_BAR; PG8_SCHED;
;             PG8_LDB(B0, 1, 0); PG8_LDB(B1, 1, 1); PG8_SCHED; PG8_LDA(At, 1, 0); PG8_STAGE(PG8_SA(0, 1), a2 + hstep, voffA);
;             PG8_WAIT_V(8); PG8_WAIT_L(0); PG8_BAR; PG8_MMA(0, 0, At, B0); PG8_MMA(0, 1, At, B1); PG8_BAR; PG8_SCHED;
	s_waitcnt lgkmcnt(0)
	v_mfma_f32_16x16x32_bf16 v[104:107], v[148:151], v[182:185], v[104:107]
	v_mfma_f32_16x16x32_bf16 v[100:103], v[156:159], v[182:185], v[100:103]
	v_mfma_f32_16x16x32_bf16 v[96:99], v[148:151], v[190:193], v[96:99]
	v_mfma_f32_16x16x32_bf16 v[92:95], v[156:159], v[190:193], v[92:95]
	v_mfma_f32_16x16x32_bf16 v[88:91], v[148:151], v[204:207], v[88:91]
	v_mfma_f32_16x16x32_bf16 v[84:87], v[156:159], v[204:207], v[84:87]
	v_mfma_f32_16x16x32_bf16 v[80:83], v[148:151], v[212:215], v[80:83]
	v_mfma_f32_16x16x32_bf16 v[76:79], v[156:159], v[212:215], v[76:79]
	v_mfma_f32_16x16x32_bf16 v[104:107], v[152:155], v[186:189], v[104:107]
	v_mfma_f32_16x16x32_bf16 v[100:103], v[162:165], v[186:189], v[100:103]
	v_mfma_f32_16x16x32_bf16 v[96:99], v[152:155], v[194:197], v[96:99]
	v_mfma_f32_16x16x32_bf16 v[92:95], v[162:165], v[194:197], v[92:95]
	v_mfma_f32_16x16x32_bf16 v[88:91], v[152:155], v[208:211], v[88:91]
	v_mfma_f32_16x16x32_bf16 v[84:87], v[162:165], v[208:211], v[84:87]
	v_mfma_f32_16x16x32_bf16 v[80:83], v[152:155], v[236:239], v[80:83]
	v_mfma_f32_16x16x32_bf16 v[76:79], v[162:165], v[236:239], v[76:79]
	v_mfma_f32_16x16x32_bf16 v[28:31], v[166:169], v[182:185], v[28:31]
	v_mfma_f32_16x16x32_bf16 v[24:27], v[174:177], v[182:185], v[24:27]
	v_mfma_f32_16x16x32_bf16 v[20:23], v[166:169], v[190:193], v[20:23]
	v_mfma_f32_16x16x32_bf16 v[16:19], v[174:177], v[190:193], v[16:19]
	v_mfma_f32_16x16x32_bf16 v[12:15], v[166:169], v[204:207], v[12:15]
	v_mfma_f32_16x16x32_bf16 v[8:11], v[174:177], v[204:207], v[8:11]
	v_mfma_f32_16x16x32_bf16 v[4:7], v[166:169], v[212:215], v[4:7]
	v_mfma_f32_16x16x32_bf16 v[0:3], v[174:177], v[212:215], v[0:3]
	v_mfma_f32_16x16x32_bf16 v[28:31], v[170:173], v[186:189], v[28:31]
	v_mfma_f32_16x16x32_bf16 v[24:27], v[178:181], v[186:189], v[24:27]
	v_mfma_f32_16x16x32_bf16 v[20:23], v[170:173], v[194:197], v[20:23]
	v_mfma_f32_16x16x32_bf16 v[16:19], v[178:181], v[194:197], v[16:19]
	v_mfma_f32_16x16x32_bf16 v[12:15], v[170:173], v[208:211], v[12:15]
	v_mfma_f32_16x16x32_bf16 v[8:11], v[178:181], v[208:211], v[8:11]
	v_mfma_f32_16x16x32_bf16 v[4:7], v[170:173], v[236:239], v[4:7]
	v_mfma_f32_16x16x32_bf16 v[0:3], v[178:181], v[236:239], v[0:3]
	s_barrier
	s_add_i32 s75, 0, 0x18000
	s_add_i32 s76, 0, 0x1c000
	v_add_u32_e32 v162, s75, v160
	v_add_u32_e32 v178, s76, v160
	ds_read_b128 v[148:151], v162
	ds_read_b128 v[152:155], v162 offset:1024
	ds_read_b128 v[156:159], v162 offset:2048
	ds_read_b128 v[162:165], v162 offset:3072
	ds_read_b128 v[166:169], v178
	ds_read_b128 v[170:173], v178 offset:1024
	ds_read_b128 v[174:177], v178 offset:2048
	ds_read_b128 v[178:181], v178 offset:3072
	s_add_u32 s0, s0, s10
	s_addc_u32 s1, s1, s11
	s_mov_b32 m0, s60
	v_lshl_add_u64 v[250:251], s[0:1], 0, v[142:143]
	ds_read_b128 v[182:185], v161 offset:32768
	ds_read_b128 v[186:189], v161 offset:33792
	ds_read_b128 v[190:193], v161 offset:34816
	ds_read_b128 v[194:197], v161 offset:35840
	ds_read_b128 v[204:207], v161 offset:36864
	ds_read_b128 v[208:211], v161 offset:37888
	ds_read_b128 v[212:215], v161 offset:38912
	ds_read_b128 v[236:239], v161 offset:39936
	global_load_lds_dwordx4 v[250:251], off
	v_lshl_add_u64 v[250:251], s[0:1], 0, v[42:43]
	s_mov_b32 m0, s61
	s_nop 0
	global_load_lds_dwordx4 v[250:251], off
	s_waitcnt vmcnt(8)
	s_waitcnt lgkmcnt(0)
	s_barrier
	s_waitcnt lgkmcnt(0)
	v_mfma_f32_16x16x32_bf16 v[136:139], v[148:151], v[182:185], v[136:139]
	v_mfma_f32_16x16x32_bf16 v[132:135], v[156:159], v[182:185], v[132:135]
	v_mfma_f32_16x16x32_bf16 v[128:131], v[148:151], v[190:193], v[128:131]
	v_mfma_f32_16x16x32_bf16 v[124:127], v[156:159], v[190:193], v[124:127]
	v_mfma_f32_16x16x32_bf16 v[120:123], v[148:151], v[204:207], v[120:123]
	v_mfma_f32_16x16x32_bf16 v[116:119], v[156:159], v[204:207], v[116:119]
	v_mfma_f32_16x16x32_bf16 v[112:115], v[148:151], v[212:215], v[112:115]
	v_mfma_f32_16x16x32_bf16 v[108:111], v[156:159], v[212:215], v[108:111]
	v_mfma_f32_16x16x32_bf16 v[136:139], v[152:155], v[186:189], v[136:139]
	v_mfma_f32_16x16x32_bf16 v[132:135], v[162:165], v[186:189], v[132:135]
	v_mfma_f32_16x16x32_bf16 v[128:131], v[152:155], v[194:197], v[128:131]
	v_mfma_f32_16x16x32_bf16 v[124:127], v[162:165], v[194:197], v[124:127]
	v_mfma_f32_16x16x32_bf16 v[120:123], v[152:155], v[208:211], v[120:123]
	v_mfma_f32_16x16x32_bf16 v[116:119], v[162:165], v[208:211], v[116:119]
	v_mfma_f32_16x16x32_bf16 v[112:115], v[152:155], v[236:239], v[112:115]
	v_mfma_f32_16x16x32_bf16 v[108:111], v[162:165], v[236:239], v[108:111]
	v_mfma_f32_16x16x32_bf16 v[72:75], v[166:169], v[182:185], v[72:75]
	v_mfma_f32_16x16x32_bf16 v[68:71], v[174:177], v[182:185], v[68:71]
	v_mfma_f32_16x16x32_bf16 v[64:67], v[166:169], v[190:193], v[64:67]
	v_mfma_f32_16x16x32_bf16 v[60:63], v[174:177], v[190:193], v[60:63]
	v_mfma_f32_16x16x32_bf16 v[56:59], v[166:169], v[204:207], v[56:59]
	v_mfma_f32_16x16x32_bf16 v[52:55], v[174:177], v[204:207], v[52:55]
	v_mfma_f32_16x16x32_bf16 v[48:51], v[166:169], v[212:215], v[48:51]
	v_mfma_f32_16x16x32_bf16 v[32:35], v[174:177], v[212:215], v[32:35]
	v_mfma_f32_16x16x32_bf16 v[72:75], v[170:173], v[186:189], v[72:75]
	v_mfma_f32_16x16x32_bf16 v[68:71], v[178:181], v[186:189], v[68:71]
	v_mfma_f32_16x16x32_bf16 v[64:67], v[170:173], v[194:197], v[64:67]
	v_mfma_f32_16x16x32_bf16 v[60:63], v[178:181], v[194:197], v[60:63]
	v_mfma_f32_16x16x32_bf16 v[56:59], v[170:173], v[208:211], v[56:59]
	v_mfma_f32_16x16x32_bf16 v[52:55], v[178:181], v[208:211], v[52:55]
	v_mfma_f32_16x16x32_bf16 v[48:51], v[170:173], v[236:239], v[48:51]
	v_mfma_f32_16x16x32_bf16 v[32:35], v[178:181], v[236:239], v[32:35]
	s_barrier
; #define PG8_STAGE(bufoff, gbase, voff) do { _Pragma("unroll") for (int _i = 0; _i < 2; ++_i) \
;         __builtin_amdgcn_global_load_lds((const unsigned*)((const char*)(gbase) + (voff)[_i]), (PG8_LAS unsigned*)(lds + (bufoff) + ldsw + _i * 8192), 16, 0, 0); } while (0)
; #define PG8_LDA(dst, b, h) do { _Pragma("unroll") for (int m = 0; m < 4; ++m) _Pragma("unroll") for (int k = 0; k < 2; ++k) dst[m][k] = *(const PG8_LAS bf16x8*)(lds + PG8_SA(b, h) + aoff + m * 2048 + k * 1024); } while (0)
; #define PG8_MMA(ai, bj, At, Bt) do { __builtin_amdgcn_s_setprio(1); _Pragma("unroll") for (int m = 0; m < 4; ++m) _Pragma("unroll") for (int n = 0; n < 2; ++n) _Pragma("unroll") for (int k = 0; k < 2; ++k) \
;         acc[ai][bj][m][n] = __builtin_amdgcn_mfma_f32_16x16x32_bf16(Bt[n][k], At[m][k], acc[ai][bj][m][n], 0, 0, 0); __builtin_amdgcn_s_setprio(0); } while (0)
; #define PG8_WAIT_V(n) asm volatile("s_waitcnt vmcnt(" #n ")" ::: "memory")
; #define PG8_WAIT_L(n) asm volatile("s_waitcnt lgkmcnt(" #n ")" ::: "memory")
; #define PG8_BAR __builtin_amdgcn_s_barrier()
; #define PG8_SCHED __builtin_amdgcn_sched_barrier(0)
; template <class Epi, class Sched, bool ALIGN_EPI = false, bool SP2 = false>
; __device__ __forceinline__ void gemm_phase(PG8_LAS unsigned char* lds, const Gemm g, const Sched& S, const Epi& E) {
;     ...
;         for (int t = 0; t < nt; t += 2) {
;     ...
;             PG8_LDA(At, 1, 1); PG8_STAGE(PG8_SB(1, 0), b3, voffB); PG8_STAGE(PG8_SB(1, 1), b3 + hstep, voffB); PG8_STAGE(PG8_SA(1, 0), a3, voffA);
;             PG8_WAIT_V(8); PG8_WAIT_L(0); PG8_BAR; PG8_MMA(1, 0, At, B0); PG8_MMA(1, 1, At, B1); PG8_BAR; PG8_SCHED;
	s_add_i32 s0, s75, s51
	v_lshl_add_u64 v[198:199], v[198:199], 0, s[22:23]
	s_mov_b32 m0, s0
	ds_read_b128 v[182:185], v161 offset:49152
	ds_read_b128 v[186:189], v161 offset:50176
	ds_read_b128 v[190:193], v161 offset:51200
	ds_read_b128 v[194:197], v161 offset:52224
	ds_read_b128 v[204:207], v161 offset:53248
	ds_read_b128 v[208:211], v161 offset:54272
	ds_read_b128 v[212:215], v161 offset:55296
	ds_read_b128 v[236:239], v161 offset:56320
	global_load_lds_dwordx4 v[198:199], off
	v_lshl_add_u64 v[198:199], v[240:241], 0, s[22:23]
	s_add_i32 m0, s0, 0x2000
	s_add_i32 s0, s76, s51
	global_load_lds_dwordx4 v[198:199], off
	v_lshl_add_u64 v[198:199], v[242:243], 0, s[22:23]
	s_mov_b32 m0, s0
	s_nop 0
	global_load_lds_dwordx4 v[198:199], off
	v_lshl_add_u64 v[198:199], v[244:245], 0, s[22:23]
	s_add_i32 m0, s0, 0x2000
	s_nop 0
	global_load_lds_dwordx4 v[198:199], off
	v_lshl_add_u64 v[198:199], v[246:247], 0, s[22:23]
	s_mov_b32 m0, s65
	s_nop 0
	global_load_lds_dwordx4 v[198:199], off
	v_lshl_add_u64 v[198:199], v[248:249], 0, s[22:23]
	s_mov_b32 m0, s66
	s_nop 0
	global_load_lds_dwordx4 v[198:199], off
	s_waitcnt vmcnt(8)
	s_waitcnt lgkmcnt(0)
	s_barrier
	s_waitcnt lgkmcnt(0)
	v_mfma_f32_16x16x32_bf16 v[104:107], v[148:151], v[182:185], v[104:107]
	v_mfma_f32_16x16x32_bf16 v[100:103], v[156:159], v[182:185], v[100:103]
	v_mfma_f32_16x16x32_bf16 v[96:99], v[148:151], v[190:193], v[96:99]
	v_mfma_f32_16x16x32_bf16 v[92:95], v[156:159], v[190:193], v[92:95]
	v_mfma_f32_16x16x32_bf16 v[88:91], v[148:151], v[204:207], v[88:91]
	v_mfma_f32_16x16x32_bf16 v[84:87], v[156:159], v[204:207], v[84:87]
	v_mfma_f32_16x16x32_bf16 v[80:83], v[148:151], v[212:215], v[80:83]
	v_mfma_f32_16x16x32_bf16 v[76:79], v[156:159], v[212:215], v[76:79]
	v_mfma_f32_16x16x32_bf16 v[104:107], v[152:155], v[186:189], v[104:107]
	v_mfma_f32_16x16x32_bf16 v[100:103], v[162:165], v[186:189], v[100:103]
	v_mfma_f32_16x16x32_bf16 v[96:99], v[152:155], v[194:197], v[96:99]
	v_mfma_f32_16x16x32_bf16 v[92:95], v[162:165], v[194:197], v[92:95]
	v_mfma_f32_16x16x32_bf16 v[88:91], v[152:155], v[208:211], v[88:91]
	v_mfma_f32_16x16x32_bf16 v[84:87], v[162:165], v[208:211], v[84:87]
	v_mfma_f32_16x16x32_bf16 v[80:83], v[152:155], v[236:239], v[80:83]
	v_mfma_f32_16x16x32_bf16 v[76:79], v[162:165], v[236:239], v[76:79]
	v_mfma_f32_16x16x32_bf16 v[28:31], v[166:169], v[182:185], v[28:31]
	v_mfma_f32_16x16x32_bf16 v[24:27], v[174:177], v[182:185], v[24:27]
	v_mfma_f32_16x16x32_bf16 v[20:23], v[166:169], v[190:193], v[20:23]
	v_mfma_f32_16x16x32_bf16 v[16:19], v[174:177], v[190:193], v[16:19]
	v_mfma_f32_16x16x32_bf16 v[12:15], v[166:169], v[204:207], v[12:15]
	v_mfma_f32_16x16x32_bf16 v[8:11], v[174:177], v[204:207], v[8:11]
	v_mfma_f32_16x16x32_bf16 v[4:7], v[166:169], v[212:215], v[4:7]
	v_mfma_f32_16x16x32_bf16 v[0:3], v[174:177], v[212:215], v[0:3]
	v_mfma_f32_16x16x32_bf16 v[28:31], v[170:173], v[186:189], v[28:31]
	v_mfma_f32_16x16x32_bf16 v[24:27], v[178:181], v[186:189], v[24:27]
	v_mfma_f32_16x16x32_bf16 v[20:23], v[170:173], v[194:197], v[20:23]
	v_mfma_f32_16x16x32_bf16 v[16:19], v[178:181], v[194:197], v[16:19]
	v_mfma_f32_16x16x32_bf16 v[12:15], v[170:173], v[208:211], v[12:15]
	v_mfma_f32_16x16x32_bf16 v[8:11], v[178:181], v[208:211], v[8:11]
	v_mfma_f32_16x16x32_bf16 v[4:7], v[170:173], v[236:239], v[4:7]
	v_mfma_f32_16x16x32_bf16 v[0:3], v[178:181], v[236:239], v[0:3]
	s_barrier
	s_add_u32 s24, s24, 0x100
	s_addc_u32 s25, s25, 0
	s_add_u32 s18, s18, 0x100
	s_addc_u32 s19, s19, 0
	s_cmp_ge_i32 s74, s62
	s_mov_b32 s0, s74
	s_cbranch_scc0 .LBB0_314
	s_mov_b32 s78, 0x14000
	s_movk_i32 s76, 0x90

; #define PG8_STAGE(bufoff, gbase, voff) do { _Pragma("unroll") for (int _i = 0; _i < 2; ++_i) \
;         __builtin_amdgcn_global_load_lds((const unsigned*)((const char*)(gbase) + (voff)[_i]), (PG8_LAS unsigned*)(lds + (bufoff) + ldsw + _i * 8192), 16, 0, 0); } while (0)
; #define PG8_LDA(dst, b, h) do { _Pragma("unroll") for (int m = 0; m < 4; ++m) _Pragma("unroll") for (int k = 0; k < 2; ++k) dst[m][k] = *(const PG8_LAS bf16x8*)(lds + PG8_SA(b, h) + aoff + m * 2048 + k * 1024); } while (0)
; #define PG8_LDB(dst, b, h) do { _Pragma("unroll") for (int n = 0; n < 2; ++n) _Pragma("unroll") for (int k = 0; k < 2; ++k) dst[n][k] = *(const PG8_LAS bf16x8*)(lds + PG8_SB(b, h) + boff + n * 2048 + k * 1024); } while (0)
; #define PG8_MMA(ai, bj, At, Bt) do { __builtin_amdgcn_s_setprio(1); _Pragma("unroll") for (int m = 0; m < 4; ++m) _Pragma("unroll") for (int n = 0; n < 2; ++n) _Pragma("unroll") for (int k = 0; k < 2; ++k) \
;         acc[ai][bj][m][n] = __builtin_amdgcn_mfma_f32_16x16x32_bf16(Bt[n][k], At[m][k], acc[ai][bj][m][n], 0, 0, 0); __builtin_amdgcn_s_setprio(0); } while (0)
; #define PG8_WAIT_V(n) asm volatile("s_waitcnt vmcnt(" #n ")" ::: "memory")
; #define PG8_WAIT_L(n) asm volatile("s_waitcnt lgkmcnt(" #n ")" ::: "memory")
; #define PG8_BAR __builtin_amdgcn_s_barrier()
; #define PG8_SCHED __builtin_amdgcn_sched_barrier(0)
; template <class Epi, class Sched, bool ALIGN_EPI = false, bool SP2 = false>
; __device__ __forceinline__ void gemm_phase(PG8_LAS unsigned char* lds, const Gemm g, const Sched& S, const Epi& E) {
;     ...
;         for (int t = 0; t < nt; t += 2) {
;             const bool last = (t == nt - 2);
;             const char* a1 = cA + (size_t)(t + 1) * kstep;
;             const char* a2 = last ? nA : cA + (size_t)(t + 2) * kstep; const char* b2 = last ? nB : cB + (size_t)(t + 2) * kstep;
;             const char* a3 = a2 + kstep; const char* b3 = b2 + kstep;
;             if (last && has_next) S.a_ready(nxt);
;             if constexpr (SP2) {
;             PG8_LDB(B0, 0, 0); PG8_LDB(B1, 0, 1); PG8_SCHED; PG8_LDA(At, 0, 0); PG8_STAGE(PG8_SA(1, 1), a1 + hstep, voffA);
;             PG8_WAIT_V(8); PG8_WAIT_L(0); PG8_BAR; PG8_MMA(0, 0, At, B0); PG8_MMA(0, 1, At, B1); PG8_BAR; PG8_SCHED;
;             PG8_LDA(At, 0, 1); PG8_STAGE(PG8_SB(0, 0), b2, voffB); PG8_STAGE(PG8_SB(0, 1), b2 + hstep, voffB); PG8_STAGE(PG8_SA(0, 0), a2, voffA);
.LBB0_336:
	s_add_i32 s81, s0, 2
	s_add_u32 s88, s24, 0x80
	s_addc_u32 s1, s25, 0
	s_add_i32 s90, 0, 0x10000
	s_cmp_eq_u32 s72, s0
	s_cselect_b32 s1, s41, s1
	s_cselect_b32 s0, s40, s88
	s_cselect_b32 s89, s43, s19
	s_cselect_b32 s88, s42, s18
	s_add_i32 s91, 0, 0x14000
	v_add_u32_e32 v162, s90, v160
	v_add_u32_e32 v178, s91, v160
	ds_read_b128 v[148:151], v162
	ds_read_b128 v[152:155], v162 offset:1024
	ds_read_b128 v[156:159], v162 offset:2048
	ds_read_b128 v[162:165], v162 offset:3072
	ds_read_b128 v[166:169], v178
	ds_read_b128 v[170:173], v178 offset:1024
	ds_read_b128 v[174:177], v178 offset:2048
	ds_read_b128 v[178:181], v178 offset:3072
	v_lshl_add_u64 v[198:199], s[24:25], 0, v[144:145]
	s_add_i32 m0, s63, 0xc000
	ds_read_b128 v[182:185], v161
	ds_read_b128 v[186:189], v161 offset:1024
	ds_read_b128 v[190:193], v161 offset:2048
	ds_read_b128 v[194:197], v161 offset:3072
	ds_read_b128 v[204:207], v161 offset:4096
	ds_read_b128 v[208:211], v161 offset:5120
	ds_read_b128 v[212:215], v161 offset:6144
	ds_read_b128 v[236:239], v161 offset:7168
	global_load_lds_dwordx4 v[198:199], off
	v_lshl_add_u64 v[198:199], s[24:25], 0, v[146:147]
	s_add_i32 m0, s63, 0xe000
	s_nop 0
	global_load_lds_dwordx4 v[198:199], off
	s_waitcnt vmcnt(8)
	s_waitcnt lgkmcnt(0)
	s_barrier
	s_waitcnt lgkmcnt(0)
	v_mfma_f32_16x16x32_bf16 v[132:135], v[148:151], v[182:185], v[132:135]
	v_mfma_f32_16x16x32_bf16 v[136:139], v[156:159], v[182:185], v[136:139]
	v_mfma_f32_16x16x32_bf16 v[128:131], v[148:151], v[190:193], v[128:131]
	v_mfma_f32_16x16x32_bf16 v[124:127], v[156:159], v[190:193], v[124:127]
	v_mfma_f32_16x16x32_bf16 v[120:123], v[148:151], v[204:207], v[120:123]
	v_mfma_f32_16x16x32_bf16 v[116:119], v[156:159], v[204:207], v[116:119]
	v_mfma_f32_16x16x32_bf16 v[112:115], v[148:151], v[212:215], v[112:115]
	v_mfma_f32_16x16x32_bf16 v[108:111], v[156:159], v[212:215], v[108:111]
	v_mfma_f32_16x16x32_bf16 v[132:135], v[152:155], v[186:189], v[132:135]
	v_mfma_f32_16x16x32_bf16 v[136:139], v[162:165], v[186:189], v[136:139]
	v_mfma_f32_16x16x32_bf16 v[128:131], v[152:155], v[194:197], v[128:131]
	v_mfma_f32_16x16x32_bf16 v[124:127], v[162:165], v[194:197], v[124:127]
	v_mfma_f32_16x16x32_bf16 v[120:123], v[152:155], v[208:211], v[120:123]
	v_mfma_f32_16x16x32_bf16 v[116:119], v[162:165], v[208:211], v[116:119]
	v_mfma_f32_16x16x32_bf16 v[112:115], v[152:155], v[236:239], v[112:115]
	v_mfma_f32_16x16x32_bf16 v[108:111], v[162:165], v[236:239], v[108:111]
	v_mfma_f32_16x16x32_bf16 v[72:75], v[166:169], v[182:185], v[72:75]
	v_mfma_f32_16x16x32_bf16 v[68:71], v[174:177], v[182:185], v[68:71]
	v_mfma_f32_16x16x32_bf16 v[64:67], v[166:169], v[190:193], v[64:67]
	v_mfma_f32_16x16x32_bf16 v[60:63], v[174:177], v[190:193], v[60:63]
	v_mfma_f32_16x16x32_bf16 v[56:59], v[166:169], v[204:207], v[56:59]
	v_mfma_f32_16x16x32_bf16 v[52:55], v[174:177], v[204:207], v[52:55]
	v_mfma_f32_16x16x32_bf16 v[48:51], v[166:169], v[212:215], v[48:51]
	v_mfma_f32_16x16x32_bf16 v[32:35], v[174:177], v[212:215], v[32:35]
	v_mfma_f32_16x16x32_bf16 v[72:75], v[170:173], v[186:189], v[72:75]
	v_mfma_f32_16x16x32_bf16 v[68:71], v[178:181], v[186:189], v[68:71]
	v_mfma_f32_16x16x32_bf16 v[64:67], v[170:173], v[194:197], v[64:67]
	v_mfma_f32_16x16x32_bf16 v[60:63], v[178:181], v[194:197], v[60:63]
	v_mfma_f32_16x16x32_bf16 v[56:59], v[170:173], v[208:211], v[56:59]
	v_mfma_f32_16x16x32_bf16 v[52:55], v[178:181], v[208:211], v[52:55]
	v_mfma_f32_16x16x32_bf16 v[48:51], v[170:173], v[236:239], v[48:51]
	v_mfma_f32_16x16x32_bf16 v[32:35], v[178:181], v[236:239], v[32:35]
	s_barrier
	s_add_i32 s90, s90, s59
	v_lshl_add_u64 v[198:199], s[88:89], 0, v[140:141]
	s_mov_b32 m0, s90
	ds_read_b128 v[182:185], v161 offset:16384
	ds_read_b128 v[186:189], v161 offset:17408
	ds_read_b128 v[190:193], v161 offset:18432
	ds_read_b128 v[194:197], v161 offset:19456
	ds_read_b128 v[204:207], v161 offset:20480
	ds_read_b128 v[208:211], v161 offset:21504
	ds_read_b128 v[212:215], v161 offset:22528
	ds_read_b128 v[236:239], v161 offset:23552
	global_load_lds_dwordx4 v[198:199], off
	s_add_i32 m0, s90, 0x2000
	v_lshl_add_u64 v[240:241], s[88:89], 0, v[38:39]
	s_add_u32 s88, s88, s2
	s_addc_u32 s89, s89, s3
	s_add_i32 s90, s91, s59
	global_load_lds_dwordx4 v[240:241], off
	v_lshl_add_u64 v[242:243], s[88:89], 0, v[140:141]
	s_mov_b32 m0, s90
	v_lshl_add_u64 v[244:245], s[88:89], 0, v[38:39]
	global_load_lds_dwordx4 v[242:243], off
	s_add_i32 m0, s90, 0x2000
	v_lshl_add_u64 v[246:247], s[0:1], 0, v[142:143]
	global_load_lds_dwordx4 v[244:245], off
	s_mov_b32 m0, s63
	v_lshl_add_u64 v[248:249], s[0:1], 0, v[42:43]
	global_load_lds_dwordx4 v[246:247], off
	s_mov_b32 m0, s64
	s_nop 0
	global_load_lds_dwordx4 v[248:249], off
	s_waitcnt vmcnt(8)
	s_waitcnt lgkmcnt(0)
	s_barrier
; #define PG8_STAGE(bufoff, gbase, voff) do { _Pragma("unroll") for (int _i = 0; _i < 2; ++_i) \
;         __builtin_amdgcn_global_load_lds((const unsigned*)((const char*)(gbase) + (voff)[_i]), (PG8_LAS unsigned*)(lds + (bufoff) + ldsw + _i * 8192), 16, 0, 0); } while (0)
; #define PG8_LDA(dst, b, h) do { _Pragma("unroll") for (int m = 0; m < 4; ++m) _Pragma("unroll") for (int k = 0; k < 2; ++k) dst[m][k] = *(const PG8_LAS bf16x8*)(lds + PG8_SA(b, h) + aoff + m * 2048 + k * 1024); } while (0)
; #define PG8_LDB(dst, b, h) do { _Pragma("unroll") for (int n = 0; n < 2; ++n) _Pragma("unroll") for (int k = 0; k < 2; ++k) dst[n][k] = *(const PG8_LAS bf16x8*)(lds + PG8_SB(b, h) + boff + n * 2048 + k * 1024); } while (0)
; #define PG8_MMA(ai, bj, At, Bt) do { __builtin_amdgcn_s_setprio(1); _Pragma("unroll") for (int m = 0; m < 4; ++m) _Pragma("unroll") for (int n = 0; n < 2; ++n) _Pragma("unroll") for (int k = 0; k < 2; ++k) \
;         acc[ai][bj][m][n] = __builtin_amdgcn_mfma_f32_16x16x32_bf16(Bt[n][k], At[m][k], acc[ai][bj][m][n], 0, 0, 0); __builtin_amdgcn_s_setprio(0); } while (0)
; #define PG8_WAIT_V(n) asm volatile("s_waitcnt vmcnt(" #n ")" ::: "memory")
; #define PG8_WAIT_L(n) asm volatile("s_waitcnt lgkmcnt(" #n ")" ::: "memory")
; #define PG8_BAR __builtin_amdgcn_s_barrier()
; #define PG8_SCHED __builtin_amdgcn_sched_barrier(0)
; template <class Epi, class Sched, bool ALIGN_EPI = false, bool SP2 = false>
; __device__ __forceinline__ void gemm_phase(PG8_LAS unsigned char* lds, const Gemm g, const Sched& S, const Epi& E) {
;     ...
;             PG8_WAIT_V(8); PG8_WAIT_L(0); PG8_BAR; PG8_MMA(1, 0, At, B0); PG8_MMA(1, 1, At, B1); PG8_BAR; PG8_SCHED;
;             PG8_LDB(B0, 1, 0); PG8_LDB(B1, 1, 1); PG8_SCHED; PG8_LDA(At, 1, 0); PG8_STAGE(PG8_SA(0, 1), a2 + hstep, voffA);
;             PG8_WAIT_V(8); PG8_WAIT_L(0); PG8_BAR; PG8_MMA(0, 0, At, B0); PG8_MMA(0, 1, At, B1); PG8_BAR; PG8_SCHED;
	s_waitcnt lgkmcnt(0)
	v_mfma_f32_16x16x32_bf16 v[104:107], v[148:151], v[182:185], v[104:107]
	v_mfma_f32_16x16x32_bf16 v[100:103], v[156:159], v[182:185], v[100:103]
	v_mfma_f32_16x16x32_bf16 v[96:99], v[148:151], v[190:193], v[96:99]
	v_mfma_f32_16x16x32_bf16 v[92:95], v[156:159], v[190:193], v[92:95]
	v_mfma_f32_16x16x32_bf16 v[88:91], v[148:151], v[204:207], v[88:91]
	v_mfma_f32_16x16x32_bf16 v[84:87], v[156:159], v[204:207], v[84:87]
	v_mfma_f32_16x16x32_bf16 v[80:83], v[148:151], v[212:215], v[80:83]
	v_mfma_f32_16x16x32_bf16 v[76:79], v[156:159], v[212:215], v[76:79]
	v_mfma_f32_16x16x32_bf16 v[104:107], v[152:155], v[186:189], v[104:107]
	v_mfma_f32_16x16x32_bf16 v[100:103], v[162:165], v[186:189], v[100:103]
	v_mfma_f32_16x16x32_bf16 v[96:99], v[152:155], v[194:197], v[96:99]
	v_mfma_f32_16x16x32_bf16 v[92:95], v[162:165], v[194:197], v[92:95]
	v_mfma_f32_16x16x32_bf16 v[88:91], v[152:155], v[208:211], v[88:91]
	v_mfma_f32_16x16x32_bf16 v[84:87], v[162:165], v[208:211], v[84:87]
	v_mfma_f32_16x16x32_bf16 v[80:83], v[152:155], v[236:239], v[80:83]
	v_mfma_f32_16x16x32_bf16 v[76:79], v[162:165], v[236:239], v[76:79]
	v_mfma_f32_16x16x32_bf16 v[28:31], v[166:169], v[182:185], v[28:31]
	v_mfma_f32_16x16x32_bf16 v[24:27], v[174:177], v[182:185], v[24:27]
	v_mfma_f32_16x16x32_bf16 v[20:23], v[166:169], v[190:193], v[20:23]
	v_mfma_f32_16x16x32_bf16 v[16:19], v[174:177], v[190:193], v[16:19]
	v_mfma_f32_16x16x32_bf16 v[12:15], v[166:169], v[204:207], v[12:15]
	v_mfma_f32_16x16x32_bf16 v[8:11], v[174:177], v[204:207], v[8:11]
	v_mfma_f32_16x16x32_bf16 v[4:7], v[166:169], v[212:215], v[4:7]
	v_mfma_f32_16x16x32_bf16 v[0:3], v[174:177], v[212:215], v[0:3]
	v_mfma_f32_16x16x32_bf16 v[28:31], v[170:173], v[186:189], v[28:31]
	v_mfma_f32_16x16x32_bf16 v[24:27], v[178:181], v[186:189], v[24:27]
	v_mfma_f32_16x16x32_bf16 v[20:23], v[170:173], v[194:197], v[20:23]
	v_mfma_f32_16x16x32_bf16 v[16:19], v[178:181], v[194:197], v[16:19]
	v_mfma_f32_16x16x32_bf16 v[12:15], v[170:173], v[208:211], v[12:15]
	v_mfma_f32_16x16x32_bf16 v[8:11], v[178:181], v[208:211], v[8:11]
	v_mfma_f32_16x16x32_bf16 v[4:7], v[170:173], v[236:239], v[4:7]
	v_mfma_f32_16x16x32_bf16 v[0:3], v[178:181], v[236:239], v[0:3]
	s_barrier
	s_add_i32 s88, 0, 0x18000
	s_add_i32 s89, 0, 0x1c000
	v_add_u32_e32 v162, s88, v160
	v_add_u32_e32 v178, s89, v160
	ds_read_b128 v[148:151], v162
	ds_read_b128 v[152:155], v162 offset:1024
	ds_read_b128 v[156:159], v162 offset:2048
	ds_read_b128 v[162:165], v162 offset:3072
	ds_read_b128 v[166:169], v178
	ds_read_b128 v[170:173], v178 offset:1024
	ds_read_b128 v[174:177], v178 offset:2048
	ds_read_b128 v[178:181], v178 offset:3072
	s_add_u32 s0, s0, s2
	s_addc_u32 s1, s1, s3
	s_mov_b32 m0, s65
	v_lshl_add_u64 v[250:251], s[0:1], 0, v[142:143]
	ds_read_b128 v[182:185], v161 offset:32768
	ds_read_b128 v[186:189], v161 offset:33792
	ds_read_b128 v[190:193], v161 offset:34816
	ds_read_b128 v[194:197], v161 offset:35840
	ds_read_b128 v[204:207], v161 offset:36864
	ds_read_b128 v[208:211], v161 offset:37888
	ds_read_b128 v[212:215], v161 offset:38912
	ds_read_b128 v[236:239], v161 offset:39936
	global_load_lds_dwordx4 v[250:251], off
	v_lshl_add_u64 v[250:251], s[0:1], 0, v[42:43]
	s_mov_b32 m0, s66
	s_nop 0
	global_load_lds_dwordx4 v[250:251], off
	s_waitcnt vmcnt(8)
	s_waitcnt lgkmcnt(0)
	s_barrier
	s_waitcnt lgkmcnt(0)
	v_mfma_f32_16x16x32_bf16 v[132:135], v[148:151], v[182:185], v[132:135]
	v_mfma_f32_16x16x32_bf16 v[136:139], v[156:159], v[182:185], v[136:139]
	v_mfma_f32_16x16x32_bf16 v[128:131], v[148:151], v[190:193], v[128:131]
	v_mfma_f32_16x16x32_bf16 v[124:127], v[156:159], v[190:193], v[124:127]
	v_mfma_f32_16x16x32_bf16 v[120:123], v[148:151], v[204:207], v[120:123]
	v_mfma_f32_16x16x32_bf16 v[116:119], v[156:159], v[204:207], v[116:119]
	v_mfma_f32_16x16x32_bf16 v[112:115], v[148:151], v[212:215], v[112:115]
	v_mfma_f32_16x16x32_bf16 v[108:111], v[156:159], v[212:215], v[108:111]
	v_mfma_f32_16x16x32_bf16 v[132:135], v[152:155], v[186:189], v[132:135]
	v_mfma_f32_16x16x32_bf16 v[136:139], v[162:165], v[186:189], v[136:139]
	v_mfma_f32_16x16x32_bf16 v[128:131], v[152:155], v[194:197], v[128:131]
	v_mfma_f32_16x16x32_bf16 v[124:127], v[162:165], v[194:197], v[124:127]
	v_mfma_f32_16x16x32_bf16 v[120:123], v[152:155], v[208:211], v[120:123]
	v_mfma_f32_16x16x32_bf16 v[116:119], v[162:165], v[208:211], v[116:119]
	v_mfma_f32_16x16x32_bf16 v[112:115], v[152:155], v[236:239], v[112:115]
	v_mfma_f32_16x16x32_bf16 v[108:111], v[162:165], v[236:239], v[108:111]
	v_mfma_f32_16x16x32_bf16 v[72:75], v[166:169], v[182:185], v[72:75]
	v_mfma_f32_16x16x32_bf16 v[68:71], v[174:177], v[182:185], v[68:71]
	v_mfma_f32_16x16x32_bf16 v[64:67], v[166:169], v[190:193], v[64:67]
	v_mfma_f32_16x16x32_bf16 v[60:63], v[174:177], v[190:193], v[60:63]
	v_mfma_f32_16x16x32_bf16 v[56:59], v[166:169], v[204:207], v[56:59]
	v_mfma_f32_16x16x32_bf16 v[52:55], v[174:177], v[204:207], v[52:55]
	v_mfma_f32_16x16x32_bf16 v[48:51], v[166:169], v[212:215], v[48:51]
	v_mfma_f32_16x16x32_bf16 v[32:35], v[174:177], v[212:215], v[32:35]
	v_mfma_f32_16x16x32_bf16 v[72:75], v[170:173], v[186:189], v[72:75]
	v_mfma_f32_16x16x32_bf16 v[68:71], v[178:181], v[186:189], v[68:71]
	v_mfma_f32_16x16x32_bf16 v[64:67], v[170:173], v[194:197], v[64:67]
	v_mfma_f32_16x16x32_bf16 v[60:63], v[178:181], v[194:197], v[60:63]
	v_mfma_f32_16x16x32_bf16 v[56:59], v[170:173], v[208:211], v[56:59]
	v_mfma_f32_16x16x32_bf16 v[52:55], v[178:181], v[208:211], v[52:55]
	v_mfma_f32_16x16x32_bf16 v[48:51], v[170:173], v[236:239], v[48:51]
	v_mfma_f32_16x16x32_bf16 v[32:35], v[178:181], v[236:239], v[32:35]
	s_barrier
; #define PG8_STAGE(bufoff, gbase, voff) do { _Pragma("unroll") for (int _i = 0; _i < 2; ++_i) \
;         __builtin_amdgcn_global_load_lds((const unsigned*)((const char*)(gbase) + (voff)[_i]), (PG8_LAS unsigned*)(lds + (bufoff) + ldsw + _i * 8192), 16, 0, 0); } while (0)
; #define PG8_LDA(dst, b, h) do { _Pragma("unroll") for (int m = 0; m < 4; ++m) _Pragma("unroll") for (int k = 0; k < 2; ++k) dst[m][k] = *(const PG8_LAS bf16x8*)(lds + PG8_SA(b, h) + aoff + m * 2048 + k * 1024); } while (0)
; #define PG8_MMA(ai, bj, At, Bt) do { __builtin_amdgcn_s_setprio(1); _Pragma("unroll") for (int m = 0; m < 4; ++m) _Pragma("unroll") for (int n = 0; n < 2; ++n) _Pragma("unroll") for (int k = 0; k < 2; ++k) \
;         acc[ai][bj][m][n] = __builtin_amdgcn_mfma_f32_16x16x32_bf16(Bt[n][k], At[m][k], acc[ai][bj][m][n], 0, 0, 0); __builtin_amdgcn_s_setprio(0); } while (0)
; #define PG8_WAIT_V(n) asm volatile("s_waitcnt vmcnt(" #n ")" ::: "memory")
; #define PG8_WAIT_L(n) asm volatile("s_waitcnt lgkmcnt(" #n ")" ::: "memory")
; #define PG8_BAR __builtin_amdgcn_s_barrier()
; #define PG8_SCHED __builtin_amdgcn_sched_barrier(0)
; template <class Epi, class Sched, bool ALIGN_EPI = false, bool SP2 = false>
; __device__ __forceinline__ void gemm_phase(PG8_LAS unsigned char* lds, const Gemm g, const Sched& S, const Epi& E) {
;     ...
;         for (int t = 0; t < nt; t += 2) {
;     ...
;             PG8_LDA(At, 1, 1); PG8_STAGE(PG8_SB(1, 0), b3, voffB); PG8_STAGE(PG8_SB(1, 1), b3 + hstep, voffB); PG8_STAGE(PG8_SA(1, 0), a3, voffA);
;             PG8_WAIT_V(8); PG8_WAIT_L(0); PG8_BAR; PG8_MMA(1, 0, At, B0); PG8_MMA(1, 1, At, B1); PG8_BAR; PG8_SCHED;
	s_add_i32 s0, s88, s59
	v_lshl_add_u64 v[198:199], v[198:199], 0, s[22:23]
	s_mov_b32 m0, s0
	ds_read_b128 v[182:185], v161 offset:49152
	ds_read_b128 v[186:189], v161 offset:50176
	ds_read_b128 v[190:193], v161 offset:51200
	ds_read_b128 v[194:197], v161 offset:52224
	ds_read_b128 v[204:207], v161 offset:53248
	ds_read_b128 v[208:211], v161 offset:54272
	ds_read_b128 v[212:215], v161 offset:55296
	ds_read_b128 v[236:239], v161 offset:56320
	global_load_lds_dwordx4 v[198:199], off
	v_lshl_add_u64 v[198:199], v[240:241], 0, s[22:23]
	s_add_i32 m0, s0, 0x2000
	s_add_i32 s0, s89, s59
	global_load_lds_dwordx4 v[198:199], off
	v_lshl_add_u64 v[198:199], v[242:243], 0, s[22:23]
	s_mov_b32 m0, s0
	s_nop 0
	global_load_lds_dwordx4 v[198:199], off
	v_lshl_add_u64 v[198:199], v[244:245], 0, s[22:23]
	s_add_i32 m0, s0, 0x2000
	s_nop 0
	global_load_lds_dwordx4 v[198:199], off
	v_lshl_add_u64 v[198:199], v[246:247], 0, s[22:23]
	s_mov_b32 m0, s70
	s_nop 0
	global_load_lds_dwordx4 v[198:199], off
	v_lshl_add_u64 v[198:199], v[248:249], 0, s[22:23]
	s_mov_b32 m0, s71
	s_nop 0
	global_load_lds_dwordx4 v[198:199], off
	s_waitcnt vmcnt(8)
	s_waitcnt lgkmcnt(0)
	s_barrier
	s_waitcnt lgkmcnt(0)
	v_mfma_f32_16x16x32_bf16 v[104:107], v[148:151], v[182:185], v[104:107]
	v_mfma_f32_16x16x32_bf16 v[100:103], v[156:159], v[182:185], v[100:103]
	v_mfma_f32_16x16x32_bf16 v[96:99], v[148:151], v[190:193], v[96:99]
	v_mfma_f32_16x16x32_bf16 v[92:95], v[156:159], v[190:193], v[92:95]
	v_mfma_f32_16x16x32_bf16 v[88:91], v[148:151], v[204:207], v[88:91]
	v_mfma_f32_16x16x32_bf16 v[84:87], v[156:159], v[204:207], v[84:87]
	v_mfma_f32_16x16x32_bf16 v[80:83], v[148:151], v[212:215], v[80:83]
	v_mfma_f32_16x16x32_bf16 v[76:79], v[156:159], v[212:215], v[76:79]
	v_mfma_f32_16x16x32_bf16 v[104:107], v[152:155], v[186:189], v[104:107]
	v_mfma_f32_16x16x32_bf16 v[100:103], v[162:165], v[186:189], v[100:103]
	v_mfma_f32_16x16x32_bf16 v[96:99], v[152:155], v[194:197], v[96:99]
	v_mfma_f32_16x16x32_bf16 v[92:95], v[162:165], v[194:197], v[92:95]
	v_mfma_f32_16x16x32_bf16 v[88:91], v[152:155], v[208:211], v[88:91]
	v_mfma_f32_16x16x32_bf16 v[84:87], v[162:165], v[208:211], v[84:87]
	v_mfma_f32_16x16x32_bf16 v[80:83], v[152:155], v[236:239], v[80:83]
	v_mfma_f32_16x16x32_bf16 v[76:79], v[162:165], v[236:239], v[76:79]
	v_mfma_f32_16x16x32_bf16 v[28:31], v[166:169], v[182:185], v[28:31]
	v_mfma_f32_16x16x32_bf16 v[24:27], v[174:177], v[182:185], v[24:27]
	v_mfma_f32_16x16x32_bf16 v[20:23], v[166:169], v[190:193], v[20:23]
	v_mfma_f32_16x16x32_bf16 v[16:19], v[174:177], v[190:193], v[16:19]
	v_mfma_f32_16x16x32_bf16 v[12:15], v[166:169], v[204:207], v[12:15]
	v_mfma_f32_16x16x32_bf16 v[8:11], v[174:177], v[204:207], v[8:11]
	v_mfma_f32_16x16x32_bf16 v[4:7], v[166:169], v[212:215], v[4:7]
	v_mfma_f32_16x16x32_bf16 v[0:3], v[174:177], v[212:215], v[0:3]
	v_mfma_f32_16x16x32_bf16 v[28:31], v[170:173], v[186:189], v[28:31]
	v_mfma_f32_16x16x32_bf16 v[24:27], v[178:181], v[186:189], v[24:27]
	v_mfma_f32_16x16x32_bf16 v[20:23], v[170:173], v[194:197], v[20:23]
	v_mfma_f32_16x16x32_bf16 v[16:19], v[178:181], v[194:197], v[16:19]
	v_mfma_f32_16x16x32_bf16 v[12:15], v[170:173], v[208:211], v[12:15]
	v_mfma_f32_16x16x32_bf16 v[8:11], v[178:181], v[208:211], v[8:11]
	v_mfma_f32_16x16x32_bf16 v[4:7], v[170:173], v[236:239], v[4:7]
	v_mfma_f32_16x16x32_bf16 v[0:3], v[178:181], v[236:239], v[0:3]
	s_barrier
	s_add_u32 s24, s24, 0x100
	s_addc_u32 s25, s25, 0
	s_add_u32 s18, s18, 0x100
	s_addc_u32 s19, s19, 0
	s_cmp_ge_i32 s81, s67
	s_mov_b32 s0, s81
	s_cbranch_scc0 .LBB0_336
	v_readlane_b32 s88, v254, 34
	v_readlane_b32 s81, v254, 12
	v_readlane_b32 s90, v254, 36
	v_readlane_b32 s91, v254, 37
	v_readlane_b32 s89, v254, 35

; #define PG8_STAGE(bufoff, gbase, voff) do { _Pragma("unroll") for (int _i = 0; _i < 2; ++_i) \
;         __builtin_amdgcn_global_load_lds((const unsigned*)((const char*)(gbase) + (voff)[_i]), (PG8_LAS unsigned*)(lds + (bufoff) + ldsw + _i * 8192), 16, 0, 0); } while (0)
; #define PG8_LDA(dst, b, h) do { _Pragma("unroll") for (int m = 0; m < 4; ++m) _Pragma("unroll") for (int k = 0; k < 2; ++k) dst[m][k] = *(const PG8_LAS bf16x8*)(lds + PG8_SA(b, h) + aoff + m * 2048 + k * 1024); } while (0)
; #define PG8_LDB(dst, b, h) do { _Pragma("unroll") for (int n = 0; n < 2; ++n) _Pragma("unroll") for (int k = 0; k < 2; ++k) dst[n][k] = *(const PG8_LAS bf16x8*)(lds + PG8_SB(b, h) + boff + n * 2048 + k * 1024); } while (0)
; #define PG8_MMA(ai, bj, At, Bt) do { __builtin_amdgcn_s_setprio(1); _Pragma("unroll") for (int m = 0; m < 4; ++m) _Pragma("unroll") for (int n = 0; n < 2; ++n) _Pragma("unroll") for (int k = 0; k < 2; ++k) \
;         acc[ai][bj][m][n] = __builtin_amdgcn_mfma_f32_16x16x32_bf16(Bt[n][k], At[m][k], acc[ai][bj][m][n], 0, 0, 0); __builtin_amdgcn_s_setprio(0); } while (0)
; #define PG8_WAIT_V(n) asm volatile("s_waitcnt vmcnt(" #n ")" ::: "memory")
; #define PG8_WAIT_L(n) asm volatile("s_waitcnt lgkmcnt(" #n ")" ::: "memory")
; #define PG8_BAR __builtin_amdgcn_s_barrier()
; #define PG8_SCHED __builtin_amdgcn_sched_barrier(0)
; template <class Epi, class Sched, bool ALIGN_EPI = false, bool SP2 = false>
; __device__ __forceinline__ void gemm_phase(PG8_LAS unsigned char* lds, const Gemm g, const Sched& S, const Epi& E) {
;     ...
;         for (int t = 0; t < nt; t += 2) {
;             const bool last = (t == nt - 2);
;             const char* a1 = cA + (size_t)(t + 1) * kstep;
;             const char* a2 = last ? nA : cA + (size_t)(t + 2) * kstep; const char* b2 = last ? nB : cB + (size_t)(t + 2) * kstep;
;             const char* a3 = a2 + kstep; const char* b3 = b2 + kstep;
;             if (last && has_next) S.a_ready(nxt);
;             if constexpr (SP2) {
;             PG8_LDB(B0, 0, 0); PG8_LDB(B1, 0, 1); PG8_SCHED; PG8_LDA(At, 0, 0); PG8_STAGE(PG8_SA(1, 1), a1 + hstep, voffA);
;             PG8_WAIT_V(8); PG8_WAIT_L(0); PG8_BAR; PG8_MMA(0, 0, At, B0); PG8_MMA(0, 1, At, B1); PG8_BAR; PG8_SCHED;
;             PG8_LDA(At, 0, 1); PG8_STAGE(PG8_SB(0, 0), b2, voffB); PG8_STAGE(PG8_SB(0, 1), b2 + hstep, voffB); PG8_STAGE(PG8_SA(0, 0), a2, voffA);
.LBB0_358:
	s_add_i32 s75, s0, 2
	s_add_u32 s76, s24, 0x80
	s_addc_u32 s1, s25, 0
	s_add_i32 s78, 0, 0x10000
	s_cmp_eq_u32 s66, s0
	s_cselect_b32 s1, s35, s1
	s_cselect_b32 s0, s34, s76
	v_add_u32_e32 v160, s78, v162
	s_cselect_b32 s77, s41, s19
	s_cselect_b32 s76, s40, s18
	s_add_i32 s79, 0, 0x14000
	ds_read_b128 v[148:151], v160
	ds_read_b128 v[152:155], v160 offset:1024
	ds_read_b128 v[156:159], v160 offset:2048
	ds_read_b128 v[164:167], v160 offset:3072
	v_add_u32_e32 v160, s79, v162
	ds_read_b128 v[168:171], v160
	ds_read_b128 v[172:175], v160 offset:1024
	ds_read_b128 v[176:179], v160 offset:2048
	ds_read_b128 v[180:183], v160 offset:3072
	v_lshl_add_u64 v[160:161], s[24:25], 0, v[144:145]
	s_add_i32 m0, s57, 0xc000
	ds_read_b128 v[184:187], v163
	ds_read_b128 v[188:191], v163 offset:1024
	ds_read_b128 v[192:195], v163 offset:2048
	ds_read_b128 v[196:199], v163 offset:3072
	ds_read_b128 v[204:207], v163 offset:4096
	ds_read_b128 v[208:211], v163 offset:5120
	ds_read_b128 v[212:215], v163 offset:6144
	ds_read_b128 v[236:239], v163 offset:7168
	global_load_lds_dwordx4 v[160:161], off
	v_lshl_add_u64 v[160:161], s[24:25], 0, v[146:147]
	s_add_i32 m0, s57, 0xe000
	s_nop 0
	global_load_lds_dwordx4 v[160:161], off
	s_waitcnt vmcnt(8)
	s_waitcnt lgkmcnt(0)
	s_barrier
	s_waitcnt lgkmcnt(0)
	v_mfma_f32_16x16x32_bf16 v[132:135], v[148:151], v[184:187], v[132:135]
	v_mfma_f32_16x16x32_bf16 v[136:139], v[156:159], v[184:187], v[136:139]
	v_mfma_f32_16x16x32_bf16 v[128:131], v[148:151], v[192:195], v[128:131]
	v_mfma_f32_16x16x32_bf16 v[124:127], v[156:159], v[192:195], v[124:127]
	v_mfma_f32_16x16x32_bf16 v[120:123], v[148:151], v[204:207], v[120:123]
	v_mfma_f32_16x16x32_bf16 v[116:119], v[156:159], v[204:207], v[116:119]
	v_mfma_f32_16x16x32_bf16 v[112:115], v[148:151], v[212:215], v[112:115]
	v_mfma_f32_16x16x32_bf16 v[108:111], v[156:159], v[212:215], v[108:111]
	v_mfma_f32_16x16x32_bf16 v[132:135], v[152:155], v[188:191], v[132:135]
	v_mfma_f32_16x16x32_bf16 v[136:139], v[164:167], v[188:191], v[136:139]
	v_mfma_f32_16x16x32_bf16 v[128:131], v[152:155], v[196:199], v[128:131]
	v_mfma_f32_16x16x32_bf16 v[124:127], v[164:167], v[196:199], v[124:127]
	v_mfma_f32_16x16x32_bf16 v[120:123], v[152:155], v[208:211], v[120:123]
	v_mfma_f32_16x16x32_bf16 v[116:119], v[164:167], v[208:211], v[116:119]
	v_mfma_f32_16x16x32_bf16 v[112:115], v[152:155], v[236:239], v[112:115]
	v_mfma_f32_16x16x32_bf16 v[108:111], v[164:167], v[236:239], v[108:111]
	v_mfma_f32_16x16x32_bf16 v[72:75], v[168:171], v[184:187], v[72:75]
	v_mfma_f32_16x16x32_bf16 v[68:71], v[176:179], v[184:187], v[68:71]
	v_mfma_f32_16x16x32_bf16 v[64:67], v[168:171], v[192:195], v[64:67]
	v_mfma_f32_16x16x32_bf16 v[60:63], v[176:179], v[192:195], v[60:63]
	v_mfma_f32_16x16x32_bf16 v[56:59], v[168:171], v[204:207], v[56:59]
	v_mfma_f32_16x16x32_bf16 v[52:55], v[176:179], v[204:207], v[52:55]
	v_mfma_f32_16x16x32_bf16 v[48:51], v[168:171], v[212:215], v[48:51]
	v_mfma_f32_16x16x32_bf16 v[32:35], v[176:179], v[212:215], v[32:35]
	v_mfma_f32_16x16x32_bf16 v[72:75], v[172:175], v[188:191], v[72:75]
	v_mfma_f32_16x16x32_bf16 v[68:71], v[180:183], v[188:191], v[68:71]
	v_mfma_f32_16x16x32_bf16 v[64:67], v[172:175], v[196:199], v[64:67]
	v_mfma_f32_16x16x32_bf16 v[60:63], v[180:183], v[196:199], v[60:63]
	v_mfma_f32_16x16x32_bf16 v[56:59], v[172:175], v[208:211], v[56:59]
	v_mfma_f32_16x16x32_bf16 v[52:55], v[180:183], v[208:211], v[52:55]
	v_mfma_f32_16x16x32_bf16 v[48:51], v[172:175], v[236:239], v[48:51]
	v_mfma_f32_16x16x32_bf16 v[32:35], v[180:183], v[236:239], v[32:35]
	s_barrier
	s_add_i32 s78, s78, s53
	v_lshl_add_u64 v[160:161], s[76:77], 0, v[140:141]
	s_mov_b32 m0, s78
	ds_read_b128 v[184:187], v163 offset:16384
	ds_read_b128 v[188:191], v163 offset:17408
	ds_read_b128 v[192:195], v163 offset:18432
	ds_read_b128 v[196:199], v163 offset:19456
	ds_read_b128 v[204:207], v163 offset:20480
	ds_read_b128 v[208:211], v163 offset:21504
	ds_read_b128 v[212:215], v163 offset:22528
	ds_read_b128 v[236:239], v163 offset:23552
	global_load_lds_dwordx4 v[160:161], off
	s_add_i32 m0, s78, 0x2000
	v_lshl_add_u64 v[240:241], s[76:77], 0, v[38:39]
	s_add_u32 s76, s76, s2
	s_addc_u32 s77, s77, s3
	s_add_i32 s78, s79, s53
	global_load_lds_dwordx4 v[240:241], off
	v_lshl_add_u64 v[242:243], s[76:77], 0, v[140:141]
	s_mov_b32 m0, s78
	v_lshl_add_u64 v[244:245], s[76:77], 0, v[38:39]
	global_load_lds_dwordx4 v[242:243], off
	s_add_i32 m0, s78, 0x2000
	v_lshl_add_u64 v[246:247], s[0:1], 0, v[142:143]
	global_load_lds_dwordx4 v[244:245], off
	s_mov_b32 m0, s57
	v_lshl_add_u64 v[248:249], s[0:1], 0, v[42:43]
	global_load_lds_dwordx4 v[246:247], off
	s_mov_b32 m0, s58
	s_nop 0
	global_load_lds_dwordx4 v[248:249], off
	s_waitcnt vmcnt(8)
	s_waitcnt lgkmcnt(0)
	s_barrier
; #define PG8_STAGE(bufoff, gbase, voff) do { _Pragma("unroll") for (int _i = 0; _i < 2; ++_i) \
;         __builtin_amdgcn_global_load_lds((const unsigned*)((const char*)(gbase) + (voff)[_i]), (PG8_LAS unsigned*)(lds + (bufoff) + ldsw + _i * 8192), 16, 0, 0); } while (0)
; #define PG8_LDA(dst, b, h) do { _Pragma("unroll") for (int m = 0; m < 4; ++m) _Pragma("unroll") for (int k = 0; k < 2; ++k) dst[m][k] = *(const PG8_LAS bf16x8*)(lds + PG8_SA(b, h) + aoff + m * 2048 + k * 1024); } while (0)
; #define PG8_LDB(dst, b, h) do { _Pragma("unroll") for (int n = 0; n < 2; ++n) _Pragma("unroll") for (int k = 0; k < 2; ++k) dst[n][k] = *(const PG8_LAS bf16x8*)(lds + PG8_SB(b, h) + boff + n * 2048 + k * 1024); } while (0)
; #define PG8_MMA(ai, bj, At, Bt) do { __builtin_amdgcn_s_setprio(1); _Pragma("unroll") for (int m = 0; m < 4; ++m) _Pragma("unroll") for (int n = 0; n < 2; ++n) _Pragma("unroll") for (int k = 0; k < 2; ++k) \
;         acc[ai][bj][m][n] = __builtin_amdgcn_mfma_f32_16x16x32_bf16(Bt[n][k], At[m][k], acc[ai][bj][m][n], 0, 0, 0); __builtin_amdgcn_s_setprio(0); } while (0)
; #define PG8_WAIT_V(n) asm volatile("s_waitcnt vmcnt(" #n ")" ::: "memory")
; #define PG8_WAIT_L(n) asm volatile("s_waitcnt lgkmcnt(" #n ")" ::: "memory")
; #define PG8_BAR __builtin_amdgcn_s_barrier()
; #define PG8_SCHED __builtin_amdgcn_sched_barrier(0)
; template <class Epi, class Sched, bool ALIGN_EPI = false, bool SP2 = false>
; __device__ __forceinline__ void gemm_phase(PG8_LAS unsigned char* lds, const Gemm g, const Sched& S, const Epi& E) {
;     ...
;             PG8_WAIT_V(8); PG8_WAIT_L(0); PG8_BAR; PG8_MMA(1, 0, At, B0); PG8_MMA(1, 1, At, B1); PG8_BAR; PG8_SCHED;
;             PG8_LDB(B0, 1, 0); PG8_LDB(B1, 1, 1); PG8_SCHED; PG8_LDA(At, 1, 0); PG8_STAGE(PG8_SA(0, 1), a2 + hstep, voffA);
;             PG8_WAIT_V(8); PG8_WAIT_L(0); PG8_BAR; PG8_MMA(0, 0, At, B0); PG8_MMA(0, 1, At, B1); PG8_BAR; PG8_SCHED;
	s_waitcnt lgkmcnt(0)
	v_mfma_f32_16x16x32_bf16 v[104:107], v[148:151], v[184:187], v[104:107]
	v_mfma_f32_16x16x32_bf16 v[100:103], v[156:159], v[184:187], v[100:103]
	v_mfma_f32_16x16x32_bf16 v[96:99], v[148:151], v[192:195], v[96:99]
	v_mfma_f32_16x16x32_bf16 v[92:95], v[156:159], v[192:195], v[92:95]
	v_mfma_f32_16x16x32_bf16 v[88:91], v[148:151], v[204:207], v[88:91]
	v_mfma_f32_16x16x32_bf16 v[84:87], v[156:159], v[204:207], v[84:87]
	v_mfma_f32_16x16x32_bf16 v[80:83], v[148:151], v[212:215], v[80:83]
	v_mfma_f32_16x16x32_bf16 v[76:79], v[156:159], v[212:215], v[76:79]
	v_mfma_f32_16x16x32_bf16 v[104:107], v[152:155], v[188:191], v[104:107]
	v_mfma_f32_16x16x32_bf16 v[100:103], v[164:167], v[188:191], v[100:103]
	v_mfma_f32_16x16x32_bf16 v[96:99], v[152:155], v[196:199], v[96:99]
	v_mfma_f32_16x16x32_bf16 v[92:95], v[164:167], v[196:199], v[92:95]
	v_mfma_f32_16x16x32_bf16 v[88:91], v[152:155], v[208:211], v[88:91]
	v_mfma_f32_16x16x32_bf16 v[84:87], v[164:167], v[208:211], v[84:87]
	v_mfma_f32_16x16x32_bf16 v[80:83], v[152:155], v[236:239], v[80:83]
	v_mfma_f32_16x16x32_bf16 v[76:79], v[164:167], v[236:239], v[76:79]
	v_mfma_f32_16x16x32_bf16 v[28:31], v[168:171], v[184:187], v[28:31]
	v_mfma_f32_16x16x32_bf16 v[24:27], v[176:179], v[184:187], v[24:27]
	v_mfma_f32_16x16x32_bf16 v[20:23], v[168:171], v[192:195], v[20:23]
	v_mfma_f32_16x16x32_bf16 v[16:19], v[176:179], v[192:195], v[16:19]
	v_mfma_f32_16x16x32_bf16 v[12:15], v[168:171], v[204:207], v[12:15]
	v_mfma_f32_16x16x32_bf16 v[8:11], v[176:179], v[204:207], v[8:11]
	v_mfma_f32_16x16x32_bf16 v[4:7], v[168:171], v[212:215], v[4:7]
	v_mfma_f32_16x16x32_bf16 v[0:3], v[176:179], v[212:215], v[0:3]
	v_mfma_f32_16x16x32_bf16 v[28:31], v[172:175], v[188:191], v[28:31]
	v_mfma_f32_16x16x32_bf16 v[24:27], v[180:183], v[188:191], v[24:27]
	v_mfma_f32_16x16x32_bf16 v[20:23], v[172:175], v[196:199], v[20:23]
	v_mfma_f32_16x16x32_bf16 v[16:19], v[180:183], v[196:199], v[16:19]
	v_mfma_f32_16x16x32_bf16 v[12:15], v[172:175], v[208:211], v[12:15]
	v_mfma_f32_16x16x32_bf16 v[8:11], v[180:183], v[208:211], v[8:11]
	v_mfma_f32_16x16x32_bf16 v[4:7], v[172:175], v[236:239], v[4:7]
	v_mfma_f32_16x16x32_bf16 v[0:3], v[180:183], v[236:239], v[0:3]
	s_barrier
	s_add_i32 s76, 0, 0x18000
	s_add_i32 s77, 0, 0x1c000
	v_add_u32_e32 v164, s76, v162
	v_add_u32_e32 v180, s77, v162
	ds_read_b128 v[148:151], v164
	ds_read_b128 v[152:155], v164 offset:1024
	ds_read_b128 v[156:159], v164 offset:2048
	ds_read_b128 v[164:167], v164 offset:3072
	ds_read_b128 v[168:171], v180
	ds_read_b128 v[172:175], v180 offset:1024
	ds_read_b128 v[176:179], v180 offset:2048
	ds_read_b128 v[180:183], v180 offset:3072
	s_add_u32 s0, s0, s2
	s_addc_u32 s1, s1, s3
	s_mov_b32 m0, s59
	v_lshl_add_u64 v[250:251], s[0:1], 0, v[142:143]
	ds_read_b128 v[184:187], v163 offset:32768
	ds_read_b128 v[188:191], v163 offset:33792
	ds_read_b128 v[192:195], v163 offset:34816
	ds_read_b128 v[196:199], v163 offset:35840
	ds_read_b128 v[204:207], v163 offset:36864
	ds_read_b128 v[208:211], v163 offset:37888
	ds_read_b128 v[212:215], v163 offset:38912
	ds_read_b128 v[236:239], v163 offset:39936
	global_load_lds_dwordx4 v[250:251], off
	v_lshl_add_u64 v[250:251], s[0:1], 0, v[42:43]
	s_mov_b32 m0, s60
	s_nop 0
	global_load_lds_dwordx4 v[250:251], off
	s_waitcnt vmcnt(8)
	s_waitcnt lgkmcnt(0)
	s_barrier
	s_waitcnt lgkmcnt(0)
	v_mfma_f32_16x16x32_bf16 v[132:135], v[148:151], v[184:187], v[132:135]
	v_mfma_f32_16x16x32_bf16 v[136:139], v[156:159], v[184:187], v[136:139]
	v_mfma_f32_16x16x32_bf16 v[128:131], v[148:151], v[192:195], v[128:131]
	v_mfma_f32_16x16x32_bf16 v[124:127], v[156:159], v[192:195], v[124:127]
	v_mfma_f32_16x16x32_bf16 v[120:123], v[148:151], v[204:207], v[120:123]
	v_mfma_f32_16x16x32_bf16 v[116:119], v[156:159], v[204:207], v[116:119]
	v_mfma_f32_16x16x32_bf16 v[112:115], v[148:151], v[212:215], v[112:115]
	v_mfma_f32_16x16x32_bf16 v[108:111], v[156:159], v[212:215], v[108:111]
	v_mfma_f32_16x16x32_bf16 v[132:135], v[152:155], v[188:191], v[132:135]
	v_mfma_f32_16x16x32_bf16 v[136:139], v[164:167], v[188:191], v[136:139]
	v_mfma_f32_16x16x32_bf16 v[128:131], v[152:155], v[196:199], v[128:131]
	v_mfma_f32_16x16x32_bf16 v[124:127], v[164:167], v[196:199], v[124:127]
	v_mfma_f32_16x16x32_bf16 v[120:123], v[152:155], v[208:211], v[120:123]
	v_mfma_f32_16x16x32_bf16 v[116:119], v[164:167], v[208:211], v[116:119]
	v_mfma_f32_16x16x32_bf16 v[112:115], v[152:155], v[236:239], v[112:115]
	v_mfma_f32_16x16x32_bf16 v[108:111], v[164:167], v[236:239], v[108:111]
	v_mfma_f32_16x16x32_bf16 v[72:75], v[168:171], v[184:187], v[72:75]
	v_mfma_f32_16x16x32_bf16 v[68:71], v[176:179], v[184:187], v[68:71]
	v_mfma_f32_16x16x32_bf16 v[64:67], v[168:171], v[192:195], v[64:67]
	v_mfma_f32_16x16x32_bf16 v[60:63], v[176:179], v[192:195], v[60:63]
	v_mfma_f32_16x16x32_bf16 v[56:59], v[168:171], v[204:207], v[56:59]
	v_mfma_f32_16x16x32_bf16 v[52:55], v[176:179], v[204:207], v[52:55]
	v_mfma_f32_16x16x32_bf16 v[48:51], v[168:171], v[212:215], v[48:51]
	v_mfma_f32_16x16x32_bf16 v[32:35], v[176:179], v[212:215], v[32:35]
	v_mfma_f32_16x16x32_bf16 v[72:75], v[172:175], v[188:191], v[72:75]
	v_mfma_f32_16x16x32_bf16 v[68:71], v[180:183], v[188:191], v[68:71]
	v_mfma_f32_16x16x32_bf16 v[64:67], v[172:175], v[196:199], v[64:67]
	v_mfma_f32_16x16x32_bf16 v[60:63], v[180:183], v[196:199], v[60:63]
	v_mfma_f32_16x16x32_bf16 v[56:59], v[172:175], v[208:211], v[56:59]
	v_mfma_f32_16x16x32_bf16 v[52:55], v[180:183], v[208:211], v[52:55]
	v_mfma_f32_16x16x32_bf16 v[48:51], v[172:175], v[236:239], v[48:51]
	v_mfma_f32_16x16x32_bf16 v[32:35], v[180:183], v[236:239], v[32:35]
	s_barrier
; #define PG8_STAGE(bufoff, gbase, voff) do { _Pragma("unroll") for (int _i = 0; _i < 2; ++_i) \
;         __builtin_amdgcn_global_load_lds((const unsigned*)((const char*)(gbase) + (voff)[_i]), (PG8_LAS unsigned*)(lds + (bufoff) + ldsw + _i * 8192), 16, 0, 0); } while (0)
; #define PG8_LDA(dst, b, h) do { _Pragma("unroll") for (int m = 0; m < 4; ++m) _Pragma("unroll") for (int k = 0; k < 2; ++k) dst[m][k] = *(const PG8_LAS bf16x8*)(lds + PG8_SA(b, h) + aoff + m * 2048 + k * 1024); } while (0)
; #define PG8_MMA(ai, bj, At, Bt) do { __builtin_amdgcn_s_setprio(1); _Pragma("unroll") for (int m = 0; m < 4; ++m) _Pragma("unroll") for (int n = 0; n < 2; ++n) _Pragma("unroll") for (int k = 0; k < 2; ++k) \
;         acc[ai][bj][m][n] = __builtin_amdgcn_mfma_f32_16x16x32_bf16(Bt[n][k], At[m][k], acc[ai][bj][m][n], 0, 0, 0); __builtin_amdgcn_s_setprio(0); } while (0)
; #define PG8_WAIT_V(n) asm volatile("s_waitcnt vmcnt(" #n ")" ::: "memory")
; #define PG8_WAIT_L(n) asm volatile("s_waitcnt lgkmcnt(" #n ")" ::: "memory")
; #define PG8_BAR __builtin_amdgcn_s_barrier()
; #define PG8_SCHED __builtin_amdgcn_sched_barrier(0)
; template <class Epi, class Sched, bool ALIGN_EPI = false, bool SP2 = false>
; __device__ __forceinline__ void gemm_phase(PG8_LAS unsigned char* lds, const Gemm g, const Sched& S, const Epi& E) {
;     ...
;         for (int t = 0; t < nt; t += 2) {
;     ...
;             PG8_LDA(At, 1, 1); PG8_STAGE(PG8_SB(1, 0), b3, voffB); PG8_STAGE(PG8_SB(1, 1), b3 + hstep, voffB); PG8_STAGE(PG8_SA(1, 0), a3, voffA);
;             PG8_WAIT_V(8); PG8_WAIT_L(0); PG8_BAR; PG8_MMA(1, 0, At, B0); PG8_MMA(1, 1, At, B1); PG8_BAR; PG8_SCHED;
	s_add_i32 s0, s76, s53
	v_lshl_add_u64 v[160:161], v[160:161], 0, s[22:23]
	s_mov_b32 m0, s0
	ds_read_b128 v[184:187], v163 offset:49152
	ds_read_b128 v[188:191], v163 offset:50176
	ds_read_b128 v[192:195], v163 offset:51200
	ds_read_b128 v[196:199], v163 offset:52224
	ds_read_b128 v[204:207], v163 offset:53248
	ds_read_b128 v[208:211], v163 offset:54272
	ds_read_b128 v[212:215], v163 offset:55296
	ds_read_b128 v[236:239], v163 offset:56320
	global_load_lds_dwordx4 v[160:161], off
	v_lshl_add_u64 v[160:161], v[240:241], 0, s[22:23]
	s_add_i32 m0, s0, 0x2000
	s_add_i32 s0, s77, s53
	global_load_lds_dwordx4 v[160:161], off
	v_lshl_add_u64 v[160:161], v[242:243], 0, s[22:23]
	s_mov_b32 m0, s0
	s_nop 0
	global_load_lds_dwordx4 v[160:161], off
	v_lshl_add_u64 v[160:161], v[244:245], 0, s[22:23]
	s_add_i32 m0, s0, 0x2000
	s_nop 0
	global_load_lds_dwordx4 v[160:161], off
	v_lshl_add_u64 v[160:161], v[246:247], 0, s[22:23]
	s_mov_b32 m0, s64
	s_nop 0
	global_load_lds_dwordx4 v[160:161], off
	v_lshl_add_u64 v[160:161], v[248:249], 0, s[22:23]
	s_mov_b32 m0, s65
	s_nop 0
	global_load_lds_dwordx4 v[160:161], off
	s_waitcnt vmcnt(8)
	s_waitcnt lgkmcnt(0)
	s_barrier
	s_waitcnt lgkmcnt(0)
	v_mfma_f32_16x16x32_bf16 v[104:107], v[148:151], v[184:187], v[104:107]
	v_mfma_f32_16x16x32_bf16 v[100:103], v[156:159], v[184:187], v[100:103]
	v_mfma_f32_16x16x32_bf16 v[96:99], v[148:151], v[192:195], v[96:99]
	v_mfma_f32_16x16x32_bf16 v[92:95], v[156:159], v[192:195], v[92:95]
	v_mfma_f32_16x16x32_bf16 v[88:91], v[148:151], v[204:207], v[88:91]
	v_mfma_f32_16x16x32_bf16 v[84:87], v[156:159], v[204:207], v[84:87]
	v_mfma_f32_16x16x32_bf16 v[80:83], v[148:151], v[212:215], v[80:83]
	v_mfma_f32_16x16x32_bf16 v[76:79], v[156:159], v[212:215], v[76:79]
	v_mfma_f32_16x16x32_bf16 v[104:107], v[152:155], v[188:191], v[104:107]
	v_mfma_f32_16x16x32_bf16 v[100:103], v[164:167], v[188:191], v[100:103]
	v_mfma_f32_16x16x32_bf16 v[96:99], v[152:155], v[196:199], v[96:99]
	v_mfma_f32_16x16x32_bf16 v[92:95], v[164:167], v[196:199], v[92:95]
	v_mfma_f32_16x16x32_bf16 v[88:91], v[152:155], v[208:211], v[88:91]
	v_mfma_f32_16x16x32_bf16 v[84:87], v[164:167], v[208:211], v[84:87]
	v_mfma_f32_16x16x32_bf16 v[80:83], v[152:155], v[236:239], v[80:83]
	v_mfma_f32_16x16x32_bf16 v[76:79], v[164:167], v[236:239], v[76:79]
	v_mfma_f32_16x16x32_bf16 v[28:31], v[168:171], v[184:187], v[28:31]
	v_mfma_f32_16x16x32_bf16 v[24:27], v[176:179], v[184:187], v[24:27]
	v_mfma_f32_16x16x32_bf16 v[20:23], v[168:171], v[192:195], v[20:23]
	v_mfma_f32_16x16x32_bf16 v[16:19], v[176:179], v[192:195], v[16:19]
	v_mfma_f32_16x16x32_bf16 v[12:15], v[168:171], v[204:207], v[12:15]
	v_mfma_f32_16x16x32_bf16 v[8:11], v[176:179], v[204:207], v[8:11]
	v_mfma_f32_16x16x32_bf16 v[4:7], v[168:171], v[212:215], v[4:7]
	v_mfma_f32_16x16x32_bf16 v[0:3], v[176:179], v[212:215], v[0:3]
	v_mfma_f32_16x16x32_bf16 v[28:31], v[172:175], v[188:191], v[28:31]
	v_mfma_f32_16x16x32_bf16 v[24:27], v[180:183], v[188:191], v[24:27]
	v_mfma_f32_16x16x32_bf16 v[20:23], v[172:175], v[196:199], v[20:23]
	v_mfma_f32_16x16x32_bf16 v[16:19], v[180:183], v[196:199], v[16:19]
	v_mfma_f32_16x16x32_bf16 v[12:15], v[172:175], v[208:211], v[12:15]
	v_mfma_f32_16x16x32_bf16 v[8:11], v[180:183], v[208:211], v[8:11]
	v_mfma_f32_16x16x32_bf16 v[4:7], v[172:175], v[236:239], v[4:7]
	v_mfma_f32_16x16x32_bf16 v[0:3], v[180:183], v[236:239], v[0:3]
	s_barrier
	s_add_u32 s24, s24, 0x100
	s_addc_u32 s25, s25, 0
	s_add_u32 s18, s18, 0x100
	s_addc_u32 s19, s19, 0
	s_cmp_ge_i32 s75, s61
	s_mov_b32 s0, s75
	s_cbranch_scc0 .LBB0_358
	s_mov_b32 s79, 0x10000
	s_mov_b32 s78, 0x14000
	s_movk_i32 s76, 0x90

; #define PG8_STAGE(bufoff, gbase, voff) do { _Pragma("unroll") for (int _i = 0; _i < 2; ++_i) \
;         __builtin_amdgcn_global_load_lds((const unsigned*)((const char*)(gbase) + (voff)[_i]), (PG8_LAS unsigned*)(lds + (bufoff) + ldsw + _i * 8192), 16, 0, 0); } while (0)
; #define PG8_LDA(dst, b, h) do { _Pragma("unroll") for (int m = 0; m < 4; ++m) _Pragma("unroll") for (int k = 0; k < 2; ++k) dst[m][k] = *(const PG8_LAS bf16x8*)(lds + PG8_SA(b, h) + aoff + m * 2048 + k * 1024); } while (0)
; #define PG8_LDB(dst, b, h) do { _Pragma("unroll") for (int n = 0; n < 2; ++n) _Pragma("unroll") for (int k = 0; k < 2; ++k) dst[n][k] = *(const PG8_LAS bf16x8*)(lds + PG8_SB(b, h) + boff + n * 2048 + k * 1024); } while (0)
; #define PG8_MMA(ai, bj, At, Bt) do { __builtin_amdgcn_s_setprio(1); _Pragma("unroll") for (int m = 0; m < 4; ++m) _Pragma("unroll") for (int n = 0; n < 2; ++n) _Pragma("unroll") for (int k = 0; k < 2; ++k) \
;         acc[ai][bj][m][n] = __builtin_amdgcn_mfma_f32_16x16x32_bf16(Bt[n][k], At[m][k], acc[ai][bj][m][n], 0, 0, 0); __builtin_amdgcn_s_setprio(0); } while (0)
; #define PG8_WAIT_V(n) asm volatile("s_waitcnt vmcnt(" #n ")" ::: "memory")
; #define PG8_WAIT_L(n) asm volatile("s_waitcnt lgkmcnt(" #n ")" ::: "memory")
; #define PG8_BAR __builtin_amdgcn_s_barrier()
; #define PG8_SCHED __builtin_amdgcn_sched_barrier(0)
; template <class Epi, class Sched, bool ALIGN_EPI = false, bool SP2 = false>
; __device__ __forceinline__ void gemm_phase(PG8_LAS unsigned char* lds, const Gemm g, const Sched& S, const Epi& E) {
;     ...
;         for (int t = 0; t < nt; t += 2) {
;             const bool last = (t == nt - 2);
;             const char* a1 = cA + (size_t)(t + 1) * kstep;
;             const char* a2 = last ? nA : cA + (size_t)(t + 2) * kstep; const char* b2 = last ? nB : cB + (size_t)(t + 2) * kstep;
;             const char* a3 = a2 + kstep; const char* b3 = b2 + kstep;
;             if (last && has_next) S.a_ready(nxt);
;             if constexpr (SP2) {
;             PG8_LDB(B0, 0, 0); PG8_LDB(B1, 0, 1); PG8_SCHED; PG8_LDA(At, 0, 0); PG8_STAGE(PG8_SA(1, 1), a1 + hstep, voffA);
;             PG8_WAIT_V(8); PG8_WAIT_L(0); PG8_BAR; PG8_MMA(0, 0, At, B0); PG8_MMA(0, 1, At, B1); PG8_BAR; PG8_SCHED;
;             PG8_LDA(At, 0, 1); PG8_STAGE(PG8_SB(0, 0), b2, voffB); PG8_STAGE(PG8_SB(0, 1), b2 + hstep, voffB); PG8_STAGE(PG8_SA(0, 0), a2, voffA);
.LBB0_380:
	s_add_i32 s71, s0, 2
	s_add_u32 s72, s24, 0x80
	s_addc_u32 s1, s25, 0
	s_add_i32 s74, 0, 0x10000
	s_cmp_eq_u32 s62, s0
	s_cselect_b32 s1, s35, s1
	s_cselect_b32 s0, s34, s72
	v_add_u32_e32 v160, s74, v162
	s_cselect_b32 s73, s41, s19
	s_cselect_b32 s72, s40, s18
	s_add_i32 s75, 0, 0x14000
	ds_read_b128 v[148:151], v160
	ds_read_b128 v[152:155], v160 offset:1024
	ds_read_b128 v[156:159], v160 offset:2048
	ds_read_b128 v[164:167], v160 offset:3072
	v_add_u32_e32 v160, s75, v162
	ds_read_b128 v[168:171], v160
	ds_read_b128 v[172:175], v160 offset:1024
	ds_read_b128 v[176:179], v160 offset:2048
	ds_read_b128 v[180:183], v160 offset:3072
	v_lshl_add_u64 v[160:161], s[24:25], 0, v[144:145]
	s_add_i32 m0, s53, 0xc000
	ds_read_b128 v[184:187], v163
	ds_read_b128 v[188:191], v163 offset:1024
	ds_read_b128 v[192:195], v163 offset:2048
	ds_read_b128 v[196:199], v163 offset:3072
	ds_read_b128 v[204:207], v163 offset:4096
	ds_read_b128 v[208:211], v163 offset:5120
	ds_read_b128 v[212:215], v163 offset:6144
	ds_read_b128 v[236:239], v163 offset:7168
	global_load_lds_dwordx4 v[160:161], off
	v_lshl_add_u64 v[160:161], s[24:25], 0, v[146:147]
	s_add_i32 m0, s53, 0xe000
	s_nop 0
	global_load_lds_dwordx4 v[160:161], off
	s_waitcnt vmcnt(8)
	s_waitcnt lgkmcnt(0)
	s_barrier
	s_waitcnt lgkmcnt(0)
	v_mfma_f32_16x16x32_bf16 v[132:135], v[148:151], v[184:187], v[132:135]
	v_mfma_f32_16x16x32_bf16 v[136:139], v[156:159], v[184:187], v[136:139]
	v_mfma_f32_16x16x32_bf16 v[128:131], v[148:151], v[192:195], v[128:131]
	v_mfma_f32_16x16x32_bf16 v[124:127], v[156:159], v[192:195], v[124:127]
	v_mfma_f32_16x16x32_bf16 v[120:123], v[148:151], v[204:207], v[120:123]
	v_mfma_f32_16x16x32_bf16 v[116:119], v[156:159], v[204:207], v[116:119]
	v_mfma_f32_16x16x32_bf16 v[112:115], v[148:151], v[212:215], v[112:115]
	v_mfma_f32_16x16x32_bf16 v[108:111], v[156:159], v[212:215], v[108:111]
	v_mfma_f32_16x16x32_bf16 v[132:135], v[152:155], v[188:191], v[132:135]
	v_mfma_f32_16x16x32_bf16 v[136:139], v[164:167], v[188:191], v[136:139]
	v_mfma_f32_16x16x32_bf16 v[128:131], v[152:155], v[196:199], v[128:131]
	v_mfma_f32_16x16x32_bf16 v[124:127], v[164:167], v[196:199], v[124:127]
	v_mfma_f32_16x16x32_bf16 v[120:123], v[152:155], v[208:211], v[120:123]
	v_mfma_f32_16x16x32_bf16 v[116:119], v[164:167], v[208:211], v[116:119]
	v_mfma_f32_16x16x32_bf16 v[112:115], v[152:155], v[236:239], v[112:115]
	v_mfma_f32_16x16x32_bf16 v[108:111], v[164:167], v[236:239], v[108:111]
	v_mfma_f32_16x16x32_bf16 v[72:75], v[168:171], v[184:187], v[72:75]
	v_mfma_f32_16x16x32_bf16 v[68:71], v[176:179], v[184:187], v[68:71]
	v_mfma_f32_16x16x32_bf16 v[64:67], v[168:171], v[192:195], v[64:67]
	v_mfma_f32_16x16x32_bf16 v[60:63], v[176:179], v[192:195], v[60:63]
	v_mfma_f32_16x16x32_bf16 v[56:59], v[168:171], v[204:207], v[56:59]
	v_mfma_f32_16x16x32_bf16 v[52:55], v[176:179], v[204:207], v[52:55]
	v_mfma_f32_16x16x32_bf16 v[48:51], v[168:171], v[212:215], v[48:51]
	v_mfma_f32_16x16x32_bf16 v[32:35], v[176:179], v[212:215], v[32:35]
	v_mfma_f32_16x16x32_bf16 v[72:75], v[172:175], v[188:191], v[72:75]
	v_mfma_f32_16x16x32_bf16 v[68:71], v[180:183], v[188:191], v[68:71]
	v_mfma_f32_16x16x32_bf16 v[64:67], v[172:175], v[196:199], v[64:67]
	v_mfma_f32_16x16x32_bf16 v[60:63], v[180:183], v[196:199], v[60:63]
	v_mfma_f32_16x16x32_bf16 v[56:59], v[172:175], v[208:211], v[56:59]
	v_mfma_f32_16x16x32_bf16 v[52:55], v[180:183], v[208:211], v[52:55]
	v_mfma_f32_16x16x32_bf16 v[48:51], v[172:175], v[236:239], v[48:51]
	v_mfma_f32_16x16x32_bf16 v[32:35], v[180:183], v[236:239], v[32:35]
	s_barrier
	s_add_i32 s74, s74, s45
	v_lshl_add_u64 v[160:161], s[72:73], 0, v[140:141]
	s_mov_b32 m0, s74
	ds_read_b128 v[184:187], v163 offset:16384
	ds_read_b128 v[188:191], v163 offset:17408
	ds_read_b128 v[192:195], v163 offset:18432
	ds_read_b128 v[196:199], v163 offset:19456
	ds_read_b128 v[204:207], v163 offset:20480
	ds_read_b128 v[208:211], v163 offset:21504
	ds_read_b128 v[212:215], v163 offset:22528
	ds_read_b128 v[236:239], v163 offset:23552
	global_load_lds_dwordx4 v[160:161], off
	s_add_i32 m0, s74, 0x2000
	v_lshl_add_u64 v[240:241], s[72:73], 0, v[38:39]
	s_add_u32 s72, s72, s2
	s_addc_u32 s73, s73, s3
	s_add_i32 s74, s75, s45
	global_load_lds_dwordx4 v[240:241], off
	v_lshl_add_u64 v[242:243], s[72:73], 0, v[140:141]
	s_mov_b32 m0, s74
	v_lshl_add_u64 v[244:245], s[72:73], 0, v[38:39]
	global_load_lds_dwordx4 v[242:243], off
	s_add_i32 m0, s74, 0x2000
	v_lshl_add_u64 v[246:247], s[0:1], 0, v[142:143]
	global_load_lds_dwordx4 v[244:245], off
	s_mov_b32 m0, s53
	v_lshl_add_u64 v[248:249], s[0:1], 0, v[42:43]
	global_load_lds_dwordx4 v[246:247], off
	s_mov_b32 m0, s54
	s_nop 0
	global_load_lds_dwordx4 v[248:249], off
	s_waitcnt vmcnt(8)
	s_waitcnt lgkmcnt(0)
	s_barrier
; #define PG8_STAGE(bufoff, gbase, voff) do { _Pragma("unroll") for (int _i = 0; _i < 2; ++_i) \
;         __builtin_amdgcn_global_load_lds((const unsigned*)((const char*)(gbase) + (voff)[_i]), (PG8_LAS unsigned*)(lds + (bufoff) + ldsw + _i * 8192), 16, 0, 0); } while (0)
; #define PG8_LDA(dst, b, h) do { _Pragma("unroll") for (int m = 0; m < 4; ++m) _Pragma("unroll") for (int k = 0; k < 2; ++k) dst[m][k] = *(const PG8_LAS bf16x8*)(lds + PG8_SA(b, h) + aoff + m * 2048 + k * 1024); } while (0)
; #define PG8_LDB(dst, b, h) do { _Pragma("unroll") for (int n = 0; n < 2; ++n) _Pragma("unroll") for (int k = 0; k < 2; ++k) dst[n][k] = *(const PG8_LAS bf16x8*)(lds + PG8_SB(b, h) + boff + n * 2048 + k * 1024); } while (0)
; #define PG8_MMA(ai, bj, At, Bt) do { __builtin_amdgcn_s_setprio(1); _Pragma("unroll") for (int m = 0; m < 4; ++m) _Pragma("unroll") for (int n = 0; n < 2; ++n) _Pragma("unroll") for (int k = 0; k < 2; ++k) \
;         acc[ai][bj][m][n] = __builtin_amdgcn_mfma_f32_16x16x32_bf16(Bt[n][k], At[m][k], acc[ai][bj][m][n], 0, 0, 0); __builtin_amdgcn_s_setprio(0); } while (0)
; #define PG8_WAIT_V(n) asm volatile("s_waitcnt vmcnt(" #n ")" ::: "memory")
; #define PG8_WAIT_L(n) asm volatile("s_waitcnt lgkmcnt(" #n ")" ::: "memory")
; #define PG8_BAR __builtin_amdgcn_s_barrier()
; #define PG8_SCHED __builtin_amdgcn_sched_barrier(0)
; template <class Epi, class Sched, bool ALIGN_EPI = false, bool SP2 = false>
; __device__ __forceinline__ void gemm_phase(PG8_LAS unsigned char* lds, const Gemm g, const Sched& S, const Epi& E) {
;     ...
;             PG8_WAIT_V(8); PG8_WAIT_L(0); PG8_BAR; PG8_MMA(1, 0, At, B0); PG8_MMA(1, 1, At, B1); PG8_BAR; PG8_SCHED;
;             PG8_LDB(B0, 1, 0); PG8_LDB(B1, 1, 1); PG8_SCHED; PG8_LDA(At, 1, 0); PG8_STAGE(PG8_SA(0, 1), a2 + hstep, voffA);
;             PG8_WAIT_V(8); PG8_WAIT_L(0); PG8_BAR; PG8_MMA(0, 0, At, B0); PG8_MMA(0, 1, At, B1); PG8_BAR; PG8_SCHED;
	s_waitcnt lgkmcnt(0)
	v_mfma_f32_16x16x32_bf16 v[104:107], v[148:151], v[184:187], v[104:107]
	v_mfma_f32_16x16x32_bf16 v[100:103], v[156:159], v[184:187], v[100:103]
	v_mfma_f32_16x16x32_bf16 v[96:99], v[148:151], v[192:195], v[96:99]
	v_mfma_f32_16x16x32_bf16 v[92:95], v[156:159], v[192:195], v[92:95]
	v_mfma_f32_16x16x32_bf16 v[88:91], v[148:151], v[204:207], v[88:91]
	v_mfma_f32_16x16x32_bf16 v[84:87], v[156:159], v[204:207], v[84:87]
	v_mfma_f32_16x16x32_bf16 v[80:83], v[148:151], v[212:215], v[80:83]
	v_mfma_f32_16x16x32_bf16 v[76:79], v[156:159], v[212:215], v[76:79]
	v_mfma_f32_16x16x32_bf16 v[104:107], v[152:155], v[188:191], v[104:107]
	v_mfma_f32_16x16x32_bf16 v[100:103], v[164:167], v[188:191], v[100:103]
	v_mfma_f32_16x16x32_bf16 v[96:99], v[152:155], v[196:199], v[96:99]
	v_mfma_f32_16x16x32_bf16 v[92:95], v[164:167], v[196:199], v[92:95]
	v_mfma_f32_16x16x32_bf16 v[88:91], v[152:155], v[208:211], v[88:91]
	v_mfma_f32_16x16x32_bf16 v[84:87], v[164:167], v[208:211], v[84:87]
	v_mfma_f32_16x16x32_bf16 v[80:83], v[152:155], v[236:239], v[80:83]
	v_mfma_f32_16x16x32_bf16 v[76:79], v[164:167], v[236:239], v[76:79]
	v_mfma_f32_16x16x32_bf16 v[28:31], v[168:171], v[184:187], v[28:31]
	v_mfma_f32_16x16x32_bf16 v[24:27], v[176:179], v[184:187], v[24:27]
	v_mfma_f32_16x16x32_bf16 v[20:23], v[168:171], v[192:195], v[20:23]
	v_mfma_f32_16x16x32_bf16 v[16:19], v[176:179], v[192:195], v[16:19]
	v_mfma_f32_16x16x32_bf16 v[12:15], v[168:171], v[204:207], v[12:15]
	v_mfma_f32_16x16x32_bf16 v[8:11], v[176:179], v[204:207], v[8:11]
	v_mfma_f32_16x16x32_bf16 v[4:7], v[168:171], v[212:215], v[4:7]
	v_mfma_f32_16x16x32_bf16 v[0:3], v[176:179], v[212:215], v[0:3]
	v_mfma_f32_16x16x32_bf16 v[28:31], v[172:175], v[188:191], v[28:31]
	v_mfma_f32_16x16x32_bf16 v[24:27], v[180:183], v[188:191], v[24:27]
	v_mfma_f32_16x16x32_bf16 v[20:23], v[172:175], v[196:199], v[20:23]
	v_mfma_f32_16x16x32_bf16 v[16:19], v[180:183], v[196:199], v[16:19]
	v_mfma_f32_16x16x32_bf16 v[12:15], v[172:175], v[208:211], v[12:15]
	v_mfma_f32_16x16x32_bf16 v[8:11], v[180:183], v[208:211], v[8:11]
	v_mfma_f32_16x16x32_bf16 v[4:7], v[172:175], v[236:239], v[4:7]
	v_mfma_f32_16x16x32_bf16 v[0:3], v[180:183], v[236:239], v[0:3]
	s_barrier
	s_add_i32 s72, 0, 0x18000
	s_add_i32 s73, 0, 0x1c000
	v_add_u32_e32 v164, s72, v162
	v_add_u32_e32 v180, s73, v162
	ds_read_b128 v[148:151], v164
	ds_read_b128 v[152:155], v164 offset:1024
	ds_read_b128 v[156:159], v164 offset:2048
	ds_read_b128 v[164:167], v164 offset:3072
	ds_read_b128 v[168:171], v180
	ds_read_b128 v[172:175], v180 offset:1024
	ds_read_b128 v[176:179], v180 offset:2048
	ds_read_b128 v[180:183], v180 offset:3072
	s_add_u32 s0, s0, s2
	s_addc_u32 s1, s1, s3
	s_mov_b32 m0, s55
	v_lshl_add_u64 v[250:251], s[0:1], 0, v[142:143]
	ds_read_b128 v[184:187], v163 offset:32768
	ds_read_b128 v[188:191], v163 offset:33792
	ds_read_b128 v[192:195], v163 offset:34816
	ds_read_b128 v[196:199], v163 offset:35840
	ds_read_b128 v[204:207], v163 offset:36864
	ds_read_b128 v[208:211], v163 offset:37888
	ds_read_b128 v[212:215], v163 offset:38912
	ds_read_b128 v[236:239], v163 offset:39936
	global_load_lds_dwordx4 v[250:251], off
	v_lshl_add_u64 v[250:251], s[0:1], 0, v[42:43]
	s_mov_b32 m0, s56
	s_nop 0
	global_load_lds_dwordx4 v[250:251], off
	s_waitcnt vmcnt(8)
	s_waitcnt lgkmcnt(0)
	s_barrier
	s_waitcnt lgkmcnt(0)
	v_mfma_f32_16x16x32_bf16 v[132:135], v[148:151], v[184:187], v[132:135]
	v_mfma_f32_16x16x32_bf16 v[136:139], v[156:159], v[184:187], v[136:139]
	v_mfma_f32_16x16x32_bf16 v[128:131], v[148:151], v[192:195], v[128:131]
	v_mfma_f32_16x16x32_bf16 v[124:127], v[156:159], v[192:195], v[124:127]
	v_mfma_f32_16x16x32_bf16 v[120:123], v[148:151], v[204:207], v[120:123]
	v_mfma_f32_16x16x32_bf16 v[116:119], v[156:159], v[204:207], v[116:119]
	v_mfma_f32_16x16x32_bf16 v[112:115], v[148:151], v[212:215], v[112:115]
	v_mfma_f32_16x16x32_bf16 v[108:111], v[156:159], v[212:215], v[108:111]
	v_mfma_f32_16x16x32_bf16 v[132:135], v[152:155], v[188:191], v[132:135]
	v_mfma_f32_16x16x32_bf16 v[136:139], v[164:167], v[188:191], v[136:139]
	v_mfma_f32_16x16x32_bf16 v[128:131], v[152:155], v[196:199], v[128:131]
	v_mfma_f32_16x16x32_bf16 v[124:127], v[164:167], v[196:199], v[124:127]
	v_mfma_f32_16x16x32_bf16 v[120:123], v[152:155], v[208:211], v[120:123]
	v_mfma_f32_16x16x32_bf16 v[116:119], v[164:167], v[208:211], v[116:119]
	v_mfma_f32_16x16x32_bf16 v[112:115], v[152:155], v[236:239], v[112:115]
	v_mfma_f32_16x16x32_bf16 v[108:111], v[164:167], v[236:239], v[108:111]
	v_mfma_f32_16x16x32_bf16 v[72:75], v[168:171], v[184:187], v[72:75]
	v_mfma_f32_16x16x32_bf16 v[68:71], v[176:179], v[184:187], v[68:71]
	v_mfma_f32_16x16x32_bf16 v[64:67], v[168:171], v[192:195], v[64:67]
	v_mfma_f32_16x16x32_bf16 v[60:63], v[176:179], v[192:195], v[60:63]
	v_mfma_f32_16x16x32_bf16 v[56:59], v[168:171], v[204:207], v[56:59]
	v_mfma_f32_16x16x32_bf16 v[52:55], v[176:179], v[204:207], v[52:55]
	v_mfma_f32_16x16x32_bf16 v[48:51], v[168:171], v[212:215], v[48:51]
	v_mfma_f32_16x16x32_bf16 v[32:35], v[176:179], v[212:215], v[32:35]
	v_mfma_f32_16x16x32_bf16 v[72:75], v[172:175], v[188:191], v[72:75]
	v_mfma_f32_16x16x32_bf16 v[68:71], v[180:183], v[188:191], v[68:71]
	v_mfma_f32_16x16x32_bf16 v[64:67], v[172:175], v[196:199], v[64:67]
	v_mfma_f32_16x16x32_bf16 v[60:63], v[180:183], v[196:199], v[60:63]
	v_mfma_f32_16x16x32_bf16 v[56:59], v[172:175], v[208:211], v[56:59]
	v_mfma_f32_16x16x32_bf16 v[52:55], v[180:183], v[208:211], v[52:55]
	v_mfma_f32_16x16x32_bf16 v[48:51], v[172:175], v[236:239], v[48:51]
	v_mfma_f32_16x16x32_bf16 v[32:35], v[180:183], v[236:239], v[32:35]
	s_barrier
; #define PG8_STAGE(bufoff, gbase, voff) do { _Pragma("unroll") for (int _i = 0; _i < 2; ++_i) \
;         __builtin_amdgcn_global_load_lds((const unsigned*)((const char*)(gbase) + (voff)[_i]), (PG8_LAS unsigned*)(lds + (bufoff) + ldsw + _i * 8192), 16, 0, 0); } while (0)
; #define PG8_LDA(dst, b, h) do { _Pragma("unroll") for (int m = 0; m < 4; ++m) _Pragma("unroll") for (int k = 0; k < 2; ++k) dst[m][k] = *(const PG8_LAS bf16x8*)(lds + PG8_SA(b, h) + aoff + m * 2048 + k * 1024); } while (0)
; #define PG8_MMA(ai, bj, At, Bt) do { __builtin_amdgcn_s_setprio(1); _Pragma("unroll") for (int m = 0; m < 4; ++m) _Pragma("unroll") for (int n = 0; n < 2; ++n) _Pragma("unroll") for (int k = 0; k < 2; ++k) \
;         acc[ai][bj][m][n] = __builtin_amdgcn_mfma_f32_16x16x32_bf16(Bt[n][k], At[m][k], acc[ai][bj][m][n], 0, 0, 0); __builtin_amdgcn_s_setprio(0); } while (0)
; #define PG8_WAIT_V(n) asm volatile("s_waitcnt vmcnt(" #n ")" ::: "memory")
; #define PG8_WAIT_L(n) asm volatile("s_waitcnt lgkmcnt(" #n ")" ::: "memory")
; #define PG8_BAR __builtin_amdgcn_s_barrier()
; #define PG8_SCHED __builtin_amdgcn_sched_barrier(0)
; template <class Epi, class Sched, bool ALIGN_EPI = false, bool SP2 = false>
; __device__ __forceinline__ void gemm_phase(PG8_LAS unsigned char* lds, const Gemm g, const Sched& S, const Epi& E) {
;     ...
;         for (int t = 0; t < nt; t += 2) {
;     ...
;             PG8_LDA(At, 1, 1); PG8_STAGE(PG8_SB(1, 0), b3, voffB); PG8_STAGE(PG8_SB(1, 1), b3 + hstep, voffB); PG8_STAGE(PG8_SA(1, 0), a3, voffA);
;             PG8_WAIT_V(8); PG8_WAIT_L(0); PG8_BAR; PG8_MMA(1, 0, At, B0); PG8_MMA(1, 1, At, B1); PG8_BAR; PG8_SCHED;
	s_add_i32 s0, s72, s45
	v_lshl_add_u64 v[160:161], v[160:161], 0, s[22:23]
	s_mov_b32 m0, s0
	ds_read_b128 v[184:187], v163 offset:49152
	ds_read_b128 v[188:191], v163 offset:50176
	ds_read_b128 v[192:195], v163 offset:51200
	ds_read_b128 v[196:199], v163 offset:52224
	ds_read_b128 v[204:207], v163 offset:53248
	ds_read_b128 v[208:211], v163 offset:54272
	ds_read_b128 v[212:215], v163 offset:55296
	ds_read_b128 v[236:239], v163 offset:56320
	global_load_lds_dwordx4 v[160:161], off
	v_lshl_add_u64 v[160:161], v[240:241], 0, s[22:23]
	s_add_i32 m0, s0, 0x2000
	s_add_i32 s0, s73, s45
	global_load_lds_dwordx4 v[160:161], off
	v_lshl_add_u64 v[160:161], v[242:243], 0, s[22:23]
	s_mov_b32 m0, s0
	s_nop 0
	global_load_lds_dwordx4 v[160:161], off
	v_lshl_add_u64 v[160:161], v[244:245], 0, s[22:23]
	s_add_i32 m0, s0, 0x2000
	s_nop 0
	global_load_lds_dwordx4 v[160:161], off
	v_lshl_add_u64 v[160:161], v[246:247], 0, s[22:23]
	s_mov_b32 m0, s60
	s_nop 0
	global_load_lds_dwordx4 v[160:161], off
	v_lshl_add_u64 v[160:161], v[248:249], 0, s[22:23]
	s_mov_b32 m0, s61
	s_nop 0
	global_load_lds_dwordx4 v[160:161], off
	s_waitcnt vmcnt(8)
	s_waitcnt lgkmcnt(0)
	s_barrier
	s_waitcnt lgkmcnt(0)
	v_mfma_f32_16x16x32_bf16 v[104:107], v[148:151], v[184:187], v[104:107]
	v_mfma_f32_16x16x32_bf16 v[100:103], v[156:159], v[184:187], v[100:103]
	v_mfma_f32_16x16x32_bf16 v[96:99], v[148:151], v[192:195], v[96:99]
	v_mfma_f32_16x16x32_bf16 v[92:95], v[156:159], v[192:195], v[92:95]
	v_mfma_f32_16x16x32_bf16 v[88:91], v[148:151], v[204:207], v[88:91]
	v_mfma_f32_16x16x32_bf16 v[84:87], v[156:159], v[204:207], v[84:87]
	v_mfma_f32_16x16x32_bf16 v[80:83], v[148:151], v[212:215], v[80:83]
	v_mfma_f32_16x16x32_bf16 v[76:79], v[156:159], v[212:215], v[76:79]
	v_mfma_f32_16x16x32_bf16 v[104:107], v[152:155], v[188:191], v[104:107]
	v_mfma_f32_16x16x32_bf16 v[100:103], v[164:167], v[188:191], v[100:103]
	v_mfma_f32_16x16x32_bf16 v[96:99], v[152:155], v[196:199], v[96:99]
	v_mfma_f32_16x16x32_bf16 v[92:95], v[164:167], v[196:199], v[92:95]
	v_mfma_f32_16x16x32_bf16 v[88:91], v[152:155], v[208:211], v[88:91]
	v_mfma_f32_16x16x32_bf16 v[84:87], v[164:167], v[208:211], v[84:87]
	v_mfma_f32_16x16x32_bf16 v[80:83], v[152:155], v[236:239], v[80:83]
	v_mfma_f32_16x16x32_bf16 v[76:79], v[164:167], v[236:239], v[76:79]
	v_mfma_f32_16x16x32_bf16 v[28:31], v[168:171], v[184:187], v[28:31]
	v_mfma_f32_16x16x32_bf16 v[24:27], v[176:179], v[184:187], v[24:27]
	v_mfma_f32_16x16x32_bf16 v[20:23], v[168:171], v[192:195], v[20:23]
	v_mfma_f32_16x16x32_bf16 v[16:19], v[176:179], v[192:195], v[16:19]
	v_mfma_f32_16x16x32_bf16 v[12:15], v[168:171], v[204:207], v[12:15]
	v_mfma_f32_16x16x32_bf16 v[8:11], v[176:179], v[204:207], v[8:11]
	v_mfma_f32_16x16x32_bf16 v[4:7], v[168:171], v[212:215], v[4:7]
	v_mfma_f32_16x16x32_bf16 v[0:3], v[176:179], v[212:215], v[0:3]
	v_mfma_f32_16x16x32_bf16 v[28:31], v[172:175], v[188:191], v[28:31]
	v_mfma_f32_16x16x32_bf16 v[24:27], v[180:183], v[188:191], v[24:27]
	v_mfma_f32_16x16x32_bf16 v[20:23], v[172:175], v[196:199], v[20:23]
	v_mfma_f32_16x16x32_bf16 v[16:19], v[180:183], v[196:199], v[16:19]
	v_mfma_f32_16x16x32_bf16 v[12:15], v[172:175], v[208:211], v[12:15]
	v_mfma_f32_16x16x32_bf16 v[8:11], v[180:183], v[208:211], v[8:11]
	v_mfma_f32_16x16x32_bf16 v[4:7], v[172:175], v[236:239], v[4:7]
	v_mfma_f32_16x16x32_bf16 v[0:3], v[180:183], v[236:239], v[0:3]
	s_barrier
	s_add_u32 s24, s24, 0x100
	s_addc_u32 s25, s25, 0
	s_add_u32 s18, s18, 0x100
	s_addc_u32 s19, s19, 0
	s_cmp_ge_i32 s71, s57
	s_mov_b32 s0, s71
	s_cbranch_scc0 .LBB0_380

; #define PG8_STAGE(bufoff, gbase, voff) do { _Pragma("unroll") for (int _i = 0; _i < 2; ++_i) \
;         __builtin_amdgcn_global_load_lds((const unsigned*)((const char*)(gbase) + (voff)[_i]), (PG8_LAS unsigned*)(lds + (bufoff) + ldsw + _i * 8192), 16, 0, 0); } while (0)
; #define PG8_LDA(dst, b, h) do { _Pragma("unroll") for (int m = 0; m < 4; ++m) _Pragma("unroll") for (int k = 0; k < 2; ++k) dst[m][k] = *(const PG8_LAS bf16x8*)(lds + PG8_SA(b, h) + aoff + m * 2048 + k * 1024); } while (0)
; #define PG8_LDB(dst, b, h) do { _Pragma("unroll") for (int n = 0; n < 2; ++n) _Pragma("unroll") for (int k = 0; k < 2; ++k) dst[n][k] = *(const PG8_LAS bf16x8*)(lds + PG8_SB(b, h) + boff + n * 2048 + k * 1024); } while (0)
; #define PG8_MMA(ai, bj, At, Bt) do { __builtin_amdgcn_s_setprio(1); _Pragma("unroll") for (int m = 0; m < 4; ++m) _Pragma("unroll") for (int n = 0; n < 2; ++n) _Pragma("unroll") for (int k = 0; k < 2; ++k) \
;         acc[ai][bj][m][n] = __builtin_amdgcn_mfma_f32_16x16x32_bf16(Bt[n][k], At[m][k], acc[ai][bj][m][n], 0, 0, 0); __builtin_amdgcn_s_setprio(0); } while (0)
; #define PG8_WAIT_V(n) asm volatile("s_waitcnt vmcnt(" #n ")" ::: "memory")
; #define PG8_WAIT_L(n) asm volatile("s_waitcnt lgkmcnt(" #n ")" ::: "memory")
; #define PG8_BAR __builtin_amdgcn_s_barrier()
; #define PG8_SCHED __builtin_amdgcn_sched_barrier(0)
; template <class Epi, class Sched, bool ALIGN_EPI = false, bool SP2 = false>
; __device__ __forceinline__ void gemm_phase(PG8_LAS unsigned char* lds, const Gemm g, const Sched& S, const Epi& E) {
;     ...
;         for (int t = 0; t < nt; t += 2) {
;             const bool last = (t == nt - 2);
;             const char* a1 = cA + (size_t)(t + 1) * kstep;
;             const char* a2 = last ? nA : cA + (size_t)(t + 2) * kstep; const char* b2 = last ? nB : cB + (size_t)(t + 2) * kstep;
;             const char* a3 = a2 + kstep; const char* b3 = b2 + kstep;
;             if (last && has_next) S.a_ready(nxt);
;             if constexpr (SP2) {
;             PG8_LDB(B0, 0, 0); PG8_LDB(B1, 0, 1); PG8_SCHED; PG8_LDA(At, 0, 0); PG8_STAGE(PG8_SA(1, 1), a1 + hstep, voffA);
;             PG8_WAIT_V(8); PG8_WAIT_L(0); PG8_BAR; PG8_MMA(0, 0, At, B0); PG8_MMA(0, 1, At, B1); PG8_BAR; PG8_SCHED;
;             PG8_LDA(At, 0, 1); PG8_STAGE(PG8_SB(0, 0), b2, voffB); PG8_STAGE(PG8_SB(0, 1), b2 + hstep, voffB); PG8_STAGE(PG8_SA(0, 0), a2, voffA);
.LBB0_532:
	s_add_i32 s40, s0, 2
	s_add_u32 s41, s24, 0x80
	s_addc_u32 s1, s25, 0
	s_add_i32 s46, 0, 0x10000
	s_cmp_eq_u32 s78, s0
	s_cselect_b32 s1, s63, s1
	s_cselect_b32 s0, s62, s41
	s_cselect_b32 s45, s65, s19
	s_cselect_b32 s44, s64, s18
	s_add_i32 s41, 0, 0x14000
	v_add_u32_e32 v162, s46, v156
	v_add_u32_e32 v178, s41, v156
	ds_read_b128 v[148:151], v162
	ds_read_b128 v[152:155], v162 offset:1024
	ds_read_b128 v[158:161], v162 offset:2048
	ds_read_b128 v[162:165], v162 offset:3072
	ds_read_b128 v[166:169], v178
	ds_read_b128 v[170:173], v178 offset:1024
	ds_read_b128 v[174:177], v178 offset:2048
	ds_read_b128 v[178:181], v178 offset:3072
	v_lshl_add_u64 v[198:199], s[24:25], 0, v[144:145]
	s_add_i32 m0, s69, 0xc000
	ds_read_b128 v[182:185], v157
	ds_read_b128 v[186:189], v157 offset:1024
	ds_read_b128 v[190:193], v157 offset:2048
	ds_read_b128 v[194:197], v157 offset:3072
	ds_read_b128 v[204:207], v157 offset:4096
	ds_read_b128 v[208:211], v157 offset:5120
	ds_read_b128 v[212:215], v157 offset:6144
	ds_read_b128 v[236:239], v157 offset:7168
	global_load_lds_dwordx4 v[198:199], off
	v_lshl_add_u64 v[198:199], s[24:25], 0, v[146:147]
	s_add_i32 m0, s69, 0xe000
	s_nop 0
	global_load_lds_dwordx4 v[198:199], off
	s_waitcnt vmcnt(8)
	s_waitcnt lgkmcnt(0)
	s_barrier
	s_waitcnt lgkmcnt(0)
	v_mfma_f32_16x16x32_bf16 v[132:135], v[148:151], v[182:185], v[132:135]
	v_mfma_f32_16x16x32_bf16 v[136:139], v[158:161], v[182:185], v[136:139]
	v_mfma_f32_16x16x32_bf16 v[128:131], v[148:151], v[190:193], v[128:131]
	v_mfma_f32_16x16x32_bf16 v[124:127], v[158:161], v[190:193], v[124:127]
	v_mfma_f32_16x16x32_bf16 v[120:123], v[148:151], v[204:207], v[120:123]
	v_mfma_f32_16x16x32_bf16 v[116:119], v[158:161], v[204:207], v[116:119]
	v_mfma_f32_16x16x32_bf16 v[112:115], v[148:151], v[212:215], v[112:115]
	v_mfma_f32_16x16x32_bf16 v[108:111], v[158:161], v[212:215], v[108:111]
	v_mfma_f32_16x16x32_bf16 v[132:135], v[152:155], v[186:189], v[132:135]
	v_mfma_f32_16x16x32_bf16 v[136:139], v[162:165], v[186:189], v[136:139]
	v_mfma_f32_16x16x32_bf16 v[128:131], v[152:155], v[194:197], v[128:131]
	v_mfma_f32_16x16x32_bf16 v[124:127], v[162:165], v[194:197], v[124:127]
	v_mfma_f32_16x16x32_bf16 v[120:123], v[152:155], v[208:211], v[120:123]
	v_mfma_f32_16x16x32_bf16 v[116:119], v[162:165], v[208:211], v[116:119]
	v_mfma_f32_16x16x32_bf16 v[112:115], v[152:155], v[236:239], v[112:115]
	v_mfma_f32_16x16x32_bf16 v[108:111], v[162:165], v[236:239], v[108:111]
	v_mfma_f32_16x16x32_bf16 v[72:75], v[166:169], v[182:185], v[72:75]
	v_mfma_f32_16x16x32_bf16 v[68:71], v[174:177], v[182:185], v[68:71]
	v_mfma_f32_16x16x32_bf16 v[64:67], v[166:169], v[190:193], v[64:67]
	v_mfma_f32_16x16x32_bf16 v[60:63], v[174:177], v[190:193], v[60:63]
	v_mfma_f32_16x16x32_bf16 v[56:59], v[166:169], v[204:207], v[56:59]
	v_mfma_f32_16x16x32_bf16 v[52:55], v[174:177], v[204:207], v[52:55]
	v_mfma_f32_16x16x32_bf16 v[48:51], v[166:169], v[212:215], v[48:51]
	v_mfma_f32_16x16x32_bf16 v[32:35], v[174:177], v[212:215], v[32:35]
	v_mfma_f32_16x16x32_bf16 v[72:75], v[170:173], v[186:189], v[72:75]
	v_mfma_f32_16x16x32_bf16 v[68:71], v[178:181], v[186:189], v[68:71]
	v_mfma_f32_16x16x32_bf16 v[64:67], v[170:173], v[194:197], v[64:67]
	v_mfma_f32_16x16x32_bf16 v[60:63], v[178:181], v[194:197], v[60:63]
	v_mfma_f32_16x16x32_bf16 v[56:59], v[170:173], v[208:211], v[56:59]
	v_mfma_f32_16x16x32_bf16 v[52:55], v[178:181], v[208:211], v[52:55]
	v_mfma_f32_16x16x32_bf16 v[48:51], v[170:173], v[236:239], v[48:51]
	v_mfma_f32_16x16x32_bf16 v[32:35], v[178:181], v[236:239], v[32:35]
	s_barrier
	s_add_i32 s46, s46, s68
	v_lshl_add_u64 v[198:199], s[44:45], 0, v[42:43]
	s_mov_b32 m0, s46
	ds_read_b128 v[182:185], v157 offset:16384
	ds_read_b128 v[186:189], v157 offset:17408
	ds_read_b128 v[190:193], v157 offset:18432
	ds_read_b128 v[194:197], v157 offset:19456
	ds_read_b128 v[204:207], v157 offset:20480
	ds_read_b128 v[208:211], v157 offset:21504
	ds_read_b128 v[212:215], v157 offset:22528
	ds_read_b128 v[236:239], v157 offset:23552
	global_load_lds_dwordx4 v[198:199], off
	s_add_i32 m0, s46, 0x2000
	v_lshl_add_u64 v[240:241], s[44:45], 0, v[142:143]
	s_add_u32 s44, s44, s10
	s_addc_u32 s45, s45, s11
	s_add_i32 s41, s41, s68
	global_load_lds_dwordx4 v[240:241], off
	v_lshl_add_u64 v[242:243], s[44:45], 0, v[42:43]
	s_mov_b32 m0, s41
	v_lshl_add_u64 v[244:245], s[44:45], 0, v[142:143]
	global_load_lds_dwordx4 v[242:243], off
	s_add_i32 m0, s41, 0x2000
	v_lshl_add_u64 v[246:247], s[0:1], 0, v[38:39]
	global_load_lds_dwordx4 v[244:245], off
	s_mov_b32 m0, s69
	v_lshl_add_u64 v[248:249], s[0:1], 0, v[140:141]
	global_load_lds_dwordx4 v[246:247], off
	s_mov_b32 m0, s70
	s_nop 0
	global_load_lds_dwordx4 v[248:249], off
	s_waitcnt vmcnt(8)
	s_waitcnt lgkmcnt(0)
	s_barrier
; #define PG8_STAGE(bufoff, gbase, voff) do { _Pragma("unroll") for (int _i = 0; _i < 2; ++_i) \
;         __builtin_amdgcn_global_load_lds((const unsigned*)((const char*)(gbase) + (voff)[_i]), (PG8_LAS unsigned*)(lds + (bufoff) + ldsw + _i * 8192), 16, 0, 0); } while (0)
; #define PG8_LDA(dst, b, h) do { _Pragma("unroll") for (int m = 0; m < 4; ++m) _Pragma("unroll") for (int k = 0; k < 2; ++k) dst[m][k] = *(const PG8_LAS bf16x8*)(lds + PG8_SA(b, h) + aoff + m * 2048 + k * 1024); } while (0)
; #define PG8_LDB(dst, b, h) do { _Pragma("unroll") for (int n = 0; n < 2; ++n) _Pragma("unroll") for (int k = 0; k < 2; ++k) dst[n][k] = *(const PG8_LAS bf16x8*)(lds + PG8_SB(b, h) + boff + n * 2048 + k * 1024); } while (0)
; #define PG8_MMA(ai, bj, At, Bt) do { __builtin_amdgcn_s_setprio(1); _Pragma("unroll") for (int m = 0; m < 4; ++m) _Pragma("unroll") for (int n = 0; n < 2; ++n) _Pragma("unroll") for (int k = 0; k < 2; ++k) \
;         acc[ai][bj][m][n] = __builtin_amdgcn_mfma_f32_16x16x32_bf16(Bt[n][k], At[m][k], acc[ai][bj][m][n], 0, 0, 0); __builtin_amdgcn_s_setprio(0); } while (0)
; #define PG8_WAIT_V(n) asm volatile("s_waitcnt vmcnt(" #n ")" ::: "memory")
; #define PG8_WAIT_L(n) asm volatile("s_waitcnt lgkmcnt(" #n ")" ::: "memory")
; #define PG8_BAR __builtin_amdgcn_s_barrier()
; #define PG8_SCHED __builtin_amdgcn_sched_barrier(0)
; template <class Epi, class Sched, bool ALIGN_EPI = false, bool SP2 = false>
; __device__ __forceinline__ void gemm_phase(PG8_LAS unsigned char* lds, const Gemm g, const Sched& S, const Epi& E) {
;     ...
;             PG8_WAIT_V(8); PG8_WAIT_L(0); PG8_BAR; PG8_MMA(1, 0, At, B0); PG8_MMA(1, 1, At, B1); PG8_BAR; PG8_SCHED;
;             PG8_LDB(B0, 1, 0); PG8_LDB(B1, 1, 1); PG8_SCHED; PG8_LDA(At, 1, 0); PG8_STAGE(PG8_SA(0, 1), a2 + hstep, voffA);
;             PG8_WAIT_V(8); PG8_WAIT_L(0); PG8_BAR; PG8_MMA(0, 0, At, B0); PG8_MMA(0, 1, At, B1); PG8_BAR; PG8_SCHED;
	s_waitcnt lgkmcnt(0)
	v_mfma_f32_16x16x32_bf16 v[104:107], v[148:151], v[182:185], v[104:107]
	v_mfma_f32_16x16x32_bf16 v[100:103], v[158:161], v[182:185], v[100:103]
	v_mfma_f32_16x16x32_bf16 v[96:99], v[148:151], v[190:193], v[96:99]
	v_mfma_f32_16x16x32_bf16 v[92:95], v[158:161], v[190:193], v[92:95]
	v_mfma_f32_16x16x32_bf16 v[88:91], v[148:151], v[204:207], v[88:91]
	v_mfma_f32_16x16x32_bf16 v[84:87], v[158:161], v[204:207], v[84:87]
	v_mfma_f32_16x16x32_bf16 v[80:83], v[148:151], v[212:215], v[80:83]
	v_mfma_f32_16x16x32_bf16 v[76:79], v[158:161], v[212:215], v[76:79]
	v_mfma_f32_16x16x32_bf16 v[104:107], v[152:155], v[186:189], v[104:107]
	v_mfma_f32_16x16x32_bf16 v[100:103], v[162:165], v[186:189], v[100:103]
	v_mfma_f32_16x16x32_bf16 v[96:99], v[152:155], v[194:197], v[96:99]
	v_mfma_f32_16x16x32_bf16 v[92:95], v[162:165], v[194:197], v[92:95]
	v_mfma_f32_16x16x32_bf16 v[88:91], v[152:155], v[208:211], v[88:91]
	v_mfma_f32_16x16x32_bf16 v[84:87], v[162:165], v[208:211], v[84:87]
	v_mfma_f32_16x16x32_bf16 v[80:83], v[152:155], v[236:239], v[80:83]
	v_mfma_f32_16x16x32_bf16 v[76:79], v[162:165], v[236:239], v[76:79]
	v_mfma_f32_16x16x32_bf16 v[28:31], v[166:169], v[182:185], v[28:31]
	v_mfma_f32_16x16x32_bf16 v[24:27], v[174:177], v[182:185], v[24:27]
	v_mfma_f32_16x16x32_bf16 v[20:23], v[166:169], v[190:193], v[20:23]
	v_mfma_f32_16x16x32_bf16 v[16:19], v[174:177], v[190:193], v[16:19]
	v_mfma_f32_16x16x32_bf16 v[12:15], v[166:169], v[204:207], v[12:15]
	v_mfma_f32_16x16x32_bf16 v[8:11], v[174:177], v[204:207], v[8:11]
	v_mfma_f32_16x16x32_bf16 v[4:7], v[166:169], v[212:215], v[4:7]
	v_mfma_f32_16x16x32_bf16 v[0:3], v[174:177], v[212:215], v[0:3]
	v_mfma_f32_16x16x32_bf16 v[28:31], v[170:173], v[186:189], v[28:31]
	v_mfma_f32_16x16x32_bf16 v[24:27], v[178:181], v[186:189], v[24:27]
	v_mfma_f32_16x16x32_bf16 v[20:23], v[170:173], v[194:197], v[20:23]
	v_mfma_f32_16x16x32_bf16 v[16:19], v[178:181], v[194:197], v[16:19]
	v_mfma_f32_16x16x32_bf16 v[12:15], v[170:173], v[208:211], v[12:15]
	v_mfma_f32_16x16x32_bf16 v[8:11], v[178:181], v[208:211], v[8:11]
	v_mfma_f32_16x16x32_bf16 v[4:7], v[170:173], v[236:239], v[4:7]
	v_mfma_f32_16x16x32_bf16 v[0:3], v[178:181], v[236:239], v[0:3]
	s_barrier
	s_add_i32 s41, 0, 0x18000
	s_add_i32 s44, 0, 0x1c000
	v_add_u32_e32 v162, s41, v156
	v_add_u32_e32 v178, s44, v156
	ds_read_b128 v[148:151], v162
	ds_read_b128 v[152:155], v162 offset:1024
	ds_read_b128 v[158:161], v162 offset:2048
	ds_read_b128 v[162:165], v162 offset:3072
	ds_read_b128 v[166:169], v178
	ds_read_b128 v[170:173], v178 offset:1024
	ds_read_b128 v[174:177], v178 offset:2048
	ds_read_b128 v[178:181], v178 offset:3072
	s_add_u32 s0, s0, s10
	s_addc_u32 s1, s1, s11
	s_mov_b32 m0, s71
	v_lshl_add_u64 v[250:251], s[0:1], 0, v[38:39]
	ds_read_b128 v[182:185], v157 offset:32768
	ds_read_b128 v[186:189], v157 offset:33792
	ds_read_b128 v[190:193], v157 offset:34816
	ds_read_b128 v[194:197], v157 offset:35840
	ds_read_b128 v[204:207], v157 offset:36864
	ds_read_b128 v[208:211], v157 offset:37888
	ds_read_b128 v[212:215], v157 offset:38912
	ds_read_b128 v[236:239], v157 offset:39936
	global_load_lds_dwordx4 v[250:251], off
	v_lshl_add_u64 v[250:251], s[0:1], 0, v[140:141]
	s_mov_b32 m0, s72
	s_nop 0
	global_load_lds_dwordx4 v[250:251], off
	s_waitcnt vmcnt(8)
	s_waitcnt lgkmcnt(0)
	s_barrier
	s_waitcnt lgkmcnt(0)
	v_mfma_f32_16x16x32_bf16 v[132:135], v[148:151], v[182:185], v[132:135]
	v_mfma_f32_16x16x32_bf16 v[136:139], v[158:161], v[182:185], v[136:139]
	v_mfma_f32_16x16x32_bf16 v[128:131], v[148:151], v[190:193], v[128:131]
	v_mfma_f32_16x16x32_bf16 v[124:127], v[158:161], v[190:193], v[124:127]
	v_mfma_f32_16x16x32_bf16 v[120:123], v[148:151], v[204:207], v[120:123]
	v_mfma_f32_16x16x32_bf16 v[116:119], v[158:161], v[204:207], v[116:119]
	v_mfma_f32_16x16x32_bf16 v[112:115], v[148:151], v[212:215], v[112:115]
	v_mfma_f32_16x16x32_bf16 v[108:111], v[158:161], v[212:215], v[108:111]
	v_mfma_f32_16x16x32_bf16 v[132:135], v[152:155], v[186:189], v[132:135]
	v_mfma_f32_16x16x32_bf16 v[136:139], v[162:165], v[186:189], v[136:139]
	v_mfma_f32_16x16x32_bf16 v[128:131], v[152:155], v[194:197], v[128:131]
	v_mfma_f32_16x16x32_bf16 v[124:127], v[162:165], v[194:197], v[124:127]
	v_mfma_f32_16x16x32_bf16 v[120:123], v[152:155], v[208:211], v[120:123]
	v_mfma_f32_16x16x32_bf16 v[116:119], v[162:165], v[208:211], v[116:119]
	v_mfma_f32_16x16x32_bf16 v[112:115], v[152:155], v[236:239], v[112:115]
	v_mfma_f32_16x16x32_bf16 v[108:111], v[162:165], v[236:239], v[108:111]
	v_mfma_f32_16x16x32_bf16 v[72:75], v[166:169], v[182:185], v[72:75]
	v_mfma_f32_16x16x32_bf16 v[68:71], v[174:177], v[182:185], v[68:71]
	v_mfma_f32_16x16x32_bf16 v[64:67], v[166:169], v[190:193], v[64:67]
	v_mfma_f32_16x16x32_bf16 v[60:63], v[174:177], v[190:193], v[60:63]
	v_mfma_f32_16x16x32_bf16 v[56:59], v[166:169], v[204:207], v[56:59]
	v_mfma_f32_16x16x32_bf16 v[52:55], v[174:177], v[204:207], v[52:55]
	v_mfma_f32_16x16x32_bf16 v[48:51], v[166:169], v[212:215], v[48:51]
	v_mfma_f32_16x16x32_bf16 v[32:35], v[174:177], v[212:215], v[32:35]
	v_mfma_f32_16x16x32_bf16 v[72:75], v[170:173], v[186:189], v[72:75]
	v_mfma_f32_16x16x32_bf16 v[68:71], v[178:181], v[186:189], v[68:71]
	v_mfma_f32_16x16x32_bf16 v[64:67], v[170:173], v[194:197], v[64:67]
	v_mfma_f32_16x16x32_bf16 v[60:63], v[178:181], v[194:197], v[60:63]
	v_mfma_f32_16x16x32_bf16 v[56:59], v[170:173], v[208:211], v[56:59]
	v_mfma_f32_16x16x32_bf16 v[52:55], v[178:181], v[208:211], v[52:55]
	v_mfma_f32_16x16x32_bf16 v[48:51], v[170:173], v[236:239], v[48:51]
	v_mfma_f32_16x16x32_bf16 v[32:35], v[178:181], v[236:239], v[32:35]
	s_barrier
; #define PG8_STAGE(bufoff, gbase, voff) do { _Pragma("unroll") for (int _i = 0; _i < 2; ++_i) \
;         __builtin_amdgcn_global_load_lds((const unsigned*)((const char*)(gbase) + (voff)[_i]), (PG8_LAS unsigned*)(lds + (bufoff) + ldsw + _i * 8192), 16, 0, 0); } while (0)
; #define PG8_LDA(dst, b, h) do { _Pragma("unroll") for (int m = 0; m < 4; ++m) _Pragma("unroll") for (int k = 0; k < 2; ++k) dst[m][k] = *(const PG8_LAS bf16x8*)(lds + PG8_SA(b, h) + aoff + m * 2048 + k * 1024); } while (0)
; #define PG8_MMA(ai, bj, At, Bt) do { __builtin_amdgcn_s_setprio(1); _Pragma("unroll") for (int m = 0; m < 4; ++m) _Pragma("unroll") for (int n = 0; n < 2; ++n) _Pragma("unroll") for (int k = 0; k < 2; ++k) \
;         acc[ai][bj][m][n] = __builtin_amdgcn_mfma_f32_16x16x32_bf16(Bt[n][k], At[m][k], acc[ai][bj][m][n], 0, 0, 0); __builtin_amdgcn_s_setprio(0); } while (0)
; #define PG8_WAIT_V(n) asm volatile("s_waitcnt vmcnt(" #n ")" ::: "memory")
; #define PG8_WAIT_L(n) asm volatile("s_waitcnt lgkmcnt(" #n ")" ::: "memory")
; #define PG8_BAR __builtin_amdgcn_s_barrier()
; #define PG8_SCHED __builtin_amdgcn_sched_barrier(0)
; template <class Epi, class Sched, bool ALIGN_EPI = false, bool SP2 = false>
; __device__ __forceinline__ void gemm_phase(PG8_LAS unsigned char* lds, const Gemm g, const Sched& S, const Epi& E) {
;     ...
;         for (int t = 0; t < nt; t += 2) {
;     ...
;             PG8_LDA(At, 1, 1); PG8_STAGE(PG8_SB(1, 0), b3, voffB); PG8_STAGE(PG8_SB(1, 1), b3 + hstep, voffB); PG8_STAGE(PG8_SA(1, 0), a3, voffA);
;             PG8_WAIT_V(8); PG8_WAIT_L(0); PG8_BAR; PG8_MMA(1, 0, At, B0); PG8_MMA(1, 1, At, B1); PG8_BAR; PG8_SCHED;
	s_add_i32 s0, s41, s68
	v_lshl_add_u64 v[198:199], v[198:199], 0, s[22:23]
	s_mov_b32 m0, s0
	ds_read_b128 v[182:185], v157 offset:49152
	ds_read_b128 v[186:189], v157 offset:50176
	ds_read_b128 v[190:193], v157 offset:51200
	ds_read_b128 v[194:197], v157 offset:52224
	ds_read_b128 v[204:207], v157 offset:53248
	ds_read_b128 v[208:211], v157 offset:54272
	ds_read_b128 v[212:215], v157 offset:55296
	ds_read_b128 v[236:239], v157 offset:56320
	global_load_lds_dwordx4 v[198:199], off
	v_lshl_add_u64 v[198:199], v[240:241], 0, s[22:23]
	s_add_i32 m0, s0, 0x2000
	s_add_i32 s0, s44, s68
	global_load_lds_dwordx4 v[198:199], off
	v_lshl_add_u64 v[198:199], v[242:243], 0, s[22:23]
	s_mov_b32 m0, s0
	s_nop 0
	global_load_lds_dwordx4 v[198:199], off
	v_lshl_add_u64 v[198:199], v[244:245], 0, s[22:23]
	s_add_i32 m0, s0, 0x2000
	s_nop 0
	global_load_lds_dwordx4 v[198:199], off
	v_lshl_add_u64 v[198:199], v[246:247], 0, s[22:23]
	s_mov_b32 m0, s76
	s_nop 0
	global_load_lds_dwordx4 v[198:199], off
	v_lshl_add_u64 v[198:199], v[248:249], 0, s[22:23]
	s_mov_b32 m0, s77
	s_nop 0
	global_load_lds_dwordx4 v[198:199], off
	s_waitcnt vmcnt(8)
	s_waitcnt lgkmcnt(0)
	s_barrier
	s_waitcnt lgkmcnt(0)
	v_mfma_f32_16x16x32_bf16 v[104:107], v[148:151], v[182:185], v[104:107]
	v_mfma_f32_16x16x32_bf16 v[100:103], v[158:161], v[182:185], v[100:103]
	v_mfma_f32_16x16x32_bf16 v[96:99], v[148:151], v[190:193], v[96:99]
	v_mfma_f32_16x16x32_bf16 v[92:95], v[158:161], v[190:193], v[92:95]
	v_mfma_f32_16x16x32_bf16 v[88:91], v[148:151], v[204:207], v[88:91]
	v_mfma_f32_16x16x32_bf16 v[84:87], v[158:161], v[204:207], v[84:87]
	v_mfma_f32_16x16x32_bf16 v[80:83], v[148:151], v[212:215], v[80:83]
	v_mfma_f32_16x16x32_bf16 v[76:79], v[158:161], v[212:215], v[76:79]
	v_mfma_f32_16x16x32_bf16 v[104:107], v[152:155], v[186:189], v[104:107]
	v_mfma_f32_16x16x32_bf16 v[100:103], v[162:165], v[186:189], v[100:103]
	v_mfma_f32_16x16x32_bf16 v[96:99], v[152:155], v[194:197], v[96:99]
	v_mfma_f32_16x16x32_bf16 v[92:95], v[162:165], v[194:197], v[92:95]
	v_mfma_f32_16x16x32_bf16 v[88:91], v[152:155], v[208:211], v[88:91]
	v_mfma_f32_16x16x32_bf16 v[84:87], v[162:165], v[208:211], v[84:87]
	v_mfma_f32_16x16x32_bf16 v[80:83], v[152:155], v[236:239], v[80:83]
	v_mfma_f32_16x16x32_bf16 v[76:79], v[162:165], v[236:239], v[76:79]
	v_mfma_f32_16x16x32_bf16 v[28:31], v[166:169], v[182:185], v[28:31]
	v_mfma_f32_16x16x32_bf16 v[24:27], v[174:177], v[182:185], v[24:27]
	v_mfma_f32_16x16x32_bf16 v[20:23], v[166:169], v[190:193], v[20:23]
	v_mfma_f32_16x16x32_bf16 v[16:19], v[174:177], v[190:193], v[16:19]
	v_mfma_f32_16x16x32_bf16 v[12:15], v[166:169], v[204:207], v[12:15]
	v_mfma_f32_16x16x32_bf16 v[8:11], v[174:177], v[204:207], v[8:11]
	v_mfma_f32_16x16x32_bf16 v[4:7], v[166:169], v[212:215], v[4:7]
	v_mfma_f32_16x16x32_bf16 v[0:3], v[174:177], v[212:215], v[0:3]
	v_mfma_f32_16x16x32_bf16 v[28:31], v[170:173], v[186:189], v[28:31]
	v_mfma_f32_16x16x32_bf16 v[24:27], v[178:181], v[186:189], v[24:27]
	v_mfma_f32_16x16x32_bf16 v[20:23], v[170:173], v[194:197], v[20:23]
	v_mfma_f32_16x16x32_bf16 v[16:19], v[178:181], v[194:197], v[16:19]
	v_mfma_f32_16x16x32_bf16 v[12:15], v[170:173], v[208:211], v[12:15]
	v_mfma_f32_16x16x32_bf16 v[8:11], v[178:181], v[208:211], v[8:11]
	v_mfma_f32_16x16x32_bf16 v[4:7], v[170:173], v[236:239], v[4:7]
	v_mfma_f32_16x16x32_bf16 v[0:3], v[178:181], v[236:239], v[0:3]
	s_barrier
	s_add_u32 s24, s24, 0x100
	s_addc_u32 s25, s25, 0
	s_add_u32 s18, s18, 0x100
	s_addc_u32 s19, s19, 0
	s_cmp_ge_i32 s40, s73
	s_mov_b32 s0, s40
	s_cbranch_scc0 .LBB0_532

; #define PG8_STAGE(bufoff, gbase, voff) do { _Pragma("unroll") for (int _i = 0; _i < 2; ++_i) \
;         __builtin_amdgcn_global_load_lds((const unsigned*)((const char*)(gbase) + (voff)[_i]), (PG8_LAS unsigned*)(lds + (bufoff) + ldsw + _i * 8192), 16, 0, 0); } while (0)
; #define PG8_LDA(dst, b, h) do { _Pragma("unroll") for (int m = 0; m < 4; ++m) _Pragma("unroll") for (int k = 0; k < 2; ++k) dst[m][k] = *(const PG8_LAS bf16x8*)(lds + PG8_SA(b, h) + aoff + m * 2048 + k * 1024); } while (0)
; #define PG8_LDB(dst, b, h) do { _Pragma("unroll") for (int n = 0; n < 2; ++n) _Pragma("unroll") for (int k = 0; k < 2; ++k) dst[n][k] = *(const PG8_LAS bf16x8*)(lds + PG8_SB(b, h) + boff + n * 2048 + k * 1024); } while (0)
; #define PG8_MMA(ai, bj, At, Bt) do { __builtin_amdgcn_s_setprio(1); _Pragma("unroll") for (int m = 0; m < 4; ++m) _Pragma("unroll") for (int n = 0; n < 2; ++n) _Pragma("unroll") for (int k = 0; k < 2; ++k) \
;         acc[ai][bj][m][n] = __builtin_amdgcn_mfma_f32_16x16x32_bf16(Bt[n][k], At[m][k], acc[ai][bj][m][n], 0, 0, 0); __builtin_amdgcn_s_setprio(0); } while (0)
; #define PG8_WAIT_V(n) asm volatile("s_waitcnt vmcnt(" #n ")" ::: "memory")
; #define PG8_WAIT_L(n) asm volatile("s_waitcnt lgkmcnt(" #n ")" ::: "memory")
; #define PG8_BAR __builtin_amdgcn_s_barrier()
; #define PG8_SCHED __builtin_amdgcn_sched_barrier(0)
; template <class Epi, class Sched, bool ALIGN_EPI = false, bool SP2 = false>
; __device__ __forceinline__ void gemm_phase(PG8_LAS unsigned char* lds, const Gemm g, const Sched& S, const Epi& E) {
;     ...
;         for (int t = 0; t < nt; t += 2) {
;             const bool last = (t == nt - 2);
;             const char* a1 = cA + (size_t)(t + 1) * kstep;
;             const char* a2 = last ? nA : cA + (size_t)(t + 2) * kstep; const char* b2 = last ? nB : cB + (size_t)(t + 2) * kstep;
;             const char* a3 = a2 + kstep; const char* b3 = b2 + kstep;
;             if (last && has_next) S.a_ready(nxt);
;             if constexpr (SP2) {
;             PG8_LDB(B0, 0, 0); PG8_LDB(B1, 0, 1); PG8_SCHED; PG8_LDA(At, 0, 0); PG8_STAGE(PG8_SA(1, 1), a1 + hstep, voffA);
;             PG8_WAIT_V(8); PG8_WAIT_L(0); PG8_BAR; PG8_MMA(0, 0, At, B0); PG8_MMA(0, 1, At, B1); PG8_BAR; PG8_SCHED;
;             PG8_LDA(At, 0, 1); PG8_STAGE(PG8_SB(0, 0), b2, voffB); PG8_STAGE(PG8_SB(0, 1), b2 + hstep, voffB); PG8_STAGE(PG8_SA(0, 0), a2, voffA);
.LBB0_595:
	s_add_i32 s40, s0, 2
	s_add_u32 s41, s24, 0x80
	s_addc_u32 s1, s25, 0
	s_add_i32 s75, 0, 0x10000
	s_cmp_eq_u32 s62, s0
	s_cselect_b32 s1, s45, s1
	s_cselect_b32 s0, s44, s41
	s_cselect_b32 s77, s47, s19
	s_cselect_b32 s76, s46, s18
	s_add_i32 s41, 0, 0x14000
	v_add_u32_e32 v162, s75, v160
	v_add_u32_e32 v178, s41, v160
	ds_read_b128 v[148:151], v162
	ds_read_b128 v[152:155], v162 offset:1024
	ds_read_b128 v[156:159], v162 offset:2048
	ds_read_b128 v[162:165], v162 offset:3072
	ds_read_b128 v[166:169], v178
	ds_read_b128 v[170:173], v178 offset:1024
	ds_read_b128 v[174:177], v178 offset:2048
	ds_read_b128 v[178:181], v178 offset:3072
	v_lshl_add_u64 v[198:199], s[24:25], 0, v[144:145]
	s_add_i32 m0, s53, 0xc000
	ds_read_b128 v[182:185], v161
	ds_read_b128 v[186:189], v161 offset:1024
	ds_read_b128 v[190:193], v161 offset:2048
	ds_read_b128 v[194:197], v161 offset:3072
	ds_read_b128 v[204:207], v161 offset:4096
	ds_read_b128 v[208:211], v161 offset:5120
	ds_read_b128 v[212:215], v161 offset:6144
	ds_read_b128 v[236:239], v161 offset:7168
	global_load_lds_dwordx4 v[198:199], off
	v_lshl_add_u64 v[198:199], s[24:25], 0, v[146:147]
	s_add_i32 m0, s53, 0xe000
	s_nop 0
	global_load_lds_dwordx4 v[198:199], off
	s_waitcnt vmcnt(8)
	s_waitcnt lgkmcnt(0)
	s_barrier
	s_waitcnt lgkmcnt(0)
	v_mfma_f32_16x16x32_bf16 v[132:135], v[148:151], v[182:185], v[132:135]
	v_mfma_f32_16x16x32_bf16 v[136:139], v[156:159], v[182:185], v[136:139]
	v_mfma_f32_16x16x32_bf16 v[128:131], v[148:151], v[190:193], v[128:131]
	v_mfma_f32_16x16x32_bf16 v[124:127], v[156:159], v[190:193], v[124:127]
	v_mfma_f32_16x16x32_bf16 v[120:123], v[148:151], v[204:207], v[120:123]
	v_mfma_f32_16x16x32_bf16 v[116:119], v[156:159], v[204:207], v[116:119]
	v_mfma_f32_16x16x32_bf16 v[112:115], v[148:151], v[212:215], v[112:115]
	v_mfma_f32_16x16x32_bf16 v[108:111], v[156:159], v[212:215], v[108:111]
	v_mfma_f32_16x16x32_bf16 v[132:135], v[152:155], v[186:189], v[132:135]
	v_mfma_f32_16x16x32_bf16 v[136:139], v[162:165], v[186:189], v[136:139]
	v_mfma_f32_16x16x32_bf16 v[128:131], v[152:155], v[194:197], v[128:131]
	v_mfma_f32_16x16x32_bf16 v[124:127], v[162:165], v[194:197], v[124:127]
	v_mfma_f32_16x16x32_bf16 v[120:123], v[152:155], v[208:211], v[120:123]
	v_mfma_f32_16x16x32_bf16 v[116:119], v[162:165], v[208:211], v[116:119]
	v_mfma_f32_16x16x32_bf16 v[112:115], v[152:155], v[236:239], v[112:115]
	v_mfma_f32_16x16x32_bf16 v[108:111], v[162:165], v[236:239], v[108:111]
	v_mfma_f32_16x16x32_bf16 v[72:75], v[166:169], v[182:185], v[72:75]
	v_mfma_f32_16x16x32_bf16 v[68:71], v[174:177], v[182:185], v[68:71]
	v_mfma_f32_16x16x32_bf16 v[64:67], v[166:169], v[190:193], v[64:67]
	v_mfma_f32_16x16x32_bf16 v[60:63], v[174:177], v[190:193], v[60:63]
	v_mfma_f32_16x16x32_bf16 v[56:59], v[166:169], v[204:207], v[56:59]
	v_mfma_f32_16x16x32_bf16 v[52:55], v[174:177], v[204:207], v[52:55]
	v_mfma_f32_16x16x32_bf16 v[48:51], v[166:169], v[212:215], v[48:51]
	v_mfma_f32_16x16x32_bf16 v[32:35], v[174:177], v[212:215], v[32:35]
	v_mfma_f32_16x16x32_bf16 v[72:75], v[170:173], v[186:189], v[72:75]
	v_mfma_f32_16x16x32_bf16 v[68:71], v[178:181], v[186:189], v[68:71]
	v_mfma_f32_16x16x32_bf16 v[64:67], v[170:173], v[194:197], v[64:67]
	v_mfma_f32_16x16x32_bf16 v[60:63], v[178:181], v[194:197], v[60:63]
	v_mfma_f32_16x16x32_bf16 v[56:59], v[170:173], v[208:211], v[56:59]
	v_mfma_f32_16x16x32_bf16 v[52:55], v[178:181], v[208:211], v[52:55]
	v_mfma_f32_16x16x32_bf16 v[48:51], v[170:173], v[236:239], v[48:51]
	v_mfma_f32_16x16x32_bf16 v[32:35], v[178:181], v[236:239], v[32:35]
	s_barrier
	s_add_i32 s75, s75, s52
	v_lshl_add_u64 v[198:199], s[76:77], 0, v[42:43]
	s_mov_b32 m0, s75
	ds_read_b128 v[182:185], v161 offset:16384
	ds_read_b128 v[186:189], v161 offset:17408
	ds_read_b128 v[190:193], v161 offset:18432
	ds_read_b128 v[194:197], v161 offset:19456
	ds_read_b128 v[204:207], v161 offset:20480
	ds_read_b128 v[208:211], v161 offset:21504
	ds_read_b128 v[212:215], v161 offset:22528
	ds_read_b128 v[236:239], v161 offset:23552
	global_load_lds_dwordx4 v[198:199], off
	s_add_i32 m0, s75, 0x2000
	v_lshl_add_u64 v[240:241], s[76:77], 0, v[142:143]
	s_add_u32 s76, s76, s10
	s_addc_u32 s77, s77, s11
	s_add_i32 s41, s41, s52
	global_load_lds_dwordx4 v[240:241], off
	v_lshl_add_u64 v[242:243], s[76:77], 0, v[42:43]
	s_mov_b32 m0, s41
	v_lshl_add_u64 v[244:245], s[76:77], 0, v[142:143]
	global_load_lds_dwordx4 v[242:243], off
	s_add_i32 m0, s41, 0x2000
	v_lshl_add_u64 v[246:247], s[0:1], 0, v[38:39]
	global_load_lds_dwordx4 v[244:245], off
	s_mov_b32 m0, s53
	v_lshl_add_u64 v[248:249], s[0:1], 0, v[140:141]
	global_load_lds_dwordx4 v[246:247], off
	s_mov_b32 m0, s54
	s_nop 0
	global_load_lds_dwordx4 v[248:249], off
	s_waitcnt vmcnt(8)
	s_waitcnt lgkmcnt(0)
	s_barrier
; #define PG8_STAGE(bufoff, gbase, voff) do { _Pragma("unroll") for (int _i = 0; _i < 2; ++_i) \
;         __builtin_amdgcn_global_load_lds((const unsigned*)((const char*)(gbase) + (voff)[_i]), (PG8_LAS unsigned*)(lds + (bufoff) + ldsw + _i * 8192), 16, 0, 0); } while (0)
; #define PG8_LDA(dst, b, h) do { _Pragma("unroll") for (int m = 0; m < 4; ++m) _Pragma("unroll") for (int k = 0; k < 2; ++k) dst[m][k] = *(const PG8_LAS bf16x8*)(lds + PG8_SA(b, h) + aoff + m * 2048 + k * 1024); } while (0)
; #define PG8_LDB(dst, b, h) do { _Pragma("unroll") for (int n = 0; n < 2; ++n) _Pragma("unroll") for (int k = 0; k < 2; ++k) dst[n][k] = *(const PG8_LAS bf16x8*)(lds + PG8_SB(b, h) + boff + n * 2048 + k * 1024); } while (0)
; #define PG8_MMA(ai, bj, At, Bt) do { __builtin_amdgcn_s_setprio(1); _Pragma("unroll") for (int m = 0; m < 4; ++m) _Pragma("unroll") for (int n = 0; n < 2; ++n) _Pragma("unroll") for (int k = 0; k < 2; ++k) \
;         acc[ai][bj][m][n] = __builtin_amdgcn_mfma_f32_16x16x32_bf16(Bt[n][k], At[m][k], acc[ai][bj][m][n], 0, 0, 0); __builtin_amdgcn_s_setprio(0); } while (0)
; #define PG8_WAIT_V(n) asm volatile("s_waitcnt vmcnt(" #n ")" ::: "memory")
; #define PG8_WAIT_L(n) asm volatile("s_waitcnt lgkmcnt(" #n ")" ::: "memory")
; #define PG8_BAR __builtin_amdgcn_s_barrier()
; #define PG8_SCHED __builtin_amdgcn_sched_barrier(0)
; template <class Epi, class Sched, bool ALIGN_EPI = false, bool SP2 = false>
; __device__ __forceinline__ void gemm_phase(PG8_LAS unsigned char* lds, const Gemm g, const Sched& S, const Epi& E) {
;     ...
;             PG8_WAIT_V(8); PG8_WAIT_L(0); PG8_BAR; PG8_MMA(1, 0, At, B0); PG8_MMA(1, 1, At, B1); PG8_BAR; PG8_SCHED;
;             PG8_LDB(B0, 1, 0); PG8_LDB(B1, 1, 1); PG8_SCHED; PG8_LDA(At, 1, 0); PG8_STAGE(PG8_SA(0, 1), a2 + hstep, voffA);
;             PG8_WAIT_V(8); PG8_WAIT_L(0); PG8_BAR; PG8_MMA(0, 0, At, B0); PG8_MMA(0, 1, At, B1); PG8_BAR; PG8_SCHED;
	s_waitcnt lgkmcnt(0)
	v_mfma_f32_16x16x32_bf16 v[104:107], v[148:151], v[182:185], v[104:107]
	v_mfma_f32_16x16x32_bf16 v[100:103], v[156:159], v[182:185], v[100:103]
	v_mfma_f32_16x16x32_bf16 v[96:99], v[148:151], v[190:193], v[96:99]
	v_mfma_f32_16x16x32_bf16 v[92:95], v[156:159], v[190:193], v[92:95]
	v_mfma_f32_16x16x32_bf16 v[88:91], v[148:151], v[204:207], v[88:91]
	v_mfma_f32_16x16x32_bf16 v[84:87], v[156:159], v[204:207], v[84:87]
	v_mfma_f32_16x16x32_bf16 v[80:83], v[148:151], v[212:215], v[80:83]
	v_mfma_f32_16x16x32_bf16 v[76:79], v[156:159], v[212:215], v[76:79]
	v_mfma_f32_16x16x32_bf16 v[104:107], v[152:155], v[186:189], v[104:107]
	v_mfma_f32_16x16x32_bf16 v[100:103], v[162:165], v[186:189], v[100:103]
	v_mfma_f32_16x16x32_bf16 v[96:99], v[152:155], v[194:197], v[96:99]
	v_mfma_f32_16x16x32_bf16 v[92:95], v[162:165], v[194:197], v[92:95]
	v_mfma_f32_16x16x32_bf16 v[88:91], v[152:155], v[208:211], v[88:91]
	v_mfma_f32_16x16x32_bf16 v[84:87], v[162:165], v[208:211], v[84:87]
	v_mfma_f32_16x16x32_bf16 v[80:83], v[152:155], v[236:239], v[80:83]
	v_mfma_f32_16x16x32_bf16 v[76:79], v[162:165], v[236:239], v[76:79]
	v_mfma_f32_16x16x32_bf16 v[28:31], v[166:169], v[182:185], v[28:31]
	v_mfma_f32_16x16x32_bf16 v[24:27], v[174:177], v[182:185], v[24:27]
	v_mfma_f32_16x16x32_bf16 v[20:23], v[166:169], v[190:193], v[20:23]
	v_mfma_f32_16x16x32_bf16 v[16:19], v[174:177], v[190:193], v[16:19]
	v_mfma_f32_16x16x32_bf16 v[12:15], v[166:169], v[204:207], v[12:15]
	v_mfma_f32_16x16x32_bf16 v[8:11], v[174:177], v[204:207], v[8:11]
	v_mfma_f32_16x16x32_bf16 v[4:7], v[166:169], v[212:215], v[4:7]
	v_mfma_f32_16x16x32_bf16 v[0:3], v[174:177], v[212:215], v[0:3]
	v_mfma_f32_16x16x32_bf16 v[28:31], v[170:173], v[186:189], v[28:31]
	v_mfma_f32_16x16x32_bf16 v[24:27], v[178:181], v[186:189], v[24:27]
	v_mfma_f32_16x16x32_bf16 v[20:23], v[170:173], v[194:197], v[20:23]
	v_mfma_f32_16x16x32_bf16 v[16:19], v[178:181], v[194:197], v[16:19]
	v_mfma_f32_16x16x32_bf16 v[12:15], v[170:173], v[208:211], v[12:15]
	v_mfma_f32_16x16x32_bf16 v[8:11], v[178:181], v[208:211], v[8:11]
	v_mfma_f32_16x16x32_bf16 v[4:7], v[170:173], v[236:239], v[4:7]
	v_mfma_f32_16x16x32_bf16 v[0:3], v[178:181], v[236:239], v[0:3]
	s_barrier
	s_add_i32 s41, 0, 0x18000
	s_add_i32 s75, 0, 0x1c000
	v_add_u32_e32 v162, s41, v160
	v_add_u32_e32 v178, s75, v160
	ds_read_b128 v[148:151], v162
	ds_read_b128 v[152:155], v162 offset:1024
	ds_read_b128 v[156:159], v162 offset:2048
	ds_read_b128 v[162:165], v162 offset:3072
	ds_read_b128 v[166:169], v178
	ds_read_b128 v[170:173], v178 offset:1024
	ds_read_b128 v[174:177], v178 offset:2048
	ds_read_b128 v[178:181], v178 offset:3072
	s_add_u32 s0, s0, s10
	s_addc_u32 s1, s1, s11
	s_mov_b32 m0, s55
	v_lshl_add_u64 v[250:251], s[0:1], 0, v[38:39]
	ds_read_b128 v[182:185], v161 offset:32768
	ds_read_b128 v[186:189], v161 offset:33792
	ds_read_b128 v[190:193], v161 offset:34816
	ds_read_b128 v[194:197], v161 offset:35840
	ds_read_b128 v[204:207], v161 offset:36864
	ds_read_b128 v[208:211], v161 offset:37888
	ds_read_b128 v[212:215], v161 offset:38912
	ds_read_b128 v[236:239], v161 offset:39936
	global_load_lds_dwordx4 v[250:251], off
	v_lshl_add_u64 v[250:251], s[0:1], 0, v[140:141]
	s_mov_b32 m0, s56
	s_nop 0
	global_load_lds_dwordx4 v[250:251], off
	s_waitcnt vmcnt(8)
	s_waitcnt lgkmcnt(0)
	s_barrier
	s_waitcnt lgkmcnt(0)
	v_mfma_f32_16x16x32_bf16 v[132:135], v[148:151], v[182:185], v[132:135]
	v_mfma_f32_16x16x32_bf16 v[136:139], v[156:159], v[182:185], v[136:139]
	v_mfma_f32_16x16x32_bf16 v[128:131], v[148:151], v[190:193], v[128:131]
	v_mfma_f32_16x16x32_bf16 v[124:127], v[156:159], v[190:193], v[124:127]
	v_mfma_f32_16x16x32_bf16 v[120:123], v[148:151], v[204:207], v[120:123]
	v_mfma_f32_16x16x32_bf16 v[116:119], v[156:159], v[204:207], v[116:119]
	v_mfma_f32_16x16x32_bf16 v[112:115], v[148:151], v[212:215], v[112:115]
	v_mfma_f32_16x16x32_bf16 v[108:111], v[156:159], v[212:215], v[108:111]
	v_mfma_f32_16x16x32_bf16 v[132:135], v[152:155], v[186:189], v[132:135]
	v_mfma_f32_16x16x32_bf16 v[136:139], v[162:165], v[186:189], v[136:139]
	v_mfma_f32_16x16x32_bf16 v[128:131], v[152:155], v[194:197], v[128:131]
	v_mfma_f32_16x16x32_bf16 v[124:127], v[162:165], v[194:197], v[124:127]
	v_mfma_f32_16x16x32_bf16 v[120:123], v[152:155], v[208:211], v[120:123]
	v_mfma_f32_16x16x32_bf16 v[116:119], v[162:165], v[208:211], v[116:119]
	v_mfma_f32_16x16x32_bf16 v[112:115], v[152:155], v[236:239], v[112:115]
	v_mfma_f32_16x16x32_bf16 v[108:111], v[162:165], v[236:239], v[108:111]
	v_mfma_f32_16x16x32_bf16 v[72:75], v[166:169], v[182:185], v[72:75]
	v_mfma_f32_16x16x32_bf16 v[68:71], v[174:177], v[182:185], v[68:71]
	v_mfma_f32_16x16x32_bf16 v[64:67], v[166:169], v[190:193], v[64:67]
	v_mfma_f32_16x16x32_bf16 v[60:63], v[174:177], v[190:193], v[60:63]
	v_mfma_f32_16x16x32_bf16 v[56:59], v[166:169], v[204:207], v[56:59]
	v_mfma_f32_16x16x32_bf16 v[52:55], v[174:177], v[204:207], v[52:55]
	v_mfma_f32_16x16x32_bf16 v[48:51], v[166:169], v[212:215], v[48:51]
	v_mfma_f32_16x16x32_bf16 v[32:35], v[174:177], v[212:215], v[32:35]
	v_mfma_f32_16x16x32_bf16 v[72:75], v[170:173], v[186:189], v[72:75]
	v_mfma_f32_16x16x32_bf16 v[68:71], v[178:181], v[186:189], v[68:71]
	v_mfma_f32_16x16x32_bf16 v[64:67], v[170:173], v[194:197], v[64:67]
	v_mfma_f32_16x16x32_bf16 v[60:63], v[178:181], v[194:197], v[60:63]
	v_mfma_f32_16x16x32_bf16 v[56:59], v[170:173], v[208:211], v[56:59]
	v_mfma_f32_16x16x32_bf16 v[52:55], v[178:181], v[208:211], v[52:55]
	v_mfma_f32_16x16x32_bf16 v[48:51], v[170:173], v[236:239], v[48:51]
	v_mfma_f32_16x16x32_bf16 v[32:35], v[178:181], v[236:239], v[32:35]
	s_barrier
; #define PG8_STAGE(bufoff, gbase, voff) do { _Pragma("unroll") for (int _i = 0; _i < 2; ++_i) \
;         __builtin_amdgcn_global_load_lds((const unsigned*)((const char*)(gbase) + (voff)[_i]), (PG8_LAS unsigned*)(lds + (bufoff) + ldsw + _i * 8192), 16, 0, 0); } while (0)
; #define PG8_LDA(dst, b, h) do { _Pragma("unroll") for (int m = 0; m < 4; ++m) _Pragma("unroll") for (int k = 0; k < 2; ++k) dst[m][k] = *(const PG8_LAS bf16x8*)(lds + PG8_SA(b, h) + aoff + m * 2048 + k * 1024); } while (0)
; #define PG8_MMA(ai, bj, At, Bt) do { __builtin_amdgcn_s_setprio(1); _Pragma("unroll") for (int m = 0; m < 4; ++m) _Pragma("unroll") for (int n = 0; n < 2; ++n) _Pragma("unroll") for (int k = 0; k < 2; ++k) \
;         acc[ai][bj][m][n] = __builtin_amdgcn_mfma_f32_16x16x32_bf16(Bt[n][k], At[m][k], acc[ai][bj][m][n], 0, 0, 0); __builtin_amdgcn_s_setprio(0); } while (0)
; #define PG8_WAIT_V(n) asm volatile("s_waitcnt vmcnt(" #n ")" ::: "memory")
; #define PG8_WAIT_L(n) asm volatile("s_waitcnt lgkmcnt(" #n ")" ::: "memory")
; #define PG8_BAR __builtin_amdgcn_s_barrier()
; #define PG8_SCHED __builtin_amdgcn_sched_barrier(0)
; template <class Epi, class Sched, bool ALIGN_EPI = false, bool SP2 = false>
; __device__ __forceinline__ void gemm_phase(PG8_LAS unsigned char* lds, const Gemm g, const Sched& S, const Epi& E) {
;     ...
;         for (int t = 0; t < nt; t += 2) {
;     ...
;             PG8_LDA(At, 1, 1); PG8_STAGE(PG8_SB(1, 0), b3, voffB); PG8_STAGE(PG8_SB(1, 1), b3 + hstep, voffB); PG8_STAGE(PG8_SA(1, 0), a3, voffA);
;             PG8_WAIT_V(8); PG8_WAIT_L(0); PG8_BAR; PG8_MMA(1, 0, At, B0); PG8_MMA(1, 1, At, B1); PG8_BAR; PG8_SCHED;
	s_add_i32 s0, s41, s52
	v_lshl_add_u64 v[198:199], v[198:199], 0, s[22:23]
	s_mov_b32 m0, s0
	ds_read_b128 v[182:185], v161 offset:49152
	ds_read_b128 v[186:189], v161 offset:50176
	ds_read_b128 v[190:193], v161 offset:51200
	ds_read_b128 v[194:197], v161 offset:52224
	ds_read_b128 v[204:207], v161 offset:53248
	ds_read_b128 v[208:211], v161 offset:54272
	ds_read_b128 v[212:215], v161 offset:55296
	ds_read_b128 v[236:239], v161 offset:56320
	global_load_lds_dwordx4 v[198:199], off
	v_lshl_add_u64 v[198:199], v[240:241], 0, s[22:23]
	s_add_i32 m0, s0, 0x2000
	s_add_i32 s0, s75, s52
	global_load_lds_dwordx4 v[198:199], off
	v_lshl_add_u64 v[198:199], v[242:243], 0, s[22:23]
	s_mov_b32 m0, s0
	s_nop 0
	global_load_lds_dwordx4 v[198:199], off
	v_lshl_add_u64 v[198:199], v[244:245], 0, s[22:23]
	s_add_i32 m0, s0, 0x2000
	s_nop 0
	global_load_lds_dwordx4 v[198:199], off
	v_lshl_add_u64 v[198:199], v[246:247], 0, s[22:23]
	s_mov_b32 m0, s60
	s_nop 0
	global_load_lds_dwordx4 v[198:199], off
	v_lshl_add_u64 v[198:199], v[248:249], 0, s[22:23]
	s_mov_b32 m0, s61
	s_nop 0
	global_load_lds_dwordx4 v[198:199], off
	s_waitcnt vmcnt(8)
	s_waitcnt lgkmcnt(0)
	s_barrier
	s_waitcnt lgkmcnt(0)
	v_mfma_f32_16x16x32_bf16 v[104:107], v[148:151], v[182:185], v[104:107]
	v_mfma_f32_16x16x32_bf16 v[100:103], v[156:159], v[182:185], v[100:103]
	v_mfma_f32_16x16x32_bf16 v[96:99], v[148:151], v[190:193], v[96:99]
	v_mfma_f32_16x16x32_bf16 v[92:95], v[156:159], v[190:193], v[92:95]
	v_mfma_f32_16x16x32_bf16 v[88:91], v[148:151], v[204:207], v[88:91]
	v_mfma_f32_16x16x32_bf16 v[84:87], v[156:159], v[204:207], v[84:87]
	v_mfma_f32_16x16x32_bf16 v[80:83], v[148:151], v[212:215], v[80:83]
	v_mfma_f32_16x16x32_bf16 v[76:79], v[156:159], v[212:215], v[76:79]
	v_mfma_f32_16x16x32_bf16 v[104:107], v[152:155], v[186:189], v[104:107]
	v_mfma_f32_16x16x32_bf16 v[100:103], v[162:165], v[186:189], v[100:103]
	v_mfma_f32_16x16x32_bf16 v[96:99], v[152:155], v[194:197], v[96:99]
	v_mfma_f32_16x16x32_bf16 v[92:95], v[162:165], v[194:197], v[92:95]
	v_mfma_f32_16x16x32_bf16 v[88:91], v[152:155], v[208:211], v[88:91]
	v_mfma_f32_16x16x32_bf16 v[84:87], v[162:165], v[208:211], v[84:87]
	v_mfma_f32_16x16x32_bf16 v[80:83], v[152:155], v[236:239], v[80:83]
	v_mfma_f32_16x16x32_bf16 v[76:79], v[162:165], v[236:239], v[76:79]
	v_mfma_f32_16x16x32_bf16 v[28:31], v[166:169], v[182:185], v[28:31]
	v_mfma_f32_16x16x32_bf16 v[24:27], v[174:177], v[182:185], v[24:27]
	v_mfma_f32_16x16x32_bf16 v[20:23], v[166:169], v[190:193], v[20:23]
	v_mfma_f32_16x16x32_bf16 v[16:19], v[174:177], v[190:193], v[16:19]
	v_mfma_f32_16x16x32_bf16 v[12:15], v[166:169], v[204:207], v[12:15]
	v_mfma_f32_16x16x32_bf16 v[8:11], v[174:177], v[204:207], v[8:11]
	v_mfma_f32_16x16x32_bf16 v[4:7], v[166:169], v[212:215], v[4:7]
	v_mfma_f32_16x16x32_bf16 v[0:3], v[174:177], v[212:215], v[0:3]
	v_mfma_f32_16x16x32_bf16 v[28:31], v[170:173], v[186:189], v[28:31]
	v_mfma_f32_16x16x32_bf16 v[24:27], v[178:181], v[186:189], v[24:27]
	v_mfma_f32_16x16x32_bf16 v[20:23], v[170:173], v[194:197], v[20:23]
	v_mfma_f32_16x16x32_bf16 v[16:19], v[178:181], v[194:197], v[16:19]
	v_mfma_f32_16x16x32_bf16 v[12:15], v[170:173], v[208:211], v[12:15]
	v_mfma_f32_16x16x32_bf16 v[8:11], v[178:181], v[208:211], v[8:11]
	v_mfma_f32_16x16x32_bf16 v[4:7], v[170:173], v[236:239], v[4:7]
	v_mfma_f32_16x16x32_bf16 v[0:3], v[178:181], v[236:239], v[0:3]
	s_barrier
	s_add_u32 s24, s24, 0x100
	s_addc_u32 s25, s25, 0
	s_add_u32 s18, s18, 0x100
	s_addc_u32 s19, s19, 0
	s_cmp_ge_i32 s40, s57
	s_mov_b32 s0, s40
	s_cbranch_scc0 .LBB0_595
	s_movk_i32 s76, 0x90

; #define PG8_STAGE(bufoff, gbase, voff) do { _Pragma("unroll") for (int _i = 0; _i < 2; ++_i) \
;         __builtin_amdgcn_global_load_lds((const unsigned*)((const char*)(gbase) + (voff)[_i]), (PG8_LAS unsigned*)(lds + (bufoff) + ldsw + _i * 8192), 16, 0, 0); } while (0)
; #define PG8_LDA(dst, b, h) do { _Pragma("unroll") for (int m = 0; m < 4; ++m) _Pragma("unroll") for (int k = 0; k < 2; ++k) dst[m][k] = *(const PG8_LAS bf16x8*)(lds + PG8_SA(b, h) + aoff + m * 2048 + k * 1024); } while (0)
; #define PG8_LDB(dst, b, h) do { _Pragma("unroll") for (int n = 0; n < 2; ++n) _Pragma("unroll") for (int k = 0; k < 2; ++k) dst[n][k] = *(const PG8_LAS bf16x8*)(lds + PG8_SB(b, h) + boff + n * 2048 + k * 1024); } while (0)
; #define PG8_MMA(ai, bj, At, Bt) do { __builtin_amdgcn_s_setprio(1); _Pragma("unroll") for (int m = 0; m < 4; ++m) _Pragma("unroll") for (int n = 0; n < 2; ++n) _Pragma("unroll") for (int k = 0; k < 2; ++k) \
;         acc[ai][bj][m][n] = __builtin_amdgcn_mfma_f32_16x16x32_bf16(Bt[n][k], At[m][k], acc[ai][bj][m][n], 0, 0, 0); __builtin_amdgcn_s_setprio(0); } while (0)
; #define PG8_WAIT_V(n) asm volatile("s_waitcnt vmcnt(" #n ")" ::: "memory")
; #define PG8_WAIT_L(n) asm volatile("s_waitcnt lgkmcnt(" #n ")" ::: "memory")
; #define PG8_BAR __builtin_amdgcn_s_barrier()
; #define PG8_SCHED __builtin_amdgcn_sched_barrier(0)
; template <class Epi, class Sched, bool ALIGN_EPI = false, bool SP2 = false>
; __device__ __forceinline__ void gemm_phase(PG8_LAS unsigned char* lds, const Gemm g, const Sched& S, const Epi& E) {
;     ...
;         for (int t = 0; t < nt; t += 2) {
;             const bool last = (t == nt - 2);
;             const char* a1 = cA + (size_t)(t + 1) * kstep;
;             const char* a2 = last ? nA : cA + (size_t)(t + 2) * kstep; const char* b2 = last ? nB : cB + (size_t)(t + 2) * kstep;
;             const char* a3 = a2 + kstep; const char* b3 = b2 + kstep;
;             if (last && has_next) S.a_ready(nxt);
;             if constexpr (SP2) {
;             PG8_LDB(B0, 0, 0); PG8_LDB(B1, 0, 1); PG8_SCHED; PG8_LDA(At, 0, 0); PG8_STAGE(PG8_SA(1, 1), a1 + hstep, voffA);
;             PG8_WAIT_V(8); PG8_WAIT_L(0); PG8_BAR; PG8_MMA(0, 0, At, B0); PG8_MMA(0, 1, At, B1); PG8_BAR; PG8_SCHED;
;             PG8_LDA(At, 0, 1); PG8_STAGE(PG8_SB(0, 0), b2, voffB); PG8_STAGE(PG8_SB(0, 1), b2 + hstep, voffB); PG8_STAGE(PG8_SA(0, 0), a2, voffA);
.LBB0_753:
	s_add_i32 s36, s0, 2
	s_add_u32 s37, s24, 0x80
	s_addc_u32 s1, s25, 0
	s_add_i32 s44, 0, 0x10000
	s_cmp_eq_u32 s11, s0
	s_cselect_b32 s1, s29, s1
	s_cselect_b32 s0, s28, s37
	s_cselect_b32 s41, s31, s19
	s_cselect_b32 s40, s30, s18
	s_add_i32 s37, 0, 0x14000
	v_add_u32_e32 v160, s44, v164
	v_add_u32_e32 v178, s37, v164
	ds_read_b128 v[148:151], v160
	ds_read_b128 v[152:155], v160 offset:1024
	ds_read_b128 v[156:159], v160 offset:2048
	ds_read_b128 v[160:163], v160 offset:3072
	ds_read_b128 v[166:169], v178
	ds_read_b128 v[170:173], v178 offset:1024
	ds_read_b128 v[174:177], v178 offset:2048
	ds_read_b128 v[178:181], v178 offset:3072
	v_lshl_add_u64 v[198:199], s[24:25], 0, v[144:145]
	s_add_i32 m0, s38, 0xc000
	ds_read_b128 v[182:185], v165
	ds_read_b128 v[186:189], v165 offset:1024
	ds_read_b128 v[190:193], v165 offset:2048
	ds_read_b128 v[194:197], v165 offset:3072
	ds_read_b128 v[204:207], v165 offset:4096
	ds_read_b128 v[208:211], v165 offset:5120
	ds_read_b128 v[212:215], v165 offset:6144
	ds_read_b128 v[236:239], v165 offset:7168
	global_load_lds_dwordx4 v[198:199], off
	v_lshl_add_u64 v[198:199], s[24:25], 0, v[146:147]
	s_add_i32 m0, s38, 0xe000
	s_nop 0
	global_load_lds_dwordx4 v[198:199], off
	s_waitcnt vmcnt(8)
	s_waitcnt lgkmcnt(0)
	s_barrier
	s_waitcnt lgkmcnt(0)
	v_mfma_f32_16x16x32_bf16 v[28:31], v[148:151], v[182:185], v[28:31]
	v_mfma_f32_16x16x32_bf16 v[32:35], v[156:159], v[182:185], v[32:35]
	v_mfma_f32_16x16x32_bf16 v[24:27], v[148:151], v[190:193], v[24:27]
	v_mfma_f32_16x16x32_bf16 v[136:139], v[156:159], v[190:193], v[136:139]
	v_mfma_f32_16x16x32_bf16 v[20:23], v[148:151], v[204:207], v[20:23]
	v_mfma_f32_16x16x32_bf16 v[132:135], v[156:159], v[204:207], v[132:135]
	v_mfma_f32_16x16x32_bf16 v[16:19], v[148:151], v[212:215], v[16:19]
	v_mfma_f32_16x16x32_bf16 v[128:131], v[156:159], v[212:215], v[128:131]
	v_mfma_f32_16x16x32_bf16 v[28:31], v[152:155], v[186:189], v[28:31]
	v_mfma_f32_16x16x32_bf16 v[32:35], v[160:163], v[186:189], v[32:35]
	v_mfma_f32_16x16x32_bf16 v[24:27], v[152:155], v[194:197], v[24:27]
	v_mfma_f32_16x16x32_bf16 v[136:139], v[160:163], v[194:197], v[136:139]
	v_mfma_f32_16x16x32_bf16 v[20:23], v[152:155], v[208:211], v[20:23]
	v_mfma_f32_16x16x32_bf16 v[132:135], v[160:163], v[208:211], v[132:135]
	v_mfma_f32_16x16x32_bf16 v[16:19], v[152:155], v[236:239], v[16:19]
	v_mfma_f32_16x16x32_bf16 v[128:131], v[160:163], v[236:239], v[128:131]
	v_mfma_f32_16x16x32_bf16 v[108:111], v[166:169], v[182:185], v[108:111]
	v_mfma_f32_16x16x32_bf16 v[104:107], v[174:177], v[182:185], v[104:107]
	v_mfma_f32_16x16x32_bf16 v[100:103], v[166:169], v[190:193], v[100:103]
	v_mfma_f32_16x16x32_bf16 v[96:99], v[174:177], v[190:193], v[96:99]
	v_mfma_f32_16x16x32_bf16 v[92:95], v[166:169], v[204:207], v[92:95]
	v_mfma_f32_16x16x32_bf16 v[88:91], v[174:177], v[204:207], v[88:91]
	v_mfma_f32_16x16x32_bf16 v[84:87], v[166:169], v[212:215], v[84:87]
	v_mfma_f32_16x16x32_bf16 v[80:83], v[174:177], v[212:215], v[80:83]
	v_mfma_f32_16x16x32_bf16 v[108:111], v[170:173], v[186:189], v[108:111]
	v_mfma_f32_16x16x32_bf16 v[104:107], v[178:181], v[186:189], v[104:107]
	v_mfma_f32_16x16x32_bf16 v[100:103], v[170:173], v[194:197], v[100:103]
	v_mfma_f32_16x16x32_bf16 v[96:99], v[178:181], v[194:197], v[96:99]
	v_mfma_f32_16x16x32_bf16 v[92:95], v[170:173], v[208:211], v[92:95]
	v_mfma_f32_16x16x32_bf16 v[88:91], v[178:181], v[208:211], v[88:91]
	v_mfma_f32_16x16x32_bf16 v[84:87], v[170:173], v[236:239], v[84:87]
	v_mfma_f32_16x16x32_bf16 v[80:83], v[178:181], v[236:239], v[80:83]
	s_barrier
	s_add_i32 s44, s44, s13
	v_lshl_add_u64 v[198:199], s[40:41], 0, v[42:43]
	s_mov_b32 m0, s44
	ds_read_b128 v[182:185], v165 offset:16384
	ds_read_b128 v[186:189], v165 offset:17408
	ds_read_b128 v[190:193], v165 offset:18432
	ds_read_b128 v[194:197], v165 offset:19456
	ds_read_b128 v[204:207], v165 offset:20480
	ds_read_b128 v[208:211], v165 offset:21504
	ds_read_b128 v[212:215], v165 offset:22528
	ds_read_b128 v[236:239], v165 offset:23552
	global_load_lds_dwordx4 v[198:199], off
	s_add_i32 m0, s44, 0x2000
	v_lshl_add_u64 v[240:241], s[40:41], 0, v[142:143]
	s_add_u32 s40, s40, s34
	s_addc_u32 s41, s41, s35
	s_add_i32 s37, s37, s13
	global_load_lds_dwordx4 v[240:241], off
	v_lshl_add_u64 v[242:243], s[40:41], 0, v[42:43]
	s_mov_b32 m0, s37
	v_lshl_add_u64 v[244:245], s[40:41], 0, v[142:143]
	global_load_lds_dwordx4 v[242:243], off
	s_add_i32 m0, s37, 0x2000
	v_lshl_add_u64 v[246:247], s[0:1], 0, v[38:39]
	global_load_lds_dwordx4 v[244:245], off
	s_mov_b32 m0, s38
	v_lshl_add_u64 v[248:249], s[0:1], 0, v[140:141]
	global_load_lds_dwordx4 v[246:247], off
	s_mov_b32 m0, s39
	s_nop 0
	global_load_lds_dwordx4 v[248:249], off
	s_waitcnt vmcnt(8)
	s_waitcnt lgkmcnt(0)
	s_barrier
; #define PG8_STAGE(bufoff, gbase, voff) do { _Pragma("unroll") for (int _i = 0; _i < 2; ++_i) \
;         __builtin_amdgcn_global_load_lds((const unsigned*)((const char*)(gbase) + (voff)[_i]), (PG8_LAS unsigned*)(lds + (bufoff) + ldsw + _i * 8192), 16, 0, 0); } while (0)
; #define PG8_LDA(dst, b, h) do { _Pragma("unroll") for (int m = 0; m < 4; ++m) _Pragma("unroll") for (int k = 0; k < 2; ++k) dst[m][k] = *(const PG8_LAS bf16x8*)(lds + PG8_SA(b, h) + aoff + m * 2048 + k * 1024); } while (0)
; #define PG8_LDB(dst, b, h) do { _Pragma("unroll") for (int n = 0; n < 2; ++n) _Pragma("unroll") for (int k = 0; k < 2; ++k) dst[n][k] = *(const PG8_LAS bf16x8*)(lds + PG8_SB(b, h) + boff + n * 2048 + k * 1024); } while (0)
; #define PG8_MMA(ai, bj, At, Bt) do { __builtin_amdgcn_s_setprio(1); _Pragma("unroll") for (int m = 0; m < 4; ++m) _Pragma("unroll") for (int n = 0; n < 2; ++n) _Pragma("unroll") for (int k = 0; k < 2; ++k) \
;         acc[ai][bj][m][n] = __builtin_amdgcn_mfma_f32_16x16x32_bf16(Bt[n][k], At[m][k], acc[ai][bj][m][n], 0, 0, 0); __builtin_amdgcn_s_setprio(0); } while (0)
; #define PG8_WAIT_V(n) asm volatile("s_waitcnt vmcnt(" #n ")" ::: "memory")
; #define PG8_WAIT_L(n) asm volatile("s_waitcnt lgkmcnt(" #n ")" ::: "memory")
; #define PG8_BAR __builtin_amdgcn_s_barrier()
; #define PG8_SCHED __builtin_amdgcn_sched_barrier(0)
; template <class Epi, class Sched, bool ALIGN_EPI = false, bool SP2 = false>
; __device__ __forceinline__ void gemm_phase(PG8_LAS unsigned char* lds, const Gemm g, const Sched& S, const Epi& E) {
;     ...
;             PG8_WAIT_V(8); PG8_WAIT_L(0); PG8_BAR; PG8_MMA(1, 0, At, B0); PG8_MMA(1, 1, At, B1); PG8_BAR; PG8_SCHED;
;             PG8_LDB(B0, 1, 0); PG8_LDB(B1, 1, 1); PG8_SCHED; PG8_LDA(At, 1, 0); PG8_STAGE(PG8_SA(0, 1), a2 + hstep, voffA);
;             PG8_WAIT_V(8); PG8_WAIT_L(0); PG8_BAR; PG8_MMA(0, 0, At, B0); PG8_MMA(0, 1, At, B1); PG8_BAR; PG8_SCHED;
	s_waitcnt lgkmcnt(0)
	v_mfma_f32_16x16x32_bf16 v[12:15], v[148:151], v[182:185], v[12:15]
	v_mfma_f32_16x16x32_bf16 v[124:127], v[156:159], v[182:185], v[124:127]
	v_mfma_f32_16x16x32_bf16 v[8:11], v[148:151], v[190:193], v[8:11]
	v_mfma_f32_16x16x32_bf16 v[120:123], v[156:159], v[190:193], v[120:123]
	v_mfma_f32_16x16x32_bf16 v[4:7], v[148:151], v[204:207], v[4:7]
	v_mfma_f32_16x16x32_bf16 v[116:119], v[156:159], v[204:207], v[116:119]
	v_mfma_f32_16x16x32_bf16 v[0:3], v[148:151], v[212:215], v[0:3]
	v_mfma_f32_16x16x32_bf16 v[112:115], v[156:159], v[212:215], v[112:115]
	v_mfma_f32_16x16x32_bf16 v[12:15], v[152:155], v[186:189], v[12:15]
	v_mfma_f32_16x16x32_bf16 v[124:127], v[160:163], v[186:189], v[124:127]
	v_mfma_f32_16x16x32_bf16 v[8:11], v[152:155], v[194:197], v[8:11]
	v_mfma_f32_16x16x32_bf16 v[120:123], v[160:163], v[194:197], v[120:123]
	v_mfma_f32_16x16x32_bf16 v[4:7], v[152:155], v[208:211], v[4:7]
	v_mfma_f32_16x16x32_bf16 v[116:119], v[160:163], v[208:211], v[116:119]
	v_mfma_f32_16x16x32_bf16 v[0:3], v[152:155], v[236:239], v[0:3]
	v_mfma_f32_16x16x32_bf16 v[112:115], v[160:163], v[236:239], v[112:115]
	v_mfma_f32_16x16x32_bf16 v[76:79], v[166:169], v[182:185], v[76:79]
	v_mfma_f32_16x16x32_bf16 v[72:75], v[174:177], v[182:185], v[72:75]
	v_mfma_f32_16x16x32_bf16 v[68:71], v[166:169], v[190:193], v[68:71]
	v_mfma_f32_16x16x32_bf16 v[64:67], v[174:177], v[190:193], v[64:67]
	v_mfma_f32_16x16x32_bf16 v[60:63], v[166:169], v[204:207], v[60:63]
	v_mfma_f32_16x16x32_bf16 v[56:59], v[174:177], v[204:207], v[56:59]
	v_mfma_f32_16x16x32_bf16 v[52:55], v[166:169], v[212:215], v[52:55]
	v_mfma_f32_16x16x32_bf16 v[48:51], v[174:177], v[212:215], v[48:51]
	v_mfma_f32_16x16x32_bf16 v[76:79], v[170:173], v[186:189], v[76:79]
	v_mfma_f32_16x16x32_bf16 v[72:75], v[178:181], v[186:189], v[72:75]
	v_mfma_f32_16x16x32_bf16 v[68:71], v[170:173], v[194:197], v[68:71]
	v_mfma_f32_16x16x32_bf16 v[64:67], v[178:181], v[194:197], v[64:67]
	v_mfma_f32_16x16x32_bf16 v[60:63], v[170:173], v[208:211], v[60:63]
	v_mfma_f32_16x16x32_bf16 v[56:59], v[178:181], v[208:211], v[56:59]
	v_mfma_f32_16x16x32_bf16 v[52:55], v[170:173], v[236:239], v[52:55]
	v_mfma_f32_16x16x32_bf16 v[48:51], v[178:181], v[236:239], v[48:51]
	s_barrier
	s_add_i32 s37, 0, 0x18000
	s_add_i32 s40, 0, 0x1c000
	v_add_u32_e32 v160, s37, v164
	v_add_u32_e32 v178, s40, v164
	ds_read_b128 v[148:151], v160
	ds_read_b128 v[152:155], v160 offset:1024
	ds_read_b128 v[156:159], v160 offset:2048
	ds_read_b128 v[160:163], v160 offset:3072
	ds_read_b128 v[166:169], v178
	ds_read_b128 v[170:173], v178 offset:1024
	ds_read_b128 v[174:177], v178 offset:2048
	ds_read_b128 v[178:181], v178 offset:3072
	s_add_u32 s0, s0, s34
	s_addc_u32 s1, s1, s35
	s_mov_b32 m0, s88
	v_lshl_add_u64 v[250:251], s[0:1], 0, v[38:39]
	ds_read_b128 v[182:185], v165 offset:32768
	ds_read_b128 v[186:189], v165 offset:33792
	ds_read_b128 v[190:193], v165 offset:34816
	ds_read_b128 v[194:197], v165 offset:35840
	ds_read_b128 v[204:207], v165 offset:36864
	ds_read_b128 v[208:211], v165 offset:37888
	ds_read_b128 v[212:215], v165 offset:38912
	ds_read_b128 v[236:239], v165 offset:39936
	global_load_lds_dwordx4 v[250:251], off
	v_lshl_add_u64 v[250:251], s[0:1], 0, v[140:141]
	s_mov_b32 m0, s89
	s_nop 0
	global_load_lds_dwordx4 v[250:251], off
	s_waitcnt vmcnt(8)
	s_waitcnt lgkmcnt(0)
	s_barrier
	s_waitcnt lgkmcnt(0)
	v_mfma_f32_16x16x32_bf16 v[28:31], v[148:151], v[182:185], v[28:31]
	v_mfma_f32_16x16x32_bf16 v[32:35], v[156:159], v[182:185], v[32:35]
	v_mfma_f32_16x16x32_bf16 v[24:27], v[148:151], v[190:193], v[24:27]
	v_mfma_f32_16x16x32_bf16 v[136:139], v[156:159], v[190:193], v[136:139]
	v_mfma_f32_16x16x32_bf16 v[20:23], v[148:151], v[204:207], v[20:23]
	v_mfma_f32_16x16x32_bf16 v[132:135], v[156:159], v[204:207], v[132:135]
	v_mfma_f32_16x16x32_bf16 v[16:19], v[148:151], v[212:215], v[16:19]
	v_mfma_f32_16x16x32_bf16 v[128:131], v[156:159], v[212:215], v[128:131]
	v_mfma_f32_16x16x32_bf16 v[28:31], v[152:155], v[186:189], v[28:31]
	v_mfma_f32_16x16x32_bf16 v[32:35], v[160:163], v[186:189], v[32:35]
	v_mfma_f32_16x16x32_bf16 v[24:27], v[152:155], v[194:197], v[24:27]
	v_mfma_f32_16x16x32_bf16 v[136:139], v[160:163], v[194:197], v[136:139]
	v_mfma_f32_16x16x32_bf16 v[20:23], v[152:155], v[208:211], v[20:23]
	v_mfma_f32_16x16x32_bf16 v[132:135], v[160:163], v[208:211], v[132:135]
	v_mfma_f32_16x16x32_bf16 v[16:19], v[152:155], v[236:239], v[16:19]
	v_mfma_f32_16x16x32_bf16 v[128:131], v[160:163], v[236:239], v[128:131]
	v_mfma_f32_16x16x32_bf16 v[108:111], v[166:169], v[182:185], v[108:111]
	v_mfma_f32_16x16x32_bf16 v[104:107], v[174:177], v[182:185], v[104:107]
	v_mfma_f32_16x16x32_bf16 v[100:103], v[166:169], v[190:193], v[100:103]
	v_mfma_f32_16x16x32_bf16 v[96:99], v[174:177], v[190:193], v[96:99]
	v_mfma_f32_16x16x32_bf16 v[92:95], v[166:169], v[204:207], v[92:95]
	v_mfma_f32_16x16x32_bf16 v[88:91], v[174:177], v[204:207], v[88:91]
	v_mfma_f32_16x16x32_bf16 v[84:87], v[166:169], v[212:215], v[84:87]
	v_mfma_f32_16x16x32_bf16 v[80:83], v[174:177], v[212:215], v[80:83]
	v_mfma_f32_16x16x32_bf16 v[108:111], v[170:173], v[186:189], v[108:111]
	v_mfma_f32_16x16x32_bf16 v[104:107], v[178:181], v[186:189], v[104:107]
	v_mfma_f32_16x16x32_bf16 v[100:103], v[170:173], v[194:197], v[100:103]
	v_mfma_f32_16x16x32_bf16 v[96:99], v[178:181], v[194:197], v[96:99]
	v_mfma_f32_16x16x32_bf16 v[92:95], v[170:173], v[208:211], v[92:95]
	v_mfma_f32_16x16x32_bf16 v[88:91], v[178:181], v[208:211], v[88:91]
	v_mfma_f32_16x16x32_bf16 v[84:87], v[170:173], v[236:239], v[84:87]
	v_mfma_f32_16x16x32_bf16 v[80:83], v[178:181], v[236:239], v[80:83]
	s_barrier
; #define PG8_STAGE(bufoff, gbase, voff) do { _Pragma("unroll") for (int _i = 0; _i < 2; ++_i) \
;         __builtin_amdgcn_global_load_lds((const unsigned*)((const char*)(gbase) + (voff)[_i]), (PG8_LAS unsigned*)(lds + (bufoff) + ldsw + _i * 8192), 16, 0, 0); } while (0)
; #define PG8_LDA(dst, b, h) do { _Pragma("unroll") for (int m = 0; m < 4; ++m) _Pragma("unroll") for (int k = 0; k < 2; ++k) dst[m][k] = *(const PG8_LAS bf16x8*)(lds + PG8_SA(b, h) + aoff + m * 2048 + k * 1024); } while (0)
; #define PG8_MMA(ai, bj, At, Bt) do { __builtin_amdgcn_s_setprio(1); _Pragma("unroll") for (int m = 0; m < 4; ++m) _Pragma("unroll") for (int n = 0; n < 2; ++n) _Pragma("unroll") for (int k = 0; k < 2; ++k) \
;         acc[ai][bj][m][n] = __builtin_amdgcn_mfma_f32_16x16x32_bf16(Bt[n][k], At[m][k], acc[ai][bj][m][n], 0, 0, 0); __builtin_amdgcn_s_setprio(0); } while (0)
; #define PG8_WAIT_V(n) asm volatile("s_waitcnt vmcnt(" #n ")" ::: "memory")
; #define PG8_WAIT_L(n) asm volatile("s_waitcnt lgkmcnt(" #n ")" ::: "memory")
; #define PG8_BAR __builtin_amdgcn_s_barrier()
; #define PG8_SCHED __builtin_amdgcn_sched_barrier(0)
; template <class Epi, class Sched, bool ALIGN_EPI = false, bool SP2 = false>
; __device__ __forceinline__ void gemm_phase(PG8_LAS unsigned char* lds, const Gemm g, const Sched& S, const Epi& E) {
;     ...
;         for (int t = 0; t < nt; t += 2) {
;     ...
;             PG8_LDA(At, 1, 1); PG8_STAGE(PG8_SB(1, 0), b3, voffB); PG8_STAGE(PG8_SB(1, 1), b3 + hstep, voffB); PG8_STAGE(PG8_SA(1, 0), a3, voffA);
;             PG8_WAIT_V(8); PG8_WAIT_L(0); PG8_BAR; PG8_MMA(1, 0, At, B0); PG8_MMA(1, 1, At, B1); PG8_BAR; PG8_SCHED;
	s_add_i32 s0, s37, s13
	v_lshl_add_u64 v[198:199], v[198:199], 0, s[22:23]
	s_mov_b32 m0, s0
	ds_read_b128 v[182:185], v165 offset:49152
	ds_read_b128 v[186:189], v165 offset:50176
	ds_read_b128 v[190:193], v165 offset:51200
	ds_read_b128 v[194:197], v165 offset:52224
	ds_read_b128 v[204:207], v165 offset:53248
	ds_read_b128 v[208:211], v165 offset:54272
	ds_read_b128 v[212:215], v165 offset:55296
	ds_read_b128 v[236:239], v165 offset:56320
	global_load_lds_dwordx4 v[198:199], off
	v_lshl_add_u64 v[198:199], v[240:241], 0, s[22:23]
	s_add_i32 m0, s0, 0x2000
	s_add_i32 s0, s40, s13
	global_load_lds_dwordx4 v[198:199], off
	v_lshl_add_u64 v[198:199], v[242:243], 0, s[22:23]
	s_mov_b32 m0, s0
	s_nop 0
	global_load_lds_dwordx4 v[198:199], off
	v_lshl_add_u64 v[198:199], v[244:245], 0, s[22:23]
	s_add_i32 m0, s0, 0x2000
	s_nop 0
	global_load_lds_dwordx4 v[198:199], off
	v_lshl_add_u64 v[198:199], v[246:247], 0, s[22:23]
	s_mov_b32 m0, s42
	s_nop 0
	global_load_lds_dwordx4 v[198:199], off
	v_lshl_add_u64 v[198:199], v[248:249], 0, s[22:23]
	s_mov_b32 m0, s43
	s_nop 0
	global_load_lds_dwordx4 v[198:199], off
	s_waitcnt vmcnt(8)
	s_waitcnt lgkmcnt(0)
	s_barrier
	s_waitcnt lgkmcnt(0)
	v_mfma_f32_16x16x32_bf16 v[12:15], v[148:151], v[182:185], v[12:15]
	v_mfma_f32_16x16x32_bf16 v[124:127], v[156:159], v[182:185], v[124:127]
	v_mfma_f32_16x16x32_bf16 v[8:11], v[148:151], v[190:193], v[8:11]
	v_mfma_f32_16x16x32_bf16 v[120:123], v[156:159], v[190:193], v[120:123]
	v_mfma_f32_16x16x32_bf16 v[4:7], v[148:151], v[204:207], v[4:7]
	v_mfma_f32_16x16x32_bf16 v[116:119], v[156:159], v[204:207], v[116:119]
	v_mfma_f32_16x16x32_bf16 v[0:3], v[148:151], v[212:215], v[0:3]
	v_mfma_f32_16x16x32_bf16 v[112:115], v[156:159], v[212:215], v[112:115]
	v_mfma_f32_16x16x32_bf16 v[12:15], v[152:155], v[186:189], v[12:15]
	v_mfma_f32_16x16x32_bf16 v[124:127], v[160:163], v[186:189], v[124:127]
	v_mfma_f32_16x16x32_bf16 v[8:11], v[152:155], v[194:197], v[8:11]
	v_mfma_f32_16x16x32_bf16 v[120:123], v[160:163], v[194:197], v[120:123]
	v_mfma_f32_16x16x32_bf16 v[4:7], v[152:155], v[208:211], v[4:7]
	v_mfma_f32_16x16x32_bf16 v[116:119], v[160:163], v[208:211], v[116:119]
	v_mfma_f32_16x16x32_bf16 v[0:3], v[152:155], v[236:239], v[0:3]
	v_mfma_f32_16x16x32_bf16 v[112:115], v[160:163], v[236:239], v[112:115]
	v_mfma_f32_16x16x32_bf16 v[76:79], v[166:169], v[182:185], v[76:79]
	v_mfma_f32_16x16x32_bf16 v[72:75], v[174:177], v[182:185], v[72:75]
	v_mfma_f32_16x16x32_bf16 v[68:71], v[166:169], v[190:193], v[68:71]
	v_mfma_f32_16x16x32_bf16 v[64:67], v[174:177], v[190:193], v[64:67]
	v_mfma_f32_16x16x32_bf16 v[60:63], v[166:169], v[204:207], v[60:63]
	v_mfma_f32_16x16x32_bf16 v[56:59], v[174:177], v[204:207], v[56:59]
	v_mfma_f32_16x16x32_bf16 v[52:55], v[166:169], v[212:215], v[52:55]
	v_mfma_f32_16x16x32_bf16 v[48:51], v[174:177], v[212:215], v[48:51]
	v_mfma_f32_16x16x32_bf16 v[76:79], v[170:173], v[186:189], v[76:79]
	v_mfma_f32_16x16x32_bf16 v[72:75], v[178:181], v[186:189], v[72:75]
	v_mfma_f32_16x16x32_bf16 v[68:71], v[170:173], v[194:197], v[68:71]
	v_mfma_f32_16x16x32_bf16 v[64:67], v[178:181], v[194:197], v[64:67]
	v_mfma_f32_16x16x32_bf16 v[60:63], v[170:173], v[208:211], v[60:63]
	v_mfma_f32_16x16x32_bf16 v[56:59], v[178:181], v[208:211], v[56:59]
	v_mfma_f32_16x16x32_bf16 v[52:55], v[170:173], v[236:239], v[52:55]
	v_mfma_f32_16x16x32_bf16 v[48:51], v[178:181], v[236:239], v[48:51]
	s_barrier
	s_add_u32 s24, s24, 0x100
	s_addc_u32 s25, s25, 0
	s_add_u32 s18, s18, 0x100
	s_addc_u32 s19, s19, 0
	s_cmp_ge_i32 s36, s10
	s_mov_b32 s0, s36
	s_cbranch_scc0 .LBB0_753
